# all packed-f32 VALU ops with register operands (v_pk_mul/add/fma_f32, 1356 of them) split into two scalar f32 ops
# speedup vs baseline: 1.0078x; 1.0078x over previous
.LBB0_85:
	v_add_co_u32_e64 v54, s[2:3], s10, v28
	v_add_co_u32_e32 v32, vcc, 0xfffa6000, v28
	s_nop 0
	v_addc_co_u32_e64 v55, s[2:3], -1, v29, s[2:3]
	v_add_co_u32_e64 v56, s[2:3], s11, v28
	v_addc_co_u32_e32 v33, vcc, -1, v29, vcc
	s_nop 0
	v_addc_co_u32_e64 v57, s[2:3], -1, v29, s[2:3]
	v_add_co_u32_e64 v58, s[2:3], s12, v28
	ds_read_b128 v[20:23], v27
	ds_read_b128 v[16:19], v27 offset:16
	ds_read_b128 v[12:15], v27 offset:32
	ds_read_b128 v[8:11], v27 offset:48
	ds_read_b128 v[0:3], v27 offset:4112
	ds_read_b128 v[4:7], v27 offset:4096
	v_addc_co_u32_e64 v59, s[2:3], -1, v29, s[2:3]
	v_add_co_u32_e64 v60, s[2:3], s13, v28
	ds_read_b128 v[42:45], v27 offset:4128
	ds_read_b128 v[46:49], v27 offset:4144
	v_addc_co_u32_e64 v61, s[2:3], -1, v29, s[2:3]
	v_add_co_u32_e64 v62, s[2:3], s14, v28
	ds_read_b96 v[50:52], v27 offset:8192
	ds_read_b32 v41, v27 offset:8252
	v_addc_co_u32_e64 v63, s[2:3], -1, v29, s[2:3]
	v_add_co_u32_e64 v64, s[2:3], s15, v28
	global_load_dword v74, v[28:29], off
	s_nop 0
	v_addc_co_u32_e64 v65, s[2:3], -1, v29, s[2:3]
	v_add_co_u32_e64 v66, s[2:3], s17, v28
	global_load_dword v61, v[60:61], off
	s_nop 0
	global_load_dword v62, v[62:63], off
	s_nop 0
	global_load_dword v60, v[58:59], off
	s_nop 0
	global_load_dword v57, v[56:57], off
	v_addc_co_u32_e64 v67, s[2:3], -1, v29, s[2:3]
	v_add_co_u32_e64 v68, s[2:3], s18, v28
	global_load_dword v63, v[64:65], off
	global_load_dword v58, v[66:67], off
	v_addc_co_u32_e64 v69, s[2:3], -1, v29, s[2:3]
	v_add_co_u32_e32 v64, vcc, 0xfffac000, v28
	v_add_co_u32_e64 v70, s[2:3], s19, v28
	s_nop 0
	v_addc_co_u32_e32 v65, vcc, -1, v29, vcc
	v_addc_co_u32_e64 v71, s[2:3], -1, v29, s[2:3]
	global_load_dword v59, v[68:69], off
	global_load_dword v66, v[70:71], off
	global_load_dword v56, v[54:55], off
	s_nop 0
	global_load_dword v32, v[32:33], off
	v_add_co_u32_e32 v54, vcc, 0xfffb2000, v28
	global_load_dword v64, v[64:65], off
	s_nop 0
	v_addc_co_u32_e32 v55, vcc, -1, v29, vcc
	v_add_co_u32_e32 v68, vcc, 0xfffb8000, v28
	v_add_co_u32_e64 v72, s[2:3], s20, v28
	s_nop 0
	v_addc_co_u32_e32 v69, vcc, -1, v29, vcc
	v_add_co_u32_e32 v70, vcc, 0xfffbe000, v28
	global_load_dword v54, v[54:55], off
	s_nop 0
	global_load_dword v68, v[68:69], off
	v_addc_co_u32_e32 v71, vcc, -1, v29, vcc
	v_addc_co_u32_e64 v73, s[2:3], -1, v29, s[2:3]
	global_load_dword v70, v[70:71], off
	s_nop 0
	global_load_dword v67, v[72:73], off
	v_add_u32_e32 v33, 0x201c, v27
	s_waitcnt lgkmcnt(9)
	v_mov_b32_e32 v86, v20
	s_waitcnt lgkmcnt(4)
	v_mov_b32_e32 v87, v4
	v_add_u32_e32 v53, 0x200c, v27
	v_add_u32_e32 v65, 0x202c, v27
	v_mov_b32_e32 v4, v21
	v_add_u32_e32 v75, 0x2014, v27
	v_add_u32_e32 v55, 0x2024, v27
	v_add_u32_e32 v69, 0x2034, v27
	ds_read2_b32 v[72:73], v53 offset1:1
	ds_read2_b32 v[76:77], v75 offset1:1
	ds_read2_b32 v[78:79], v33 offset1:1
	ds_read2_b32 v[80:81], v55 offset1:1
	ds_read2_b32 v[82:83], v65 offset1:1
	ds_read2_b32 v[84:85], v69 offset1:1
	v_mov_b32_e32 v20, v22
	v_mov_b32_e32 v21, v6
	v_mov_b32_e32 v6, v23
	v_mov_b32_e32 v22, v16
	v_mov_b32_e32 v23, v0
	v_mov_b32_e32 v0, v17
	v_mov_b32_e32 v16, v18
	v_mov_b32_e32 v17, v2
	v_mov_b32_e32 v2, v19
	v_mov_b32_e32 v18, v12
	s_waitcnt lgkmcnt(9)
	v_mov_b32_e32 v19, v42
	v_mov_b32_e32 v42, v13
	v_mov_b32_e32 v12, v14
	v_mov_b32_e32 v13, v44
	v_mov_b32_e32 v44, v15
	v_mov_b32_e32 v14, v8
	s_waitcnt lgkmcnt(8)
	v_mov_b32_e32 v15, v46
	v_mov_b32_e32 v46, v9
	v_mov_b32_e32 v8, v10
	v_mov_b32_e32 v9, v48
	v_mov_b32_e32 v48, v11
	v_add_u32_e32 v39, -16, v39
	v_cmp_eq_u32_e32 vcc, 0, v39
	v_add_u32_e32 v27, 64, v27
	s_or_b64 s[6:7], vcc, s[6:7]
	v_lshl_add_u64 v[28:29], v[28:29], 0, s[4:5]
	s_waitcnt vmcnt(14)
	v_mov_b32_e32 v88, v61
	s_waitcnt vmcnt(12) lgkmcnt(3)
	v_mul_f32_e32 v10, v60, v78
	v_mul_f32_e32 v11, v61, v79
	s_waitcnt vmcnt(10) lgkmcnt(2)
	v_mul_f32_e32 v78, v62, v80
	v_mul_f32_e32 v79, v63, v81
	v_mov_b32_e32 v90, v63
	s_waitcnt vmcnt(8) lgkmcnt(1)
	v_mul_f32_e32 v80, v58, v82
	v_mul_f32_e32 v81, v59, v83
	v_mov_b32_e32 v92, v59
	s_waitcnt vmcnt(6)
	v_mul_f32_e32 v76, v56, v76
	v_mul_f32_e32 v77, v57, v77
	s_waitcnt vmcnt(5)
	v_fma_f32 v30, v32, v86, v30
	v_fma_f32 v31, v32, v87, v31
	v_fmac_f32_e32 v40, v32, v50
	s_waitcnt vmcnt(4)
	v_fma_f32 v4, v64, v4, v30
	v_fma_f32 v5, v64, v5, v31
	v_fmac_f32_e32 v40, v64, v51
	s_waitcnt vmcnt(3)
	v_fma_f32 v4, v54, v20, v4
	v_fma_f32 v5, v54, v21, v5
	s_waitcnt vmcnt(2)
	v_fma_f32 v4, v68, v6, v4
	v_fma_f32 v5, v68, v7, v5
	v_fmac_f32_e32 v40, v54, v52
	s_waitcnt vmcnt(1)
	v_fma_f32 v4, v70, v22, v4
	v_fma_f32 v5, v70, v23, v5
	v_mov_b32_e32 v69, v70
	v_fma_f32 v0, v56, v0, v4
	v_fma_f32 v1, v56, v1, v5
	v_mul_f32_e32 v4, v68, v72
	v_mul_f32_e32 v5, v69, v73
	s_waitcnt vmcnt(0) lgkmcnt(0)
	v_mul_f32_e32 v82, v66, v84
	v_mul_f32_e32 v83, v67, v85
	v_mov_b32_e32 v84, v57
	v_add_f32_e32 v4, v40, v4
	v_fma_f32 v0, v84, v16, v0
	v_fma_f32 v1, v84, v17, v1
	v_add_f32_e32 v4, v4, v5
	v_fma_f32 v0, v60, v2, v0
	v_fma_f32 v1, v60, v3, v1
	v_add_f32_e32 v2, v4, v76
	v_fma_f32 v0, v88, v18, v0
	v_fma_f32 v1, v88, v19, v1
	v_add_f32_e32 v2, v2, v77
	v_fma_f32 v0, v62, v42, v0
	v_fma_f32 v1, v62, v43, v1
	v_add_f32_e32 v2, v2, v10
	v_fma_f32 v0, v90, v12, v0
	v_fma_f32 v1, v90, v13, v1
	v_add_f32_e32 v2, v2, v11
	v_fma_f32 v0, v58, v44, v0
	v_fma_f32 v1, v58, v45, v1
	v_add_f32_e32 v2, v2, v78
	v_fma_f32 v0, v92, v14, v0
	v_fma_f32 v1, v92, v15, v1
	v_add_f32_e32 v2, v2, v79
	v_mov_b32_e32 v94, v67
	v_fma_f32 v0, v66, v46, v0
	v_fma_f32 v1, v66, v47, v1
	v_add_f32_e32 v2, v2, v80
	v_fma_f32 v0, v94, v8, v0
	v_fma_f32 v1, v94, v9, v1
	v_add_f32_e32 v2, v2, v81
	v_fma_f32 v30, v74, v48, v0
	v_fma_f32 v31, v74, v49, v1
	v_add_f32_e32 v0, v2, v82
	v_add_f32_e32 v40, v0, v83
	v_fmac_f32_e32 v40, v74, v41
	s_andn2_b64 exec, exec, s[6:7]
	s_cbranch_execnz .LBB0_85
	s_or_b64 exec, exec, s[6:7]
	v_add_u32_e32 v0, 0x3000, v38
	s_barrier
	ds_write2_b32 v0, v30, v31 offset1:1
	ds_write_b32 v38, v40 offset:12296
	s_waitcnt lgkmcnt(0)
	s_barrier
	s_and_saveexec_b64 s[2:3], s[0:1]
	s_cbranch_execz .LBB0_83
	s_load_dwordx16 s[36:51], s[78:79], 0x0
	s_mul_i32 s6, s22, 0x1800
	v_add_u32_e32 v2, s6, v26
	v_ashrrev_i32_e32 v3, 31, v2
	v_add_u32_e32 v8, 0x3300, v38
	s_waitcnt lgkmcnt(0)
	v_lshl_add_u64 v[4:5], v[2:3], 2, s[46:47]
	global_load_dword v32, v[4:5], off
	ds_read2_b32 v[4:5], v0 offset1:1
	ds_read2_b32 v[0:1], v0 offset0:2 offset1:98
	v_add_u32_e32 v3, 0x3180, v38
	v_add_u32_e32 v10, 0x3480, v38
	v_add_u32_e32 v12, 0x3600, v38
	v_add_u32_e32 v14, 0x3780, v38
	v_add_u32_e32 v16, 0x3900, v38
	v_add_u32_e32 v18, 0x3a80, v38
	v_add_u32_e32 v20, 0x3200, v38
	v_add_u32_e32 v22, 0x3400, v38
	v_add_u32_e32 v26, 0x3800, v38
	ds_read2_b32 v[6:7], v3 offset1:1
	ds_read2_b32 v[8:9], v8 offset1:1
	ds_read2_b32 v[10:11], v10 offset1:1
	ds_read2_b32 v[12:13], v12 offset1:1
	ds_read2_b32 v[14:15], v14 offset1:1
	ds_read2_b32 v[16:17], v16 offset1:1
	ds_read2_b32 v[18:19], v18 offset1:1
	ds_read2_b32 v[20:21], v20 offset0:66 offset1:162
	ds_read2_b32 v[22:23], v22 offset0:130 offset1:226
	ds_read2_b32 v[26:27], v26 offset0:66 offset1:162
	s_waitcnt lgkmcnt(11)
	v_add_f32_e32 v33, 0, v4
	v_add_f32_e32 v39, 0, v5
	s_waitcnt lgkmcnt(10)
	v_add_f32_e32 v0, 0, v0
	s_waitcnt lgkmcnt(9)
	v_add_f32_e32 v6, v33, v6
	v_add_f32_e32 v7, v39, v7
	v_add_f32_e32 v0, v0, v1
	s_waitcnt lgkmcnt(8)
	v_add_f32_e32 v1, v6, v8
	v_add_f32_e32 v6, v7, v9
	s_waitcnt lgkmcnt(2)
	v_add_f32_e32 v0, v0, v20
	v_add_f32_e32 v1, v1, v10
	v_add_f32_e32 v6, v6, v11
	v_add_f32_e32 v0, v0, v21
	v_add_f32_e32 v1, v1, v12
	s_mulk_i32 s22, 0x3000
	v_add_f32_e32 v6, v6, v13
	s_waitcnt lgkmcnt(1)
	v_add_f32_e32 v0, v0, v22
	v_add_f32_e32 v1, v1, v14
	v_add_u32_e32 v2, s22, v2
	v_add_f32_e32 v6, v6, v15
	v_add_f32_e32 v0, v0, v23
	v_add_f32_e32 v1, v1, v16
	v_ashrrev_i32_e32 v3, 31, v2
	v_add_u32_e32 v28, 0x1800, v2
	v_add_u32_e32 v30, 0x3000, v2
	v_add_f32_e32 v6, v6, v17
	s_waitcnt lgkmcnt(0)
	v_add_f32_e32 v0, v0, v26
	v_add_f32_e32 v1, v1, v18
	v_lshl_add_u64 v[2:3], v[2:3], 2, s[94:95]
	v_ashrrev_i32_e32 v29, 31, v28
	v_ashrrev_i32_e32 v31, 31, v30
	v_add_f32_e32 v6, v6, v19
	v_add_f32_e32 v0, v0, v27
	v_lshl_add_u64 v[4:5], v[28:29], 2, s[94:95]
	v_lshl_add_u64 v[28:29], v[30:31], 2, s[94:95]
	s_waitcnt vmcnt(0)
	v_add_f32_e32 v1, v32, v1
	v_add_f32_e32 v6, v32, v6
	v_add_f32_e32 v0, v32, v0
	global_store_dword v[2:3], v1, off
	global_store_dword v[4:5], v6, off
	global_store_dword v[28:29], v0, off
	s_branch .LBB0_83
.LBB0_88:
	v_lshl_add_u32 v0, s74, 8, v144
	s_mov_b32 s0, 0x40000
	v_cmp_gt_i32_e32 vcc, s0, v0
	s_and_saveexec_b64 s[10:11], vcc
	s_cbranch_execz .LBB0_103
	v_and_b32_e32 v1, 15, v144
	v_cvt_f32_ubyte0_e32 v1, v1
	v_mul_f32_e32 v1, 0xbd800000, v1
	v_mov_b32_e32 v2, 0x461c4000
	v_cmp_eq_f32_e32 vcc, 0, v1
	s_mov_b32 s0, 0x3f2aaaab
	s_movk_i32 s2, 0x204
	v_cndmask_b32_e64 v12, v2, 1.0, vcc
	v_frexp_mant_f32_e32 v2, v12
	v_cmp_gt_f32_e64 s[0:1], s0, v2
	s_mov_b32 s4, 0x42b17218
	s_mov_b32 s3, 0x7f800000
	v_cndmask_b32_e64 v3, 1.0, 2.0, s[0:1]
	v_mul_f32_e32 v2, v2, v3
	v_add_f32_e32 v5, 1.0, v2
	v_rcp_f32_e32 v10, v5
	v_add_f32_e32 v3, -1.0, v5
	v_sub_f32_e32 v7, v2, v3
	v_add_f32_e32 v3, -1.0, v2
	v_mul_f32_e32 v11, v3, v10
	v_mul_f32_e32 v4, v5, v11
	v_fma_f32 v6, v11, v5, -v4
	v_fmac_f32_e32 v6, v11, v7
	v_add_f32_e32 v2, v4, v6
	v_sub_f32_e32 v5, v3, v2
	v_add_f32_e64 v8, v2, -v4
	v_add_f32_e64 v9, v3, -v5
	v_mov_b32_e32 v7, v2
	v_add_f32_e64 v2, v8, -v6
	v_add_f32_e64 v3, v9, -v7
	v_mov_b32_e32 v6, 0x3e91f4c4
	v_add_f32_e32 v2, v2, v3
	v_add_f32_e32 v2, v5, v2
	v_mul_f32_e32 v3, v10, v2
	v_add_f32_e32 v2, v11, v3
	v_sub_f32_e32 v4, v2, v11
	v_sub_f32_e32 v13, v3, v4
	v_mul_f32_e32 v3, v2, v2
	v_fma_f32 v5, v2, v2, -v3
	v_add_f32_e32 v4, v13, v13
	v_fmac_f32_e32 v5, v2, v4
	v_add_f32_e32 v4, v3, v5
	v_fmac_f32_e32 v6, 0x3e76c4e1, v4
	v_fmaak_f32 v6, v4, v6, 0x3ecccdef
	v_sub_f32_e32 v3, v4, v3
	v_sub_f32_e32 v14, v5, v3
	v_mul_f32_e32 v3, v4, v6
	v_fma_f32 v5, v4, v6, -v3
	v_fmac_f32_e32 v5, v14, v6
	v_add_f32_e32 v6, v3, v5
	v_add_f32_e32 v7, 0x3f2aaaaa, v6
	v_sub_f32_e32 v3, v6, v3
	v_sub_f32_e32 v3, v5, v3
	v_add_f32_e32 v5, 0xbf2aaaaa, v7
	v_add_f32_e32 v3, 0x31739010, v3
	v_sub_f32_e32 v5, v6, v5
	v_mul_f32_e32 v8, v2, v4
	v_mul_f32_e32 v9, v3, v5
	v_add_f32_e32 v10, v2, v4
	v_add_f32_e32 v11, v3, v5
	v_fma_f32 v6, v4, v2, -v8
	v_fmac_f32_e32 v6, v4, v13
	v_mov_b32_e32 v9, v11
	v_fmac_f32_e32 v6, v14, v2
	v_add_f32_e32 v4, v8, v6
	v_add_f32_e32 v5, v9, v7
	v_ldexp_f32 v14, v13, 1
	v_sub_f32_e32 v3, v4, v8
	v_sub_f32_e32 v3, v6, v3
	v_sub_f32_e32 v6, v7, v5
	v_add_f32_e32 v9, v11, v6
	v_mul_f32_e32 v6, v4, v5
	v_mul_f32_e32 v7, v5, v4
	v_cvt_f64_f32_e32 v[10:11], v12
	v_frexp_exp_i32_f64_e32 v7, v[10:11]
	v_subbrev_co_u32_e64 v7, s[0:1], 0, v7, s[0:1]
	v_cvt_f32_i32_e32 v7, v7
	v_fma_f32 v8, v4, v5, -v6
	v_fmac_f32_e32 v8, v4, v9
	s_mov_b32 s0, 0x3f317218
	v_mul_f32_e32 v4, 0x3f317218, v7
	v_fmac_f32_e32 v8, v3, v5
	v_fma_f32 v3, v7, s0, -v4
	v_fmamk_f32 v10, v7, 0xb102e308, v3
	v_ldexp_f32 v11, v2, 1
	v_add_f32_e32 v5, v6, v8
	v_add_f32_e32 v2, v4, v10
	v_add_f32_e32 v3, v5, v11
	v_mov_b32_e32 v12, v5
	v_mov_b32_e32 v13, v3
	v_mov_b32_e32 v7, v11
	v_add_f32_e64 v6, v12, -v6
	v_add_f32_e64 v7, v13, -v7
	v_mov_b32_e32 v9, v5
	v_add_f32_e64 v6, v8, -v6
	v_add_f32_e64 v7, v9, -v7
	v_mov_b32_e32 v11, v2
	v_add_f32_e32 v5, v14, v6
	v_add_f32_e32 v5, v5, v7
	v_add_f32_e64 v6, v2, -v4
	v_add_f32_e64 v7, v3, -v5
	v_add_f32_e32 v8, v2, v4
	v_add_f32_e32 v9, v3, v5
	v_mov_b32_e32 v4, v5
	v_mov_b32_e32 v7, v9
	v_add_f32_e64 v12, v10, -v6
	v_add_f32_e64 v13, v11, -v7
	v_add_f32_e32 v6, v10, v6
	v_add_f32_e32 v7, v11, v7
	v_mov_b32_e32 v5, v2
	v_add_f32_e64 v10, v7, -v2
	v_add_f32_e64 v11, v6, -v3
	v_add_f32_e64 v14, v8, -v10
	v_add_f32_e64 v15, v9, -v10
	v_mov_b32_e32 v8, v9
	v_mov_b32_e32 v9, v7
	v_pk_mov_b32 v[10:11], v[2:3], v[10:11] op_sel:[1,0]
	v_mov_b32_e32 v14, v12
	v_add_f32_e64 v8, v8, -v10
	v_add_f32_e64 v9, v9, -v11
	v_mov_b32_e32 v13, v7
	v_add_f32_e64 v2, v4, -v8
	v_add_f32_e64 v3, v5, -v9
	s_add_u32 s12, s94, 0x40000
	v_add_f32_e32 v4, v14, v2
	v_add_f32_e32 v5, v15, v3
	s_addc_u32 s13, s95, 0
	v_add_f32_e32 v8, v4, v5
	v_add_f32_e32 v9, v5, v4
	s_add_u32 s14, s94, 0x140000
	v_pk_add_f32 v[6:7], v[6:7], v[8:9] op_sel:[1,0] op_sel_hi:[0,1]
	v_mov_b32_e32 v5, v6
	v_add_f32_e64 v10, v4, -v12
	v_add_f32_e64 v11, v5, -v13
	v_mov_b32_e32 v3, v8
	v_sub_f32_e32 v4, v4, v10
	v_add_f32_e64 v2, v2, -v10
	v_add_f32_e64 v3, v3, -v11
	v_sub_f32_e32 v4, v12, v4
	v_add_f32_e32 v2, v2, v4
	v_add_f32_e32 v2, v2, v3
	v_add_f32_e32 v3, v6, v2
	v_sub_f32_e32 v4, v3, v6
	v_sub_f32_e32 v2, v2, v4
	v_mul_f32_e32 v4, v1, v3
	v_fma_f32 v3, v1, v3, -v4
	v_fmac_f32_e32 v3, v1, v2
	v_add_f32_e32 v2, v4, v3
	v_cmp_class_f32_e64 s[0:1], v4, s2
	v_sub_f32_e32 v5, v2, v4
	v_sub_f32_e32 v3, v3, v5
	v_cndmask_b32_e64 v2, v2, v4, s[0:1]
	v_mov_b32_e32 v4, 0x37000000
	v_cmp_eq_f32_e64 s[0:1], s4, v2
	s_addc_u32 s15, s95, 0
	s_waitcnt lgkmcnt(0)
	s_lshl_b32 s20, s16, 8
	v_cndmask_b32_e64 v4, 0, v4, s[0:1]
	v_sub_f32_e32 v5, v2, v4
	s_mov_b32 s0, 0x3fb8aa3b
	v_mul_f32_e32 v6, 0x3fb8aa3b, v5
	v_fma_f32 v7, v5, s0, -v6
	v_rndne_f32_e32 v8, v6
	v_fmamk_f32 v7, v5, 0x32a5705f, v7
	v_sub_f32_e32 v6, v6, v8
	v_add_f32_e32 v6, v6, v7
	v_exp_f32_e32 v6, v6
	v_cvt_i32_f32_e32 v7, v8
	v_cmp_neq_f32_e64 s[0:1], |v2|, s3
	s_mov_b64 s[16:17], 0
	s_brev_b32 s21, 18
	v_cndmask_b32_e64 v2, 0, v3, s[0:1]
	s_mov_b32 s0, 0xc2ce8ed0
	v_ldexp_f32 v3, v6, v7
	v_cmp_ngt_f32_e64 s[0:1], s0, v5
	v_add_f32_e32 v2, v4, v2
	v_mov_b32_e32 v4, 0x7f800000
	v_cndmask_b32_e64 v3, 0, v3, s[0:1]
	v_cmp_nlt_f32_e64 s[0:1], s4, v5
	s_mov_b32 s22, 0xfe5163ab
	s_mov_b32 s23, 0x3c439041
	v_cndmask_b32_e64 v3, v4, v3, s[0:1]
	v_fma_f32 v2, v3, v2, v3
	v_cmp_class_f32_e64 s[0:1], v3, s2
	s_mov_b32 s24, 0xdb629599
	s_mov_b32 s25, 0xf534ddc0
	v_cndmask_b32_e64 v2, v2, v3, s[0:1]
	v_cmp_neq_f32_e64 s[0:1], v1, |v1|
	s_mov_b32 s26, 0xfc2757d1
	s_mov_b32 s27, 0x4e441529
	v_cndmask_b32_e64 v3, v4, 0, s[0:1]
	v_cndmask_b32_e64 v3, v3, 1.0, vcc
	v_cmp_class_f32_e64 s[0:1], v1, s2
	s_mov_b32 s28, 0xa2f9836e
	s_mov_b32 s29, 0x3fc90fda
	v_cndmask_b32_e64 v4, |v2|, v3, s[0:1]
	v_mov_b32_e32 v3, 0
	s_mov_b32 s30, 0x3f22f983
	s_mov_b32 s31, 0xbfc90fda
	v_mov_b32_e32 v5, 0x3c0881c4
	v_mov_b32_e32 v6, 0xbab64f3b
	s_brev_b32 s33, 1
	s_movk_i32 s34, 0x1f8
	s_mov_b32 s35, 0x3ffff
	v_not_b32_e32 v7, 63
	v_not_b32_e32 v8, 31
	v_mov_b32_e32 v9, 0x7fc00000
	s_branch .LBB0_91

.LBB0_161:
	s_or_b64 exec, exec, s[10:11]
	v_ashrrev_i32_e32 v1, 31, v0
	v_lshlrev_b64 v[0:1], 12, v[0:1]
	v_lshl_add_u64 v[0:1], v[2:3], 0, v[0:1]
	v_lshl_add_u64 v[40:41], v[0:1], 0, v[4:5]
	global_load_dwordx4 v[28:31], v[40:41], off
	global_load_dwordx4 v[32:35], v[40:41], off offset:1024
	global_load_dwordx4 v[36:39], v[40:41], off offset:2048
	global_load_dwordx4 v[0:3], v[40:41], off offset:3072
	v_lshl_add_u64 v[18:19], s[94:95], 0, v[18:19]
	v_lshl_add_u64 v[52:53], v[18:19], 0, s[8:9]
	v_lshl_add_u64 v[48:49], v[52:53], 0, v[10:11]
	global_load_dwordx4 v[40:43], v[48:49], off
	global_load_dwordx4 v[44:47], v[6:7], off
	v_lshl_add_u64 v[18:19], v[18:19], 0, v[10:11]
	global_load_dwordx4 v[48:51], v[18:19], off
	v_add_u32_e32 v20, s12, v20
	s_waitcnt vmcnt(6)
	v_mov_b32_e32 v56, v29
	s_waitcnt vmcnt(5)
	v_mov_b32_e32 v57, v33
	v_mov_b32_e32 v54, v28
	v_mov_b32_e32 v55, v32
	s_waitcnt vmcnt(4)
	v_mov_b32_e32 v64, v37
	s_waitcnt vmcnt(3)
	v_mov_b32_e32 v65, v1
	v_mul_f32_e32 v56, v56, v56
	v_mul_f32_e32 v57, v57, v57
	v_mov_b32_e32 v58, v30
	v_mov_b32_e32 v59, v34
	v_mov_b32_e32 v62, v36
	v_mov_b32_e32 v63, v0
	v_mul_f32_e32 v64, v64, v64
	v_mul_f32_e32 v65, v65, v65
	v_fma_f32 v54, v54, v54, v56
	v_fma_f32 v55, v55, v55, v57
	v_mov_b32_e32 v60, v31
	v_mov_b32_e32 v61, v35
	v_mov_b32_e32 v66, v38
	v_mov_b32_e32 v67, v2
	v_fma_f32 v56, v62, v62, v64
	v_fma_f32 v57, v63, v63, v65
	v_fma_f32 v54, v58, v58, v54
	v_fma_f32 v55, v59, v59, v55
	v_mov_b32_e32 v68, v39
	v_mov_b32_e32 v69, v3
	v_fma_f32 v56, v66, v66, v56
	v_fma_f32 v57, v67, v67, v57
	v_fma_f32 v54, v60, v60, v54
	v_fma_f32 v55, v61, v61, v55
	v_fma_f32 v56, v68, v68, v56
	v_fma_f32 v57, v69, v69, v57
	v_add_f32_e32 v54, v54, v55
	v_add_f32_e32 v54, v54, v56
	v_add_f32_e32 v54, v54, v57
	ds_bpermute_b32 v55, v21, v54
	s_waitcnt vmcnt(2)
	v_pk_add_f32 v[40:41], v[40:41], 1.0 op_sel_hi:[1,0]
	v_pk_add_f32 v[42:43], v[42:43], 1.0 op_sel_hi:[1,0]
	s_waitcnt lgkmcnt(0)
	v_add_f32_e32 v54, v54, v55
	ds_bpermute_b32 v55, v22, v54
	s_waitcnt lgkmcnt(0)
	v_add_f32_e32 v54, v54, v55
	ds_bpermute_b32 v55, v23, v54
	s_waitcnt lgkmcnt(0)
	v_add_f32_e32 v54, v54, v55
	ds_bpermute_b32 v55, v24, v54
	s_waitcnt lgkmcnt(0)
	v_add_f32_e32 v54, v54, v55
	ds_bpermute_b32 v55, v25, v54
	s_waitcnt lgkmcnt(0)
	v_add_f32_e32 v54, v54, v55
	ds_bpermute_b32 v55, v26, v54
	s_waitcnt lgkmcnt(0)
	v_add_f32_e32 v54, v54, v55
	v_fmamk_f32 v54, v54, 0x3a800000, v27
	v_mul_f32_e32 v55, 0x4b800000, v54
	v_cmp_gt_f32_e32 vcc, s17, v54
	s_nop 1
	v_cndmask_b32_e32 v54, v54, v55, vcc
	v_rsq_f32_e32 v56, v54
	v_lshl_add_u64 v[54:55], v[52:53], 0, v[12:13]
	v_mul_f32_e32 v57, 0x45800000, v56
	v_cndmask_b32_e32 v56, v56, v57, vcc
	v_mul_f32_e32 v28, v28, v56
	v_mul_f32_e32 v29, v29, v56
	v_mul_f32_e32 v30, v30, v56
	v_mul_f32_e32 v31, v31, v56
	s_waitcnt vmcnt(1)
	v_mul_f32_e32 v28, v44, v28
	v_mul_f32_e32 v29, v45, v29
	v_mul_f32_e32 v30, v46, v30
	v_mul_f32_e32 v31, v47, v31
	s_waitcnt vmcnt(0)
	v_fma_f32 v28, v40, v28, v48
	v_fma_f32 v29, v41, v29, v49
	v_fma_f32 v30, v42, v30, v50
	v_fma_f32 v31, v43, v31, v51
	v_cvt_pk_bf16_f32 v28, v28, v29
	v_cvt_pk_bf16_f32 v29, v30, v31
	global_store_dwordx2 v[8:9], v[28:29], off
	global_load_dwordx4 v[28:31], v[6:7], off offset:1024
	s_nop 0
	global_load_dwordx4 v[40:43], v[54:55], off
	global_load_dwordx4 v[44:47], v[18:19], off offset:1024
	v_mul_f32_e32 v32, v32, v56
	v_mul_f32_e32 v33, v33, v56
	v_mul_f32_e32 v34, v34, v56
	v_mul_f32_e32 v35, v35, v56
	v_lshl_add_u64 v[48:49], v[52:53], 0, v[14:15]
	v_mul_f32_e32 v36, v36, v56
	v_mul_f32_e32 v37, v37, v56
	v_mul_f32_e32 v38, v38, v56
	v_mul_f32_e32 v39, v39, v56
	v_mul_f32_e32 v0, v0, v56
	v_mul_f32_e32 v1, v1, v56
	v_mul_f32_e32 v2, v2, v56
	v_mul_f32_e32 v3, v3, v56
	v_cmp_lt_i32_e32 vcc, s18, v20
	s_or_b64 s[6:7], vcc, s[6:7]
	s_waitcnt vmcnt(2)
	v_mul_f32_e32 v28, v28, v32
	v_mul_f32_e32 v29, v29, v33
	s_waitcnt vmcnt(1)
	v_pk_add_f32 v[32:33], v[40:41], 1.0 op_sel_hi:[1,0]
	v_mul_f32_e32 v30, v30, v34
	v_mul_f32_e32 v31, v31, v35
	v_pk_add_f32 v[34:35], v[42:43], 1.0 op_sel_hi:[1,0]
	s_waitcnt vmcnt(0)
	v_fma_f32 v28, v32, v28, v44
	v_fma_f32 v29, v33, v29, v45
	v_fma_f32 v30, v34, v30, v46
	v_fma_f32 v31, v35, v31, v47
	v_cvt_pk_bf16_f32 v28, v28, v29
	v_cvt_pk_bf16_f32 v29, v30, v31
	global_store_dwordx2 v[8:9], v[28:29], off offset:512
	global_load_dwordx4 v[28:31], v[6:7], off offset:2048
	s_nop 0
	global_load_dwordx4 v[32:35], v[48:49], off
	global_load_dwordx4 v[40:43], v[18:19], off offset:2048
	v_lshl_add_u64 v[44:45], v[52:53], 0, v[16:17]
	s_waitcnt vmcnt(2)
	v_mul_f32_e32 v28, v28, v36
	v_mul_f32_e32 v29, v29, v37
	s_waitcnt vmcnt(1)
	v_pk_add_f32 v[32:33], v[32:33], 1.0 op_sel_hi:[1,0]
	v_mul_f32_e32 v30, v30, v38
	v_mul_f32_e32 v31, v31, v39
	v_pk_add_f32 v[34:35], v[34:35], 1.0 op_sel_hi:[1,0]
	s_waitcnt vmcnt(0)
	v_fma_f32 v28, v28, v32, v40
	v_fma_f32 v29, v29, v33, v41
	v_fma_f32 v30, v30, v34, v42
	v_fma_f32 v31, v31, v35, v43
	v_cvt_pk_bf16_f32 v28, v28, v29
	v_cvt_pk_bf16_f32 v29, v30, v31
	global_store_dwordx2 v[8:9], v[28:29], off offset:1024
	global_load_dwordx4 v[28:31], v[6:7], off offset:3072
	s_nop 0
	global_load_dwordx4 v[32:35], v[44:45], off
	global_load_dwordx4 v[36:39], v[18:19], off offset:3072
	s_waitcnt vmcnt(2)
	v_mul_f32_e32 v0, v0, v28
	v_mul_f32_e32 v1, v1, v29
	s_waitcnt vmcnt(1)
	v_pk_add_f32 v[18:19], v[32:33], 1.0 op_sel_hi:[1,0]
	v_mul_f32_e32 v2, v2, v30
	v_mul_f32_e32 v3, v3, v31
	v_pk_add_f32 v[28:29], v[34:35], 1.0 op_sel_hi:[1,0]
	s_waitcnt vmcnt(0)
	v_fma_f32 v0, v0, v18, v36
	v_fma_f32 v1, v1, v19, v37
	v_fma_f32 v2, v2, v28, v38
	v_fma_f32 v3, v3, v29, v39
	v_cvt_pk_bf16_f32 v0, v0, v1
	v_cvt_pk_bf16_f32 v1, v2, v3
	global_store_dwordx2 v[8:9], v[0:1], off offset:1536
	v_lshl_add_u64 v[8:9], v[8:9], 0, s[4:5]
	s_andn2_b64 exec, exec, s[6:7]
	s_cbranch_execz .LBB0_166

.LBB0_231:
	s_add_i32 s47, s48, 0x8000
	s_and_b32 s27, s48, 0x8000
	s_and_b32 s50, s47, 0x8000
	s_add_i32 s48, s27, 0
	s_add_i32 s27, s50, 0
	s_add_u32 s70, s27, s71
	s_mov_b32 m0, s70
	s_waitcnt vmcnt(0) lgkmcnt(0)
	s_barrier
	global_load_lds_dwordx4 v244, s[96:97]
	s_add_u32 m0, s70, 0x4000
	s_nop 0
	global_load_lds_dwordx4 v245, s[72:73]
	s_add_u32 m0, s70, 0x1000
	s_nop 0
	global_load_lds_dwordx4 v246, s[96:97]
	s_add_u32 m0, s70, 0x5000
	s_nop 0
	global_load_lds_dwordx4 v247, s[72:73]
	s_add_u32 m0, s70, 0x2000
	s_nop 0
	global_load_lds_dwordx4 v248, s[96:97]
	s_add_u32 m0, s70, 0x6000
	s_nop 0
	global_load_lds_dwordx4 v249, s[72:73]
	s_add_u32 m0, s70, 0x3000
	s_nop 0
	global_load_lds_dwordx4 v250, s[96:97]
	s_add_u32 m0, s70, 0x7000
	s_nop 0
	global_load_lds_dwordx4 v251, s[72:73]
	s_add_u32 s96, s96, 0x80
	s_addc_u32 s97, s97, 0
	s_add_u32 s72, s72, 0x80
	s_addc_u32 s73, s73, 0
	v_add3_u32 v145, s48, v86, v87
	v_add3_u32 v208, s48, v87, v88
	v_add3_u32 v209, s48, v86, v89
	v_add3_u32 v210, s48, v88, v89
	ds_read_b128 v[104:107], v208
	ds_read_b128 v[100:103], v145 offset:16384
	ds_read_b128 v[108:111], v145 offset:18432
	ds_read_b128 v[164:167], v208 offset:2048
	ds_read_b128 v[112:115], v145 offset:20480
	ds_read_b128 v[116:119], v145 offset:22528
	ds_read_b128 v[120:123], v145 offset:24576
	ds_read_b128 v[124:127], v145 offset:26624
	ds_read_b128 v[128:131], v145 offset:28672
	ds_read_b128 v[132:135], v145 offset:30720
	ds_read_b128 v[200:203], v210
	ds_read_b128 v[168:171], v209 offset:16384
	ds_read_b128 v[172:175], v209 offset:18432
	ds_read_b128 v[204:207], v210 offset:2048
	ds_read_b128 v[176:179], v209 offset:20480
	ds_read_b128 v[180:183], v209 offset:22528
	ds_read_b128 v[184:187], v209 offset:24576
	ds_read_b128 v[188:191], v209 offset:26624
	ds_read_b128 v[192:195], v209 offset:28672
	ds_read_b128 v[196:199], v209 offset:30720
	s_add_u32 s24, s24, 0x80
	s_addc_u32 s25, s25, 0
	s_cmpk_eq_i32 s24, 0x780
	s_mov_b32 s48, s47
	s_waitcnt lgkmcnt(15)
	v_mfma_f32_16x16x32_bf16 v[60:63], v[100:103], v[104:107], v[60:63]
	v_mfma_f32_16x16x32_bf16 v[56:59], v[108:111], v[104:107], v[56:59]
	v_mfma_f32_16x16x32_bf16 v[24:27], v[100:103], v[164:167], v[24:27]
	v_mfma_f32_16x16x32_bf16 v[20:23], v[108:111], v[164:167], v[20:23]
	v_mfma_f32_16x16x32_bf16 v[52:55], v[112:115], v[104:107], v[52:55]
	v_mfma_f32_16x16x32_bf16 v[16:19], v[112:115], v[164:167], v[16:19]
	s_waitcnt lgkmcnt(14)
	v_mfma_f32_16x16x32_bf16 v[48:51], v[116:119], v[104:107], v[48:51]
	v_mfma_f32_16x16x32_bf16 v[12:15], v[116:119], v[164:167], v[12:15]
	s_waitcnt lgkmcnt(13)
	v_mfma_f32_16x16x32_bf16 v[44:47], v[120:123], v[104:107], v[44:47]
	v_mfma_f32_16x16x32_bf16 v[8:11], v[120:123], v[164:167], v[8:11]
	s_waitcnt lgkmcnt(12)
	v_mfma_f32_16x16x32_bf16 v[40:43], v[124:127], v[104:107], v[40:43]
	v_mfma_f32_16x16x32_bf16 v[4:7], v[124:127], v[164:167], v[4:7]
	s_waitcnt lgkmcnt(11)
	v_mfma_f32_16x16x32_bf16 v[36:39], v[128:131], v[104:107], v[36:39]
	v_mfma_f32_16x16x32_bf16 v[0:3], v[128:131], v[164:167], v[0:3]
	s_waitcnt lgkmcnt(10)
	v_mfma_f32_16x16x32_bf16 v[32:35], v[132:135], v[104:107], v[32:35]
	v_mfma_f32_16x16x32_bf16 v[28:31], v[132:135], v[164:167], v[28:31]
	s_waitcnt lgkmcnt(8)
	v_mfma_f32_16x16x32_bf16 v[60:63], v[168:171], v[200:203], v[60:63]
	s_waitcnt lgkmcnt(7)
	v_mfma_f32_16x16x32_bf16 v[56:59], v[172:175], v[200:203], v[56:59]
	s_waitcnt lgkmcnt(6)
	v_mfma_f32_16x16x32_bf16 v[24:27], v[168:171], v[204:207], v[24:27]
	v_mfma_f32_16x16x32_bf16 v[20:23], v[172:175], v[204:207], v[20:23]
	s_waitcnt lgkmcnt(5)
	v_mfma_f32_16x16x32_bf16 v[52:55], v[176:179], v[200:203], v[52:55]
	v_mfma_f32_16x16x32_bf16 v[16:19], v[176:179], v[204:207], v[16:19]
	s_waitcnt lgkmcnt(4)
	v_mfma_f32_16x16x32_bf16 v[48:51], v[180:183], v[200:203], v[48:51]
	v_mfma_f32_16x16x32_bf16 v[12:15], v[180:183], v[204:207], v[12:15]
	s_waitcnt lgkmcnt(3)
	v_mfma_f32_16x16x32_bf16 v[44:47], v[184:187], v[200:203], v[44:47]
	v_mfma_f32_16x16x32_bf16 v[8:11], v[184:187], v[204:207], v[8:11]
	s_waitcnt lgkmcnt(2)
	v_mfma_f32_16x16x32_bf16 v[40:43], v[188:191], v[200:203], v[40:43]
	v_mfma_f32_16x16x32_bf16 v[4:7], v[188:191], v[204:207], v[4:7]
	s_waitcnt lgkmcnt(1)
	v_mfma_f32_16x16x32_bf16 v[36:39], v[192:195], v[200:203], v[36:39]
	v_mfma_f32_16x16x32_bf16 v[0:3], v[192:195], v[204:207], v[0:3]
	s_waitcnt lgkmcnt(0)
	v_mfma_f32_16x16x32_bf16 v[32:35], v[196:199], v[200:203], v[32:35]
	v_mfma_f32_16x16x32_bf16 v[28:31], v[196:199], v[204:207], v[28:31]
	s_cbranch_scc0 .LBB0_231
	v_add_u32_e32 v64, s27, v86
	v_add_u32_e32 v136, v64, v87
	v_add3_u32 v108, s27, v87, v88
	s_waitcnt vmcnt(0)
	s_barrier
	ds_read_b128 v[80:83], v136 offset:16384
	ds_read_b128 v[100:103], v136 offset:18432
	ds_read_b128 v[104:107], v108
	ds_read_b128 v[108:111], v108 offset:2048
	ds_read_b128 v[112:115], v136 offset:20480
	ds_read_b128 v[116:119], v136 offset:22528
	ds_read_b128 v[128:131], v136 offset:28672
	s_waitcnt lgkmcnt(2)
	v_mfma_f32_16x16x32_bf16 v[120:123], v[112:115], v[104:107], v[52:55]
	s_nop 2
	ds_read_b128 v[52:55], v136 offset:24576
	ds_read_b128 v[124:127], v136 offset:26624
	s_cmp_gt_i32 s26, 11
	s_waitcnt lgkmcnt(0)
	v_mfma_f32_16x16x32_bf16 v[132:135], v[124:127], v[104:107], v[40:43]
	s_nop 2
	ds_read_b128 v[40:43], v136 offset:30720
	s_cselect_b64 s[24:25], -1, 0
	s_cmp_lt_i32 s26, 12
	v_mfma_f32_16x16x32_bf16 v[60:63], v[80:83], v[104:107], v[60:63]
	s_cselect_b64 s[48:49], -1, 0
	v_mfma_f32_16x16x32_bf16 v[56:59], v[100:103], v[104:107], v[56:59]
	v_mfma_f32_16x16x32_bf16 v[48:51], v[116:119], v[104:107], v[48:51]
	v_mfma_f32_16x16x32_bf16 v[44:47], v[52:55], v[104:107], v[44:47]
	v_mfma_f32_16x16x32_bf16 v[136:139], v[128:131], v[104:107], v[36:39]
	s_waitcnt lgkmcnt(0)
	v_mfma_f32_16x16x32_bf16 v[32:35], v[40:43], v[104:107], v[32:35]
	v_mfma_f32_16x16x32_bf16 v[104:107], v[52:55], v[108:111], v[8:11]
	s_nop 2
	v_add_u32_e32 v8, v64, v89
	v_mfma_f32_16x16x32_bf16 v[24:27], v[80:83], v[108:111], v[24:27]
	v_add3_u32 v9, s27, v89, v88
	v_lshl_or_b32 v64, s26, 7, v90
	s_sub_i32 s26, s26, 18
	v_mfma_f32_16x16x32_bf16 v[80:83], v[112:115], v[108:111], v[16:19]
	s_cmp_lt_u32 s26, 8
	s_cselect_b64 s[26:27], -1, 0
	s_or_b64 s[48:49], s[48:49], s[26:27]
	v_mfma_f32_16x16x32_bf16 v[112:115], v[124:127], v[108:111], v[4:7]
	s_mov_b64 s[26:27], -1
	s_andn2_b64 vcc, exec, s[48:49]
	s_nop 0
	ds_read_b128 v[4:7], v8 offset:16384
	v_mfma_f32_16x16x32_bf16 v[20:23], v[100:103], v[108:111], v[20:23]
	v_mfma_f32_16x16x32_bf16 v[100:103], v[116:119], v[108:111], v[12:15]
	v_mfma_f32_16x16x32_bf16 v[116:119], v[128:131], v[108:111], v[0:3]
	ds_read_b128 v[124:127], v8 offset:18432
	s_nop 1
	ds_read_b128 v[0:3], v9
	ds_read_b128 v[128:131], v9 offset:2048
	ds_read_b128 v[140:143], v8 offset:22528
	ds_read_b128 v[146:149], v8 offset:28672
	s_waitcnt lgkmcnt(3)
	v_mfma_f32_16x16x32_bf16 v[52:55], v[4:7], v[0:3], v[60:63]
	s_nop 2
	ds_read_b128 v[60:63], v8 offset:20480
	v_mfma_f32_16x16x32_bf16 v[108:111], v[40:43], v[108:111], v[28:31]
	s_waitcnt lgkmcnt(0)
	v_mfma_f32_16x16x32_bf16 v[36:39], v[60:63], v[0:3], v[120:123]
	s_nop 2
	ds_read_b128 v[120:123], v8 offset:24576
	v_mfma_f32_16x16x32_bf16 v[40:43], v[140:143], v[0:3], v[48:51]
	s_nop 2
	ds_read_b128 v[48:51], v8 offset:26624
	s_waitcnt lgkmcnt(0)
	v_mfma_f32_16x16x32_bf16 v[16:19], v[48:51], v[0:3], v[132:135]
	s_nop 2
	ds_read_b128 v[132:135], v8 offset:30720
	v_mfma_f32_16x16x32_bf16 v[56:59], v[124:127], v[0:3], v[56:59]
	v_mfma_f32_16x16x32_bf16 v[12:15], v[120:123], v[0:3], v[44:47]
	v_mfma_f32_16x16x32_bf16 v[8:11], v[146:149], v[0:3], v[136:139]
	s_waitcnt lgkmcnt(0)
	v_mfma_f32_16x16x32_bf16 v[0:3], v[132:135], v[0:3], v[32:35]
	v_mfma_f32_16x16x32_bf16 v[28:31], v[4:7], v[128:131], v[24:27]
	v_mfma_f32_16x16x32_bf16 v[20:23], v[124:127], v[128:131], v[20:23]
	v_mfma_f32_16x16x32_bf16 v[4:7], v[60:63], v[128:131], v[80:83]
	v_mfma_f32_16x16x32_bf16 v[24:27], v[140:143], v[128:131], v[100:103]
	s_nop 1
	v_lshl_add_u32 v80, s46, 7, v85
	v_mfma_f32_16x16x32_bf16 v[32:35], v[120:123], v[128:131], v[104:107]
	v_mfma_f32_16x16x32_bf16 v[44:47], v[48:51], v[128:131], v[112:115]
	v_mfma_f32_16x16x32_bf16 v[48:51], v[146:149], v[128:131], v[116:119]
	v_mfma_f32_16x16x32_bf16 v[60:63], v[132:135], v[128:131], v[108:111]
	s_cbranch_vccz .LBB0_240
	s_and_b32 s47, 0xffff, s45
	s_cmp_gt_u32 s47, 17
	s_cbranch_scc0 .LBB0_237
	s_cmp_eq_u32 s47, 26
	s_cselect_b64 s[26:27], -1, 0
	s_and_b64 s[48:49], s[10:11], s[26:27]
	s_and_saveexec_b64 s[26:27], s[48:49]
	s_cbranch_execz .LBB0_236
	global_load_dwordx4 v[100:103], v[72:73], off
	v_mad_i64_i32 v[82:83], s[48:49], v80, s28, v[70:71]
	v_or_b32_e32 v81, 16, v80
	s_waitcnt vmcnt(0)
	v_add_f32_e32 v102, v54, v102
	v_add_f32_e32 v103, v55, v103
	v_add_f32_e32 v100, v52, v100
	v_add_f32_e32 v101, v53, v101
	global_store_dwordx4 v[82:83], v[100:103], off
	global_load_dwordx4 v[100:103], v[72:73], off offset:16
	v_mad_i64_i32 v[82:83], s[48:49], v80, s28, v[74:75]
	s_waitcnt vmcnt(0)
	v_add_f32_e32 v102, v58, v102
	v_add_f32_e32 v103, v59, v103
	v_add_f32_e32 v100, v56, v100
	v_add_f32_e32 v101, v57, v101
	global_store_dwordx4 v[82:83], v[100:103], off
	global_load_dwordx4 v[100:103], v[72:73], off
	v_mad_i64_i32 v[82:83], s[48:49], v81, s28, v[70:71]
	s_waitcnt vmcnt(0)
	v_add_f32_e32 v102, v30, v102
	v_add_f32_e32 v103, v31, v103
	v_add_f32_e32 v100, v28, v100
	v_add_f32_e32 v101, v29, v101
	global_store_dwordx4 v[82:83], v[100:103], off
	global_load_dwordx4 v[100:103], v[72:73], off offset:16
	v_mad_i64_i32 v[82:83], s[48:49], v81, s28, v[74:75]
	s_waitcnt vmcnt(0)
	v_add_f32_e32 v102, v22, v102
	v_add_f32_e32 v103, v23, v103
	v_add_f32_e32 v100, v20, v100
	v_add_f32_e32 v101, v21, v101
	global_store_dwordx4 v[82:83], v[100:103], off

.LBB0_324:
	s_or_b64 exec, exec, s[0:1]
	s_load_dwordx16 s[36:51], s[78:79], 0x40
	v_lshlrev_b64 v[12:13], 2, v[6:7]
	v_lshl_add_u64 v[10:11], s[8:9], 0, v[12:13]
	global_load_dwordx4 v[44:47], v[10:11], off
	global_load_dwordx4 v[48:51], v[10:11], off offset:16
	v_lshl_add_u64 v[16:17], s[10:11], 0, v[12:13]
	s_waitcnt lgkmcnt(0)
	v_lshl_add_u64 v[14:15], s[38:39], 0, v[12:13]
	global_load_dwordx4 v[52:55], v[14:15], off
	global_load_dwordx4 v[56:59], v[14:15], off offset:16
	global_load_dwordx4 v[60:63], v[16:17], off
	global_load_dwordx4 v[64:67], v[16:17], off offset:16
	s_waitcnt vmcnt(6)
	v_lshlrev_b32_e32 v70, 16, v0
	v_and_b32_e32 v71, 0xffff0000, v0
	v_lshlrev_b32_e32 v0, 16, v1
	v_and_b32_e32 v1, 0xffff0000, v1
	v_lshlrev_b32_e32 v76, 16, v2
	v_and_b32_e32 v77, 0xffff0000, v2
	v_lshlrev_b32_e32 v2, 16, v3
	v_and_b32_e32 v3, 0xffff0000, v3
	v_lshlrev_b32_e32 v68, 16, v21
	v_and_b32_e32 v69, 0xffff0000, v21
	v_lshlrev_b32_e32 v74, 16, v20
	v_and_b32_e32 v75, 0xffff0000, v20
	v_lshlrev_b32_e32 v20, 16, v18
	v_lshlrev_b32_e32 v78, 16, v41
	v_and_b32_e32 v21, 0xffff0000, v18
	v_and_b32_e32 v79, 0xffff0000, v41
	v_lshlrev_b32_e32 v18, 16, v19
	v_lshlrev_b32_e32 v80, 16, v40
	v_and_b32_e32 v19, 0xffff0000, v19
	v_and_b32_e32 v81, 0xffff0000, v40
	v_lshlrev_b32_e32 v72, 16, v42
	v_and_b32_e32 v73, 0xffff0000, v42
	v_lshlrev_b32_e32 v42, 16, v43
	v_and_b32_e32 v43, 0xffff0000, v43
	s_mul_i32 s16, s25, -12
	s_add_i32 s26, s24, s16
	s_cmp_gt_i32 s26, 5
	v_lshlrev_b64 v[12:13], 1, v[6:7]
	s_cselect_b64 s[16:17], -1, 0
	s_mov_b64 s[0:1], -1
	v_lshl_add_u64 v[6:7], s[94:95], 0, v[12:13]
	s_and_b64 vcc, exec, s[16:17]
	s_waitcnt vmcnt(5)
	v_mul_f32_e32 v40, v44, v70
	v_mul_f32_e32 v41, v45, v71
	v_mul_f32_e32 v0, v46, v0
	v_mul_f32_e32 v1, v47, v1
	s_waitcnt vmcnt(4)
	v_mul_f32_e32 v44, v48, v76
	v_mul_f32_e32 v45, v49, v77
	v_mul_f32_e32 v2, v50, v2
	v_mul_f32_e32 v3, v51, v3
	s_waitcnt vmcnt(3)
	v_fma_f32 v40, v52, v68, v40
	v_fma_f32 v41, v53, v69, v41
	v_fma_f32 v0, v54, v74, v0
	v_fma_f32 v1, v55, v75, v1
	s_waitcnt vmcnt(2)
	v_fma_f32 v20, v56, v20, v44
	v_fma_f32 v21, v57, v21, v45
	v_fma_f32 v2, v58, v18, v2
	v_fma_f32 v3, v59, v19, v3
	s_waitcnt vmcnt(1)
	v_fma_f32 v18, v60, v72, v40
	v_fma_f32 v19, v61, v73, v41
	v_fma_f32 v0, v62, v42, v0
	v_fma_f32 v1, v63, v43, v1
	s_waitcnt vmcnt(0)
	v_fma_f32 v40, v64, v78, v20
	v_fma_f32 v41, v65, v79, v21
	v_fma_f32 v42, v66, v80, v2
	v_fma_f32 v43, v67, v81, v3
	v_mul_f32_e32 v2, 0xbfb8aa3b, v18
	v_mul_f32_e32 v3, 0xbfb8aa3b, v19
	v_mul_f32_e32 v20, 0xbfb8aa3b, v0
	v_mul_f32_e32 v21, 0xbfb8aa3b, v1
	v_mul_f32_e32 v44, 0xbfb8aa3b, v40
	v_mul_f32_e32 v45, 0xbfb8aa3b, v41
	v_mul_f32_e32 v46, 0xbfb8aa3b, v42
	v_mul_f32_e32 v47, 0xbfb8aa3b, v43
	v_exp_f32_e32 v2, v2
	v_exp_f32_e32 v3, v3
	v_exp_f32_e32 v20, v20
	v_exp_f32_e32 v21, v21
	v_exp_f32_e32 v44, v44
	v_exp_f32_e32 v45, v45
	v_exp_f32_e32 v46, v46
	v_exp_f32_e32 v47, v47
	v_add_f32_e32 v2, 1.0, v2
	v_add_f32_e32 v3, 1.0, v3
	v_add_f32_e32 v20, 1.0, v20
	v_add_f32_e32 v21, 1.0, v21
	v_add_f32_e32 v48, 1.0, v44
	v_add_f32_e32 v49, 1.0, v45
	v_add_f32_e32 v50, 1.0, v46
	v_add_f32_e32 v51, 1.0, v47
	v_rcp_f32_e32 v2, v2
	v_rcp_f32_e32 v3, v3
	v_rcp_f32_e32 v44, v20
	v_rcp_f32_e32 v45, v21
	v_rcp_f32_e32 v46, v48
	v_rcp_f32_e32 v47, v49
	v_rcp_f32_e32 v48, v50
	v_rcp_f32_e32 v49, v51
	v_mul_f32_e32 v20, v18, v2
	v_mul_f32_e32 v21, v19, v3
	v_mul_f32_e32 v18, v0, v44
	v_mul_f32_e32 v19, v1, v45
	v_mul_f32_e32 v2, v40, v46
	v_mul_f32_e32 v3, v41, v47
	v_mul_f32_e32 v0, v42, v48
	v_mul_f32_e32 v1, v43, v49
	s_cbranch_vccz .LBB0_326
	v_mad_i64_i32 v[44:45], s[0:1], v39, s22, v[6:7]
	v_add_co_u32_e32 v44, vcc, 0xc0cf000, v44
	v_cvt_pk_bf16_f32 v40, v20, v21
	v_cvt_pk_bf16_f32 v41, v18, v19
	v_cvt_pk_bf16_f32 v42, v2, v3
	v_cvt_pk_bf16_f32 v43, v0, v1
	v_addc_co_u32_e32 v45, vcc, 0, v45, vcc
	global_store_dwordx4 v[44:45], v[40:43], off offset:2560
	s_nop 1
	v_cvt_pk_bf16_f32 v40, v20, s0
	ds_write_b16 v31, v40
	v_cvt_pk_bf16_f32 v40, v21, s0
	ds_write_b16 v31, v40 offset:144
	v_cvt_pk_bf16_f32 v40, v18, s0
	ds_write_b16 v31, v40 offset:288
	v_cvt_pk_bf16_f32 v40, v19, s0
	ds_write_b16 v31, v40 offset:432
	v_cvt_pk_bf16_f32 v40, v2, s0
	ds_write_b16 v31, v40 offset:576
	v_cvt_pk_bf16_f32 v40, v3, s0
	ds_write_b16 v31, v40 offset:720
	v_cvt_pk_bf16_f32 v40, v0, s0
	ds_write_b16 v31, v40 offset:864
	v_cvt_pk_bf16_f32 v40, v1, s0
	ds_write_b16 v31, v40 offset:1008
	s_mov_b64 s[0:1], 0
.LBB0_326:
	s_andn2_b64 vcc, exec, s[0:1]
	v_lshl_add_u64 v[12:13], s[6:7], 0, v[12:13]
	s_cbranch_vccnz .LBB0_328
	v_mul_f32_e32 v20, s12, v20
	v_mul_f32_e32 v21, s12, v21
	v_mul_f32_e32 v18, s12, v18
	v_mul_f32_e32 v19, s12, v19
	v_mul_f32_e32 v2, s12, v2
	v_mul_f32_e32 v3, s12, v3
	v_mul_f32_e32 v0, s12, v0
	v_mul_f32_e32 v1, s12, v1
	v_cvt_pk_bf16_f32 v40, v20, v21
	v_cvt_pk_bf16_f32 v41, v18, v19
	v_cvt_pk_bf16_f32 v42, v2, v3
	v_cvt_pk_bf16_f32 v43, v0, v1
	v_mad_i64_i32 v[0:1], s[0:1], v39, s22, v[12:13]
	global_store_dwordx4 v[0:1], v[40:43], off

.LBB0_344:
	s_or_b64 exec, exec, s[0:1]
	global_load_dwordx4 v[46:49], v[10:11], off
	global_load_dwordx4 v[50:53], v[10:11], off offset:16
	global_load_dwordx4 v[54:57], v[14:15], off
	global_load_dwordx4 v[58:61], v[14:15], off offset:16
	global_load_dwordx4 v[62:65], v[16:17], off
	global_load_dwordx4 v[66:69], v[16:17], off offset:16
	s_waitcnt vmcnt(6)
	v_lshlrev_b32_e32 v70, 16, v0
	v_and_b32_e32 v71, 0xffff0000, v0
	v_lshlrev_b32_e32 v0, 16, v1
	v_and_b32_e32 v1, 0xffff0000, v1
	v_lshlrev_b32_e32 v78, 16, v2
	v_and_b32_e32 v79, 0xffff0000, v2
	v_lshlrev_b32_e32 v80, 16, v20
	v_lshlrev_b32_e32 v2, 16, v3
	v_and_b32_e32 v81, 0xffff0000, v20
	v_and_b32_e32 v3, 0xffff0000, v3
	v_cndmask_b32_e64 v20, 0, 1, s[16:17]
	v_lshlrev_b32_e32 v18, 16, v42
	v_lshlrev_b32_e32 v72, 16, v45
	v_and_b32_e32 v19, 0xffff0000, v42
	v_and_b32_e32 v73, 0xffff0000, v45
	v_lshlrev_b32_e32 v74, 16, v40
	v_lshlrev_b32_e32 v76, 16, v44
	v_and_b32_e32 v75, 0xffff0000, v40
	v_and_b32_e32 v77, 0xffff0000, v44
	v_lshlrev_b32_e32 v44, 16, v21
	v_and_b32_e32 v45, 0xffff0000, v21
	v_cmp_ne_u32_e64 s[0:1], 1, v20
	v_lshlrev_b32_e32 v42, 16, v43
	v_and_b32_e32 v43, 0xffff0000, v43
	v_lshlrev_b32_e32 v40, 16, v41
	v_and_b32_e32 v41, 0xffff0000, v41
	s_andn2_b64 vcc, exec, s[16:17]
	s_mov_b64 s[16:17], -1
	s_waitcnt vmcnt(5)
	v_mul_f32_e32 v20, v46, v70
	v_mul_f32_e32 v21, v47, v71
	v_mul_f32_e32 v0, v48, v0
	v_mul_f32_e32 v1, v49, v1
	s_waitcnt vmcnt(4)
	v_mul_f32_e32 v46, v50, v78
	v_mul_f32_e32 v47, v51, v79
	v_mul_f32_e32 v2, v52, v2
	v_mul_f32_e32 v3, v53, v3
	s_waitcnt vmcnt(3)
	v_fma_f32 v18, v54, v18, v20
	v_fma_f32 v19, v55, v19, v21
	v_fma_f32 v0, v56, v74, v0
	v_fma_f32 v1, v57, v75, v1
	s_waitcnt vmcnt(2)
	v_fma_f32 v20, v58, v44, v46
	v_fma_f32 v21, v59, v45, v47
	v_fma_f32 v2, v60, v80, v2
	v_fma_f32 v3, v61, v81, v3
	s_waitcnt vmcnt(1)
	v_fma_f32 v18, v62, v72, v18
	v_fma_f32 v19, v63, v73, v19
	v_fma_f32 v0, v64, v76, v0
	v_fma_f32 v1, v65, v77, v1
	s_waitcnt vmcnt(0)
	v_fma_f32 v42, v66, v42, v20
	v_fma_f32 v43, v67, v43, v21
	v_fma_f32 v40, v68, v40, v2
	v_fma_f32 v41, v69, v41, v3
	v_mul_f32_e32 v2, 0xbfb8aa3b, v18
	v_mul_f32_e32 v3, 0xbfb8aa3b, v19
	v_mul_f32_e32 v20, 0xbfb8aa3b, v0
	v_mul_f32_e32 v21, 0xbfb8aa3b, v1
	v_mul_f32_e32 v44, 0xbfb8aa3b, v42
	v_mul_f32_e32 v45, 0xbfb8aa3b, v43
	v_mul_f32_e32 v46, 0xbfb8aa3b, v40
	v_mul_f32_e32 v47, 0xbfb8aa3b, v41
	v_exp_f32_e32 v2, v2
	v_exp_f32_e32 v3, v3
	v_exp_f32_e32 v20, v20
	v_exp_f32_e32 v21, v21
	v_exp_f32_e32 v44, v44
	v_exp_f32_e32 v45, v45
	v_exp_f32_e32 v46, v46
	v_exp_f32_e32 v47, v47
	v_add_f32_e32 v2, 1.0, v2
	v_add_f32_e32 v3, 1.0, v3
	v_add_f32_e32 v20, 1.0, v20
	v_add_f32_e32 v21, 1.0, v21
	v_add_f32_e32 v48, 1.0, v44
	v_add_f32_e32 v49, 1.0, v45
	v_add_f32_e32 v50, 1.0, v46
	v_add_f32_e32 v51, 1.0, v47
	v_rcp_f32_e32 v2, v2
	v_rcp_f32_e32 v3, v3
	v_rcp_f32_e32 v44, v20
	v_rcp_f32_e32 v45, v21
	v_rcp_f32_e32 v46, v48
	v_rcp_f32_e32 v47, v49
	v_rcp_f32_e32 v48, v50
	v_rcp_f32_e32 v49, v51
	v_mul_f32_e32 v20, v18, v2
	v_mul_f32_e32 v21, v19, v3
	v_mul_f32_e32 v18, v0, v44
	v_mul_f32_e32 v19, v1, v45
	v_mul_f32_e32 v2, v42, v46
	v_mul_f32_e32 v3, v43, v47
	v_mul_f32_e32 v0, v40, v48
	v_mul_f32_e32 v1, v41, v49
	s_cbranch_vccnz .LBB0_346
	v_mad_i64_i32 v[44:45], s[16:17], v39, s22, v[6:7]
	v_add_co_u32_e32 v44, vcc, 0xc0cf000, v44
	v_cvt_pk_bf16_f32 v40, v20, v21
	v_cvt_pk_bf16_f32 v41, v18, v19
	v_cvt_pk_bf16_f32 v42, v2, v3
	v_cvt_pk_bf16_f32 v43, v0, v1
	v_addc_co_u32_e32 v45, vcc, 0, v45, vcc
	global_store_dwordx4 v[44:45], v[40:43], off offset:2560
	s_mov_b64 s[16:17], 0
	s_nop 0
	v_cvt_pk_bf16_f32 v40, v20, s0
	ds_write_b16 v32, v40
	v_cvt_pk_bf16_f32 v40, v21, s0
	ds_write_b16 v32, v40 offset:144
	v_cvt_pk_bf16_f32 v40, v18, s0
	ds_write_b16 v32, v40 offset:288
	v_cvt_pk_bf16_f32 v40, v19, s0
	ds_write_b16 v32, v40 offset:432
	v_cvt_pk_bf16_f32 v40, v2, s0
	ds_write_b16 v32, v40 offset:576
	v_cvt_pk_bf16_f32 v40, v3, s0
	ds_write_b16 v32, v40 offset:720
	v_cvt_pk_bf16_f32 v40, v0, s0
	ds_write_b16 v32, v40 offset:864
	v_cvt_pk_bf16_f32 v40, v1, s0
	ds_write_b16 v32, v40 offset:1008
.LBB0_346:
	s_andn2_b64 vcc, exec, s[16:17]
	s_cbranch_vccnz .LBB0_348
	v_mul_f32_e32 v20, s12, v20
	v_mul_f32_e32 v21, s12, v21
	v_mul_f32_e32 v18, s12, v18
	v_mul_f32_e32 v19, s12, v19
	v_mul_f32_e32 v2, s12, v2
	v_mul_f32_e32 v3, s12, v3
	v_mul_f32_e32 v0, s12, v0
	v_mul_f32_e32 v1, s12, v1
	v_cvt_pk_bf16_f32 v40, v20, v21
	v_cvt_pk_bf16_f32 v41, v18, v19
	v_cvt_pk_bf16_f32 v42, v2, v3
	v_cvt_pk_bf16_f32 v43, v0, v1
	v_mad_i64_i32 v[0:1], s[16:17], v39, s22, v[12:13]
	global_store_dwordx4 v[0:1], v[40:43], off

.LBB0_364:
	s_or_b64 exec, exec, s[16:17]
	global_load_dwordx4 v[46:49], v[10:11], off
	global_load_dwordx4 v[50:53], v[10:11], off offset:16
	global_load_dwordx4 v[54:57], v[14:15], off
	global_load_dwordx4 v[58:61], v[14:15], off offset:16
	global_load_dwordx4 v[62:65], v[16:17], off
	global_load_dwordx4 v[66:69], v[16:17], off offset:16
	s_waitcnt vmcnt(6)
	v_lshlrev_b32_e32 v70, 16, v0
	v_and_b32_e32 v71, 0xffff0000, v0
	v_lshlrev_b32_e32 v0, 16, v1
	v_and_b32_e32 v1, 0xffff0000, v1
	v_lshlrev_b32_e32 v78, 16, v2
	v_and_b32_e32 v79, 0xffff0000, v2
	v_lshlrev_b32_e32 v2, 16, v3
	v_and_b32_e32 v3, 0xffff0000, v3
	v_lshlrev_b32_e32 v18, 16, v42
	v_lshlrev_b32_e32 v72, 16, v45
	v_and_b32_e32 v19, 0xffff0000, v42
	v_and_b32_e32 v73, 0xffff0000, v45
	v_lshlrev_b32_e32 v74, 16, v40
	v_lshlrev_b32_e32 v76, 16, v44
	v_and_b32_e32 v75, 0xffff0000, v40
	v_and_b32_e32 v77, 0xffff0000, v44
	v_lshlrev_b32_e32 v44, 16, v21
	v_and_b32_e32 v45, 0xffff0000, v21
	v_lshlrev_b32_e32 v80, 16, v20
	v_and_b32_e32 v81, 0xffff0000, v20
	v_lshlrev_b32_e32 v42, 16, v43
	v_and_b32_e32 v43, 0xffff0000, v43
	v_lshlrev_b32_e32 v40, 16, v41
	v_and_b32_e32 v41, 0xffff0000, v41
	s_and_b64 vcc, exec, s[0:1]
	s_mov_b64 s[16:17], -1
	s_waitcnt vmcnt(5)
	v_mul_f32_e32 v20, v46, v70
	v_mul_f32_e32 v21, v47, v71
	v_mul_f32_e32 v0, v48, v0
	v_mul_f32_e32 v1, v49, v1
	s_waitcnt vmcnt(4)
	v_mul_f32_e32 v46, v50, v78
	v_mul_f32_e32 v47, v51, v79
	v_mul_f32_e32 v2, v52, v2
	v_mul_f32_e32 v3, v53, v3
	s_waitcnt vmcnt(3)
	v_fma_f32 v18, v54, v18, v20
	v_fma_f32 v19, v55, v19, v21
	v_fma_f32 v0, v56, v74, v0
	v_fma_f32 v1, v57, v75, v1
	s_waitcnt vmcnt(2)
	v_fma_f32 v20, v58, v44, v46
	v_fma_f32 v21, v59, v45, v47
	v_fma_f32 v2, v60, v80, v2
	v_fma_f32 v3, v61, v81, v3
	s_waitcnt vmcnt(1)
	v_fma_f32 v18, v62, v72, v18
	v_fma_f32 v19, v63, v73, v19
	v_fma_f32 v0, v64, v76, v0
	v_fma_f32 v1, v65, v77, v1
	s_waitcnt vmcnt(0)
	v_fma_f32 v42, v66, v42, v20
	v_fma_f32 v43, v67, v43, v21
	v_fma_f32 v40, v68, v40, v2
	v_fma_f32 v41, v69, v41, v3
	v_mul_f32_e32 v2, 0xbfb8aa3b, v18
	v_mul_f32_e32 v3, 0xbfb8aa3b, v19
	v_mul_f32_e32 v20, 0xbfb8aa3b, v0
	v_mul_f32_e32 v21, 0xbfb8aa3b, v1
	v_mul_f32_e32 v44, 0xbfb8aa3b, v42
	v_mul_f32_e32 v45, 0xbfb8aa3b, v43
	v_mul_f32_e32 v46, 0xbfb8aa3b, v40
	v_mul_f32_e32 v47, 0xbfb8aa3b, v41
	v_exp_f32_e32 v2, v2
	v_exp_f32_e32 v3, v3
	v_exp_f32_e32 v20, v20
	v_exp_f32_e32 v21, v21
	v_exp_f32_e32 v44, v44
	v_exp_f32_e32 v45, v45
	v_exp_f32_e32 v46, v46
	v_exp_f32_e32 v47, v47
	v_add_f32_e32 v2, 1.0, v2
	v_add_f32_e32 v3, 1.0, v3
	v_add_f32_e32 v20, 1.0, v20
	v_add_f32_e32 v21, 1.0, v21
	v_add_f32_e32 v48, 1.0, v44
	v_add_f32_e32 v49, 1.0, v45
	v_add_f32_e32 v50, 1.0, v46
	v_add_f32_e32 v51, 1.0, v47
	v_rcp_f32_e32 v2, v2
	v_rcp_f32_e32 v3, v3
	v_rcp_f32_e32 v44, v20
	v_rcp_f32_e32 v45, v21
	v_rcp_f32_e32 v46, v48
	v_rcp_f32_e32 v47, v49
	v_rcp_f32_e32 v48, v50
	v_rcp_f32_e32 v49, v51
	v_mul_f32_e32 v20, v18, v2
	v_mul_f32_e32 v21, v19, v3
	v_mul_f32_e32 v18, v0, v44
	v_mul_f32_e32 v19, v1, v45
	v_mul_f32_e32 v2, v42, v46
	v_mul_f32_e32 v3, v43, v47
	v_mul_f32_e32 v0, v40, v48
	v_mul_f32_e32 v1, v41, v49
	s_cbranch_vccnz .LBB0_366
	v_mad_i64_i32 v[44:45], s[16:17], v39, s22, v[6:7]
	v_add_co_u32_e32 v44, vcc, 0xc0cf000, v44
	v_cvt_pk_bf16_f32 v40, v20, v21
	v_cvt_pk_bf16_f32 v41, v18, v19
	v_cvt_pk_bf16_f32 v42, v2, v3
	v_cvt_pk_bf16_f32 v43, v0, v1
	v_addc_co_u32_e32 v45, vcc, 0, v45, vcc
	global_store_dwordx4 v[44:45], v[40:43], off offset:2560
	s_mov_b64 s[16:17], 0
	s_nop 0
	v_cvt_pk_bf16_f32 v40, v20, s0
	ds_write_b16 v33, v40
	v_cvt_pk_bf16_f32 v40, v21, s0
	ds_write_b16 v33, v40 offset:144
	v_cvt_pk_bf16_f32 v40, v18, s0
	ds_write_b16 v33, v40 offset:288
	v_cvt_pk_bf16_f32 v40, v19, s0
	ds_write_b16 v33, v40 offset:432
	v_cvt_pk_bf16_f32 v40, v2, s0
	ds_write_b16 v33, v40 offset:576
	v_cvt_pk_bf16_f32 v40, v3, s0
	ds_write_b16 v33, v40 offset:720
	v_cvt_pk_bf16_f32 v40, v0, s0
	ds_write_b16 v33, v40 offset:864
	v_cvt_pk_bf16_f32 v40, v1, s0
	ds_write_b16 v33, v40 offset:1008

.LBB0_384:
	s_or_b64 exec, exec, s[16:17]
	global_load_dwordx4 v[44:47], v[10:11], off
	s_nop 0
	global_load_dwordx4 v[8:11], v[10:11], off offset:16
	s_nop 0
	global_load_dwordx4 v[48:51], v[14:15], off
	global_load_dwordx4 v[52:55], v[14:15], off offset:16
	global_load_dwordx4 v[56:59], v[16:17], off
	s_nop 0
	global_load_dwordx4 v[14:17], v[16:17], off offset:16
	s_waitcnt vmcnt(6)
	v_lshlrev_b32_e32 v62, 16, v0
	v_and_b32_e32 v63, 0xffff0000, v0
	v_lshlrev_b32_e32 v0, 16, v1
	v_and_b32_e32 v1, 0xffff0000, v1
	v_lshlrev_b32_e32 v70, 16, v2
	v_and_b32_e32 v71, 0xffff0000, v2
	v_lshlrev_b32_e32 v2, 16, v3
	v_and_b32_e32 v3, 0xffff0000, v3
	v_lshlrev_b32_e32 v60, 16, v40
	v_lshlrev_b32_e32 v64, 16, v43
	v_and_b32_e32 v61, 0xffff0000, v40
	v_and_b32_e32 v65, 0xffff0000, v43
	v_lshlrev_b32_e32 v66, 16, v21
	v_lshlrev_b32_e32 v68, 16, v42
	v_and_b32_e32 v67, 0xffff0000, v21
	v_and_b32_e32 v69, 0xffff0000, v42
	v_lshlrev_b32_e32 v42, 16, v20
	v_and_b32_e32 v43, 0xffff0000, v20
	v_lshlrev_b32_e32 v20, 16, v19
	v_and_b32_e32 v21, 0xffff0000, v19
	v_lshlrev_b32_e32 v40, 16, v41
	v_and_b32_e32 v41, 0xffff0000, v41
	v_lshlrev_b32_e32 v72, 16, v39
	v_and_b32_e32 v73, 0xffff0000, v39
	s_and_b64 vcc, exec, s[0:1]
	s_mov_b64 s[0:1], -1
	s_waitcnt vmcnt(5)
	v_mul_f32_e32 v44, v44, v62
	v_mul_f32_e32 v45, v45, v63
	v_mul_f32_e32 v0, v46, v0
	v_mul_f32_e32 v1, v47, v1
	s_waitcnt vmcnt(4)
	v_mul_f32_e32 v8, v8, v70
	v_mul_f32_e32 v9, v9, v71
	v_mul_f32_e32 v2, v10, v2
	v_mul_f32_e32 v3, v11, v3
	s_waitcnt vmcnt(3)
	v_fma_f32 v10, v48, v60, v44
	v_fma_f32 v11, v49, v61, v45
	v_fma_f32 v0, v50, v66, v0
	v_fma_f32 v1, v51, v67, v1
	s_waitcnt vmcnt(2)
	v_fma_f32 v8, v52, v42, v8
	v_fma_f32 v9, v53, v43, v9
	v_fma_f32 v2, v54, v20, v2
	v_fma_f32 v3, v55, v21, v3
	s_waitcnt vmcnt(1)
	v_fma_f32 v10, v56, v64, v10
	v_fma_f32 v11, v57, v65, v11
	v_fma_f32 v0, v58, v68, v0
	v_fma_f32 v1, v59, v69, v1
	s_waitcnt vmcnt(0)
	v_fma_f32 v14, v14, v40, v8
	v_fma_f32 v15, v15, v41, v9
	v_fma_f32 v16, v16, v72, v2
	v_fma_f32 v17, v17, v73, v3
	v_mul_f32_e32 v2, 0xbfb8aa3b, v10
	v_mul_f32_e32 v3, 0xbfb8aa3b, v11
	v_mul_f32_e32 v8, 0xbfb8aa3b, v0
	v_mul_f32_e32 v9, 0xbfb8aa3b, v1
	v_mul_f32_e32 v19, 0xbfb8aa3b, v14
	v_mul_f32_e32 v20, 0xbfb8aa3b, v15
	v_mul_f32_e32 v21, 0xbfb8aa3b, v16
	v_mul_f32_e32 v39, 0xbfb8aa3b, v17
	v_exp_f32_e32 v2, v2
	v_exp_f32_e32 v3, v3
	v_exp_f32_e32 v8, v8
	v_exp_f32_e32 v9, v9
	v_exp_f32_e32 v19, v19
	v_exp_f32_e32 v20, v20
	v_exp_f32_e32 v21, v21
	v_exp_f32_e32 v39, v39
	v_add_f32_e32 v2, 1.0, v2
	v_add_f32_e32 v3, 1.0, v3
	v_add_f32_e32 v8, 1.0, v8
	v_add_f32_e32 v9, 1.0, v9
	v_add_f32_e32 v19, 1.0, v19
	v_add_f32_e32 v40, 1.0, v20
	v_add_f32_e32 v41, 1.0, v21
	v_add_f32_e32 v39, 1.0, v39
	v_rcp_f32_e32 v2, v2
	v_rcp_f32_e32 v3, v3
	v_rcp_f32_e32 v8, v8
	v_rcp_f32_e32 v9, v9
	v_rcp_f32_e32 v20, v19
	v_rcp_f32_e32 v21, v40
	v_rcp_f32_e32 v40, v41
	v_rcp_f32_e32 v41, v39
	v_mul_f32_e32 v10, v10, v2
	v_mul_f32_e32 v11, v11, v3
	v_mul_f32_e32 v8, v0, v8
	v_mul_f32_e32 v9, v1, v9
	v_mul_f32_e32 v2, v14, v20
	v_mul_f32_e32 v3, v15, v21
	v_mul_f32_e32 v0, v16, v40
	v_mul_f32_e32 v1, v17, v41
	s_cbranch_vccnz .LBB0_386
	v_mad_i64_i32 v[6:7], s[0:1], v18, s22, v[6:7]
	v_add_co_u32_e32 v6, vcc, 0xc0cf000, v6
	v_cvt_pk_bf16_f32 v14, v10, v11
	v_cvt_pk_bf16_f32 v15, v8, v9
	v_cvt_pk_bf16_f32 v16, v2, v3
	v_cvt_pk_bf16_f32 v17, v0, v1
	v_addc_co_u32_e32 v7, vcc, 0, v7, vcc
	global_store_dwordx4 v[6:7], v[14:17], off offset:2560
	v_cvt_pk_bf16_f32 v6, v10, s0
	ds_write_b16 v34, v6
	v_cvt_pk_bf16_f32 v6, v11, s0
	ds_write_b16 v34, v6 offset:144
	v_cvt_pk_bf16_f32 v6, v8, s0
	ds_write_b16 v34, v6 offset:288
	v_cvt_pk_bf16_f32 v6, v9, s0
	ds_write_b16 v34, v6 offset:432
	v_cvt_pk_bf16_f32 v6, v2, s0
	ds_write_b16 v34, v6 offset:576
	v_cvt_pk_bf16_f32 v6, v3, s0
	ds_write_b16 v34, v6 offset:720
	v_cvt_pk_bf16_f32 v6, v0, s0
	ds_write_b16 v34, v6 offset:864
	v_cvt_pk_bf16_f32 v6, v1, s0
	s_mov_b64 s[0:1], 0
	ds_write_b16 v34, v6 offset:1008
.LBB0_386:
	s_andn2_b64 vcc, exec, s[0:1]
	s_cbranch_vccnz .LBB0_388
	v_mul_f32_e32 v6, s12, v10
	v_mul_f32_e32 v7, s12, v11
	v_mul_f32_e32 v8, s12, v8
	v_mul_f32_e32 v9, s12, v9
	v_mul_f32_e32 v2, s12, v2
	v_mul_f32_e32 v3, s12, v3
	v_mul_f32_e32 v0, s12, v0
	v_mul_f32_e32 v1, s12, v1
	v_cvt_pk_bf16_f32 v6, v6, v7
	v_cvt_pk_bf16_f32 v7, v8, v9
	v_cvt_pk_bf16_f32 v8, v2, v3
	v_cvt_pk_bf16_f32 v9, v0, v1
	v_mad_i64_i32 v[0:1], s[0:1], v18, s22, v[12:13]
	global_store_dwordx4 v[0:1], v[6:9], off

.LBB0_449:
	v_and_b32_e32 v65, 64, v183
	v_xor_b32_e32 v64, 1, v183
	v_add_u32_e32 v65, 64, v65
	v_add_u32_e32 v85, s30, v152
	v_cmp_lt_i32_e32 vcc, v64, v65
	v_mul_u32_u24_e32 v65, v85, v141
	v_cvt_f32_u32_e32 v65, v65
	v_cndmask_b32_e32 v64, v183, v64, vcc
	v_lshlrev_b32_e32 v86, 2, v64
	ds_bpermute_b32 v70, v86, v60
	v_mul_f32_e32 v65, 0x39000000, v65
	v_cos_f32_e32 v66, v65
	v_sin_f32_e32 v68, v65
	v_mad_u32_u24 v65, v85, v141, v85
	v_cvt_f32_u32_e32 v67, v65
	ds_bpermute_b32 v71, v86, v61
	ds_bpermute_b32 v74, v86, v62
	ds_bpermute_b32 v75, v86, v63
	v_mul_f32_e32 v69, 0x39000000, v67
	v_cos_f32_e32 v67, v69
	v_sin_f32_e32 v69, v69
	s_and_b32 s38, s66, -2
	v_lshl_add_u32 v64, v85, 9, s38
	v_mov_b32_e32 v119, v99
	s_waitcnt lgkmcnt(2)
	v_mul_f32_e32 v70, v68, v70
	v_mul_f32_e32 v71, v69, v71
	ds_bpermute_b32 v80, v86, v58
	v_cndmask_b32_e64 v71, -v71, v71, s[18:19]
	v_cndmask_b32_e64 v70, -v70, v70, s[18:19]
	v_fma_f32 v72, v66, v60, v70
	v_fma_f32 v73, v67, v61, v71
	v_add_u32_e32 v61, v65, v85
	v_cvt_f32_u32_e32 v60, v61
	v_add_u32_e32 v76, v61, v85
	v_cvt_f32_u32_e32 v61, v76
	v_cvt_pk_bf16_f32 v72, v72, v73
	v_mul_f32_e32 v65, 0x39000000, v60
	v_cos_f32_e32 v60, v65
	v_sin_f32_e32 v70, v65
	v_mul_f32_e32 v65, 0x39000000, v61
	v_sin_f32_e32 v71, v65
	v_cos_f32_e32 v61, v65
	v_ashrrev_i32_e32 v65, 31, v64
	ds_bpermute_b32 v81, v86, v59
	s_waitcnt lgkmcnt(2)
	v_mul_f32_e32 v74, v70, v74
	v_mul_f32_e32 v75, v71, v75
	ds_bpermute_b32 v88, v86, v54
	v_cndmask_b32_e64 v75, -v75, v75, s[18:19]
	v_cndmask_b32_e64 v74, -v74, v74, s[18:19]
	v_fma_f32 v62, v60, v62, v74
	v_fma_f32 v63, v61, v63, v75
	ds_bpermute_b32 v74, v86, v56
	v_cvt_pk_bf16_f32 v73, v62, v63
	v_lshlrev_b64 v[62:63], 8, v[64:65]
	v_lshl_add_u64 v[62:63], s[28:29], 0, v[62:63]
	v_lshl_add_u64 v[78:79], v[62:63], 0, v[118:119]
	v_mad_u32_u24 v63, v85, 13, v76
	v_and_b32_e32 v62, 0x1ffc, v63
	v_cvt_f32_u32_e32 v62, v62
	global_store_dwordx2 v[78:79], v[72:73], off
	ds_bpermute_b32 v75, v86, v57
	ds_bpermute_b32 v89, v86, v55
	v_mul_f32_e32 v65, 0x39000000, v62
	v_cos_f32_e32 v62, v65
	v_sin_f32_e32 v72, v65
	v_add_u32_e32 v65, v63, v85
	v_and_b32_e32 v63, 0x1fff, v65
	v_cvt_f32_u32_e32 v63, v63
	ds_bpermute_b32 v90, v86, v50
	ds_bpermute_b32 v91, v86, v51
	v_mul_f32_e32 v73, 0x39000000, v63
	v_cos_f32_e32 v63, v73
	v_sin_f32_e32 v73, v73
	s_waitcnt lgkmcnt(3)
	v_mul_f32_e32 v74, v72, v74
	v_mul_f32_e32 v75, v73, v75
	s_nop 0
	v_cndmask_b32_e64 v75, -v75, v75, s[18:19]
	v_cndmask_b32_e64 v74, -v74, v74, s[18:19]
	v_fma_f32 v76, v62, v56, v74
	v_fma_f32 v77, v63, v57, v75
	v_add_u32_e32 v57, v65, v85
	v_and_b32_e32 v56, 0x1ffe, v57
	v_cvt_f32_u32_e32 v56, v56
	v_cvt_pk_bf16_f32 v76, v76, v77
	v_mul_f32_e32 v65, 0x39000000, v56
	v_cos_f32_e32 v56, v65
	v_sin_f32_e32 v74, v65
	v_add_u32_e32 v65, v57, v85
	v_and_b32_e32 v57, 0x1fff, v65
	v_cvt_f32_u32_e32 v57, v57
	v_mul_f32_e32 v75, 0x39000000, v57
	v_cos_f32_e32 v57, v75
	v_sin_f32_e32 v75, v75
	s_nop 0
	v_mul_f32_e32 v80, v74, v80
	v_mul_f32_e32 v81, v75, v81
	s_nop 0
	v_cndmask_b32_e64 v81, -v81, v81, s[18:19]
	v_cndmask_b32_e64 v80, -v80, v80, s[18:19]
	v_fma_f32 v58, v56, v58, v80
	v_fma_f32 v59, v57, v59, v81
	ds_bpermute_b32 v80, v86, v52
	v_cvt_pk_bf16_f32 v77, v58, v59
	v_mad_u32_u24 v59, v85, 13, v65
	v_and_b32_e32 v58, 0x1ffc, v59
	v_cvt_f32_u32_e32 v58, v58
	global_store_dwordx2 v[78:79], v[76:77], off offset:32
	ds_bpermute_b32 v81, v86, v53
	v_mul_f32_e32 v65, 0x39000000, v58
	v_cos_f32_e32 v58, v65
	v_sin_f32_e32 v76, v65
	v_add_u32_e32 v65, v59, v85
	v_and_b32_e32 v59, 0x1fff, v65
	v_cvt_f32_u32_e32 v59, v59
	v_mul_f32_e32 v77, 0x39000000, v59
	v_cos_f32_e32 v59, v77
	v_sin_f32_e32 v77, v77
	s_waitcnt lgkmcnt(0)
	v_mul_f32_e32 v80, v76, v80
	v_mul_f32_e32 v81, v77, v81
	s_nop 0
	v_cndmask_b32_e64 v81, -v81, v81, s[18:19]
	v_cndmask_b32_e64 v80, -v80, v80, s[18:19]
	v_fma_f32 v82, v58, v52, v80
	v_fma_f32 v83, v59, v53, v81
	v_add_u32_e32 v53, v65, v85
	v_and_b32_e32 v52, 0x1ffe, v53
	v_cvt_f32_u32_e32 v52, v52
	v_cvt_pk_bf16_f32 v82, v82, v83
	v_mul_f32_e32 v65, 0x39000000, v52
	v_cos_f32_e32 v52, v65
	v_sin_f32_e32 v80, v65
	v_add_u32_e32 v65, v53, v85
	v_and_b32_e32 v53, 0x1fff, v65
	v_cvt_f32_u32_e32 v53, v53
	v_mul_f32_e32 v81, 0x39000000, v53
	v_cos_f32_e32 v53, v81
	v_sin_f32_e32 v81, v81
	s_nop 0
	v_mul_f32_e32 v88, v80, v88
	v_mul_f32_e32 v89, v81, v89
	s_nop 0
	v_cndmask_b32_e64 v89, -v89, v89, s[18:19]
	v_cndmask_b32_e64 v88, -v88, v88, s[18:19]
	v_fma_f32 v54, v52, v54, v88
	v_fma_f32 v55, v53, v55, v89
	ds_bpermute_b32 v88, v86, v48
	v_cvt_pk_bf16_f32 v83, v54, v55
	v_mad_u32_u24 v55, v85, 13, v65
	v_and_b32_e32 v54, 0x1ffc, v55
	v_cvt_f32_u32_e32 v54, v54
	global_store_dwordx2 v[78:79], v[82:83], off offset:64
	ds_bpermute_b32 v89, v86, v49
	v_mul_f32_e32 v65, 0x39000000, v54
	v_cos_f32_e32 v54, v65
	v_sin_f32_e32 v82, v65
	v_add_u32_e32 v65, v55, v85
	v_and_b32_e32 v55, 0x1fff, v65
	v_cvt_f32_u32_e32 v55, v55
	v_mul_f32_e32 v83, 0x39000000, v55
	v_cos_f32_e32 v55, v83
	v_sin_f32_e32 v83, v83
	s_waitcnt lgkmcnt(0)
	v_mul_f32_e32 v88, v82, v88
	v_mul_f32_e32 v89, v83, v89
	s_nop 0
	v_cndmask_b32_e64 v89, -v89, v89, s[18:19]
	v_cndmask_b32_e64 v88, -v88, v88, s[18:19]
	v_fma_f32 v88, v54, v48, v88
	v_fma_f32 v89, v55, v49, v89
	v_add_u32_e32 v49, v65, v85
	v_and_b32_e32 v48, 0x1ffe, v49
	v_add_u32_e32 v49, v49, v85
	v_cvt_f32_u32_e32 v48, v48
	v_and_b32_e32 v49, 0x1fff, v49
	v_cvt_f32_u32_e32 v49, v49
	v_cvt_pk_bf16_f32 v88, v88, v89
	v_mul_f32_e32 v65, 0x39000000, v48
	v_cos_f32_e32 v48, v65
	v_sin_f32_e32 v84, v65
	v_mul_f32_e32 v65, 0x39000000, v49
	v_sin_f32_e32 v85, v65
	v_cos_f32_e32 v49, v65
	v_mul_f32_e32 v90, v84, v90
	v_mul_f32_e32 v91, v85, v91
	s_nop 0
	v_cndmask_b32_e64 v91, -v91, v91, s[18:19]
	v_cndmask_b32_e64 v90, -v90, v90, s[18:19]
	v_fma_f32 v50, v48, v50, v90
	v_fma_f32 v51, v49, v51, v91
	s_nop 0
	v_cvt_pk_bf16_f32 v89, v50, v51
	ds_bpermute_b32 v50, v86, v44
	ds_bpermute_b32 v51, v86, v45
	global_store_dwordx2 v[78:79], v[88:89], off offset:96
	s_waitcnt lgkmcnt(0)
	v_mul_f32_e32 v50, v68, v50
	v_mul_f32_e32 v51, v69, v51
	s_nop 0
	v_cndmask_b32_e64 v51, -v51, v51, s[18:19]
	v_cndmask_b32_e64 v50, -v50, v50, s[18:19]
	v_fma_f32 v44, v66, v44, v50
	v_fma_f32 v45, v67, v45, v51
	ds_bpermute_b32 v50, v86, v46
	ds_bpermute_b32 v51, v86, v47
	v_cvt_pk_bf16_f32 v44, v44, v45
	s_waitcnt lgkmcnt(0)
	v_mul_f32_e32 v50, v70, v50
	v_mul_f32_e32 v51, v71, v51
	s_nop 0
	v_cndmask_b32_e64 v51, -v51, v51, s[18:19]
	v_cndmask_b32_e64 v50, -v50, v50, s[18:19]
	v_fma_f32 v46, v60, v46, v50
	v_fma_f32 v47, v61, v47, v51
	v_or_b32_e32 v50, 1, v64
	v_ashrrev_i32_e32 v51, 31, v50
	v_cvt_pk_bf16_f32 v45, v46, v47
	v_lshlrev_b64 v[46:47], 8, v[50:51]
	v_lshl_add_u64 v[46:47], s[28:29], 0, v[46:47]
	v_lshl_add_u64 v[46:47], v[46:47], 0, v[118:119]
	global_store_dwordx2 v[46:47], v[44:45], off
	ds_bpermute_b32 v44, v86, v40
	ds_bpermute_b32 v45, v86, v41
	s_waitcnt lgkmcnt(0)
	v_mul_f32_e32 v44, v72, v44
	v_mul_f32_e32 v45, v73, v45
	s_nop 0
	v_cndmask_b32_e64 v45, -v45, v45, s[18:19]
	v_cndmask_b32_e64 v44, -v44, v44, s[18:19]
	v_fma_f32 v40, v62, v40, v44
	v_fma_f32 v41, v63, v41, v45
	ds_bpermute_b32 v44, v86, v42
	ds_bpermute_b32 v45, v86, v43
	v_cvt_pk_bf16_f32 v40, v40, v41
	s_waitcnt lgkmcnt(0)
	v_mul_f32_e32 v44, v74, v44
	v_mul_f32_e32 v45, v75, v45
	s_nop 0
	v_cndmask_b32_e64 v45, -v45, v45, s[18:19]
	v_cndmask_b32_e64 v44, -v44, v44, s[18:19]
	v_fma_f32 v42, v56, v42, v44
	v_fma_f32 v43, v57, v43, v45
	ds_bpermute_b32 v56, v86, v14
	v_cvt_pk_bf16_f32 v41, v42, v43
	global_store_dwordx2 v[46:47], v[40:41], off offset:32
	ds_bpermute_b32 v40, v86, v36
	ds_bpermute_b32 v41, v86, v37
	ds_bpermute_b32 v42, v86, v30
	ds_bpermute_b32 v43, v86, v31
	ds_bpermute_b32 v57, v86, v15
	s_waitcnt lgkmcnt(3)
	v_mul_f32_e32 v40, v76, v40
	v_mul_f32_e32 v41, v77, v41
	s_nop 0
	v_cndmask_b32_e64 v41, -v41, v41, s[18:19]
	v_cndmask_b32_e64 v40, -v40, v40, s[18:19]
	v_fma_f32 v36, v58, v36, v40
	v_fma_f32 v37, v59, v37, v41
	ds_bpermute_b32 v40, v86, v38
	ds_bpermute_b32 v41, v86, v39
	v_cvt_pk_bf16_f32 v36, v36, v37
	s_waitcnt lgkmcnt(0)
	v_mul_f32_e32 v40, v80, v40
	v_mul_f32_e32 v41, v81, v41
	s_nop 0
	v_cndmask_b32_e64 v41, -v41, v41, s[18:19]
	v_cndmask_b32_e64 v40, -v40, v40, s[18:19]
	v_fma_f32 v38, v52, v38, v40
	v_fma_f32 v39, v53, v39, v41
	s_nop 0
	v_cvt_pk_bf16_f32 v37, v38, v39
	global_store_dwordx2 v[46:47], v[36:37], off offset:64
	ds_bpermute_b32 v36, v86, v32
	ds_bpermute_b32 v37, v86, v33
	ds_bpermute_b32 v38, v86, v28
	ds_bpermute_b32 v39, v86, v29
	s_waitcnt lgkmcnt(2)
	v_mul_f32_e32 v36, v82, v36
	v_mul_f32_e32 v37, v83, v37
	s_nop 0
	v_cndmask_b32_e64 v37, -v37, v37, s[18:19]
	v_cndmask_b32_e64 v36, -v36, v36, s[18:19]
	v_fma_f32 v32, v54, v32, v36
	v_fma_f32 v33, v55, v33, v37
	ds_bpermute_b32 v36, v86, v34
	ds_bpermute_b32 v37, v86, v35
	v_cvt_pk_bf16_f32 v32, v32, v33
	ds_bpermute_b32 v54, v86, v22
	ds_bpermute_b32 v55, v86, v23
	s_waitcnt lgkmcnt(2)
	v_mul_f32_e32 v36, v84, v36
	v_mul_f32_e32 v37, v85, v37
	s_nop 0
	v_cndmask_b32_e64 v37, -v37, v37, s[18:19]
	v_cndmask_b32_e64 v36, -v36, v36, s[18:19]
	v_fma_f32 v34, v48, v34, v36
	v_fma_f32 v35, v49, v35, v37
	ds_bpermute_b32 v48, v86, v26
	v_cvt_pk_bf16_f32 v33, v34, v35
	global_store_dwordx2 v[46:47], v[32:33], off offset:96
	v_or_b32_e32 v32, 8, v152
	v_add_u32_e32 v53, s30, v32
	v_mul_u32_u24_e32 v33, v53, v141
	v_cvt_f32_u32_e32 v33, v33
	v_lshl_add_u32 v32, v53, 9, s38
	ds_bpermute_b32 v49, v86, v27
	v_mul_f32_e32 v33, 0x39000000, v33
	v_cos_f32_e32 v34, v33
	v_sin_f32_e32 v36, v33
	v_mad_u32_u24 v33, v53, v141, v53
	v_cvt_f32_u32_e32 v35, v33
	v_mul_f32_e32 v37, 0x39000000, v35
	v_cos_f32_e32 v35, v37
	v_sin_f32_e32 v37, v37
	s_nop 0
	v_mul_f32_e32 v38, v36, v38
	v_mul_f32_e32 v39, v37, v39
	s_nop 0
	v_cndmask_b32_e64 v39, -v39, v39, s[18:19]
	v_cndmask_b32_e64 v38, -v38, v38, s[18:19]
	v_fma_f32 v40, v34, v28, v38
	v_fma_f32 v41, v35, v29, v39
	v_add_u32_e32 v29, v33, v53
	v_cvt_f32_u32_e32 v28, v29
	v_add_u32_e32 v44, v29, v53
	v_cvt_f32_u32_e32 v29, v44
	v_cvt_pk_bf16_f32 v40, v40, v41
	v_mul_f32_e32 v33, 0x39000000, v28
	v_cos_f32_e32 v28, v33
	v_sin_f32_e32 v38, v33
	v_mul_f32_e32 v33, 0x39000000, v29
	v_sin_f32_e32 v39, v33
	v_cos_f32_e32 v29, v33
	v_ashrrev_i32_e32 v33, 31, v32
	v_mul_f32_e32 v42, v38, v42
	v_mul_f32_e32 v43, v39, v43
	s_nop 0
	v_cndmask_b32_e64 v43, -v43, v43, s[18:19]
	v_cndmask_b32_e64 v42, -v42, v42, s[18:19]
	v_fma_f32 v30, v28, v30, v42
	v_fma_f32 v31, v29, v31, v43
	ds_bpermute_b32 v42, v86, v24
	v_cvt_pk_bf16_f32 v41, v30, v31
	v_lshlrev_b64 v[30:31], 8, v[32:33]
	v_lshl_add_u64 v[30:31], s[28:29], 0, v[30:31]
	v_lshl_add_u64 v[46:47], v[30:31], 0, v[118:119]
	v_mad_u32_u24 v31, v53, 13, v44
	v_and_b32_e32 v30, 0x1ffc, v31
	v_cvt_f32_u32_e32 v30, v30
	global_store_dwordx2 v[46:47], v[40:41], off
	ds_bpermute_b32 v43, v86, v25
	v_mul_f32_e32 v33, 0x39000000, v30
	v_cos_f32_e32 v30, v33
	v_sin_f32_e32 v40, v33
	v_add_u32_e32 v33, v31, v53
	v_and_b32_e32 v31, 0x1fff, v33
	v_cvt_f32_u32_e32 v31, v31
	v_mul_f32_e32 v41, 0x39000000, v31
	v_cos_f32_e32 v31, v41
	v_sin_f32_e32 v41, v41
	s_waitcnt lgkmcnt(0)
	v_mul_f32_e32 v42, v40, v42
	v_mul_f32_e32 v43, v41, v43
	s_nop 0
	v_cndmask_b32_e64 v43, -v43, v43, s[18:19]
	v_cndmask_b32_e64 v42, -v42, v42, s[18:19]
	v_fma_f32 v44, v30, v24, v42
	v_fma_f32 v45, v31, v25, v43
	v_add_u32_e32 v25, v33, v53
	v_and_b32_e32 v24, 0x1ffe, v25
	v_cvt_f32_u32_e32 v24, v24
	v_cvt_pk_bf16_f32 v44, v44, v45
	v_mul_f32_e32 v33, 0x39000000, v24
	v_cos_f32_e32 v24, v33
	v_sin_f32_e32 v42, v33
	v_add_u32_e32 v33, v25, v53
	v_and_b32_e32 v25, 0x1fff, v33
	v_cvt_f32_u32_e32 v25, v25
	v_mul_f32_e32 v43, 0x39000000, v25
	v_cos_f32_e32 v25, v43
	v_sin_f32_e32 v43, v43
	s_nop 0
	v_mul_f32_e32 v48, v42, v48
	v_mul_f32_e32 v49, v43, v49
	s_nop 0
	v_cndmask_b32_e64 v49, -v49, v49, s[18:19]
	v_cndmask_b32_e64 v48, -v48, v48, s[18:19]
	v_fma_f32 v26, v24, v26, v48
	v_fma_f32 v27, v25, v27, v49
	ds_bpermute_b32 v48, v86, v20
	v_cvt_pk_bf16_f32 v45, v26, v27
	v_mad_u32_u24 v27, v53, 13, v33
	v_and_b32_e32 v26, 0x1ffc, v27
	v_cvt_f32_u32_e32 v26, v26
	global_store_dwordx2 v[46:47], v[44:45], off offset:32
	ds_bpermute_b32 v49, v86, v21
	v_mul_f32_e32 v33, 0x39000000, v26
	v_cos_f32_e32 v26, v33
	v_sin_f32_e32 v44, v33
	v_add_u32_e32 v33, v27, v53
	v_and_b32_e32 v27, 0x1fff, v33
	v_cvt_f32_u32_e32 v27, v27
	v_mul_f32_e32 v45, 0x39000000, v27
	v_cos_f32_e32 v27, v45
	v_sin_f32_e32 v45, v45
	s_waitcnt lgkmcnt(0)
	v_mul_f32_e32 v48, v44, v48
	v_mul_f32_e32 v49, v45, v49
	s_nop 0
	v_cndmask_b32_e64 v49, -v49, v49, s[18:19]
	v_cndmask_b32_e64 v48, -v48, v48, s[18:19]
	v_fma_f32 v50, v26, v20, v48
	v_fma_f32 v51, v27, v21, v49
	v_add_u32_e32 v21, v33, v53
	v_and_b32_e32 v20, 0x1ffe, v21
	v_cvt_f32_u32_e32 v20, v20
	v_cvt_pk_bf16_f32 v50, v50, v51
	v_mul_f32_e32 v33, 0x39000000, v20
	v_cos_f32_e32 v20, v33
	v_sin_f32_e32 v48, v33
	v_add_u32_e32 v33, v21, v53
	v_and_b32_e32 v21, 0x1fff, v33
	v_cvt_f32_u32_e32 v21, v21
	v_mul_f32_e32 v49, 0x39000000, v21
	v_cos_f32_e32 v21, v49
	v_sin_f32_e32 v49, v49
	s_nop 0
	v_mul_f32_e32 v54, v48, v54
	v_mul_f32_e32 v55, v49, v55
	s_nop 0
	v_cndmask_b32_e64 v55, -v55, v55, s[18:19]
	v_cndmask_b32_e64 v54, -v54, v54, s[18:19]
	v_fma_f32 v22, v20, v22, v54
	v_fma_f32 v23, v21, v23, v55
	ds_bpermute_b32 v54, v86, v12
	v_cvt_pk_bf16_f32 v51, v22, v23
	v_mad_u32_u24 v23, v53, 13, v33
	v_and_b32_e32 v22, 0x1ffc, v23
	v_cvt_f32_u32_e32 v22, v22
	global_store_dwordx2 v[46:47], v[50:51], off offset:64
	ds_bpermute_b32 v55, v86, v13
	v_mul_f32_e32 v33, 0x39000000, v22
	v_cos_f32_e32 v22, v33
	v_sin_f32_e32 v50, v33
	v_add_u32_e32 v33, v23, v53
	v_and_b32_e32 v23, 0x1fff, v33
	v_cvt_f32_u32_e32 v23, v23
	v_mul_f32_e32 v51, 0x39000000, v23
	v_cos_f32_e32 v23, v51
	v_sin_f32_e32 v51, v51
	s_waitcnt lgkmcnt(0)
	v_mul_f32_e32 v54, v50, v54
	v_mul_f32_e32 v55, v51, v55
	s_nop 0
	v_cndmask_b32_e64 v55, -v55, v55, s[18:19]
	v_cndmask_b32_e64 v54, -v54, v54, s[18:19]
	v_fma_f32 v54, v22, v12, v54
	v_fma_f32 v55, v23, v13, v55
	v_add_u32_e32 v13, v33, v53
	v_and_b32_e32 v12, 0x1ffe, v13
	v_add_u32_e32 v13, v13, v53
	v_cvt_f32_u32_e32 v12, v12
	v_and_b32_e32 v13, 0x1fff, v13
	v_cvt_f32_u32_e32 v13, v13
	v_cvt_pk_bf16_f32 v54, v54, v55
	v_mul_f32_e32 v33, 0x39000000, v12
	v_cos_f32_e32 v12, v33
	v_sin_f32_e32 v52, v33
	v_mul_f32_e32 v33, 0x39000000, v13
	v_sin_f32_e32 v53, v33
	v_cos_f32_e32 v13, v33
	v_mul_f32_e32 v56, v52, v56
	v_mul_f32_e32 v57, v53, v57
	s_nop 0
	v_cndmask_b32_e64 v57, -v57, v57, s[18:19]
	v_cndmask_b32_e64 v56, -v56, v56, s[18:19]
	v_fma_f32 v14, v12, v14, v56
	v_fma_f32 v15, v13, v15, v57
	s_nop 0
	v_cvt_pk_bf16_f32 v55, v14, v15
	ds_bpermute_b32 v14, v86, v16
	ds_bpermute_b32 v15, v86, v17
	global_store_dwordx2 v[46:47], v[54:55], off offset:96
	s_waitcnt lgkmcnt(0)
	v_mul_f32_e32 v14, v36, v14
	v_mul_f32_e32 v15, v37, v15
	s_nop 0
	v_cndmask_b32_e64 v15, -v15, v15, s[18:19]
	v_cndmask_b32_e64 v14, -v14, v14, s[18:19]
	v_fma_f32 v14, v34, v16, v14
	v_fma_f32 v15, v35, v17, v15
	ds_bpermute_b32 v16, v86, v18
	ds_bpermute_b32 v17, v86, v19
	v_cvt_pk_bf16_f32 v14, v14, v15
	s_waitcnt lgkmcnt(0)
	v_mul_f32_e32 v16, v38, v16
	v_mul_f32_e32 v17, v39, v17
	s_nop 0
	v_cndmask_b32_e64 v17, -v17, v17, s[18:19]
	v_cndmask_b32_e64 v16, -v16, v16, s[18:19]
	v_fma_f32 v16, v28, v18, v16
	v_fma_f32 v17, v29, v19, v17
	v_or_b32_e32 v18, 1, v32
	v_ashrrev_i32_e32 v19, 31, v18
	v_cvt_pk_bf16_f32 v15, v16, v17
	v_lshlrev_b64 v[16:17], 8, v[18:19]
	v_lshl_add_u64 v[16:17], s[28:29], 0, v[16:17]
	v_lshl_add_u64 v[16:17], v[16:17], 0, v[118:119]
	global_store_dwordx2 v[16:17], v[14:15], off
	ds_bpermute_b32 v14, v86, v8
	ds_bpermute_b32 v15, v86, v9
	s_waitcnt lgkmcnt(0)
	v_mul_f32_e32 v14, v40, v14
	v_mul_f32_e32 v15, v41, v15
	s_nop 0
	v_cndmask_b32_e64 v15, -v15, v15, s[18:19]
	v_cndmask_b32_e64 v14, -v14, v14, s[18:19]
	v_fma_f32 v8, v30, v8, v14
	v_fma_f32 v9, v31, v9, v15
	ds_bpermute_b32 v14, v86, v10
	ds_bpermute_b32 v15, v86, v11
	v_cvt_pk_bf16_f32 v8, v8, v9
	s_waitcnt lgkmcnt(0)
	v_mul_f32_e32 v14, v42, v14
	v_mul_f32_e32 v15, v43, v15
	s_nop 0
	v_cndmask_b32_e64 v15, -v15, v15, s[18:19]
	v_cndmask_b32_e64 v14, -v14, v14, s[18:19]
	v_fma_f32 v10, v24, v10, v14
	v_fma_f32 v11, v25, v11, v15
	s_nop 0
	v_cvt_pk_bf16_f32 v9, v10, v11
	global_store_dwordx2 v[16:17], v[8:9], off offset:32
	ds_bpermute_b32 v8, v86, v4
	ds_bpermute_b32 v9, v86, v5
	s_waitcnt lgkmcnt(0)
	v_mul_f32_e32 v8, v44, v8
	v_mul_f32_e32 v9, v45, v9
	s_nop 0
	v_cndmask_b32_e64 v9, -v9, v9, s[18:19]
	v_cndmask_b32_e64 v8, -v8, v8, s[18:19]
	v_fma_f32 v4, v26, v4, v8
	v_fma_f32 v5, v27, v5, v9
	ds_bpermute_b32 v8, v86, v6
	ds_bpermute_b32 v9, v86, v7
	v_cvt_pk_bf16_f32 v4, v4, v5
	s_waitcnt lgkmcnt(0)
	v_mul_f32_e32 v8, v48, v8
	v_mul_f32_e32 v9, v49, v9
	s_nop 0
	v_cndmask_b32_e64 v9, -v9, v9, s[18:19]
	v_cndmask_b32_e64 v8, -v8, v8, s[18:19]
	v_fma_f32 v6, v20, v6, v8
	v_fma_f32 v7, v21, v7, v9
	s_nop 0
	v_cvt_pk_bf16_f32 v5, v6, v7
	global_store_dwordx2 v[16:17], v[4:5], off offset:64
	ds_bpermute_b32 v4, v86, v0
	ds_bpermute_b32 v5, v86, v1
	s_waitcnt lgkmcnt(0)
	v_mul_f32_e32 v4, v50, v4
	v_mul_f32_e32 v5, v51, v5
	s_nop 0
	v_cndmask_b32_e64 v5, -v5, v5, s[18:19]
	v_cndmask_b32_e64 v4, -v4, v4, s[18:19]
	v_fma_f32 v0, v22, v0, v4
	v_fma_f32 v1, v23, v1, v5
	ds_bpermute_b32 v4, v86, v2
	ds_bpermute_b32 v5, v86, v3
	v_cvt_pk_bf16_f32 v0, v0, v1
	s_waitcnt lgkmcnt(0)
	v_mul_f32_e32 v4, v52, v4
	v_mul_f32_e32 v5, v53, v5
	s_nop 0
	v_cndmask_b32_e64 v5, -v5, v5, s[18:19]
	v_cndmask_b32_e64 v4, -v4, v4, s[18:19]
	v_fma_f32 v2, v12, v2, v4
	v_fma_f32 v3, v13, v3, v5
	s_nop 0
	v_cvt_pk_bf16_f32 v1, v2, v3
	global_store_dwordx2 v[16:17], v[0:1], off offset:96

.LBB0_456:
	s_or_b64 exec, exec, s[38:39]
	s_and_b32 s30, s69, 0xff
	s_mulk_i32 s68, 0x300
	s_lshl_b32 s30, s30, 7
	s_add_i32 s68, s30, s68
	s_mul_i32 s30, s68, 0x4200
	s_add_u32 s38, s42, s30
	s_addc_u32 s39, s43, 0
	s_lshl_b32 s40, s40, 1
	s_add_u32 s38, s38, s40
	s_addc_u32 s39, s39, 0
	s_add_u32 s30, s92, s30
	s_addc_u32 s69, s93, 0
	s_add_u32 s70, s30, s40
	s_addc_u32 s71, s69, 0
	v_lshlrev_b32_e32 v98, 1, v96
	v_lshl_add_u64 v[4:5], s[70:71], 0, v[98:99]
	s_waitcnt lgkmcnt(2)
	v_lshl_add_u64 v[0:1], s[38:39], 0, v[98:99]
	v_lshl_add_u64 v[32:33], v[4:5], 0, v[102:103]
	s_waitcnt lgkmcnt(0)
	s_barrier
	v_lshl_add_u64 v[80:81], v[0:1], 0, v[100:101]
	global_load_dwordx4 v[0:3], v[32:33], off
	v_lshl_add_u64 v[34:35], v[4:5], 0, v[104:105]
	v_lshl_add_u64 v[36:37], v[4:5], 0, v[106:107]
	v_lshl_add_u64 v[38:39], v[4:5], 0, v[108:109]
	s_mov_b32 s30, 0x84000
	v_add_u32_e32 v98, v135, v139
	s_mov_b64 s[38:39], 0x84000
	v_lshl_add_u64 v[84:85], v[80:81], 0, s[38:39]
	s_mov_b64 s[38:39], 0x108000
	v_lshl_add_u64 v[86:87], v[80:81], 0, s[38:39]
	s_mov_b64 s[38:39], 0x18c000
	v_lshl_add_u64 v[120:121], v[80:81], 0, s[38:39]
	s_waitcnt vmcnt(0)
	v_lshlrev_b32_e32 v6, 16, v0
	v_and_b32_e32 v7, 0xffff0000, v0
	v_lshlrev_b32_e32 v10, 16, v1
	v_and_b32_e32 v11, 0xffff0000, v1
	v_lshlrev_b32_e32 v22, 16, v2
	v_and_b32_e32 v23, 0xffff0000, v2
	v_lshlrev_b32_e32 v24, 16, v3
	v_and_b32_e32 v25, 0xffff0000, v3
	global_load_dwordx4 v[0:3], v[34:35], off
	s_waitcnt vmcnt(0)
	v_lshlrev_b32_e32 v8, 16, v0
	v_and_b32_e32 v9, 0xffff0000, v0
	v_lshlrev_b32_e32 v26, 16, v1
	v_and_b32_e32 v27, 0xffff0000, v1
	v_lshlrev_b32_e32 v28, 16, v2
	v_and_b32_e32 v29, 0xffff0000, v2
	v_lshlrev_b32_e32 v30, 16, v3
	v_and_b32_e32 v31, 0xffff0000, v3
	global_load_dwordx4 v[0:3], v[36:37], off
	s_waitcnt vmcnt(0)
	v_lshlrev_b32_e32 v40, 16, v0
	v_and_b32_e32 v41, 0xffff0000, v0
	v_lshlrev_b32_e32 v42, 16, v1
	v_and_b32_e32 v43, 0xffff0000, v1
	v_lshlrev_b32_e32 v44, 16, v2
	v_and_b32_e32 v45, 0xffff0000, v2
	v_lshlrev_b32_e32 v46, 16, v3
	v_and_b32_e32 v47, 0xffff0000, v3
	global_load_dwordx4 v[0:3], v[38:39], off
	ds_read_b128 v[14:17], v127
	ds_read_b128 v[18:21], v127 offset:16
	s_waitcnt lgkmcnt(1)
	v_mul_f32_e32 v4, v14, v6
	v_mul_f32_e32 v5, v15, v7
	v_mul_f32_e32 v10, v16, v10
	v_mul_f32_e32 v11, v17, v11
	v_cvt_pk_bf16_f32 v12, v4, v5
	v_mul_f32_e32 v4, v14, v8
	v_mul_f32_e32 v5, v15, v9
	v_cvt_pk_bf16_f32 v13, v10, v11
	v_mul_f32_e32 v10, v16, v26
	v_mul_f32_e32 v11, v17, v27
	v_cvt_pk_bf16_f32 v8, v4, v5
	v_mul_f32_e32 v4, v14, v40
	v_mul_f32_e32 v5, v15, v41
	v_cvt_pk_bf16_f32 v9, v10, v11
	v_mul_f32_e32 v10, v16, v42
	v_mul_f32_e32 v11, v17, v43
	v_cvt_pk_bf16_f32 v4, v4, v5
	v_cvt_pk_bf16_f32 v5, v10, v11
	s_waitcnt vmcnt(0)
	v_lshlrev_b32_e32 v48, 16, v0
	v_and_b32_e32 v49, 0xffff0000, v0
	v_mul_f32_e32 v6, v14, v48
	v_mul_f32_e32 v7, v15, v49
	s_nop 0
	v_cvt_pk_bf16_f32 v0, v6, v7
	v_lshlrev_b32_e32 v6, 16, v1
	v_and_b32_e32 v7, 0xffff0000, v1
	v_mul_f32_e32 v6, v16, v6
	v_mul_f32_e32 v7, v17, v7
	v_lshlrev_b32_e32 v16, 16, v2
	v_cvt_pk_bf16_f32 v1, v6, v7
	s_waitcnt lgkmcnt(0)
	v_mul_f32_e32 v6, v18, v22
	v_mul_f32_e32 v7, v19, v23
	v_and_b32_e32 v17, 0xffff0000, v2
	v_cvt_pk_bf16_f32 v14, v6, v7
	v_mul_f32_e32 v6, v18, v28
	v_mul_f32_e32 v7, v19, v29
	v_mul_f32_e32 v16, v18, v16
	v_mul_f32_e32 v17, v19, v17
	v_cvt_pk_bf16_f32 v10, v6, v7
	v_mul_f32_e32 v6, v18, v44
	v_mul_f32_e32 v7, v19, v45
	v_mul_f32_e32 v18, v20, v24
	v_mul_f32_e32 v19, v21, v25
	v_cvt_pk_bf16_f32 v2, v16, v17
	v_lshlrev_b32_e32 v16, 16, v3
	v_and_b32_e32 v17, 0xffff0000, v3
	v_cvt_pk_bf16_f32 v15, v18, v19
	v_mul_f32_e32 v18, v20, v30
	v_mul_f32_e32 v19, v21, v31
	v_mul_f32_e32 v16, v20, v16
	v_mul_f32_e32 v17, v21, v17
	v_cvt_pk_bf16_f32 v11, v18, v19
	v_mul_f32_e32 v18, v20, v46
	v_mul_f32_e32 v19, v21, v47
	v_cvt_pk_bf16_f32 v6, v6, v7
	v_cvt_pk_bf16_f32 v7, v18, v19
	v_cvt_pk_bf16_f32 v3, v16, v17
	global_load_dwordx4 v[16:19], v[80:81], off
	v_add_co_u32_e32 v20, vcc, s30, v80
	s_mov_b32 s30, 0x108000
	s_nop 0
	v_addc_co_u32_e32 v21, vcc, 0, v81, vcc
	global_load_dwordx4 v[20:23], v[20:21], off
	v_add_co_u32_e32 v24, vcc, s30, v80
	s_mov_b32 s30, 0x18c000
	s_nop 0
	v_addc_co_u32_e32 v25, vcc, 0, v81, vcc
	global_load_dwordx4 v[24:27], v[24:25], off
	v_add_co_u32_e32 v28, vcc, s30, v80
	s_add_i32 s30, s41, s67
	s_nop 0
	v_addc_co_u32_e32 v29, vcc, 0, v81, vcc
	global_load_dwordx4 v[28:31], v[28:29], off
	s_barrier
	s_lshl_b64 s[38:39], s[30:31], 15
	s_waitcnt vmcnt(3)
	ds_write_b128 v136, v[16:19]
	ds_write_b128 v136, v[12:15] offset:18432
	s_waitcnt vmcnt(2)
	ds_write_b128 v136, v[20:23] offset:4608
	ds_write_b128 v136, v[8:11] offset:23040
	s_waitcnt vmcnt(1)
	ds_write_b128 v136, v[24:27] offset:9216
	ds_write_b128 v136, v[4:7] offset:27648
	s_waitcnt vmcnt(0)
	ds_write_b128 v136, v[28:31] offset:13824
	ds_write_b128 v136, v[0:3] offset:32256
	s_waitcnt lgkmcnt(0)
	s_barrier
	global_load_dwordx4 v[0:3], v[38:39], off offset:128
	s_waitcnt vmcnt(0)
	v_lshlrev_b32_e32 v4, 16, v3
	v_and_b32_e32 v5, 0xffff0000, v3
	v_lshlrev_b32_e32 v8, 16, v2
	v_and_b32_e32 v9, 0xffff0000, v2
	v_lshlrev_b32_e32 v20, 16, v1
	v_and_b32_e32 v21, 0xffff0000, v1
	v_lshlrev_b32_e32 v22, 16, v0
	v_and_b32_e32 v23, 0xffff0000, v0
	global_load_dwordx4 v[0:3], v[36:37], off offset:128
	s_waitcnt vmcnt(0)
	v_lshlrev_b32_e32 v6, 16, v3
	v_and_b32_e32 v7, 0xffff0000, v3
	v_lshlrev_b32_e32 v24, 16, v2
	v_and_b32_e32 v25, 0xffff0000, v2
	v_lshlrev_b32_e32 v26, 16, v1
	v_and_b32_e32 v27, 0xffff0000, v1
	v_lshlrev_b32_e32 v28, 16, v0
	v_and_b32_e32 v29, 0xffff0000, v0
	global_load_dwordx4 v[0:3], v[34:35], off offset:128
	s_waitcnt vmcnt(0)
	v_lshlrev_b32_e32 v10, 16, v3
	v_and_b32_e32 v11, 0xffff0000, v3
	v_lshlrev_b32_e32 v30, 16, v2
	v_and_b32_e32 v31, 0xffff0000, v2
	v_lshlrev_b32_e32 v34, 16, v1
	v_and_b32_e32 v35, 0xffff0000, v1
	v_lshlrev_b32_e32 v36, 16, v0
	v_and_b32_e32 v37, 0xffff0000, v0
	global_load_dwordx4 v[0:3], v[32:33], off offset:128
	ds_read_b128 v[16:19], v138
	ds_read_b128 v[12:15], v138 offset:16
	s_waitcnt lgkmcnt(0)
	v_mul_f32_e32 v4, v14, v4
	v_mul_f32_e32 v5, v15, v5
	v_mul_f32_e32 v8, v12, v8
	v_mul_f32_e32 v9, v13, v9
	s_waitcnt vmcnt(0)
	v_lshlrev_b32_e32 v32, 16, v3
	v_and_b32_e32 v33, 0xffff0000, v3
	v_cvt_pk_bf16_f32 v3, v4, v5
	v_mul_f32_e32 v4, v14, v6
	v_mul_f32_e32 v5, v15, v7
	s_nop 0
	v_cvt_pk_bf16_f32 v7, v4, v5
	v_mul_f32_e32 v4, v14, v10
	v_mul_f32_e32 v5, v15, v11
	s_nop 0
	v_cvt_pk_bf16_f32 v11, v4, v5
	v_mul_f32_e32 v4, v14, v32
	v_mul_f32_e32 v5, v15, v33
	s_nop 0
	v_cvt_pk_bf16_f32 v15, v4, v5
	v_lshlrev_b32_e32 v4, 16, v2
	v_and_b32_e32 v5, 0xffff0000, v2
	v_cvt_pk_bf16_f32 v2, v8, v9
	v_mul_f32_e32 v8, v12, v24
	v_mul_f32_e32 v9, v13, v25
	v_mul_f32_e32 v4, v12, v4
	v_mul_f32_e32 v5, v13, v5
	v_cvt_pk_bf16_f32 v6, v8, v9
	v_mul_f32_e32 v8, v12, v30
	v_mul_f32_e32 v9, v13, v31
	v_cvt_pk_bf16_f32 v14, v4, v5
	v_lshlrev_b32_e32 v12, 16, v1
	v_and_b32_e32 v13, 0xffff0000, v1
	v_mul_f32_e32 v4, v18, v20
	v_mul_f32_e32 v5, v19, v21
	v_mul_f32_e32 v20, v16, v22
	v_mul_f32_e32 v21, v17, v23
	v_cvt_pk_bf16_f32 v10, v8, v9
	v_cvt_pk_bf16_f32 v1, v4, v5
	v_mul_f32_e32 v4, v18, v26
	v_mul_f32_e32 v5, v19, v27
	v_mul_f32_e32 v8, v18, v34
	v_mul_f32_e32 v9, v19, v35
	v_mul_f32_e32 v12, v18, v12
	v_mul_f32_e32 v13, v19, v13
	v_lshlrev_b32_e32 v18, 16, v0
	v_and_b32_e32 v19, 0xffff0000, v0
	v_cvt_pk_bf16_f32 v0, v20, v21
	v_mul_f32_e32 v20, v16, v28
	v_mul_f32_e32 v21, v17, v29
	v_cvt_pk_bf16_f32 v5, v4, v5
	v_cvt_pk_bf16_f32 v4, v20, v21
	v_mul_f32_e32 v20, v16, v36
	v_mul_f32_e32 v21, v17, v37
	v_mul_f32_e32 v16, v16, v18
	v_mul_f32_e32 v17, v17, v19
	v_cvt_pk_bf16_f32 v9, v8, v9
	v_cvt_pk_bf16_f32 v13, v12, v13
	v_cvt_pk_bf16_f32 v8, v20, v21
	v_cvt_pk_bf16_f32 v12, v16, v17
	ds_read_b128 v[20:23], v98
	ds_read_b128 v[16:19], v98 offset:2304
	ds_read_b128 v[24:27], v140 offset:18432
	ds_read_b128 v[28:31], v140 offset:20736
	ds_read_b128 v[32:35], v140 offset:23040
	ds_read_b128 v[36:39], v140 offset:25344
	ds_read_b128 v[40:43], v140 offset:27648
	ds_read_b128 v[44:47], v140 offset:29952
	ds_read_b128 v[48:51], v140 offset:32256
	ds_read_b128 v[52:55], v140 offset:34560
	s_waitcnt lgkmcnt(2)
	v_mfma_f32_16x16x32_bf16 v[76:79], v[44:47], v[20:23], 0
	s_waitcnt lgkmcnt(1)
	v_mfma_f32_16x16x32_bf16 v[88:91], v[48:51], v[20:23], 0
	s_waitcnt lgkmcnt(0)
	v_mfma_f32_16x16x32_bf16 v[92:95], v[52:55], v[20:23], 0
	v_mfma_f32_16x16x32_bf16 v[198:201], v[44:47], v[16:19], 0
	v_mfma_f32_16x16x32_bf16 v[202:205], v[48:51], v[16:19], 0
	v_mfma_f32_16x16x32_bf16 v[206:209], v[52:55], v[16:19], 0
	ds_read_b128 v[44:47], v98 offset:64
	ds_read_b128 v[210:213], v98 offset:2368
	ds_read_b128 v[48:51], v140 offset:18496
	ds_read_b128 v[52:55], v140 offset:20800
	ds_read_b128 v[214:217], v140 offset:23104
	ds_read_b128 v[218:221], v140 offset:25408
	ds_read_b128 v[222:225], v140 offset:27712
	ds_read_b128 v[226:229], v140 offset:30016
	ds_read_b128 v[230:233], v140 offset:32320
	ds_read_b128 v[234:237], v140 offset:34624
	v_mfma_f32_16x16x32_bf16 v[56:59], v[24:27], v[20:23], 0
	v_mfma_f32_16x16x32_bf16 v[60:63], v[28:31], v[20:23], 0
	v_mfma_f32_16x16x32_bf16 v[64:67], v[32:35], v[20:23], 0
	v_mfma_f32_16x16x32_bf16 v[68:71], v[36:39], v[20:23], 0
	v_mfma_f32_16x16x32_bf16 v[72:75], v[40:43], v[20:23], 0
	v_mfma_f32_16x16x32_bf16 v[122:125], v[24:27], v[16:19], 0
	v_mfma_f32_16x16x32_bf16 v[154:157], v[28:31], v[16:19], 0
	v_mfma_f32_16x16x32_bf16 v[186:189], v[32:35], v[16:19], 0
	v_mfma_f32_16x16x32_bf16 v[190:193], v[36:39], v[16:19], 0
	v_mfma_f32_16x16x32_bf16 v[194:197], v[40:43], v[16:19], 0
	s_waitcnt lgkmcnt(7)
	v_mfma_f32_16x16x32_bf16 v[16:19], v[48:51], v[44:47], v[56:59]
	s_waitcnt lgkmcnt(6)
	v_mfma_f32_16x16x32_bf16 v[20:23], v[52:55], v[44:47], v[60:63]
	s_waitcnt lgkmcnt(5)
	v_mfma_f32_16x16x32_bf16 v[24:27], v[214:217], v[44:47], v[64:67]
	s_waitcnt lgkmcnt(4)
	v_mfma_f32_16x16x32_bf16 v[28:31], v[218:221], v[44:47], v[68:71]
	s_waitcnt lgkmcnt(3)
	v_mfma_f32_16x16x32_bf16 v[32:35], v[222:225], v[44:47], v[72:75]
	s_waitcnt lgkmcnt(2)
	v_mfma_f32_16x16x32_bf16 v[36:39], v[226:229], v[44:47], v[76:79]
	s_waitcnt lgkmcnt(1)
	v_mfma_f32_16x16x32_bf16 v[40:43], v[230:233], v[44:47], v[88:91]
	s_waitcnt lgkmcnt(0)
	v_mfma_f32_16x16x32_bf16 v[44:47], v[234:237], v[44:47], v[92:95]
	global_load_dwordx4 v[80:83], v[80:81], off offset:128
	s_nop 1
	global_load_dwordx4 v[92:95], v[84:85], off offset:128
	global_load_dwordx4 v[88:91], v[86:87], off offset:128
	s_nop 0
	global_load_dwordx4 v[84:87], v[120:121], off offset:128
	s_barrier
	v_mfma_f32_16x16x32_bf16 v[48:51], v[48:51], v[210:213], v[122:125]
	s_waitcnt vmcnt(3)
	ds_write_b128 v136, v[80:83]
	ds_write_b128 v136, v[12:15] offset:18432
	s_waitcnt vmcnt(2)
	ds_write_b128 v136, v[92:95] offset:4608
	ds_write_b128 v136, v[8:11] offset:23040
	s_waitcnt vmcnt(1)
	ds_write_b128 v136, v[88:91] offset:9216
	ds_write_b128 v136, v[4:7] offset:27648
	s_waitcnt vmcnt(0)
	ds_write_b128 v136, v[84:87] offset:13824
	ds_write_b128 v136, v[0:3] offset:32256
	v_mfma_f32_16x16x32_bf16 v[52:55], v[52:55], v[210:213], v[154:157]
	s_waitcnt lgkmcnt(0)
	s_barrier
	ds_read_b128 v[0:3], v140 offset:34560
	ds_read_b128 v[4:7], v140 offset:32256
	ds_read_b128 v[8:11], v140 offset:29952
	ds_read_b128 v[12:15], v140 offset:27648
	ds_read_b128 v[80:83], v140 offset:25344
	ds_read_b128 v[84:87], v140 offset:23040
	ds_read_b128 v[88:91], v140 offset:20736
	ds_read_b128 v[92:95], v140 offset:18432
	ds_read_b128 v[120:123], v98 offset:2304
	ds_read_b128 v[154:157], v98
	v_mfma_f32_16x16x32_bf16 v[56:59], v[214:217], v[210:213], v[186:189]
	v_mfma_f32_16x16x32_bf16 v[60:63], v[218:221], v[210:213], v[190:193]
	v_mfma_f32_16x16x32_bf16 v[64:67], v[222:225], v[210:213], v[194:197]
	v_mfma_f32_16x16x32_bf16 v[68:71], v[226:229], v[210:213], v[198:201]
	v_mfma_f32_16x16x32_bf16 v[72:75], v[230:233], v[210:213], v[202:205]
	v_mfma_f32_16x16x32_bf16 v[76:79], v[234:237], v[210:213], v[206:209]
	s_waitcnt lgkmcnt(0)
	v_mfma_f32_16x16x32_bf16 v[16:19], v[92:95], v[154:157], v[16:19]
	v_mfma_f32_16x16x32_bf16 v[20:23], v[88:91], v[154:157], v[20:23]
	v_mfma_f32_16x16x32_bf16 v[24:27], v[84:87], v[154:157], v[24:27]
	v_mfma_f32_16x16x32_bf16 v[28:31], v[80:83], v[154:157], v[28:31]
	v_mfma_f32_16x16x32_bf16 v[32:35], v[12:15], v[154:157], v[32:35]
	v_mfma_f32_16x16x32_bf16 v[36:39], v[8:11], v[154:157], v[36:39]
	v_mfma_f32_16x16x32_bf16 v[40:43], v[4:7], v[154:157], v[40:43]
	v_mfma_f32_16x16x32_bf16 v[44:47], v[0:3], v[154:157], v[44:47]
	v_mfma_f32_16x16x32_bf16 v[48:51], v[92:95], v[120:123], v[48:51]
	v_mfma_f32_16x16x32_bf16 v[52:55], v[88:91], v[120:123], v[52:55]
	v_mfma_f32_16x16x32_bf16 v[56:59], v[84:87], v[120:123], v[56:59]
	v_mfma_f32_16x16x32_bf16 v[60:63], v[80:83], v[120:123], v[60:63]
	v_mfma_f32_16x16x32_bf16 v[12:15], v[12:15], v[120:123], v[64:67]
	v_mfma_f32_16x16x32_bf16 v[8:11], v[8:11], v[120:123], v[68:71]
	v_mfma_f32_16x16x32_bf16 v[4:7], v[4:7], v[120:123], v[72:75]
	v_mfma_f32_16x16x32_bf16 v[0:3], v[0:3], v[120:123], v[76:79]
	ds_read_b128 v[64:67], v98 offset:64
	ds_read_b128 v[68:71], v98 offset:2368
	ds_read_b128 v[72:75], v140 offset:18496
	ds_read_b128 v[76:79], v140 offset:20800
	ds_read_b128 v[80:83], v140 offset:23104
	ds_read_b128 v[84:87], v140 offset:25408
	ds_read_b128 v[88:91], v140 offset:27712
	ds_read_b128 v[92:95], v140 offset:30016
	ds_read_b128 v[120:123], v140 offset:32320
	ds_read_b128 v[154:157], v140 offset:34624
	s_waitcnt lgkmcnt(7)
	v_mfma_f32_16x16x32_bf16 v[16:19], v[72:75], v[64:67], v[16:19]
	s_waitcnt lgkmcnt(6)
	v_mfma_f32_16x16x32_bf16 v[20:23], v[76:79], v[64:67], v[20:23]
	s_waitcnt lgkmcnt(5)
	v_mfma_f32_16x16x32_bf16 v[24:27], v[80:83], v[64:67], v[24:27]
	s_nop 3
	v_cvt_pk_bf16_f32 v16, v16, v17
	v_cvt_pk_bf16_f32 v17, v18, v19
	v_cvt_pk_bf16_f32 v18, v20, v21
	s_waitcnt lgkmcnt(4)
	v_mfma_f32_16x16x32_bf16 v[28:31], v[84:87], v[64:67], v[28:31]
	v_cvt_pk_bf16_f32 v19, v22, v23
	s_waitcnt lgkmcnt(3)
	v_mfma_f32_16x16x32_bf16 v[32:35], v[88:91], v[64:67], v[32:35]
	s_waitcnt lgkmcnt(2)
	v_mfma_f32_16x16x32_bf16 v[36:39], v[92:95], v[64:67], v[36:39]
	s_waitcnt lgkmcnt(1)
	v_mfma_f32_16x16x32_bf16 v[40:43], v[120:123], v[64:67], v[40:43]
	s_waitcnt lgkmcnt(0)
	v_mfma_f32_16x16x32_bf16 v[44:47], v[154:157], v[64:67], v[44:47]
	v_lshl_add_u64 v[64:65], v[112:113], 0, s[38:39]
	global_store_dwordx4 v[64:65], v[16:19], off
	s_movk_i32 s38, 0x1000
	v_mfma_f32_16x16x32_bf16 v[48:51], v[72:75], v[68:71], v[48:51]
	v_cvt_pk_bf16_f32 v16, v24, v25
	v_cvt_pk_bf16_f32 v17, v26, v27
	v_cvt_pk_bf16_f32 v18, v28, v29
	v_mfma_f32_16x16x32_bf16 v[52:55], v[76:79], v[68:71], v[52:55]
	v_cvt_pk_bf16_f32 v19, v30, v31
	global_store_dwordx4 v[64:65], v[16:19], off offset:64
	v_add_co_u32_e32 v20, vcc, s38, v64
	v_mfma_f32_16x16x32_bf16 v[56:59], v[80:83], v[68:71], v[56:59]
	v_cvt_pk_bf16_f32 v16, v32, v33
	v_cvt_pk_bf16_f32 v17, v34, v35
	v_cvt_pk_bf16_f32 v18, v36, v37
	v_mfma_f32_16x16x32_bf16 v[60:63], v[84:87], v[68:71], v[60:63]
	v_cvt_pk_bf16_f32 v19, v38, v39
	global_store_dwordx4 v[64:65], v[16:19], off offset:128
	v_addc_co_u32_e32 v21, vcc, 0, v65, vcc
	v_mfma_f32_16x16x32_bf16 v[12:15], v[88:91], v[68:71], v[12:15]
	v_cvt_pk_bf16_f32 v16, v40, v41
	v_cvt_pk_bf16_f32 v17, v42, v43
	v_cvt_pk_bf16_f32 v18, v44, v45
	v_mfma_f32_16x16x32_bf16 v[8:11], v[92:95], v[68:71], v[8:11]
	v_cvt_pk_bf16_f32 v19, v46, v47
	global_store_dwordx4 v[64:65], v[16:19], off offset:192
	s_nop 1
	v_cvt_pk_bf16_f32 v12, v12, v13
	v_mfma_f32_16x16x32_bf16 v[4:7], v[120:123], v[68:71], v[4:7]
	v_cvt_pk_bf16_f32 v16, v48, v49
	v_cvt_pk_bf16_f32 v17, v50, v51
	v_cvt_pk_bf16_f32 v18, v52, v53
	v_mfma_f32_16x16x32_bf16 v[0:3], v[154:157], v[68:71], v[0:3]
	v_cvt_pk_bf16_f32 v19, v54, v55
	global_store_dwordx4 v[20:21], v[16:19], off
	v_cvt_pk_bf16_f32 v13, v14, v15
	v_cvt_pk_bf16_f32 v14, v8, v9
	v_cvt_pk_bf16_f32 v16, v56, v57
	v_cvt_pk_bf16_f32 v17, v58, v59
	v_cvt_pk_bf16_f32 v18, v60, v61
	v_cvt_pk_bf16_f32 v19, v62, v63
	v_cvt_pk_bf16_f32 v15, v10, v11
	v_cvt_pk_bf16_f32 v4, v4, v5
	v_cvt_pk_bf16_f32 v5, v6, v7
	v_cvt_pk_bf16_f32 v6, v0, v1
	v_cvt_pk_bf16_f32 v7, v2, v3
	global_store_dwordx4 v[20:21], v[16:19], off offset:64
	global_store_dwordx4 v[20:21], v[12:15], off offset:128
	global_store_dwordx4 v[20:21], v[4:7], off offset:192
	s_and_saveexec_b64 s[38:39], s[2:3]
	s_cbranch_execz .LBB0_458
	v_mov_b32_e32 v16, v144
	v_mov_b64_e32 v[0:1], s[92:93]
	v_add_u32_e32 v2, s68, v16
	v_mad_i64_i32 v[0:1], s[68:69], v2, s45, v[0:1]
	s_mov_b32 s41, s31
	v_lshl_add_u64 v[18:19], v[0:1], 0, s[40:41]
	global_load_dwordx4 v[0:3], v[18:19], off offset:48
	global_load_dwordx4 v[4:7], v[18:19], off offset:32
	global_load_dwordx4 v[8:11], v[18:19], off offset:16
	global_load_dwordx4 v[12:15], v[18:19], off
	v_mov_b32_e32 v20, s44
	ds_read_b128 v[20:23], v20
	v_mov_b32_e32 v32, s58
	s_lshl_b32 s30, s30, 9
	s_add_u32 s40, s33, s30
	s_addc_u32 s41, s37, 0
	s_waitcnt vmcnt(0)
	v_lshlrev_b32_e32 v17, 16, v12
	v_and_b32_e32 v12, 0xffff0000, v12
	s_waitcnt lgkmcnt(0)
	v_mul_f32_e32 v12, v21, v12
	v_fmac_f32_e32 v12, v20, v17
	v_lshlrev_b32_e32 v17, 16, v13
	v_fmac_f32_e32 v12, v22, v17
	v_and_b32_e32 v13, 0xffff0000, v13
	v_mov_b32_e32 v17, s51
	v_fmac_f32_e32 v12, v23, v13
	ds_read_b128 v[20:23], v17
	v_lshlrev_b32_e32 v13, 16, v14
	s_waitcnt lgkmcnt(0)
	v_fmac_f32_e32 v12, v20, v13
	v_and_b32_e32 v13, 0xffff0000, v14
	v_fmac_f32_e32 v12, v21, v13
	v_lshlrev_b32_e32 v13, 16, v15
	v_fmac_f32_e32 v12, v22, v13
	v_and_b32_e32 v13, 0xffff0000, v15
	v_fmac_f32_e32 v12, v23, v13
	v_add_f32_e32 v17, 0, v12
	v_mov_b32_e32 v12, s52
	ds_read_b128 v[12:15], v12
	v_lshlrev_b32_e32 v20, 16, v8
	v_and_b32_e32 v8, 0xffff0000, v8
	s_waitcnt lgkmcnt(0)
	v_mul_f32_e32 v8, v13, v8
	v_fmac_f32_e32 v8, v12, v20
	v_lshlrev_b32_e32 v12, 16, v9
	v_fmac_f32_e32 v8, v14, v12
	v_and_b32_e32 v9, 0xffff0000, v9
	v_mov_b32_e32 v12, s53
	v_fmac_f32_e32 v8, v15, v9
	ds_read_b128 v[12:15], v12
	v_lshlrev_b32_e32 v9, 16, v10
	s_waitcnt lgkmcnt(0)
	v_fmac_f32_e32 v8, v12, v9
	v_and_b32_e32 v9, 0xffff0000, v10
	v_fmac_f32_e32 v8, v13, v9
	v_lshlrev_b32_e32 v9, 16, v11
	v_fmac_f32_e32 v8, v14, v9
	v_and_b32_e32 v9, 0xffff0000, v11
	v_fmac_f32_e32 v8, v15, v9
	v_add_f32_e32 v12, v17, v8
	v_mov_b32_e32 v8, s54
	ds_read_b128 v[8:11], v8
	v_lshlrev_b32_e32 v13, 16, v4
	v_and_b32_e32 v4, 0xffff0000, v4
	s_waitcnt lgkmcnt(0)
	v_mul_f32_e32 v4, v9, v4
	v_fmac_f32_e32 v4, v8, v13
	v_lshlrev_b32_e32 v8, 16, v5
	v_fmac_f32_e32 v4, v10, v8
	v_and_b32_e32 v5, 0xffff0000, v5
	v_mov_b32_e32 v8, s55
	v_fmac_f32_e32 v4, v11, v5
	ds_read_b128 v[8:11], v8
	v_lshlrev_b32_e32 v5, 16, v6
	s_waitcnt lgkmcnt(0)
	v_fmac_f32_e32 v4, v8, v5
	v_and_b32_e32 v5, 0xffff0000, v6
	v_fmac_f32_e32 v4, v9, v5
	v_lshlrev_b32_e32 v5, 16, v7
	v_fmac_f32_e32 v4, v10, v5
	v_and_b32_e32 v5, 0xffff0000, v7
	v_fmac_f32_e32 v4, v11, v5
	v_add_f32_e32 v8, v12, v4
	v_mov_b32_e32 v4, s56
	ds_read_b128 v[4:7], v4
	v_lshlrev_b32_e32 v9, 16, v0
	v_and_b32_e32 v0, 0xffff0000, v0
	s_waitcnt lgkmcnt(0)
	v_mul_f32_e32 v0, v5, v0
	v_fmac_f32_e32 v0, v4, v9
	v_lshlrev_b32_e32 v4, 16, v1
	v_fmac_f32_e32 v0, v6, v4
	v_and_b32_e32 v1, 0xffff0000, v1
	v_mov_b32_e32 v4, s57
	v_fmac_f32_e32 v0, v7, v1
	ds_read_b128 v[4:7], v4
	v_lshlrev_b32_e32 v1, 16, v2
	s_waitcnt lgkmcnt(0)
	v_fmac_f32_e32 v0, v4, v1
	v_and_b32_e32 v1, 0xffff0000, v2
	v_fmac_f32_e32 v0, v5, v1
	v_lshlrev_b32_e32 v1, 16, v3
	v_fmac_f32_e32 v0, v6, v1
	v_and_b32_e32 v1, 0xffff0000, v3
	v_fmac_f32_e32 v0, v7, v1
	v_add_f32_e32 v17, v8, v0
	global_load_dwordx4 v[0:3], v[18:19], off offset:112
	global_load_dwordx4 v[4:7], v[18:19], off offset:96
	global_load_dwordx4 v[8:11], v[18:19], off offset:80
	global_load_dwordx4 v[12:15], v[18:19], off offset:64
	ds_read_b128 v[20:23], v32
	ds_read_b128 v[24:27], v32 offset:16
	ds_read_b128 v[28:31], v32 offset:32
	ds_read_b128 v[32:35], v32 offset:48
	s_waitcnt lgkmcnt(3)
	v_mov_b32_e32 v38, v20
	s_waitcnt lgkmcnt(1)
	v_mov_b32_e32 v39, v28
	v_mov_b32_e32 v28, v21
	s_waitcnt vmcnt(1)
	v_and_b32_e32 v41, 0xffff0000, v8
	s_waitcnt vmcnt(0)
	v_and_b32_e32 v40, 0xffff0000, v12
	v_lshlrev_b32_e32 v37, 16, v8
	v_lshlrev_b32_e32 v36, 16, v12
	v_mul_f32_e32 v20, v28, v40
	v_mul_f32_e32 v21, v29, v41
	v_lshlrev_b32_e32 v29, 16, v9
	v_fma_f32 v20, v38, v36, v20
	v_fma_f32 v21, v39, v37, v21
	v_lshlrev_b32_e32 v28, 16, v13
	v_mov_b32_e32 v36, v22
	v_mov_b32_e32 v37, v30
	v_fma_f32 v20, v36, v28, v20
	v_fma_f32 v21, v37, v29, v21
	v_and_b32_e32 v9, 0xffff0000, v9
	v_and_b32_e32 v8, 0xffff0000, v13
	v_mov_b32_e32 v30, v23
	v_fma_f32 v8, v30, v8, v20
	v_fma_f32 v9, v31, v9, v21
	v_lshlrev_b32_e32 v13, 16, v10
	v_lshlrev_b32_e32 v12, 16, v14
	v_mov_b32_e32 v20, v24
	s_waitcnt lgkmcnt(0)
	v_mov_b32_e32 v21, v32
	v_fma_f32 v8, v20, v12, v8
	v_fma_f32 v9, v21, v13, v9
	v_and_b32_e32 v13, 0xffff0000, v10
	v_and_b32_e32 v12, 0xffff0000, v14
	v_mov_b32_e32 v32, v25
	v_fma_f32 v8, v32, v12, v8
	v_fma_f32 v9, v33, v13, v9
	v_lshlrev_b32_e32 v13, 16, v11
	v_lshlrev_b32_e32 v12, 16, v15
	v_mov_b32_e32 v20, v26
	v_mov_b32_e32 v21, v34
	v_fma_f32 v8, v20, v12, v8
	v_fma_f32 v9, v21, v13, v9
	v_and_b32_e32 v11, 0xffff0000, v11
	v_and_b32_e32 v10, 0xffff0000, v15
	v_mov_b32_e32 v34, v27
	v_fma_f32 v8, v34, v10, v8
	v_fma_f32 v9, v35, v11, v9
	v_mov_b32_e32 v24, s59
	v_add_f32_e32 v8, v17, v8
	v_add_f32_e32 v17, v8, v9
	ds_read_b128 v[8:11], v24
	ds_read_b128 v[12:15], v24 offset:16
	ds_read_b128 v[20:23], v24 offset:32
	ds_read_b128 v[24:27], v24 offset:48
	v_and_b32_e32 v33, 0xffff0000, v0
	v_and_b32_e32 v32, 0xffff0000, v4
	v_lshlrev_b32_e32 v29, 16, v0
	s_waitcnt lgkmcnt(1)
	v_mov_b32_e32 v31, v20
	v_mov_b32_e32 v20, v9
	v_lshlrev_b32_e32 v28, 16, v4
	v_mov_b32_e32 v30, v8
	v_mul_f32_e32 v8, v20, v32
	v_mul_f32_e32 v9, v21, v33
	v_lshlrev_b32_e32 v21, 16, v1
	v_fma_f32 v8, v30, v28, v8
	v_fma_f32 v9, v31, v29, v9
	v_lshlrev_b32_e32 v20, 16, v5
	v_mov_b32_e32 v28, v10
	v_mov_b32_e32 v29, v22
	v_fma_f32 v8, v28, v20, v8
	v_fma_f32 v9, v29, v21, v9
	v_and_b32_e32 v1, 0xffff0000, v1
	v_and_b32_e32 v0, 0xffff0000, v5
	v_mov_b32_e32 v22, v11
	v_fma_f32 v0, v22, v0, v8
	v_fma_f32 v1, v23, v1, v9
	v_lshlrev_b32_e32 v5, 16, v2
	v_lshlrev_b32_e32 v4, 16, v6
	v_mov_b32_e32 v8, v12
	s_waitcnt lgkmcnt(0)
	v_mov_b32_e32 v9, v24
	v_fma_f32 v0, v8, v4, v0
	v_fma_f32 v1, v9, v5, v1
	v_and_b32_e32 v5, 0xffff0000, v2
	v_and_b32_e32 v4, 0xffff0000, v6
	v_mov_b32_e32 v24, v13
	v_fma_f32 v0, v24, v4, v0
	v_fma_f32 v1, v25, v5, v1
	v_lshlrev_b32_e32 v5, 16, v3
	v_lshlrev_b32_e32 v4, 16, v7
	v_mov_b32_e32 v8, v14
	v_mov_b32_e32 v9, v26
	v_fma_f32 v0, v8, v4, v0
	v_fma_f32 v1, v9, v5, v1
	v_and_b32_e32 v3, 0xffff0000, v3
	v_and_b32_e32 v2, 0xffff0000, v7
	v_mov_b32_e32 v26, v15
	v_fma_f32 v0, v26, v2, v0
	v_fma_f32 v1, v27, v3, v1
	v_mov_b32_e32 v32, s60
	v_add_f32_e32 v0, v17, v0
	v_add_f32_e32 v17, v0, v1
	global_load_dwordx4 v[0:3], v[18:19], off offset:176
	global_load_dwordx4 v[4:7], v[18:19], off offset:160
	global_load_dwordx4 v[8:11], v[18:19], off offset:144
	global_load_dwordx4 v[12:15], v[18:19], off offset:128
	ds_read_b128 v[20:23], v32
	ds_read_b128 v[24:27], v32 offset:16
	ds_read_b128 v[28:31], v32 offset:32
	ds_read_b128 v[32:35], v32 offset:48
	s_waitcnt lgkmcnt(3)
	v_mov_b32_e32 v38, v20
	s_waitcnt lgkmcnt(1)
	v_mov_b32_e32 v39, v28
	v_mov_b32_e32 v28, v21
	s_waitcnt vmcnt(1)
	v_and_b32_e32 v41, 0xffff0000, v8
	s_waitcnt vmcnt(0)
	v_and_b32_e32 v40, 0xffff0000, v12
	v_lshlrev_b32_e32 v37, 16, v8
	v_lshlrev_b32_e32 v36, 16, v12
	v_mul_f32_e32 v20, v28, v40
	v_mul_f32_e32 v21, v29, v41
	v_lshlrev_b32_e32 v29, 16, v9
	v_fma_f32 v20, v38, v36, v20
	v_fma_f32 v21, v39, v37, v21
	v_lshlrev_b32_e32 v28, 16, v13
	v_mov_b32_e32 v36, v22
	v_mov_b32_e32 v37, v30
	v_fma_f32 v20, v36, v28, v20
	v_fma_f32 v21, v37, v29, v21
	v_and_b32_e32 v9, 0xffff0000, v9
	v_and_b32_e32 v8, 0xffff0000, v13
	v_mov_b32_e32 v30, v23
	v_fma_f32 v8, v30, v8, v20
	v_fma_f32 v9, v31, v9, v21
	v_lshlrev_b32_e32 v13, 16, v10
	v_lshlrev_b32_e32 v12, 16, v14
	v_mov_b32_e32 v20, v24
	s_waitcnt lgkmcnt(0)
	v_mov_b32_e32 v21, v32
	v_fma_f32 v8, v20, v12, v8
	v_fma_f32 v9, v21, v13, v9
	v_and_b32_e32 v13, 0xffff0000, v10
	v_and_b32_e32 v12, 0xffff0000, v14
	v_mov_b32_e32 v32, v25
	v_fma_f32 v8, v32, v12, v8
	v_fma_f32 v9, v33, v13, v9
	v_lshlrev_b32_e32 v13, 16, v11
	v_lshlrev_b32_e32 v12, 16, v15
	v_mov_b32_e32 v20, v26
	v_mov_b32_e32 v21, v34
	v_fma_f32 v8, v20, v12, v8
	v_fma_f32 v9, v21, v13, v9
	v_and_b32_e32 v11, 0xffff0000, v11
	v_and_b32_e32 v10, 0xffff0000, v15
	v_mov_b32_e32 v34, v27
	v_fma_f32 v8, v34, v10, v8
	v_fma_f32 v9, v35, v11, v9
	v_mov_b32_e32 v24, s61
	v_add_f32_e32 v8, v17, v8
	v_add_f32_e32 v17, v8, v9
	ds_read_b128 v[8:11], v24
	ds_read_b128 v[12:15], v24 offset:16
	ds_read_b128 v[20:23], v24 offset:32
	ds_read_b128 v[24:27], v24 offset:48
	v_and_b32_e32 v33, 0xffff0000, v0
	v_and_b32_e32 v32, 0xffff0000, v4
	v_lshlrev_b32_e32 v29, 16, v0
	s_waitcnt lgkmcnt(1)
	v_mov_b32_e32 v31, v20
	v_mov_b32_e32 v20, v9
	v_lshlrev_b32_e32 v28, 16, v4
	v_mov_b32_e32 v30, v8
	v_mul_f32_e32 v8, v20, v32
	v_mul_f32_e32 v9, v21, v33
	v_lshlrev_b32_e32 v21, 16, v1
	v_fma_f32 v8, v30, v28, v8
	v_fma_f32 v9, v31, v29, v9
	v_lshlrev_b32_e32 v20, 16, v5
	v_mov_b32_e32 v28, v10
	v_mov_b32_e32 v29, v22
	v_fma_f32 v8, v28, v20, v8
	v_fma_f32 v9, v29, v21, v9
	v_and_b32_e32 v1, 0xffff0000, v1
	v_and_b32_e32 v0, 0xffff0000, v5
	v_mov_b32_e32 v22, v11
	v_fma_f32 v0, v22, v0, v8
	v_fma_f32 v1, v23, v1, v9
	v_lshlrev_b32_e32 v5, 16, v2
	v_lshlrev_b32_e32 v4, 16, v6
	v_mov_b32_e32 v8, v12
	s_waitcnt lgkmcnt(0)
	v_mov_b32_e32 v9, v24
	v_fma_f32 v0, v8, v4, v0
	v_fma_f32 v1, v9, v5, v1
	v_and_b32_e32 v5, 0xffff0000, v2
	v_and_b32_e32 v4, 0xffff0000, v6
	v_mov_b32_e32 v24, v13
	v_fma_f32 v0, v24, v4, v0
	v_fma_f32 v1, v25, v5, v1
	v_lshlrev_b32_e32 v5, 16, v3
	v_lshlrev_b32_e32 v4, 16, v7
	v_mov_b32_e32 v8, v14
	v_mov_b32_e32 v9, v26
	v_fma_f32 v0, v8, v4, v0
	v_fma_f32 v1, v9, v5, v1
	v_and_b32_e32 v3, 0xffff0000, v3
	v_and_b32_e32 v2, 0xffff0000, v7
	v_mov_b32_e32 v26, v15
	v_fma_f32 v0, v26, v2, v0
	v_fma_f32 v1, v27, v3, v1
	v_mov_b32_e32 v30, s62
	v_add_f32_e32 v0, v17, v0
	v_add_f32_e32 v17, v0, v1
	global_load_dwordx4 v[0:3], v[18:19], off offset:240
	global_load_dwordx4 v[4:7], v[18:19], off offset:224
	global_load_dwordx4 v[8:11], v[18:19], off offset:208
	global_load_dwordx4 v[12:15], v[18:19], off offset:192
	ds_read_b128 v[18:21], v30
	ds_read_b128 v[22:25], v30 offset:16
	ds_read_b128 v[26:29], v30 offset:32
	ds_read_b128 v[30:33], v30 offset:48
	s_waitcnt lgkmcnt(3)
	v_mov_b32_e32 v36, v18
	s_waitcnt lgkmcnt(1)
	v_mov_b32_e32 v37, v26
	v_mov_b32_e32 v26, v19
	s_waitcnt vmcnt(1)
	v_and_b32_e32 v39, 0xffff0000, v8
	s_waitcnt vmcnt(0)
	v_and_b32_e32 v38, 0xffff0000, v12
	v_lshlrev_b32_e32 v35, 16, v8
	v_lshlrev_b32_e32 v34, 16, v12
	v_mul_f32_e32 v18, v26, v38
	v_mul_f32_e32 v19, v27, v39
	v_lshlrev_b32_e32 v27, 16, v9
	v_fma_f32 v18, v36, v34, v18
	v_fma_f32 v19, v37, v35, v19
	v_lshlrev_b32_e32 v26, 16, v13
	v_mov_b32_e32 v34, v20
	v_mov_b32_e32 v35, v28
	v_fma_f32 v18, v34, v26, v18
	v_fma_f32 v19, v35, v27, v19
	v_and_b32_e32 v9, 0xffff0000, v9
	v_and_b32_e32 v8, 0xffff0000, v13
	v_mov_b32_e32 v28, v21
	v_fma_f32 v8, v28, v8, v18
	v_fma_f32 v9, v29, v9, v19
	v_lshlrev_b32_e32 v13, 16, v10
	v_lshlrev_b32_e32 v12, 16, v14
	v_mov_b32_e32 v18, v22
	s_waitcnt lgkmcnt(0)
	v_mov_b32_e32 v19, v30
	v_fma_f32 v8, v18, v12, v8
	v_fma_f32 v9, v19, v13, v9
	v_and_b32_e32 v13, 0xffff0000, v10
	v_and_b32_e32 v12, 0xffff0000, v14
	v_mov_b32_e32 v30, v23
	v_fma_f32 v8, v30, v12, v8
	v_fma_f32 v9, v31, v13, v9
	v_lshlrev_b32_e32 v13, 16, v11
	v_lshlrev_b32_e32 v12, 16, v15
	v_mov_b32_e32 v18, v24
	v_mov_b32_e32 v19, v32
	v_fma_f32 v8, v18, v12, v8
	v_fma_f32 v9, v19, v13, v9
	v_and_b32_e32 v11, 0xffff0000, v11
	v_and_b32_e32 v10, 0xffff0000, v15
	v_mov_b32_e32 v32, v25
	v_fma_f32 v8, v32, v10, v8
	v_fma_f32 v9, v33, v11, v9
	v_mov_b32_e32 v22, s63
	v_add_f32_e32 v8, v17, v8
	v_add_f32_e32 v17, v8, v9
	ds_read_b128 v[8:11], v22
	ds_read_b128 v[12:15], v22 offset:16
	ds_read_b128 v[18:21], v22 offset:32
	ds_read_b128 v[22:25], v22 offset:48
	v_and_b32_e32 v31, 0xffff0000, v0
	v_and_b32_e32 v30, 0xffff0000, v4
	v_lshlrev_b32_e32 v27, 16, v0
	s_waitcnt lgkmcnt(1)
	v_mov_b32_e32 v29, v18
	v_mov_b32_e32 v18, v9
	v_lshlrev_b32_e32 v26, 16, v4
	v_mov_b32_e32 v28, v8
	v_mul_f32_e32 v8, v18, v30
	v_mul_f32_e32 v9, v19, v31
	v_lshlrev_b32_e32 v19, 16, v1
	v_fma_f32 v8, v28, v26, v8
	v_fma_f32 v9, v29, v27, v9
	v_lshlrev_b32_e32 v18, 16, v5
	v_mov_b32_e32 v26, v10
	v_mov_b32_e32 v27, v20
	v_fma_f32 v8, v26, v18, v8
	v_fma_f32 v9, v27, v19, v9
	v_and_b32_e32 v1, 0xffff0000, v1
	v_and_b32_e32 v0, 0xffff0000, v5
	v_mov_b32_e32 v20, v11
	v_fma_f32 v0, v20, v0, v8
	v_fma_f32 v1, v21, v1, v9
	v_lshlrev_b32_e32 v5, 16, v2
	v_lshlrev_b32_e32 v4, 16, v6
	v_mov_b32_e32 v8, v12
	s_waitcnt lgkmcnt(0)
	v_mov_b32_e32 v9, v22
	v_fma_f32 v0, v8, v4, v0
	v_fma_f32 v1, v9, v5, v1
	v_and_b32_e32 v5, 0xffff0000, v2
	v_and_b32_e32 v4, 0xffff0000, v6
	v_mov_b32_e32 v22, v13
	v_fma_f32 v0, v22, v4, v0
	v_fma_f32 v1, v23, v5, v1
	v_lshlrev_b32_e32 v5, 16, v3
	v_lshlrev_b32_e32 v4, 16, v7
	v_mov_b32_e32 v8, v14
	v_mov_b32_e32 v9, v24
	v_fma_f32 v0, v8, v4, v0
	v_fma_f32 v1, v9, v5, v1
	v_and_b32_e32 v3, 0xffff0000, v3
	v_and_b32_e32 v2, 0xffff0000, v7
	v_mov_b32_e32 v24, v15
	v_fma_f32 v0, v24, v2, v0
	v_fma_f32 v1, v25, v3, v1
	s_nop 0
	v_add_f32_e32 v0, v17, v0
	v_ashrrev_i32_e32 v17, 31, v16
	v_add_f32_e32 v2, v0, v1
	v_lshl_add_u64 v[0:1], v[16:17], 2, s[40:41]
	global_store_dword v[0:1], v2, off

.LBB0_461:
	s_add_i32 s40, s41, 1
	s_cmp_gt_u32 s41, 2
	s_cselect_b64 vcc, -1, 0
	s_waitcnt vmcnt(63) expcnt(7) lgkmcnt(15)
	s_barrier
	ds_write_b128 v136, v[4:7]
	s_waitcnt vmcnt(3)
	ds_write_b128 v136, v[44:47] offset:18432
	ds_write_b128 v136, v[72:75] offset:4608
	s_waitcnt vmcnt(2)
	ds_write_b128 v136, v[76:79] offset:23040
	ds_write_b128 v136, v[80:83] offset:9216
	s_waitcnt vmcnt(1)
	ds_write_b128 v136, v[84:87] offset:27648
	ds_write_b128 v136, v[88:91] offset:13824
	s_waitcnt vmcnt(0)
	ds_write_b128 v136, v[92:95] offset:32256
	v_cndmask_b32_e64 v4, 0, 1, vcc
	v_or_b32_e32 v94, s39, v4
	v_and_b32_e32 v4, 0xf8, v189
	v_cvt_f32_ubyte0_e32 v4, v4
	v_and_b32_e32 v5, 0xf8, v191
	v_mul_f32_e32 v4, 0x3b800000, v4
	v_lshlrev_b32_e32 v98, 1, v5
	v_sin_f32_e32 v5, v4
	v_cos_f32_e32 v4, v4
	s_movk_i32 s41, 0xc000
	v_lshl_add_u64 v[92:93], s[26:27], 0, v[98:99]
	s_waitcnt lgkmcnt(0)
	v_cndmask_b32_e32 v4, v4, v5, vcc
	v_add3_u32 v5, v115, v189, s41
	v_cvt_f32_ubyte0_e32 v5, v5
	v_mul_f32_e32 v5, 0x3b800000, v5
	v_sin_f32_e32 v6, v5
	v_cos_f32_e32 v5, v5
	s_movk_i32 s41, 0x8000
	s_barrier
	v_cndmask_b32_e32 v5, v5, v6, vcc
	v_add3_u32 v6, v120, v189, s41
	v_and_b32_e32 v6, 0xfe, v6
	v_cvt_f32_ubyte0_e32 v6, v6
	v_mul_f32_e32 v6, 0x3b800000, v6
	v_sin_f32_e32 v7, v6
	v_cos_f32_e32 v6, v6
	s_mov_b32 s41, 0xffff4000
	v_cvt_pk_bf16_f32 v4, v4, v5
	v_add_u32_e32 v191, 64, v191
	v_cndmask_b32_e32 v6, v6, v7, vcc
	v_add3_u32 v7, v121, v189, s41
	v_cvt_f32_ubyte0_e32 v7, v7
	v_mul_f32_e32 v7, 0x3b800000, v7
	v_sin_f32_e32 v44, v7
	v_cos_f32_e32 v7, v7
	s_mov_b32 s41, 0xffff0000
	s_cmp_lg_u32 s40, 7
	v_cndmask_b32_e32 v7, v7, v44, vcc
	v_add3_u32 v44, v122, v189, s41
	v_and_b32_e32 v44, 0xfc, v44
	v_cvt_f32_ubyte0_e32 v44, v44
	v_mul_f32_e32 v44, 0x3b800000, v44
	v_sin_f32_e32 v45, v44
	v_cos_f32_e32 v44, v44
	s_mov_b32 s41, 0xfffec000
	v_cvt_pk_bf16_f32 v5, v6, v7
	v_cndmask_b32_e32 v44, v44, v45, vcc
	v_add3_u32 v45, v123, v189, s41
	v_cvt_f32_ubyte0_e32 v45, v45
	v_mul_f32_e32 v45, 0x3b800000, v45
	v_sin_f32_e32 v46, v45
	v_cos_f32_e32 v45, v45
	s_mov_b32 s41, 0xfffe8000
	v_cndmask_b32_e32 v45, v45, v46, vcc
	v_add3_u32 v46, v124, v189, s41
	v_and_b32_e32 v46, 0xfe, v46
	v_cvt_f32_ubyte0_e32 v46, v46
	v_mul_f32_e32 v46, 0x3b800000, v46
	v_sin_f32_e32 v47, v46
	v_cos_f32_e32 v46, v46
	s_mov_b32 s41, 0xfffe4000
	v_cvt_pk_bf16_f32 v6, v44, v45
	v_or_b32_e32 v44, v94, v128
	v_cndmask_b32_e32 v46, v46, v47, vcc
	v_add3_u32 v47, v125, v189, s41
	v_cvt_f32_ubyte0_e32 v47, v47
	v_mul_f32_e32 v47, 0x3b800000, v47
	v_sin_f32_e32 v72, v47
	v_cos_f32_e32 v47, v47
	s_movk_i32 s41, 0xc020
	v_mul_u32_u24_e32 v98, 0x4200, v44
	v_lshl_add_u64 v[44:45], v[92:93], 0, v[98:99]
	v_cndmask_b32_e32 v47, v47, v72, vcc
	v_and_b32_e32 v72, 0xf8, v187
	v_cvt_f32_ubyte0_e32 v72, v72
	v_mul_f32_e32 v72, 0x3b800000, v72
	v_sin_f32_e32 v73, v72
	v_cos_f32_e32 v72, v72
	v_cvt_pk_bf16_f32 v7, v46, v47
	global_load_dwordx4 v[44:47], v[44:45], off
	v_add_u32_e32 v189, v189, v190
	v_cndmask_b32_e32 v72, v72, v73, vcc
	v_add3_u32 v73, v115, v187, s41
	v_cvt_f32_ubyte0_e32 v73, v73
	v_mul_f32_e32 v73, 0x3b800000, v73
	v_sin_f32_e32 v74, v73
	v_cos_f32_e32 v73, v73
	s_movk_i32 s41, 0x8040
	v_cndmask_b32_e32 v73, v73, v74, vcc
	v_add3_u32 v74, v120, v187, s41
	v_and_b32_e32 v74, 0xfe, v74
	v_cvt_f32_ubyte0_e32 v74, v74
	v_mul_f32_e32 v74, 0x3b800000, v74
	v_sin_f32_e32 v75, v74
	v_cos_f32_e32 v74, v74
	s_mov_b32 s41, 0xffff4060
	v_cvt_pk_bf16_f32 v72, v72, v73
	v_cndmask_b32_e32 v74, v74, v75, vcc
	v_add3_u32 v75, v121, v187, s41
	v_cvt_f32_ubyte0_e32 v75, v75
	v_mul_f32_e32 v75, 0x3b800000, v75
	v_sin_f32_e32 v76, v75
	v_cos_f32_e32 v75, v75
	s_mov_b32 s41, 0xffff0080
	v_cndmask_b32_e32 v75, v75, v76, vcc
	v_add3_u32 v76, v122, v187, s41
	v_and_b32_e32 v76, 0xfc, v76
	v_cvt_f32_ubyte0_e32 v76, v76
	v_mul_f32_e32 v76, 0x3b800000, v76
	v_sin_f32_e32 v77, v76
	v_cos_f32_e32 v76, v76
	s_mov_b32 s41, 0xfffec0a0
	v_cvt_pk_bf16_f32 v73, v74, v75
	v_cndmask_b32_e32 v76, v76, v77, vcc
	v_add3_u32 v77, v123, v187, s41
	v_cvt_f32_ubyte0_e32 v77, v77
	v_mul_f32_e32 v77, 0x3b800000, v77
	v_sin_f32_e32 v78, v77
	v_cos_f32_e32 v77, v77
	s_mov_b32 s41, 0xfffe80c0
	v_cndmask_b32_e32 v77, v77, v78, vcc
	v_add3_u32 v78, v124, v187, s41
	v_and_b32_e32 v78, 0xfe, v78
	v_cvt_f32_ubyte0_e32 v78, v78
	v_mul_f32_e32 v78, 0x3b800000, v78
	v_sin_f32_e32 v79, v78
	v_cos_f32_e32 v78, v78
	s_mov_b32 s41, 0xfffe40e0
	v_cvt_pk_bf16_f32 v74, v76, v77
	v_add_u32_e32 v76, v94, v130
	v_cndmask_b32_e32 v78, v78, v79, vcc
	v_add3_u32 v79, v125, v187, s41
	v_cvt_f32_ubyte0_e32 v79, v79
	v_mul_f32_e32 v79, 0x3b800000, v79
	v_sin_f32_e32 v80, v79
	v_cos_f32_e32 v79, v79
	s_movk_i32 s41, 0xc040
	v_mul_u32_u24_e32 v98, 0x4200, v76
	v_lshl_add_u64 v[76:77], v[92:93], 0, v[98:99]
	v_cndmask_b32_e32 v79, v79, v80, vcc
	v_and_b32_e32 v80, 0xf8, v185
	v_cvt_f32_ubyte0_e32 v80, v80
	v_mul_f32_e32 v80, 0x3b800000, v80
	v_sin_f32_e32 v81, v80
	v_cos_f32_e32 v80, v80
	v_cvt_pk_bf16_f32 v75, v78, v79
	global_load_dwordx4 v[76:79], v[76:77], off
	v_add_u32_e32 v187, v187, v188
	v_cndmask_b32_e32 v80, v80, v81, vcc
	v_add3_u32 v81, v115, v185, s41
	v_cvt_f32_ubyte0_e32 v81, v81
	v_mul_f32_e32 v81, 0x3b800000, v81
	v_sin_f32_e32 v82, v81
	v_cos_f32_e32 v81, v81
	s_movk_i32 s41, 0x8080
	v_cndmask_b32_e32 v81, v81, v82, vcc
	v_add3_u32 v82, v120, v185, s41
	v_and_b32_e32 v82, 0xfe, v82
	v_cvt_f32_ubyte0_e32 v82, v82
	v_mul_f32_e32 v82, 0x3b800000, v82
	v_sin_f32_e32 v83, v82
	v_cos_f32_e32 v82, v82
	s_mov_b32 s41, 0xffff40c0
	v_cvt_pk_bf16_f32 v80, v80, v81
	v_cndmask_b32_e32 v82, v82, v83, vcc
	v_add3_u32 v83, v121, v185, s41
	v_cvt_f32_ubyte0_e32 v83, v83
	v_mul_f32_e32 v83, 0x3b800000, v83
	v_sin_f32_e32 v84, v83
	v_cos_f32_e32 v83, v83
	s_mov_b32 s41, 0xffff0100
	v_cndmask_b32_e32 v83, v83, v84, vcc
	v_add3_u32 v84, v122, v185, s41
	v_and_b32_e32 v84, 0xfc, v84
	v_cvt_f32_ubyte0_e32 v84, v84
	v_mul_f32_e32 v84, 0x3b800000, v84
	v_sin_f32_e32 v85, v84
	v_cos_f32_e32 v84, v84
	s_mov_b32 s41, 0xfffec140
	v_cvt_pk_bf16_f32 v81, v82, v83
	v_cndmask_b32_e32 v84, v84, v85, vcc
	v_add3_u32 v85, v123, v185, s41
	v_cvt_f32_ubyte0_e32 v85, v85
	v_mul_f32_e32 v85, 0x3b800000, v85
	v_sin_f32_e32 v86, v85
	v_cos_f32_e32 v85, v85
	s_mov_b32 s41, 0xfffe8180
	v_cndmask_b32_e32 v85, v85, v86, vcc
	v_add3_u32 v86, v124, v185, s41
	v_and_b32_e32 v86, 0xfe, v86
	v_cvt_f32_ubyte0_e32 v86, v86
	v_mul_f32_e32 v86, 0x3b800000, v86
	v_sin_f32_e32 v87, v86
	v_cos_f32_e32 v86, v86
	s_mov_b32 s41, 0xfffe41c0
	v_cvt_pk_bf16_f32 v82, v84, v85
	v_add_u32_e32 v84, v94, v132
	v_cndmask_b32_e32 v86, v86, v87, vcc
	v_add3_u32 v87, v125, v185, s41
	v_cvt_f32_ubyte0_e32 v87, v87
	v_mul_f32_e32 v87, 0x3b800000, v87
	v_sin_f32_e32 v88, v87
	v_cos_f32_e32 v87, v87
	s_movk_i32 s41, 0xc060
	v_mul_u32_u24_e32 v98, 0x4200, v84
	v_lshl_add_u64 v[84:85], v[92:93], 0, v[98:99]
	v_cndmask_b32_e32 v87, v87, v88, vcc
	v_and_b32_e32 v88, 0xf8, v117
	v_cvt_f32_ubyte0_e32 v88, v88
	v_mul_f32_e32 v88, 0x3b800000, v88
	v_sin_f32_e32 v89, v88
	v_cos_f32_e32 v88, v88
	v_add_u32_e32 v94, v94, v134
	v_cvt_pk_bf16_f32 v83, v86, v87
	global_load_dwordx4 v[84:87], v[84:85], off
	v_cndmask_b32_e32 v88, v88, v89, vcc
	v_add3_u32 v89, v115, v117, s41
	v_cvt_f32_ubyte0_e32 v89, v89
	v_mul_f32_e32 v89, 0x3b800000, v89
	v_sin_f32_e32 v90, v89
	v_cos_f32_e32 v89, v89
	s_movk_i32 s41, 0x80c0
	v_add_u32_e32 v185, v185, v186
	v_cndmask_b32_e32 v89, v89, v90, vcc
	v_add3_u32 v90, v120, v117, s41
	v_and_b32_e32 v90, 0xfe, v90
	v_cvt_f32_ubyte0_e32 v90, v90
	v_mul_f32_e32 v90, 0x3b800000, v90
	v_sin_f32_e32 v91, v90
	v_cos_f32_e32 v90, v90
	s_mov_b32 s41, 0xffff4120
	v_cvt_pk_bf16_f32 v88, v88, v89
	v_cndmask_b32_e32 v90, v90, v91, vcc
	v_add3_u32 v91, v121, v117, s41
	v_cvt_f32_ubyte0_e32 v91, v91
	v_mul_f32_e32 v91, 0x3b800000, v91
	v_sin_f32_e32 v95, v91
	v_cos_f32_e32 v91, v91
	s_mov_b32 s41, 0xffff0180
	v_cndmask_b32_e32 v91, v91, v95, vcc
	v_add3_u32 v95, v122, v117, s41
	v_and_b32_e32 v95, 0xfc, v95
	v_cvt_f32_ubyte0_e32 v95, v95
	v_mul_f32_e32 v95, 0x3b800000, v95
	v_sin_f32_e32 v98, v95
	v_cos_f32_e32 v95, v95
	s_mov_b32 s41, 0xfffec1e0
	v_cvt_pk_bf16_f32 v89, v90, v91
	v_cndmask_b32_e32 v95, v95, v98, vcc
	v_add3_u32 v98, v123, v117, s41
	v_cvt_f32_ubyte0_e32 v98, v98
	v_mul_f32_e32 v98, 0x3b800000, v98
	v_sin_f32_e32 v154, v98
	v_cos_f32_e32 v98, v98
	s_mov_b32 s41, 0xfffe8240
	v_cndmask_b32_e32 v98, v98, v154, vcc
	v_cvt_pk_bf16_f32 v90, v95, v98
	v_mul_u32_u24_e32 v98, 0x4200, v94
	v_lshl_add_u64 v[92:93], v[92:93], 0, v[98:99]
	global_load_dwordx4 v[92:95], v[92:93], off
	v_add3_u32 v154, v124, v117, s41
	v_and_b32_e32 v154, 0xfe, v154
	v_cvt_f32_ubyte0_e32 v154, v154
	v_mul_f32_e32 v154, 0x3b800000, v154
	v_sin_f32_e32 v155, v154
	v_cos_f32_e32 v154, v154
	s_mov_b32 s41, 0xfffe42a0
	v_add_u32_e32 v98, v135, v139
	v_cndmask_b32_e32 v154, v154, v155, vcc
	v_add3_u32 v155, v125, v117, s41
	v_cvt_f32_ubyte0_e32 v155, v155
	v_mul_f32_e32 v155, 0x3b800000, v155
	v_sin_f32_e32 v156, v155
	v_cos_f32_e32 v155, v155
	v_add_u32_e32 v117, v117, v119
	s_mov_b32 s41, s40
	v_cndmask_b32_e32 v155, v155, v156, vcc
	v_cvt_pk_bf16_f32 v91, v154, v155
	ds_read_b128 v[154:157], v98
	ds_read_b128 v[192:195], v98 offset:2304
	ds_read_b128 v[196:199], v140 offset:18432
	ds_read_b128 v[200:203], v140 offset:20736
	ds_read_b128 v[204:207], v140 offset:23040
	ds_read_b128 v[208:211], v140 offset:25344
	ds_read_b128 v[212:215], v140 offset:27648
	ds_read_b128 v[216:219], v140 offset:29952
	ds_read_b128 v[220:223], v140 offset:32256
	ds_read_b128 v[224:227], v140 offset:34560
	s_waitcnt lgkmcnt(7)
	v_mfma_f32_16x16x32_bf16 v[68:71], v[196:199], v[154:157], v[68:71]
	s_waitcnt lgkmcnt(6)
	v_mfma_f32_16x16x32_bf16 v[64:67], v[200:203], v[154:157], v[64:67]
	s_waitcnt lgkmcnt(5)
	v_mfma_f32_16x16x32_bf16 v[60:63], v[204:207], v[154:157], v[60:63]
	s_waitcnt lgkmcnt(4)
	v_mfma_f32_16x16x32_bf16 v[56:59], v[208:211], v[154:157], v[56:59]
	s_waitcnt lgkmcnt(3)
	v_mfma_f32_16x16x32_bf16 v[52:55], v[212:215], v[154:157], v[52:55]
	s_waitcnt lgkmcnt(2)
	v_mfma_f32_16x16x32_bf16 v[48:51], v[216:219], v[154:157], v[48:51]
	s_waitcnt lgkmcnt(1)
	v_mfma_f32_16x16x32_bf16 v[40:43], v[220:223], v[154:157], v[40:43]
	s_waitcnt lgkmcnt(0)
	v_mfma_f32_16x16x32_bf16 v[36:39], v[224:227], v[154:157], v[36:39]
	v_mfma_f32_16x16x32_bf16 v[32:35], v[196:199], v[192:195], v[32:35]
	v_mfma_f32_16x16x32_bf16 v[28:31], v[200:203], v[192:195], v[28:31]
	v_mfma_f32_16x16x32_bf16 v[24:27], v[204:207], v[192:195], v[24:27]
	v_mfma_f32_16x16x32_bf16 v[20:23], v[208:211], v[192:195], v[20:23]
	v_mfma_f32_16x16x32_bf16 v[16:19], v[212:215], v[192:195], v[16:19]
	v_mfma_f32_16x16x32_bf16 v[12:15], v[216:219], v[192:195], v[12:15]
	v_mfma_f32_16x16x32_bf16 v[8:11], v[220:223], v[192:195], v[8:11]
	v_mfma_f32_16x16x32_bf16 v[0:3], v[224:227], v[192:195], v[0:3]
	ds_read_b128 v[154:157], v98 offset:64
	ds_read_b128 v[192:195], v98 offset:2368
	ds_read_b128 v[196:199], v140 offset:18496
	ds_read_b128 v[200:203], v140 offset:20800
	ds_read_b128 v[204:207], v140 offset:23104
	ds_read_b128 v[208:211], v140 offset:25408
	ds_read_b128 v[212:215], v140 offset:27712
	ds_read_b128 v[216:219], v140 offset:30016
	ds_read_b128 v[220:223], v140 offset:32320
	ds_read_b128 v[224:227], v140 offset:34624
	s_waitcnt lgkmcnt(7)
	v_mfma_f32_16x16x32_bf16 v[68:71], v[196:199], v[154:157], v[68:71]
	s_waitcnt lgkmcnt(6)
	v_mfma_f32_16x16x32_bf16 v[64:67], v[200:203], v[154:157], v[64:67]
	s_waitcnt lgkmcnt(5)
	v_mfma_f32_16x16x32_bf16 v[60:63], v[204:207], v[154:157], v[60:63]
	s_waitcnt lgkmcnt(4)
	v_mfma_f32_16x16x32_bf16 v[56:59], v[208:211], v[154:157], v[56:59]
	s_waitcnt lgkmcnt(3)
	v_mfma_f32_16x16x32_bf16 v[52:55], v[212:215], v[154:157], v[52:55]
	s_waitcnt lgkmcnt(2)
	v_mfma_f32_16x16x32_bf16 v[48:51], v[216:219], v[154:157], v[48:51]
	s_waitcnt lgkmcnt(1)
	v_mfma_f32_16x16x32_bf16 v[40:43], v[220:223], v[154:157], v[40:43]
	s_waitcnt lgkmcnt(0)
	v_mfma_f32_16x16x32_bf16 v[36:39], v[224:227], v[154:157], v[36:39]
	v_mfma_f32_16x16x32_bf16 v[32:35], v[196:199], v[192:195], v[32:35]
	v_mfma_f32_16x16x32_bf16 v[28:31], v[200:203], v[192:195], v[28:31]
	v_mfma_f32_16x16x32_bf16 v[24:27], v[204:207], v[192:195], v[24:27]
	v_mfma_f32_16x16x32_bf16 v[20:23], v[208:211], v[192:195], v[20:23]
	v_mfma_f32_16x16x32_bf16 v[16:19], v[212:215], v[192:195], v[16:19]
	v_mfma_f32_16x16x32_bf16 v[12:15], v[216:219], v[192:195], v[12:15]
	v_mfma_f32_16x16x32_bf16 v[8:11], v[220:223], v[192:195], v[8:11]
	v_mfma_f32_16x16x32_bf16 v[0:3], v[224:227], v[192:195], v[0:3]
	s_cbranch_scc1 .LBB0_461
	s_barrier
	ds_write_b128 v136, v[4:7]
	s_waitcnt vmcnt(3)
	ds_write_b128 v136, v[44:47] offset:18432
	ds_write_b128 v136, v[72:75] offset:4608
	s_waitcnt vmcnt(2)
	ds_write_b128 v136, v[76:79] offset:23040
	ds_write_b128 v136, v[80:83] offset:9216
	s_waitcnt vmcnt(1)
	ds_write_b128 v136, v[84:87] offset:27648
	ds_write_b128 v136, v[88:91] offset:13824
	s_waitcnt vmcnt(0)
	ds_write_b128 v136, v[92:95] offset:32256
	s_waitcnt lgkmcnt(0)
	s_barrier
	ds_read_b128 v[4:7], v140 offset:34560
	ds_read_b128 v[44:47], v140 offset:32256
	ds_read_b128 v[72:75], v140 offset:29952
	ds_read_b128 v[76:79], v140 offset:27648
	ds_read_b128 v[80:83], v140 offset:25344
	ds_read_b128 v[84:87], v140 offset:23040
	ds_read_b128 v[88:91], v140 offset:20736
	ds_read_b128 v[92:95], v140 offset:18432
	ds_read_b128 v[120:123], v98 offset:2304
	ds_read_b128 v[154:157], v98
	s_waitcnt lgkmcnt(0)
	v_mfma_f32_16x16x32_bf16 v[68:71], v[92:95], v[154:157], v[68:71]
	s_lshr_b32 s30, s30, 1
	s_mulk_i32 s30, 0x2100
	s_lshl_b32 s39, s66, 7
	v_mfma_f32_16x16x32_bf16 v[48:51], v[72:75], v[154:157], v[48:51]
	s_add_i32 s30, s30, s38
	v_mfma_f32_16x16x32_bf16 v[32:35], v[92:95], v[120:123], v[32:35]
	v_mfma_f32_16x16x32_bf16 v[72:75], v[72:75], v[120:123], v[12:15]
	v_mfma_f32_16x16x32_bf16 v[64:67], v[88:91], v[154:157], v[64:67]
	v_mfma_f32_16x16x32_bf16 v[60:63], v[84:87], v[154:157], v[60:63]
	v_mfma_f32_16x16x32_bf16 v[56:59], v[80:83], v[154:157], v[56:59]
	v_mfma_f32_16x16x32_bf16 v[52:55], v[76:79], v[154:157], v[52:55]
	v_mfma_f32_16x16x32_bf16 v[40:43], v[44:47], v[154:157], v[40:43]
	v_mfma_f32_16x16x32_bf16 v[36:39], v[4:7], v[154:157], v[36:39]
	v_mfma_f32_16x16x32_bf16 v[88:91], v[88:91], v[120:123], v[28:31]
	v_mfma_f32_16x16x32_bf16 v[84:87], v[84:87], v[120:123], v[24:27]
	v_mfma_f32_16x16x32_bf16 v[80:83], v[80:83], v[120:123], v[20:23]
	v_mfma_f32_16x16x32_bf16 v[76:79], v[76:79], v[120:123], v[16:19]
	v_mfma_f32_16x16x32_bf16 v[44:47], v[44:47], v[120:123], v[8:11]
	v_mfma_f32_16x16x32_bf16 v[0:3], v[4:7], v[120:123], v[0:3]
	ds_read_b128 v[4:7], v98 offset:64
	ds_read_b128 v[92:95], v98 offset:2368
	ds_read_b128 v[8:11], v140 offset:18496
	ds_read_b128 v[12:15], v140 offset:20800
	ds_read_b128 v[16:19], v140 offset:23104
	ds_read_b128 v[120:123], v140 offset:25408
	ds_read_b128 v[154:157], v140 offset:27712
	ds_read_b128 v[186:189], v140 offset:30016
	ds_read_b128 v[190:193], v140 offset:32320
	ds_read_b128 v[194:197], v140 offset:34624
	s_waitcnt lgkmcnt(7)
	v_mfma_f32_16x16x32_bf16 v[68:71], v[8:11], v[4:7], v[68:71]
	v_mfma_f32_16x16x32_bf16 v[28:31], v[8:11], v[92:95], v[32:35]
	s_waitcnt lgkmcnt(2)
	v_mfma_f32_16x16x32_bf16 v[8:11], v[186:189], v[92:95], v[72:75]
	s_nop 0
	v_mov_b64_e32 v[32:33], s[94:95]
	s_nop 3
	v_mul_f32_e32 v30, s36, v30
	v_mul_f32_e32 v31, s36, v31
	v_mul_f32_e32 v28, s36, v28
	v_mul_f32_e32 v29, s36, v29
	v_add_u32_e32 v72, s30, v142
	s_and_b32 s30, s39, 0x80
	v_or_b32_e32 v73, s30, v141
	v_mfma_f32_16x16x32_bf16 v[64:67], v[12:15], v[4:7], v[64:67]
	v_mad_u64_u32 v[34:35], s[38:39], v72, s64, v[32:33]
	v_lshlrev_b32_e32 v98, 1, v73
	v_lshl_add_u64 v[34:35], v[34:35], 0, v[98:99]
	v_mfma_f32_16x16x32_bf16 v[60:63], v[16:19], v[4:7], v[60:63]
	v_add_co_u32_e32 v34, vcc, s65, v34
	v_cvt_pk_bf16_f32 v28, v28, v29
	v_mfma_f32_16x16x32_bf16 v[56:59], v[120:123], v[4:7], v[56:59]
	v_addc_co_u32_e32 v35, vcc, 0, v35, vcc
	v_cvt_pk_bf16_f32 v29, v30, v31
	v_mfma_f32_16x16x32_bf16 v[52:55], v[154:157], v[4:7], v[52:55]
	v_mul_f32_e64 v10, v10, s36
	v_mul_f32_e64 v11, v11, s36
	v_mul_f32_e32 v8, s36, v8
	v_mul_f32_e32 v9, s36, v9
	v_mfma_f32_16x16x32_bf16 v[48:51], v[186:189], v[4:7], v[48:51]
	v_cvt_pk_bf16_f32 v8, v8, v9
	v_cvt_pk_bf16_f32 v9, v10, v11
	s_waitcnt lgkmcnt(1)
	v_mfma_f32_16x16x32_bf16 v[40:43], v[190:193], v[4:7], v[40:43]
	s_waitcnt lgkmcnt(0)
	v_mfma_f32_16x16x32_bf16 v[36:39], v[194:197], v[4:7], v[36:39]
	v_mfma_f32_16x16x32_bf16 v[4:7], v[190:193], v[92:95], v[44:47]
	s_nop 4
	v_mul_f32_e64 v42, v42, s36
	v_mul_f32_e64 v43, v43, s36
	v_mul_f32_e32 v40, s36, v40
	v_mul_f32_e32 v41, s36, v41
	v_mul_f32_e32 v38, s36, v38
	v_mul_f32_e32 v39, s36, v39
	v_mul_f32_e32 v44, s36, v70
	v_mul_f32_e32 v45, s36, v71
	v_mul_f32_e32 v46, s36, v68
	v_mul_f32_e32 v47, s36, v69
	v_mul_f32_e32 v36, s36, v36
	v_mul_f32_e32 v37, s36, v37
	v_cvt_pk_bf16_f32 v46, v46, v47
	v_cvt_pk_bf16_f32 v47, v44, v45
	global_store_dwordx2 v[34:35], v[46:47], off offset:1536
	v_mul_f32_e32 v44, s36, v66
	v_mul_f32_e32 v45, s36, v67
	v_mul_f32_e32 v46, s36, v64
	v_mul_f32_e32 v47, s36, v65
	v_mfma_f32_16x16x32_bf16 v[24:27], v[12:15], v[92:95], v[88:91]
	v_cvt_pk_bf16_f32 v46, v46, v47
	v_cvt_pk_bf16_f32 v47, v44, v45
	global_store_dwordx2 v[34:35], v[46:47], off offset:1568
	v_mul_f32_e32 v44, s36, v62
	v_mul_f32_e32 v45, s36, v63
	v_mul_f32_e32 v46, s36, v60
	v_mul_f32_e32 v47, s36, v61
	v_mfma_f32_16x16x32_bf16 v[20:23], v[16:19], v[92:95], v[84:87]
	v_cvt_pk_bf16_f32 v46, v46, v47
	v_cvt_pk_bf16_f32 v47, v44, v45
	global_store_dwordx2 v[34:35], v[46:47], off offset:1600
	v_mul_f32_e32 v44, s36, v58
	v_mul_f32_e32 v45, s36, v59
	v_mul_f32_e32 v46, s36, v56
	v_mul_f32_e32 v47, s36, v57
	v_mfma_f32_16x16x32_bf16 v[16:19], v[120:123], v[92:95], v[80:83]
	v_cvt_pk_bf16_f32 v46, v46, v47
	v_cvt_pk_bf16_f32 v47, v44, v45
	global_store_dwordx2 v[34:35], v[46:47], off offset:1632
	v_mul_f32_e32 v44, s36, v54
	v_mul_f32_e32 v45, s36, v55
	v_mul_f32_e32 v46, s36, v52
	v_mul_f32_e32 v47, s36, v53
	v_mfma_f32_16x16x32_bf16 v[12:15], v[154:157], v[92:95], v[76:79]
	v_cvt_pk_bf16_f32 v46, v46, v47
	v_cvt_pk_bf16_f32 v47, v44, v45
	global_store_dwordx2 v[34:35], v[46:47], off offset:1664
	v_mul_f32_e32 v44, s36, v50
	v_mul_f32_e32 v45, s36, v51
	v_mul_f32_e32 v46, s36, v48
	v_mul_f32_e32 v47, s36, v49
	v_mfma_f32_16x16x32_bf16 v[0:3], v[194:197], v[92:95], v[0:3]
	v_cvt_pk_bf16_f32 v46, v46, v47
	v_cvt_pk_bf16_f32 v47, v44, v45
	v_cvt_pk_bf16_f32 v40, v40, v41
	v_cvt_pk_bf16_f32 v41, v42, v43
	v_cvt_pk_bf16_f32 v36, v36, v37
	v_cvt_pk_bf16_f32 v37, v38, v39
	global_store_dwordx2 v[34:35], v[46:47], off offset:1696
	global_store_dwordx2 v[34:35], v[40:41], off offset:1728
	global_store_dwordx2 v[34:35], v[36:37], off offset:1760
	v_or_b32_e32 v34, 16, v72
	v_mad_u64_u32 v[32:33], s[38:39], v34, s64, v[32:33]
	v_lshl_add_u64 v[30:31], v[32:33], 0, v[98:99]
	v_add_co_u32_e32 v30, vcc, s65, v30
	v_mul_f32_e32 v26, s36, v26
	v_mul_f32_e32 v27, s36, v27
	v_mul_f32_e32 v24, s36, v24
	v_mul_f32_e32 v25, s36, v25
	v_mul_f32_e32 v22, s36, v22
	v_mul_f32_e32 v23, s36, v23
	v_mul_f32_e32 v20, s36, v20
	v_mul_f32_e32 v21, s36, v21
	v_mul_f32_e32 v18, s36, v18
	v_mul_f32_e32 v19, s36, v19
	v_mul_f32_e32 v16, s36, v16
	v_mul_f32_e32 v17, s36, v17
	v_mul_f32_e32 v14, s36, v14
	v_mul_f32_e32 v15, s36, v15
	v_mul_f32_e32 v12, s36, v12
	v_mul_f32_e32 v13, s36, v13
	v_mul_f32_e32 v6, s36, v6
	v_mul_f32_e32 v7, s36, v7
	v_mul_f32_e32 v4, s36, v4
	v_mul_f32_e32 v5, s36, v5
	v_mul_f32_e32 v2, s36, v2
	v_mul_f32_e32 v3, s36, v3
	v_mul_f32_e32 v0, s36, v0
	v_mul_f32_e32 v1, s36, v1
	v_addc_co_u32_e32 v31, vcc, 0, v31, vcc
	v_cvt_pk_bf16_f32 v24, v24, v25
	v_cvt_pk_bf16_f32 v25, v26, v27
	v_cvt_pk_bf16_f32 v20, v20, v21
	v_cvt_pk_bf16_f32 v21, v22, v23
	v_cvt_pk_bf16_f32 v16, v16, v17
	v_cvt_pk_bf16_f32 v17, v18, v19
	v_cvt_pk_bf16_f32 v12, v12, v13
	v_cvt_pk_bf16_f32 v13, v14, v15
	v_cvt_pk_bf16_f32 v4, v4, v5
	v_cvt_pk_bf16_f32 v5, v6, v7
	v_cvt_pk_bf16_f32 v0, v0, v1
	v_cvt_pk_bf16_f32 v1, v2, v3
	global_store_dwordx2 v[30:31], v[28:29], off offset:1536
	global_store_dwordx2 v[30:31], v[24:25], off offset:1568
	global_store_dwordx2 v[30:31], v[20:21], off offset:1600
	global_store_dwordx2 v[30:31], v[16:17], off offset:1632
	global_store_dwordx2 v[30:31], v[12:13], off offset:1664
	global_store_dwordx2 v[30:31], v[8:9], off offset:1696
	global_store_dwordx2 v[30:31], v[4:5], off offset:1728
	global_store_dwordx2 v[30:31], v[0:1], off offset:1760

.LBB0_583:
	s_andn2_saveexec_b64 s[4:5], s[4:5]
	v_lshlrev_b64 v[0:1], 15, v[78:79]
	v_lshl_add_u64 v[30:31], v[56:57], 0, v[0:1]
	v_lshl_add_u64 v[32:33], v[30:31], 0, 4
	v_lshl_add_u64 v[34:35], v[30:31], 0, 8
	v_lshl_add_u64 v[72:73], v[30:31], 0, 12
	v_mov_b32_e32 v3, v7
	v_mov_b32_e32 v0, v4
	v_mov_b64_e32 v[74:75], v[42:43]
	s_or_b64 exec, exec, s[4:5]
	global_load_dword v78, v[30:31], off
	global_load_dword v79, v[32:33], off
	s_nop 0
	global_load_dword v34, v[34:35], off
	s_nop 0
	global_load_dword v35, v[72:73], off
	s_waitcnt vmcnt(24)
	v_max_f32_e32 v1, v26, v26
	v_max_f32_e32 v1, 0, v1
	v_mul_f32_e64 v2, -v1, s40
	v_exp_f32_e32 v98, v2
	v_sub_f32_e32 v2, v26, v1
	v_mul_f32_e32 v2, 0x3fb8aa3b, v2
	v_exp_f32_e32 v99, v2
	s_and_saveexec_b64 s[4:5], s[2:3]
	s_xor_b64 s[4:5], exec, s[4:5]
	s_cbranch_execz .LBB0_669
	v_add_co_u32_e32 v30, vcc, 0xffff0000, v10
	s_mov_b32 s10, s8
	s_nop 0
	v_addc_co_u32_e32 v31, vcc, -1, v11, vcc
	s_mov_b32 s11, s8
	s_mov_b32 s9, s8
	v_mov_b64_e32 v[72:73], s[10:11]
	v_add_co_u32_e32 v10, vcc, 0xffff1000, v10
	v_mov_b64_e32 v[70:71], s[8:9]
	s_nop 0
	v_addc_co_u32_e32 v11, vcc, -1, v11, vcc
	global_store_dwordx4 v[10:11], v[70:73], off offset:-4080
	v_mov_b32_e32 v10, v53
	v_mov_b32_e32 v11, v4
	v_mul_f32_e32 v94, v98, v10
	v_mul_f32_e32 v95, v99, v11
	v_mov_b32_e32 v2, v99
	global_store_dwordx4 v[30:31], v[70:73], off
	s_waitcnt vmcnt(24)
	v_fma_f32 v30, v2, v68, v94
	v_fma_f32 v31, v2, v69, v94
	s_waitcnt vmcnt(22)
	v_fma_f32 v32, v2, v64, v94
	v_fma_f32 v33, v2, v65, v94
	v_add_f32_e32 v6, v94, v95
	v_fma_f32 v96, v2, v42, v94
	v_fma_f32 v97, v2, v43, v94
	s_andn2_saveexec_b64 s[4:5], s[4:5]
	s_cbranch_execnz .LBB0_670

.LBB0_593:
	s_or_b64 exec, exec, s[10:11]
	global_load_dword v70, v[4:5], off
	s_nop 0
	global_load_dword v72, v[72:73], off
	s_nop 0
	global_load_dword v73, v[100:101], off
	global_load_dword v64, v[102:103], off
	v_add_f32_e32 v10, v27, v1
	s_waitcnt vmcnt(24)
	v_max_f32_e32 v1, v24, v24
	v_max_f32_e32 v1, v10, v1
	v_sub_f32_e32 v2, v10, v1
	v_sub_f32_e32 v4, v24, v1
	v_mul_f32_e32 v2, 0x3fb8aa3b, v2
	v_mul_f32_e32 v4, 0x3fb8aa3b, v4
	v_exp_f32_e32 v2, v2
	v_exp_f32_e32 v98, v4
	v_fmac_f32_e32 v94, v99, v7
	s_and_saveexec_b64 s[10:11], s[2:3]
	s_xor_b64 s[10:11], exec, s[10:11]
	s_cbranch_execz .LBB0_671
	v_add_co_u32_e32 v4, vcc, 0xffff0000, v28
	v_mov_b32_e32 v7, v96
	s_nop 0
	v_addc_co_u32_e32 v5, vcc, -1, v29, vcc
	global_store_dwordx4 v[4:5], v[30:33], off
	v_add_co_u32_e32 v4, vcc, 0xffff1000, v28
	v_mov_b32_e32 v8, v97
	v_mov_b32_e32 v9, v94
	v_addc_co_u32_e32 v5, vcc, -1, v29, vcc
	global_store_dwordx4 v[4:5], v[6:9], off offset:-4080
	v_mul_f32_e32 v4, v2, v30
	v_mul_f32_e32 v5, v2, v31
	s_waitcnt vmcnt(24)
	v_fma_f32 v26, v98, v50, v4
	v_fma_f32 v27, v98, v51, v5
	v_mul_f32_e32 v4, v2, v32
	v_mul_f32_e32 v5, v2, v33
	s_waitcnt vmcnt(22)
	v_fma_f32 v28, v98, v46, v4
	v_fma_f32 v29, v98, v47, v5
	v_mov_b32_e32 v99, v2
	v_mov_b32_e32 v21, v6
	v_mul_f32_e32 v4, v98, v20
	v_mul_f32_e32 v5, v99, v21
	s_nop 0
	v_add_f32_e32 v22, v4, v5
	v_mul_f32_e32 v4, v2, v96
	v_mul_f32_e32 v5, v2, v97
	v_fma_f32 v4, v98, v48, v4
	v_fma_f32 v5, v98, v49, v5
	s_andn2_saveexec_b64 s[10:11], s[10:11]
	s_cbranch_execnz .LBB0_672

.LBB0_601:
	s_or_b64 exec, exec, s[10:11]
	global_load_dword v50, v[20:21], off
	global_load_dword v51, v[30:31], off
	global_load_dword v48, v[32:33], off
	global_load_dword v49, v[96:97], off
	v_add_f32_e32 v6, v25, v1
	s_waitcnt vmcnt(24)
	v_max_f32_e32 v1, v76, v76
	v_max_f32_e32 v1, v6, v1
	v_sub_f32_e32 v7, v6, v1
	v_mul_f32_e32 v7, 0x3fb8aa3b, v7
	v_exp_f32_e32 v8, v7
	v_sub_f32_e32 v7, v76, v1
	v_mul_f32_e32 v7, 0x3fb8aa3b, v7
	v_exp_f32_e32 v20, v7
	v_mul_f32_e32 v25, v98, v23
	v_fmac_f32_e32 v25, v2, v94
	s_and_saveexec_b64 s[10:11], s[2:3]
	s_xor_b64 s[10:11], exec, s[10:11]
	s_cbranch_execz .LBB0_673
	v_add_co_u32_e32 v30, vcc, 0xffff0000, v60
	v_mov_b32_e32 v23, v4
	s_nop 0
	v_addc_co_u32_e32 v31, vcc, -1, v61, vcc
	global_store_dwordx4 v[30:31], v[26:29], off
	v_add_co_u32_e32 v30, vcc, 0xffff1000, v60
	v_mov_b32_e32 v24, v5
	s_nop 0
	v_addc_co_u32_e32 v31, vcc, -1, v61, vcc
	v_mul_f32_e32 v26, v8, v26
	v_mul_f32_e32 v27, v8, v27
	global_store_dwordx4 v[30:31], v[22:25], off offset:-4080
	s_waitcnt vmcnt(24)
	v_fma_f32 v30, v20, v90, v26
	v_fma_f32 v31, v20, v91, v27
	v_mul_f32_e32 v26, v8, v28
	v_mul_f32_e32 v27, v8, v29
	s_waitcnt vmcnt(22)
	v_fma_f32 v32, v20, v62, v26
	v_fma_f32 v33, v20, v63, v27
	v_mov_b32_e32 v21, v8
	v_mov_b32_e32 v17, v22
	v_mul_f32_e32 v16, v20, v16
	v_mul_f32_e32 v17, v21, v17
	v_mul_f32_e32 v4, v8, v4
	v_mul_f32_e32 v5, v8, v5
	v_add_f32_e32 v18, v16, v17
	v_fma_f32 v94, v20, v88, v4
	v_fma_f32 v95, v20, v89, v5
	s_andn2_saveexec_b64 s[10:11], s[10:11]
	s_cbranch_execnz .LBB0_674

.LBB0_609:
	s_or_b64 exec, exec, s[10:11]
	global_load_dword v62, v[16:17], off
	global_load_dword v63, v[22:23], off
	global_load_dword v60, v[26:27], off
	global_load_dword v61, v[28:29], off
	v_add_f32_e32 v22, v77, v1
	s_waitcnt vmcnt(24)
	v_max_f32_e32 v1, v36, v36
	v_max_f32_e32 v10, v22, v1
	v_sub_f32_e32 v1, v22, v10
	v_mul_f32_e32 v1, 0x3fb8aa3b, v1
	v_exp_f32_e32 v2, v1
	v_sub_f32_e32 v1, v36, v10
	v_mul_f32_e32 v1, 0x3fb8aa3b, v1
	v_exp_f32_e32 v16, v1
	v_mul_f32_e32 v21, v20, v19
	v_fmac_f32_e32 v21, v8, v25
	s_and_saveexec_b64 s[10:11], s[2:3]
	s_xor_b64 s[10:11], exec, s[10:11]
	s_cbranch_execz .LBB0_675
	v_add_co_u32_e32 v24, vcc, 0xffff0000, v80
	v_mov_b32_e32 v19, v94
	s_nop 0
	v_addc_co_u32_e32 v25, vcc, -1, v81, vcc
	global_store_dwordx4 v[24:25], v[30:33], off
	v_add_co_u32_e32 v24, vcc, 0xffff1000, v80
	v_mov_b32_e32 v20, v95
	s_nop 0
	v_addc_co_u32_e32 v25, vcc, -1, v81, vcc
	global_store_dwordx4 v[24:25], v[18:21], off offset:-4080
	v_mul_f32_e32 v24, v2, v30
	v_mul_f32_e32 v25, v2, v31
	v_mul_f32_e32 v26, v2, v32
	v_mul_f32_e32 v27, v2, v33
	s_waitcnt vmcnt(24)
	v_fma_f32 v24, v16, v84, v24
	v_fma_f32 v25, v16, v85, v25
	s_waitcnt vmcnt(22)
	v_fma_f32 v26, v16, v82, v26
	v_fma_f32 v27, v16, v83, v27
	v_mov_b32_e32 v17, v2
	v_mov_b32_e32 v28, v12
	v_mov_b32_e32 v29, v18
	v_mul_f32_e32 v18, v16, v28
	v_mul_f32_e32 v19, v17, v29
	v_pk_mov_b32 v[12:13], v[12:13], v[14:15] op_sel:[1,0]
	v_add_f32_e32 v1, v18, v19
	v_mul_f32_e32 v18, v2, v94
	v_mul_f32_e32 v19, v2, v95
	v_fma_f32 v88, v16, v12, v18
	v_fma_f32 v89, v16, v13, v19
	s_andn2_saveexec_b64 s[10:11], s[10:11]
	s_cbranch_execnz .LBB0_676

.LBB0_623:
	v_mov_b32_e32 v2, s43
	v_mov_b32_e32 v8, s42
	v_cndmask_b32_e64 v8, v2, v8, s[0:1]
	v_max_f32_e32 v2, v71, v71
	s_waitcnt vmcnt(20)
	v_max_f32_e32 v10, v40, v40
	v_max_f32_e32 v2, v2, v10
	v_sub_f32_e32 v10, v71, v2
	v_mul_f32_e32 v10, 0x3fb8aa3b, v10
	v_exp_f32_e32 v87, v10
	v_sub_f32_e32 v10, v40, v2
	v_mul_f32_e32 v10, 0x3fb8aa3b, v10
	v_exp_f32_e32 v86, v10
	v_add_u32_e32 v30, v8, v106
	v_ashrrev_i32_e32 v31, 31, v30
	v_mul_f32_e32 v32, v87, v88
	v_mul_f32_e32 v82, v25, v87
	v_mul_f32_e32 v80, v87, v27
	s_and_saveexec_b64 s[34:35], s[2:3]
	s_xor_b64 s[34:35], exec, s[34:35]
	s_cbranch_execz .LBB0_650
	v_lshlrev_b64 v[20:21], 9, v[30:31]
	v_lshl_add_u64 v[36:37], v[54:55], 0, v[20:21]
	v_add_co_u32_e32 v20, vcc, 0xffff0000, v36
	v_mov_b32_e32 v22, v29
	s_nop 0
	v_addc_co_u32_e32 v21, vcc, -1, v37, vcc
	v_add_co_u32_e32 v36, vcc, s39, v36
	global_store_dwordx4 v[20:21], v[24:27], off
	v_mov_b32_e32 v20, v1
	v_mov_b32_e32 v21, v88
	v_addc_co_u32_e32 v37, vcc, -1, v37, vcc
	global_store_dwordx4 v[36:37], v[20:23], off offset:-4080
	v_mov_b32_e32 v36, v86
	v_mov_b32_e32 v37, v26
	s_waitcnt vmcnt(19)
	v_mov_b32_e32 v26, v34
	v_mov_b32_e32 v27, v87
	v_mul_f32_e32 v26, v36, v26
	v_mul_f32_e32 v27, v37, v27
	v_mov_b32_e32 v21, v24
	v_mul_f32_e32 v24, v86, v79
	v_mov_b32_e32 v25, v26
	v_mov_b32_e32 v83, v27
	v_mul_f32_e32 v0, v0, v86
	v_mul_f32_e32 v1, v1, v87
	v_add_f32_e32 v84, v24, v82
	v_add_f32_e32 v85, v25, v83
	s_waitcnt vmcnt(18)
	v_mul_f32_e32 v24, v86, v35
	v_mov_b32_e32 v25, v0
	v_mov_b32_e32 v81, v1
	v_mov_b32_e32 v20, v78
	v_add_f32_e32 v36, v24, v80
	v_add_f32_e32 v37, v25, v81
	v_mul_f32_e32 v24, v28, v86
	v_mul_f32_e32 v25, v29, v87
	v_mul_f32_e32 v20, v86, v20
	v_mul_f32_e32 v21, v87, v21
	v_mul_f32_e32 v0, v74, v86
	v_mov_b32_e32 v1, v24
	v_mov_b32_e32 v33, v25
	v_add_f32_e32 v20, v20, v21
	v_add_f32_e32 v38, v0, v32
	v_add_f32_e32 v39, v1, v33
	s_andn2_saveexec_b64 s[34:35], s[34:35]
	s_cbranch_execnz .LBB0_651

.LBB0_633:
	s_add_i32 s10, s9, -6
	s_add_i32 s11, s42, -1
	v_mov_b32_e32 v0, s10
	v_mov_b32_e32 v1, s11
	v_add_f32_e32 v8, v41, v2
	v_cndmask_b32_e64 v0, v0, v1, s[0:1]
	v_max_f32_e32 v1, v42, v42
	v_max_f32_e32 v19, v8, v1
	v_sub_f32_e32 v1, v8, v19
	v_mul_f32_e32 v1, 0x3fb8aa3b, v1
	v_exp_f32_e32 v27, v1
	v_sub_f32_e32 v1, v42, v19
	v_mul_f32_e32 v1, 0x3fb8aa3b, v1
	v_exp_f32_e32 v26, v1
	v_mul_f32_e32 v10, v86, v3
	v_add_u32_e32 v40, v0, v106
	v_fmac_f32_e32 v10, v87, v23
	v_ashrrev_i32_e32 v41, 31, v40
	s_and_saveexec_b64 s[10:11], s[2:3]
	s_xor_b64 s[10:11], exec, s[10:11]
	s_cbranch_execz .LBB0_652
	v_lshlrev_b64 v[0:1], 9, v[40:41]
	v_lshl_add_u64 v[0:1], v[54:55], 0, v[0:1]
	v_add_co_u32_e32 v2, vcc, 0xffff0000, v0
	v_mov_b32_e32 v21, v84
	s_nop 0
	v_addc_co_u32_e32 v3, vcc, -1, v1, vcc
	v_add_co_u32_e32 v0, vcc, 0xffff1000, v0
	v_mov_b32_e32 v22, v85
	s_nop 0
	v_addc_co_u32_e32 v1, vcc, -1, v1, vcc
	v_mov_b32_e32 v71, v20
	global_store_dwordx3 v[2:3], v[20:22], off
	global_store_dwordx4 v[0:1], v[36:39], off offset:-4084
	global_store_dword v[0:1], v10, off offset:-4068
	v_mul_f32_e32 v0, v26, v70
	v_mul_f32_e32 v1, v27, v71
	v_mov_b32_e32 v2, v27
	v_add_f32_e32 v24, v0, v1
	v_mul_f32_e32 v0, v2, v84
	v_mul_f32_e32 v1, v2, v85
	v_fma_f32 v74, v26, v72, v0
	v_fma_f32 v75, v26, v73, v1
	v_mul_f32_e32 v0, v2, v36
	v_mul_f32_e32 v1, v2, v37
	v_mul_f32_e32 v3, v2, v39
	v_mul_f32_e32 v2, v2, v38
	v_fma_f32 v0, v64, v26, v0
	v_fma_f32 v1, v65, v26, v1
	v_fma_f32 v2, v68, v26, v2
	v_fma_f32 v3, v69, v26, v3
	s_andn2_saveexec_b64 s[10:11], s[10:11]
	s_cbranch_execnz .LBB0_653

.LBB0_644:
	v_max_f32_e32 v8, v71, v71
	v_max_f32_e32 v10, v44, v44
	v_max_f32_e32 v8, v8, v10
	v_sub_f32_e32 v10, v71, v8
	v_mul_f32_e32 v10, 0x3fb8aa3b, v10
	v_exp_f32_e32 v11, v10
	v_sub_f32_e32 v10, v44, v8
	s_add_i32 s10, s42, -2
	v_mul_f32_e32 v10, 0x3fb8aa3b, v10
	v_mov_b32_e32 v19, s34
	v_mov_b32_e32 v22, s10
	v_exp_f32_e32 v10, v10
	v_cndmask_b32_e64 v19, v19, v22, s[0:1]
	v_add_u32_e32 v64, v19, v106
	v_ashrrev_i32_e32 v65, 31, v64
	s_and_saveexec_b64 s[10:11], s[2:3]
	s_xor_b64 s[10:11], exec, s[10:11]
	s_cbranch_execz .LBB0_664
	v_lshlrev_b64 v[26:27], 9, v[64:65]
	v_lshl_add_u64 v[68:69], v[54:55], 0, v[26:27]
	v_add_co_u32_e32 v84, vcc, 0xffff0000, v68
	v_mov_b32_e32 v25, v74
	v_mov_b32_e32 v26, v75
	v_addc_co_u32_e32 v85, vcc, -1, v69, vcc
	global_store_dwordx3 v[84:85], v[24:26], off
	v_mov_b32_e32 v22, v11
	v_mov_b32_e32 v66, v49
	v_add_co_u32_e32 v26, vcc, 0xffff1000, v68
	s_nop 1
	v_addc_co_u32_e32 v27, vcc, -1, v69, vcc
	global_store_dwordx4 v[26:27], v[0:3], off offset:-4084
	global_store_dword v[26:27], v23, off offset:-4068
	v_mov_b32_e32 v26, v50
	v_mov_b32_e32 v27, v24
	v_mul_f32_e32 v24, v10, v26
	v_mul_f32_e32 v25, v11, v27
	v_mul_f32_e32 v26, v22, v74
	v_mul_f32_e32 v27, v22, v75
	v_pk_mov_b32 v[50:51], v[50:51], v[48:49] op_sel:[1,0]
	v_mul_f32_e32 v0, v22, v0
	v_mul_f32_e32 v1, v22, v1
	v_mul_f32_e32 v2, v22, v2
	v_mul_f32_e32 v3, v22, v3
	v_add_f32_e32 v24, v24, v25
	v_fma_f32 v74, v10, v50, v26
	v_fma_f32 v75, v10, v51, v27
	v_fma_f32 v0, v66, v10, v0
	v_fma_f32 v1, v67, v10, v1
	v_fma_f32 v2, v46, v10, v2
	v_fma_f32 v3, v47, v10, v3
	s_andn2_saveexec_b64 s[10:11], s[10:11]
	s_cbranch_execnz .LBB0_665

.LBB0_651:
	v_lshlrev_b64 v[20:21], 15, v[30:31]
	v_lshl_add_u64 v[20:21], v[56:57], 0, v[20:21]
	v_cvt_pk_bf16_f32 v36, v24, v25
	v_cvt_pk_bf16_f32 v37, v26, v27
	v_cvt_pk_bf16_f32 v38, v1, v88
	v_cvt_pk_bf16_f32 v39, v29, v23
	global_store_dwordx4 v[20:21], v[36:39], off
	s_waitcnt vmcnt(20)
	v_and_b32_e32 v0, 0xffff0000, v78
	v_mov_b32_e32 v21, v24
	s_waitcnt vmcnt(19)
	v_lshlrev_b32_e32 v36, 16, v79
	v_mov_b32_e32 v38, v86
	v_mov_b32_e32 v39, v26
	v_mov_b32_e32 v37, v87
	v_mul_f32_e32 v26, v38, v36
	v_mul_f32_e32 v27, v39, v37
	v_mul_f32_e32 v24, v86, v0
	v_mov_b32_e32 v25, v26
	v_mov_b32_e32 v83, v27
	v_and_b32_e32 v0, 0xffff0000, v79
	v_add_f32_e32 v84, v24, v82
	v_add_f32_e32 v85, v25, v83
	v_mul_f32_e32 v24, v86, v0
	s_waitcnt vmcnt(18)
	v_lshlrev_b32_e32 v0, 16, v34
	v_mul_f32_e32 v0, v86, v0
	v_mul_f32_e32 v1, v87, v1
	s_waitcnt vmcnt(17)
	v_lshlrev_b32_e32 v28, 16, v35
	v_mov_b32_e32 v25, v0
	v_mov_b32_e32 v81, v1
	v_lshlrev_b32_e32 v20, 16, v78
	v_add_f32_e32 v36, v24, v80
	v_add_f32_e32 v37, v25, v81
	v_and_b32_e32 v0, 0xffff0000, v34
	v_mul_f32_e32 v24, v86, v28
	v_mul_f32_e32 v25, v87, v29
	v_mul_f32_e32 v20, v86, v20
	v_mul_f32_e32 v21, v87, v21
	v_mul_f32_e32 v0, v86, v0
	v_mov_b32_e32 v1, v24
	v_mov_b32_e32 v33, v25
	v_add_f32_e32 v20, v20, v21
	v_add_f32_e32 v38, v0, v32
	v_add_f32_e32 v39, v1, v33
	v_and_b32_e32 v3, 0xffff0000, v35
	s_or_b64 exec, exec, s[34:35]
	s_and_saveexec_b64 s[34:35], s[4:5]
	s_cbranch_execnz .LBB0_626
	s_branch .LBB0_627

.LBB0_653:
	v_lshlrev_b64 v[0:1], 15, v[40:41]
	v_pk_mov_b32 v[2:3], v[84:85], v[36:37] op_sel:[1,0]
	v_lshl_add_u64 v[22:23], v[56:57], 0, v[0:1]
	v_cvt_pk_bf16_f32 v1, v2, v3
	v_pk_mov_b32 v[2:3], v[36:37], v[38:39] op_sel:[1,0]
	v_cvt_pk_bf16_f32 v0, v20, v84
	v_cvt_pk_bf16_f32 v2, v2, v3
	v_cvt_pk_bf16_f32 v3, v39, v10
	global_store_dwordx4 v[22:23], v[0:3], off
	v_lshlrev_b32_e32 v21, 16, v72
	v_and_b32_e32 v11, 0xffff0000, v64
	v_lshlrev_b32_e32 v0, 16, v70
	v_mov_b32_e32 v1, v20
	v_mul_f32_e32 v0, v26, v0
	v_mul_f32_e32 v1, v27, v1
	v_mov_b32_e32 v2, v27
	v_add_f32_e32 v24, v0, v1
	v_mul_f32_e32 v0, v2, v84
	v_mul_f32_e32 v1, v2, v85
	v_and_b32_e32 v20, 0xffff0000, v70
	v_fma_f32 v74, v26, v20, v0
	v_fma_f32 v75, v26, v21, v1
	v_mul_f32_e32 v0, v2, v36
	v_mul_f32_e32 v1, v2, v37
	v_and_b32_e32 v20, 0xffff0000, v72
	v_lshlrev_b32_e32 v21, 16, v73
	v_fma_f32 v0, v26, v20, v0
	v_fma_f32 v1, v26, v21, v1
	v_mul_f32_e32 v3, v2, v39
	v_mul_f32_e32 v2, v2, v38
	v_and_b32_e32 v20, 0xffff0000, v73
	v_lshlrev_b32_e32 v21, 16, v64
	v_fma_f32 v2, v26, v20, v2
	v_fma_f32 v3, v26, v21, v3
	s_or_b64 exec, exec, s[10:11]
	s_and_saveexec_b64 s[10:11], s[4:5]
	s_cbranch_execnz .LBB0_636
	s_branch .LBB0_637

.LBB0_661:
	v_max_f32_e32 v9, v71, v71
	v_max_f32_e32 v10, v58, v58
	v_max_f32_e32 v19, v9, v10
	v_sub_f32_e32 v9, v71, v19
	v_sub_f32_e32 v10, v58, v19
	s_add_i32 s10, s42, -3
	v_mul_f32_e32 v9, 0x3fb8aa3b, v9
	v_mul_f32_e32 v10, 0x3fb8aa3b, v10
	v_mov_b32_e32 v8, s34
	v_mov_b32_e32 v11, s10
	v_exp_f32_e32 v9, v9
	v_exp_f32_e32 v10, v10
	v_cndmask_b32_e64 v8, v8, v11, s[0:1]
	v_add_u32_e32 v64, v8, v106
	v_ashrrev_i32_e32 v65, 31, v64
	s_and_saveexec_b64 s[10:11], s[2:3]
	s_xor_b64 s[10:11], exec, s[10:11]
	s_cbranch_execz .LBB0_666
	v_lshlrev_b64 v[26:27], 9, v[64:65]
	v_lshl_add_u64 v[66:67], v[54:55], 0, v[26:27]
	v_add_co_u32_e32 v84, vcc, 0xffff0000, v66
	v_mov_b32_e32 v25, v74
	v_mov_b32_e32 v26, v75
	v_addc_co_u32_e32 v85, vcc, -1, v67, vcc
	global_store_dwordx3 v[84:85], v[24:26], off
	v_mov_b32_e32 v11, v24
	v_mov_b32_e32 v8, v62
	v_add_co_u32_e32 v26, vcc, 0xffff1000, v66
	v_mul_f32_e32 v24, v10, v8
	v_mul_f32_e32 v25, v11, v9
	s_nop 0
	v_addc_co_u32_e32 v27, vcc, -1, v67, vcc
	v_mov_b32_e32 v8, v9
	global_store_dwordx4 v[26:27], v[0:3], off offset:-4084
	global_store_dword v[26:27], v23, off offset:-4068
	v_mul_f32_e32 v26, v74, v8
	v_mul_f32_e32 v27, v75, v8
	v_pk_mov_b32 v[62:63], v[62:63], v[60:61] op_sel:[1,0]
	v_mul_f32_e32 v0, v0, v8
	v_mul_f32_e32 v1, v1, v8
	v_fma_f32 v74, v10, v62, v26
	v_fma_f32 v75, v10, v63, v27
	v_mov_b32_e32 v26, v61
	v_mov_b32_e32 v27, v4
	v_mul_f32_e32 v2, v2, v8
	v_mul_f32_e32 v3, v3, v8
	v_pk_mov_b32 v[4:5], v[4:5], v[6:7] op_sel:[1,0]
	v_add_f32_e32 v24, v24, v25
	v_fma_f32 v0, v26, v10, v0
	v_fma_f32 v1, v27, v10, v1
	v_fma_f32 v88, v4, v10, v2
	v_fma_f32 v89, v5, v10, v3
	s_andn2_saveexec_b64 s[10:11], s[10:11]
	s_cbranch_execnz .LBB0_667

.LBB0_665:
	v_pk_mov_b32 v[46:47], v[74:75], v[0:1] op_sel:[1,0]
	v_lshlrev_b64 v[26:27], 15, v[64:65]
	v_cvt_pk_bf16_f32 v67, v46, v47
	v_pk_mov_b32 v[46:47], v[0:1], v[2:3] op_sel:[1,0]
	v_lshl_add_u64 v[26:27], v[56:57], 0, v[26:27]
	v_cvt_pk_bf16_f32 v66, v24, v74
	v_cvt_pk_bf16_f32 v68, v46, v47
	v_cvt_pk_bf16_f32 v69, v3, v23
	global_store_dwordx4 v[26:27], v[66:69], off
	v_lshlrev_b32_e32 v26, 16, v50
	v_mov_b32_e32 v27, v24
	v_mov_b32_e32 v22, v11
	v_mul_f32_e32 v24, v10, v26
	v_mul_f32_e32 v25, v11, v27
	v_mul_f32_e32 v26, v22, v74
	v_mul_f32_e32 v27, v22, v75
	v_lshlrev_b32_e32 v47, 16, v51
	v_and_b32_e32 v46, 0xffff0000, v50
	v_fma_f32 v74, v10, v46, v26
	v_fma_f32 v75, v10, v47, v27
	v_mul_f32_e32 v0, v22, v0
	v_mul_f32_e32 v1, v22, v1
	v_lshlrev_b32_e32 v27, 16, v48
	v_and_b32_e32 v26, 0xffff0000, v51
	v_fma_f32 v0, v10, v26, v0
	v_fma_f32 v1, v10, v27, v1
	v_mul_f32_e32 v2, v22, v2
	v_mul_f32_e32 v3, v22, v3
	v_lshlrev_b32_e32 v27, 16, v49
	v_and_b32_e32 v26, 0xffff0000, v48
	v_add_f32_e32 v24, v24, v25
	v_fma_f32 v2, v10, v26, v2
	v_fma_f32 v3, v10, v27, v3
	v_and_b32_e32 v9, 0xffff0000, v49
	s_or_b64 exec, exec, s[10:11]
	s_and_saveexec_b64 s[10:11], s[4:5]
	s_cbranch_execnz .LBB0_647
	s_branch .LBB0_648

.LBB0_667:
	v_lshlrev_b64 v[4:5], 15, v[64:65]
	v_pk_mov_b32 v[6:7], v[74:75], v[0:1] op_sel:[1,0]
	v_lshl_add_u64 v[26:27], v[56:57], 0, v[4:5]
	v_cvt_pk_bf16_f32 v5, v6, v7
	v_pk_mov_b32 v[6:7], v[0:1], v[2:3] op_sel:[1,0]
	v_cvt_pk_bf16_f32 v4, v24, v74
	v_cvt_pk_bf16_f32 v6, v6, v7
	v_cvt_pk_bf16_f32 v7, v3, v23
	v_lshlrev_b32_e32 v8, 16, v62
	v_mov_b32_e32 v11, v24
	global_store_dwordx4 v[26:27], v[4:7], off
	v_lshlrev_b32_e32 v27, 16, v63
	v_and_b32_e32 v26, 0xffff0000, v62
	v_mul_f32_e32 v4, v10, v8
	v_mul_f32_e32 v5, v11, v9
	s_nop 0
	v_add_f32_e32 v24, v4, v5
	v_mov_b32_e32 v4, v9
	v_mul_f32_e32 v6, v74, v4
	v_mul_f32_e32 v7, v75, v4
	v_mul_f32_e32 v0, v0, v4
	v_mul_f32_e32 v1, v1, v4
	v_fma_f32 v74, v10, v26, v6
	v_fma_f32 v75, v10, v27, v7
	v_lshlrev_b32_e32 v7, 16, v60
	v_and_b32_e32 v6, 0xffff0000, v63
	v_mul_f32_e32 v2, v2, v4
	v_mul_f32_e32 v3, v3, v4
	v_lshlrev_b32_e32 v5, 16, v61
	v_and_b32_e32 v4, 0xffff0000, v60
	v_fma_f32 v0, v10, v6, v0
	v_fma_f32 v1, v10, v7, v1
	v_fma_f32 v88, v10, v4, v2
	v_fma_f32 v89, v10, v5, v3
	v_and_b32_e32 v7, 0xffff0000, v61
	s_or_b64 exec, exec, s[10:11]
	s_and_saveexec_b64 s[10:11], s[4:5]
	s_cbranch_execz .LBB0_614

.LBB0_670:
	s_waitcnt vmcnt(21)
	v_lshlrev_b32_e32 v11, 16, v64
	v_mov_b32_e32 v10, v53
	v_lshlrev_b32_e32 v4, 16, v68
	v_and_b32_e32 v5, 0xffff0000, v68
	v_mul_f32_e32 v94, v98, v10
	v_mul_f32_e32 v95, v99, v11
	v_mov_b32_e32 v2, v99
	v_lshlrev_b32_e32 v6, 16, v69
	v_and_b32_e32 v7, 0xffff0000, v69
	v_fma_f32 v30, v2, v4, v94
	v_fma_f32 v31, v2, v5, v94
	v_and_b32_e32 v4, 0xffff0000, v64
	s_waitcnt vmcnt(20)
	v_lshlrev_b32_e32 v5, 16, v65
	v_fma_f32 v32, v2, v6, v94
	v_fma_f32 v33, v2, v7, v94
	v_add_f32_e32 v6, v94, v95
	v_fma_f32 v96, v2, v4, v94
	v_fma_f32 v97, v2, v5, v94
	v_and_b32_e32 v7, 0xffff0000, v65
	global_store_dwordx4 v[70:71], v[108:111], off
	s_or_b64 exec, exec, s[4:5]
	v_cmp_eq_u32_e64 s[4:5], 0, v100
	s_and_saveexec_b64 s[10:11], s[4:5]
	s_cbranch_execnz .LBB0_588
	s_branch .LBB0_589

.LBB0_672:
	v_mul_f32_e32 v4, v2, v30
	v_mul_f32_e32 v5, v2, v31
	s_waitcnt vmcnt(23)
	v_lshlrev_b32_e32 v8, 16, v50
	v_and_b32_e32 v9, 0xffff0000, v50
	v_fma_f32 v26, v98, v8, v4
	v_fma_f32 v27, v98, v9, v5
	v_mul_f32_e32 v4, v2, v32
	v_mul_f32_e32 v5, v2, v33
	s_waitcnt vmcnt(22)
	v_lshlrev_b32_e32 v8, 16, v51
	v_and_b32_e32 v9, 0xffff0000, v51
	v_fma_f32 v28, v98, v8, v4
	v_fma_f32 v29, v98, v9, v5
	s_waitcnt vmcnt(21)
	v_lshlrev_b32_e32 v4, 16, v46
	v_mov_b32_e32 v99, v2
	v_mov_b32_e32 v5, v6
	v_cvt_pk_bf16_f32 v20, v30, v31
	v_cvt_pk_bf16_f32 v21, v32, v33
	v_cvt_pk_bf16_f32 v22, v6, v96
	v_cvt_pk_bf16_f32 v23, v97, v94
	v_mul_f32_e32 v4, v98, v4
	v_mul_f32_e32 v5, v99, v5
	global_store_dwordx4 v[66:67], v[20:23], off
	s_waitcnt vmcnt(21)
	v_lshlrev_b32_e32 v7, 16, v47
	v_and_b32_e32 v6, 0xffff0000, v46
	v_add_f32_e32 v22, v4, v5
	v_mul_f32_e32 v4, v2, v96
	v_mul_f32_e32 v5, v2, v97
	v_fma_f32 v4, v98, v6, v4
	v_fma_f32 v5, v98, v7, v5
	v_and_b32_e32 v23, 0xffff0000, v47
	s_or_b64 exec, exec, s[10:11]
	s_and_saveexec_b64 s[10:11], s[4:5]
	s_cbranch_execnz .LBB0_596
	s_branch .LBB0_597

.LBB0_674:
	v_cvt_pk_bf16_f32 v16, v26, v27
	v_cvt_pk_bf16_f32 v17, v28, v29
	v_cvt_pk_bf16_f32 v18, v22, v4
	v_cvt_pk_bf16_f32 v19, v5, v25
	global_store_dwordx4 v[92:93], v[16:19], off
	v_mul_f32_e32 v4, v8, v4
	v_mul_f32_e32 v5, v8, v5
	s_nop 0
	v_mul_f32_e32 v16, v8, v26
	v_mul_f32_e32 v17, v8, v27
	s_waitcnt vmcnt(24)
	v_lshlrev_b32_e32 v18, 16, v90
	v_and_b32_e32 v19, 0xffff0000, v90
	v_fma_f32 v30, v20, v18, v16
	v_fma_f32 v31, v20, v19, v17
	v_mul_f32_e32 v16, v8, v28
	v_mul_f32_e32 v17, v8, v29
	s_waitcnt vmcnt(23)
	v_lshlrev_b32_e32 v18, 16, v91
	v_and_b32_e32 v19, 0xffff0000, v91
	v_fma_f32 v32, v20, v18, v16
	v_fma_f32 v33, v20, v19, v17
	s_waitcnt vmcnt(22)
	v_lshlrev_b32_e32 v16, 16, v62
	v_mov_b32_e32 v21, v8
	v_mov_b32_e32 v17, v22
	v_mul_f32_e32 v16, v20, v16
	v_mul_f32_e32 v17, v21, v17
	s_waitcnt vmcnt(21)
	v_and_b32_e32 v19, 0xffff0000, v63
	v_add_f32_e32 v18, v16, v17
	v_lshlrev_b32_e32 v17, 16, v63
	v_and_b32_e32 v16, 0xffff0000, v62
	v_fma_f32 v94, v20, v16, v4
	v_fma_f32 v95, v20, v17, v5
	s_or_b64 exec, exec, s[10:11]
	s_and_saveexec_b64 s[10:11], s[4:5]
	s_cbranch_execnz .LBB0_604
	s_branch .LBB0_605

.LBB0_676:
	v_cvt_pk_bf16_f32 v12, v30, v31
	v_cvt_pk_bf16_f32 v13, v32, v33
	v_cvt_pk_bf16_f32 v14, v18, v94
	v_cvt_pk_bf16_f32 v15, v95, v21
	global_store_dwordx4 v[86:87], v[12:15], off
	s_nop 1
	v_mul_f32_e32 v12, v2, v30
	v_mul_f32_e32 v13, v2, v31
	s_waitcnt vmcnt(24)
	v_lshlrev_b32_e32 v14, 16, v84
	v_and_b32_e32 v15, 0xffff0000, v84
	v_fma_f32 v24, v16, v14, v12
	v_fma_f32 v25, v16, v15, v13
	v_mul_f32_e32 v12, v2, v32
	v_mul_f32_e32 v13, v2, v33
	s_waitcnt vmcnt(23)
	v_lshlrev_b32_e32 v14, 16, v85
	v_and_b32_e32 v15, 0xffff0000, v85
	v_fma_f32 v26, v16, v14, v12
	v_fma_f32 v27, v16, v15, v13
	s_waitcnt vmcnt(22)
	v_lshlrev_b32_e32 v12, 16, v82
	v_mov_b32_e32 v17, v2
	v_mov_b32_e32 v13, v18
	v_mul_f32_e32 v12, v16, v12
	v_mul_f32_e32 v13, v17, v13
	s_waitcnt vmcnt(21)
	v_lshlrev_b32_e32 v15, 16, v83
	v_add_f32_e32 v1, v12, v13
	v_mul_f32_e32 v12, v2, v94
	v_mul_f32_e32 v13, v2, v95
	v_and_b32_e32 v14, 0xffff0000, v82
	v_fma_f32 v88, v16, v14, v12
	v_fma_f32 v89, v16, v15, v13
	v_and_b32_e32 v15, 0xffff0000, v83
	s_or_b64 exec, exec, s[10:11]
	s_and_saveexec_b64 s[10:11], s[4:5]
	s_cbranch_execnz .LBB0_612
	s_branch .LBB0_613

.LBB0_737:
	s_or_b64 exec, exec, s[2:3]
	v_mul_f32_e32 v64, v72, v64
	v_mul_f32_e32 v65, v73, v65
	ds_read_b128 v[68:71], v193
	ds_read_b128 v[72:75], v194
	v_mul_f32_e32 v67, v153, v242
	v_mul_f32_e32 v66, v155, v245
	v_readlane_b32 s0, v253, 7
	s_waitcnt lgkmcnt(1)
	v_mul_f32_e32 v76, v67, v68
	s_waitcnt lgkmcnt(0)
	v_mul_f32_e32 v72, v66, v72
	v_cndmask_b32_e64 v76, v76, 0, s[22:23]
	v_cndmask_b32_e64 v72, v72, 0, s[24:25]
	v_add_f32_e32 v72, v76, v72
	v_mul_f32_e32 v56, v56, v72
	v_mul_f32_e32 v72, v67, v69
	v_mul_f32_e32 v73, v66, v73
	v_readlane_b32 s1, v253, 8
	v_cndmask_b32_e64 v72, 0, v72, s[24:25]
	v_readlane_b32 s2, v252, 47
	v_cndmask_b32_e64 v73, v73, 0, s[0:1]
	v_add_f32_e32 v72, v72, v73
	v_readlane_b32 s0, v253, 9
	v_mul_f32_e32 v57, v57, v72
	v_mul_f32_e32 v72, v67, v70
	v_readlane_b32 s1, v253, 10
	v_mul_f32_e32 v73, v66, v74
	v_cvt_pk_bf16_f32 v56, v56, v57
	v_cndmask_b32_e64 v72, v72, 0, s[0:1]
	v_readlane_b32 s0, v253, 11
	v_readlane_b32 s1, v253, 12
	v_mov_b32_e32 v155, v125
	s_movk_i32 s97, 0x880
	v_cndmask_b32_e64 v73, v73, 0, s[0:1]
	v_add_f32_e32 v72, v72, v73
	v_readlane_b32 s0, v253, 13
	v_mul_f32_e32 v58, v58, v72
	v_mul_f32_e32 v72, v67, v71
	v_readlane_b32 s1, v253, 14
	v_mul_f32_e32 v73, v66, v75
	s_nop 0
	v_cndmask_b32_e64 v72, v72, 0, s[0:1]
	v_readlane_b32 s0, v253, 15
	v_readlane_b32 s1, v253, 16
	s_nop 1
	v_cndmask_b32_e64 v73, v73, 0, s[0:1]
	v_add_f32_e32 v72, v72, v73
	v_mul_f32_e32 v59, v59, v72
	v_cvt_pk_bf16_f32 v57, v58, v59
	ds_write_b64 v235, v[56:57] offset:36864
	v_pk_fma_f32 v[56:57], v[64:65], v[68:69], 0 op_sel_hi:[0,1,0]
	v_pk_fma_f32 v[58:59], v[64:65], v[70:71], 0 op_sel_hi:[0,1,0]
	v_mul_f32_e32 v56, v60, v56
	v_mul_f32_e32 v57, v61, v57
	v_mul_f32_e32 v58, v62, v58
	v_mul_f32_e32 v59, v63, v59
	v_cvt_pk_bf16_f32 v56, v56, v57
	v_cvt_pk_bf16_f32 v57, v58, v59
	ds_write_b64 v235, v[56:57] offset:41216
	ds_read_b128 v[56:59], v195
	ds_read_b128 v[60:63], v196
	v_readlane_b32 s0, v253, 17
	v_readlane_b32 s1, v253, 18
	s_waitcnt lgkmcnt(1)
	v_mul_f32_e32 v68, v67, v56
	v_cndmask_b32_e64 v68, v68, 0, s[0:1]
	v_readlane_b32 s0, v253, 19
	s_waitcnt lgkmcnt(0)
	v_mul_f32_e32 v69, v66, v60
	v_readlane_b32 s1, v253, 20
	s_nop 1
	v_cndmask_b32_e64 v69, v69, 0, s[0:1]
	v_add_f32_e32 v68, v68, v69
	v_readlane_b32 s0, v253, 21
	v_mul_f32_e32 v52, v52, v68
	v_mul_f32_e32 v68, v67, v57
	v_readlane_b32 s1, v253, 22
	v_mul_f32_e32 v69, v66, v61
	s_nop 0
	v_cndmask_b32_e64 v68, v68, 0, s[0:1]
	v_readlane_b32 s0, v253, 23
	v_readlane_b32 s1, v253, 24
	s_nop 1
	v_cndmask_b32_e64 v69, v69, 0, s[0:1]
	v_add_f32_e32 v68, v68, v69
	v_readlane_b32 s0, v253, 25
	v_mul_f32_e32 v53, v53, v68
	v_mul_f32_e32 v68, v67, v58
	v_readlane_b32 s1, v253, 26
	v_mul_f32_e32 v69, v66, v62
	v_cvt_pk_bf16_f32 v52, v52, v53
	v_cndmask_b32_e64 v68, v68, 0, s[0:1]
	v_readlane_b32 s0, v253, 27
	v_readlane_b32 s1, v253, 28
	s_nop 1
	v_cndmask_b32_e64 v69, v69, 0, s[0:1]
	v_add_f32_e32 v68, v68, v69
	v_readlane_b32 s0, v253, 29
	v_mul_f32_e32 v54, v54, v68
	v_mul_f32_e32 v68, v67, v59
	v_readlane_b32 s1, v253, 30
	v_mul_f32_e32 v69, v66, v63
	s_nop 0
	v_cndmask_b32_e64 v68, v68, 0, s[0:1]
	v_readlane_b32 s0, v253, 31
	v_readlane_b32 s1, v253, 32
	s_nop 1
	v_cndmask_b32_e64 v69, v69, 0, s[0:1]
	v_add_f32_e32 v68, v68, v69
	v_mul_f32_e32 v55, v55, v68
	v_cvt_pk_bf16_f32 v53, v54, v55
	ds_write_b64 v235, v[52:53] offset:36896
	v_mul_f32_e32 v52, v64, v56
	v_mul_f32_e32 v53, v65, v60
	v_cndmask_b32_e64 v52, v52, 0, s[22:23]
	v_cndmask_b32_e64 v53, v53, 0, s[24:25]
	v_add_f32_e32 v52, v52, v53
	v_readlane_b32 s0, v253, 33
	v_mul_f32_e32 v48, v48, v52
	v_mul_f32_e32 v52, v64, v57
	v_readlane_b32 s1, v253, 34
	v_mul_f32_e32 v53, v65, v61
	s_nop 0
	v_cndmask_b32_e64 v52, v52, 0, s[0:1]
	v_readlane_b32 s0, v253, 35
	v_readlane_b32 s1, v253, 36
	s_nop 1
	v_cndmask_b32_e64 v53, v53, 0, s[0:1]
	v_add_f32_e32 v52, v52, v53
	v_readlane_b32 s0, v253, 37
	v_mul_f32_e32 v49, v49, v52
	v_mul_f32_e32 v52, v64, v58
	v_readlane_b32 s1, v253, 38
	v_mul_f32_e32 v53, v65, v62
	v_cvt_pk_bf16_f32 v48, v48, v49
	v_cndmask_b32_e64 v52, v52, 0, s[0:1]
	v_readlane_b32 s0, v253, 39
	v_readlane_b32 s1, v253, 40
	s_nop 1
	v_cndmask_b32_e64 v53, v53, 0, s[0:1]
	v_add_f32_e32 v52, v52, v53
	v_readlane_b32 s0, v253, 41
	v_mul_f32_e32 v50, v50, v52
	v_mul_f32_e32 v52, v64, v59
	v_readlane_b32 s1, v253, 42
	v_mul_f32_e32 v53, v65, v63
	s_nop 0
	v_cndmask_b32_e64 v52, v52, 0, s[0:1]
	v_readlane_b32 s0, v253, 43
	v_readlane_b32 s1, v253, 44
	s_nop 1
	v_cndmask_b32_e64 v53, v53, 0, s[0:1]
	v_add_f32_e32 v52, v52, v53
	v_mul_f32_e32 v51, v51, v52
	v_cvt_pk_bf16_f32 v49, v50, v51
	ds_write_b64 v235, v[48:49] offset:41248
	ds_read_b128 v[48:51], v197
	ds_read_b128 v[52:55], v198
	v_readlane_b32 s0, v253, 45
	v_readlane_b32 s1, v253, 46
	s_waitcnt lgkmcnt(1)
	v_mul_f32_e32 v56, v67, v48
	v_cndmask_b32_e64 v56, v56, 0, s[0:1]
	v_readlane_b32 s0, v253, 47
	s_waitcnt lgkmcnt(0)
	v_mul_f32_e32 v57, v66, v52
	v_readlane_b32 s1, v253, 48
	s_nop 1
	v_cndmask_b32_e64 v57, v57, 0, s[0:1]
	v_add_f32_e32 v56, v56, v57
	v_readlane_b32 s0, v253, 49
	v_mul_f32_e32 v44, v44, v56
	v_mul_f32_e32 v56, v67, v49
	v_readlane_b32 s1, v253, 50
	v_mul_f32_e32 v57, v66, v53
	s_nop 0
	v_cndmask_b32_e64 v56, v56, 0, s[0:1]
	v_readlane_b32 s0, v253, 51
	v_readlane_b32 s1, v253, 52
	s_nop 1
	v_cndmask_b32_e64 v57, v57, 0, s[0:1]
	v_add_f32_e32 v56, v56, v57
	v_readlane_b32 s0, v253, 53
	v_mul_f32_e32 v45, v45, v56
	v_mul_f32_e32 v56, v67, v50
	v_readlane_b32 s1, v253, 54
	v_mul_f32_e32 v57, v66, v54
	v_cvt_pk_bf16_f32 v44, v44, v45
	v_cndmask_b32_e64 v56, v56, 0, s[0:1]
	v_readlane_b32 s0, v253, 55
	v_readlane_b32 s1, v253, 56
	s_nop 1
	v_cndmask_b32_e64 v57, v57, 0, s[0:1]
	v_add_f32_e32 v56, v56, v57
	v_readlane_b32 s0, v253, 57
	v_mul_f32_e32 v46, v46, v56
	v_mul_f32_e32 v56, v67, v51
	v_readlane_b32 s1, v253, 58
	v_mul_f32_e32 v57, v66, v55
	s_nop 0
	v_cndmask_b32_e64 v56, v56, 0, s[0:1]
	v_readlane_b32 s0, v253, 59
	v_readlane_b32 s1, v253, 60
	s_nop 1
	v_cndmask_b32_e64 v57, v57, 0, s[0:1]
	v_add_f32_e32 v56, v56, v57
	v_mul_f32_e32 v47, v47, v56
	v_cvt_pk_bf16_f32 v45, v46, v47
	v_readlane_b32 s0, v253, 61
	ds_write_b64 v235, v[44:45] offset:36928
	v_mul_f32_e32 v44, v64, v48
	v_readlane_b32 s1, v253, 62
	v_mul_f32_e32 v45, v65, v52
	s_nop 0
	v_cndmask_b32_e64 v44, v44, 0, s[0:1]
	v_readlane_b32 s0, v253, 63
	v_readlane_b32 s1, v254, 0
	s_nop 1
	v_cndmask_b32_e64 v45, v45, 0, s[0:1]
	v_add_f32_e32 v44, v44, v45
	v_readlane_b32 s0, v254, 1
	v_mul_f32_e32 v40, v40, v44
	v_mul_f32_e32 v44, v64, v49
	v_readlane_b32 s1, v254, 2
	v_mul_f32_e32 v45, v65, v53
	s_nop 0
	v_cndmask_b32_e64 v44, v44, 0, s[0:1]
	v_readlane_b32 s0, v254, 3
	v_readlane_b32 s1, v254, 4
	s_nop 1
	v_cndmask_b32_e64 v45, v45, 0, s[0:1]
	v_add_f32_e32 v44, v44, v45
	v_readlane_b32 s0, v254, 5
	v_mul_f32_e32 v41, v41, v44
	v_mul_f32_e32 v44, v64, v50
	v_readlane_b32 s1, v254, 6
	v_mul_f32_e32 v45, v65, v54
	v_cvt_pk_bf16_f32 v40, v40, v41
	v_cndmask_b32_e64 v44, v44, 0, s[0:1]
	v_readlane_b32 s0, v254, 7
	v_readlane_b32 s1, v254, 8
	s_nop 1
	v_cndmask_b32_e64 v45, v45, 0, s[0:1]
	v_add_f32_e32 v44, v44, v45
	v_readlane_b32 s0, v254, 9
	v_mul_f32_e32 v42, v42, v44
	v_mul_f32_e32 v44, v64, v51
	v_readlane_b32 s1, v254, 10
	v_mul_f32_e32 v45, v65, v55
	s_nop 0
	v_cndmask_b32_e64 v44, v44, 0, s[0:1]
	v_readlane_b32 s0, v254, 11
	v_readlane_b32 s1, v254, 12
	s_nop 1
	v_cndmask_b32_e64 v45, v45, 0, s[0:1]
	v_add_f32_e32 v44, v44, v45
	v_mul_f32_e32 v43, v43, v44
	v_cvt_pk_bf16_f32 v41, v42, v43
	ds_write_b64 v235, v[40:41] offset:41280
	ds_read_b128 v[40:43], v199
	ds_read_b128 v[44:47], v200
	v_readlane_b32 s0, v254, 13
	v_readlane_b32 s1, v254, 14
	s_waitcnt lgkmcnt(1)
	v_mul_f32_e32 v48, v67, v40
	v_cndmask_b32_e64 v48, v48, 0, s[0:1]
	v_readlane_b32 s0, v254, 15
	s_waitcnt lgkmcnt(0)
	v_mul_f32_e32 v49, v66, v44
	v_readlane_b32 s1, v254, 16
	s_nop 1
	v_cndmask_b32_e64 v49, v49, 0, s[0:1]
	v_add_f32_e32 v48, v48, v49
	v_readlane_b32 s0, v254, 17
	v_mul_f32_e32 v36, v36, v48
	v_mul_f32_e32 v48, v67, v41
	v_readlane_b32 s1, v254, 18
	v_mul_f32_e32 v49, v66, v45
	s_nop 0
	v_cndmask_b32_e64 v48, v48, 0, s[0:1]
	v_readlane_b32 s0, v254, 19
	v_readlane_b32 s1, v254, 20
	s_nop 1
	v_cndmask_b32_e64 v49, v49, 0, s[0:1]
	v_add_f32_e32 v48, v48, v49
	v_readlane_b32 s0, v254, 21
	v_mul_f32_e32 v37, v37, v48
	v_mul_f32_e32 v48, v67, v42
	v_readlane_b32 s1, v254, 22
	v_mul_f32_e32 v49, v66, v46
	v_cvt_pk_bf16_f32 v36, v36, v37
	v_cndmask_b32_e64 v48, v48, 0, s[0:1]
	v_readlane_b32 s0, v254, 23
	v_readlane_b32 s1, v254, 24
	s_nop 1
	v_cndmask_b32_e64 v49, v49, 0, s[0:1]
	v_add_f32_e32 v48, v48, v49
	v_readlane_b32 s0, v254, 25
	v_mul_f32_e32 v38, v38, v48
	v_mul_f32_e32 v48, v67, v43
	v_readlane_b32 s1, v254, 26
	v_mul_f32_e32 v49, v66, v47
	s_nop 0
	v_cndmask_b32_e64 v48, v48, 0, s[0:1]
	v_readlane_b32 s0, v254, 27
	v_readlane_b32 s1, v254, 28
	s_nop 1
	v_cndmask_b32_e64 v49, v49, 0, s[0:1]
	v_add_f32_e32 v48, v48, v49
	v_mul_f32_e32 v39, v39, v48
	v_cvt_pk_bf16_f32 v37, v38, v39
	v_readlane_b32 s0, v254, 29
	ds_write_b64 v235, v[36:37] offset:36960
	v_mul_f32_e32 v36, v64, v40
	v_readlane_b32 s1, v254, 30
	v_mul_f32_e32 v37, v65, v44
	s_nop 0
	v_cndmask_b32_e64 v36, v36, 0, s[0:1]
	v_readlane_b32 s0, v254, 31
	v_readlane_b32 s1, v254, 32
	s_nop 1
	v_cndmask_b32_e64 v37, v37, 0, s[0:1]
	v_add_f32_e32 v36, v36, v37
	v_readlane_b32 s0, v254, 33
	v_mul_f32_e32 v32, v32, v36
	v_mul_f32_e32 v36, v64, v41
	v_readlane_b32 s1, v254, 34
	v_mul_f32_e32 v37, v65, v45
	s_nop 0
	v_cndmask_b32_e64 v36, v36, 0, s[0:1]
	v_readlane_b32 s0, v254, 35
	v_readlane_b32 s1, v254, 36
	s_nop 1
	v_cndmask_b32_e64 v37, v37, 0, s[0:1]
	v_add_f32_e32 v36, v36, v37
	v_readlane_b32 s0, v254, 37
	v_mul_f32_e32 v33, v33, v36
	v_mul_f32_e32 v36, v64, v42
	v_readlane_b32 s1, v254, 38
	v_mul_f32_e32 v37, v65, v46
	v_cvt_pk_bf16_f32 v32, v32, v33
	v_cndmask_b32_e64 v36, v36, 0, s[0:1]
	v_readlane_b32 s0, v254, 39
	v_readlane_b32 s1, v254, 40
	s_nop 1
	v_cndmask_b32_e64 v37, v37, 0, s[0:1]
	v_add_f32_e32 v36, v36, v37
	v_readlane_b32 s0, v254, 41
	v_mul_f32_e32 v34, v34, v36
	v_mul_f32_e32 v36, v64, v43
	v_readlane_b32 s1, v254, 42
	v_mul_f32_e32 v37, v65, v47
	s_nop 0
	v_cndmask_b32_e64 v36, v36, 0, s[0:1]
	v_readlane_b32 s0, v254, 43
	v_readlane_b32 s1, v254, 44
	s_nop 1
	v_cndmask_b32_e64 v37, v37, 0, s[0:1]
	v_add_f32_e32 v36, v36, v37
	v_mul_f32_e32 v35, v35, v36
	v_cvt_pk_bf16_f32 v33, v34, v35
	ds_write_b64 v235, v[32:33] offset:41312
	ds_read_b128 v[32:35], v201
	ds_read_b128 v[36:39], v202
	v_readlane_b32 s0, v254, 45
	v_readlane_b32 s1, v254, 46
	s_waitcnt lgkmcnt(1)
	v_mul_f32_e32 v40, v67, v32
	v_cndmask_b32_e64 v40, v40, 0, s[0:1]
	v_readlane_b32 s0, v254, 47
	s_waitcnt lgkmcnt(0)
	v_mul_f32_e32 v41, v66, v36
	v_readlane_b32 s1, v254, 48
	s_nop 1
	v_cndmask_b32_e64 v41, v41, 0, s[0:1]
	v_add_f32_e32 v40, v40, v41
	v_readlane_b32 s0, v254, 49
	v_mul_f32_e32 v28, v28, v40
	v_mul_f32_e32 v40, v67, v33
	v_readlane_b32 s1, v254, 50
	v_mul_f32_e32 v41, v66, v37
	s_nop 0
	v_cndmask_b32_e64 v40, v40, 0, s[0:1]
	v_readlane_b32 s0, v254, 51
	v_readlane_b32 s1, v254, 52
	s_nop 1
	v_cndmask_b32_e64 v41, v41, 0, s[0:1]
	v_add_f32_e32 v40, v40, v41
	v_readlane_b32 s0, v254, 53
	v_mul_f32_e32 v29, v29, v40
	v_mul_f32_e32 v40, v67, v34
	v_readlane_b32 s1, v254, 54
	v_mul_f32_e32 v41, v66, v38
	v_cvt_pk_bf16_f32 v28, v28, v29
	v_cndmask_b32_e64 v40, v40, 0, s[0:1]
	v_readlane_b32 s0, v254, 55
	v_readlane_b32 s1, v254, 56
	s_nop 1
	v_cndmask_b32_e64 v41, v41, 0, s[0:1]
	v_add_f32_e32 v40, v40, v41
	v_readlane_b32 s0, v254, 57
	v_mul_f32_e32 v30, v30, v40
	v_mul_f32_e32 v40, v67, v35
	v_readlane_b32 s1, v254, 58
	v_mul_f32_e32 v41, v66, v39
	s_nop 0
	v_cndmask_b32_e64 v40, v40, 0, s[0:1]
	v_readlane_b32 s0, v254, 59
	v_readlane_b32 s1, v254, 60
	s_nop 1
	v_cndmask_b32_e64 v41, v41, 0, s[0:1]
	v_add_f32_e32 v40, v40, v41
	v_mul_f32_e32 v31, v31, v40
	v_cvt_pk_bf16_f32 v29, v30, v31
	v_readlane_b32 s0, v254, 61
	ds_write_b64 v235, v[28:29] offset:36992
	v_mul_f32_e32 v28, v64, v32
	v_readlane_b32 s1, v254, 62
	v_mul_f32_e32 v29, v65, v36
	s_nop 0
	v_cndmask_b32_e64 v28, v28, 0, s[0:1]
	v_readlane_b32 s0, v254, 63
	v_readlane_b32 s1, v255, 0
	s_nop 1
	v_cndmask_b32_e64 v29, v29, 0, s[0:1]
	v_add_f32_e32 v28, v28, v29
	v_readlane_b32 s0, v255, 1
	v_mul_f32_e32 v24, v24, v28
	v_mul_f32_e32 v28, v64, v33
	v_readlane_b32 s1, v255, 2
	v_mul_f32_e32 v29, v65, v37
	s_nop 0
	v_cndmask_b32_e64 v28, v28, 0, s[0:1]
	v_readlane_b32 s0, v255, 3
	v_readlane_b32 s1, v255, 4
	s_nop 1
	v_cndmask_b32_e64 v29, v29, 0, s[0:1]
	v_add_f32_e32 v28, v28, v29
	v_readlane_b32 s0, v255, 5
	v_mul_f32_e32 v25, v25, v28
	v_mul_f32_e32 v28, v64, v34
	v_readlane_b32 s1, v255, 6
	v_mul_f32_e32 v29, v65, v38
	v_cvt_pk_bf16_f32 v24, v24, v25
	v_cndmask_b32_e64 v28, v28, 0, s[0:1]
	v_readlane_b32 s0, v255, 7
	v_readlane_b32 s1, v255, 8
	s_nop 1
	v_cndmask_b32_e64 v29, v29, 0, s[0:1]
	v_add_f32_e32 v28, v28, v29
	v_readlane_b32 s0, v255, 9
	v_mul_f32_e32 v26, v26, v28
	v_mul_f32_e32 v28, v64, v35
	v_readlane_b32 s1, v255, 10
	v_mul_f32_e32 v29, v65, v39
	s_nop 0
	v_cndmask_b32_e64 v28, v28, 0, s[0:1]
	v_readlane_b32 s0, v255, 11
	v_readlane_b32 s1, v255, 12
	s_nop 1
	v_cndmask_b32_e64 v29, v29, 0, s[0:1]
	v_add_f32_e32 v28, v28, v29
	v_mul_f32_e32 v27, v27, v28
	v_cvt_pk_bf16_f32 v25, v26, v27
	ds_write_b64 v235, v[24:25] offset:41344
	ds_read_b128 v[24:27], v203
	ds_read_b128 v[28:31], v204
	v_readlane_b32 s0, v255, 13
	v_readlane_b32 s1, v255, 14
	s_waitcnt lgkmcnt(1)
	v_mul_f32_e32 v32, v67, v24
	v_cndmask_b32_e64 v32, v32, 0, s[0:1]
	v_readlane_b32 s0, v255, 15
	s_waitcnt lgkmcnt(0)
	v_mul_f32_e32 v33, v66, v28
	v_readlane_b32 s1, v255, 16
	s_nop 1
	v_cndmask_b32_e64 v33, v33, 0, s[0:1]
	v_add_f32_e32 v32, v32, v33
	v_readlane_b32 s0, v255, 17
	v_mul_f32_e32 v20, v20, v32
	v_mul_f32_e32 v32, v67, v25
	v_readlane_b32 s1, v255, 18
	v_mul_f32_e32 v33, v66, v29
	s_nop 0
	v_cndmask_b32_e64 v32, v32, 0, s[0:1]
	v_readlane_b32 s0, v255, 19
	v_readlane_b32 s1, v255, 20
	s_nop 1
	v_cndmask_b32_e64 v33, v33, 0, s[0:1]
	v_add_f32_e32 v32, v32, v33
	v_readlane_b32 s0, v255, 21
	v_mul_f32_e32 v21, v21, v32
	v_mul_f32_e32 v32, v67, v26
	v_readlane_b32 s1, v255, 22
	v_mul_f32_e32 v33, v66, v30
	v_cvt_pk_bf16_f32 v20, v20, v21
	v_cndmask_b32_e64 v32, v32, 0, s[0:1]
	v_readlane_b32 s0, v255, 23
	v_readlane_b32 s1, v255, 24
	s_nop 1
	v_cndmask_b32_e64 v33, v33, 0, s[0:1]
	v_add_f32_e32 v32, v32, v33
	v_readlane_b32 s0, v255, 25
	v_mul_f32_e32 v22, v22, v32
	v_mul_f32_e32 v32, v67, v27
	v_readlane_b32 s1, v255, 26
	v_mul_f32_e32 v33, v66, v31
	s_nop 0
	v_cndmask_b32_e64 v32, v32, 0, s[0:1]
	v_readlane_b32 s0, v255, 27
	v_readlane_b32 s1, v255, 28
	s_nop 1
	v_cndmask_b32_e64 v33, v33, 0, s[0:1]
	v_add_f32_e32 v32, v32, v33
	v_mul_f32_e32 v23, v23, v32
	v_cvt_pk_bf16_f32 v21, v22, v23
	v_readlane_b32 s0, v255, 29
	ds_write_b64 v235, v[20:21] offset:37024
	v_mul_f32_e32 v20, v64, v24
	v_readlane_b32 s1, v255, 30
	v_mul_f32_e32 v21, v65, v28
	s_nop 0
	v_cndmask_b32_e64 v20, v20, 0, s[0:1]
	v_readlane_b32 s0, v255, 31
	v_readlane_b32 s1, v255, 32
	s_nop 1
	v_cndmask_b32_e64 v21, v21, 0, s[0:1]
	v_add_f32_e32 v20, v20, v21
	v_readlane_b32 s0, v255, 33
	v_mul_f32_e32 v16, v16, v20
	v_mul_f32_e32 v20, v64, v25
	v_readlane_b32 s1, v255, 34
	v_mul_f32_e32 v21, v65, v29
	s_nop 0
	v_cndmask_b32_e64 v20, v20, 0, s[0:1]
	v_readlane_b32 s0, v255, 35
	v_readlane_b32 s1, v255, 36
	s_nop 1
	v_cndmask_b32_e64 v21, v21, 0, s[0:1]
	v_add_f32_e32 v20, v20, v21
	v_readlane_b32 s0, v255, 37
	v_mul_f32_e32 v17, v17, v20
	v_mul_f32_e32 v20, v64, v26
	v_readlane_b32 s1, v255, 38
	v_mul_f32_e32 v21, v65, v30
	v_cvt_pk_bf16_f32 v16, v16, v17
	v_cndmask_b32_e64 v20, v20, 0, s[0:1]
	v_readlane_b32 s0, v255, 39
	v_readlane_b32 s1, v255, 40
	s_nop 1
	v_cndmask_b32_e64 v21, v21, 0, s[0:1]
	v_add_f32_e32 v20, v20, v21
	v_readlane_b32 s0, v255, 41
	v_mul_f32_e32 v18, v18, v20
	v_mul_f32_e32 v20, v64, v27
	v_readlane_b32 s1, v255, 42
	v_mul_f32_e32 v21, v65, v31
	s_nop 0
	v_cndmask_b32_e64 v20, v20, 0, s[0:1]
	v_readlane_b32 s0, v255, 43
	v_readlane_b32 s1, v255, 44
	s_nop 1
	v_cndmask_b32_e64 v21, v21, 0, s[0:1]
	v_add_f32_e32 v20, v20, v21
	v_mul_f32_e32 v19, v19, v20
	v_cvt_pk_bf16_f32 v17, v18, v19
	ds_write_b64 v235, v[16:17] offset:41376
	ds_read_b128 v[16:19], v205
	ds_read_b128 v[20:23], v206
	v_readlane_b32 s0, v255, 45
	v_readlane_b32 s1, v255, 46
	s_waitcnt lgkmcnt(1)
	v_mul_f32_e32 v24, v67, v16
	v_cndmask_b32_e64 v24, v24, 0, s[0:1]
	v_readlane_b32 s0, v255, 47
	s_waitcnt lgkmcnt(0)
	v_mul_f32_e32 v25, v66, v20
	v_readlane_b32 s1, v255, 48
	s_nop 1
	v_cndmask_b32_e64 v25, v25, 0, s[0:1]
	v_add_f32_e32 v24, v24, v25
	v_readlane_b32 s0, v255, 49
	v_mul_f32_e32 v12, v12, v24
	v_mul_f32_e32 v24, v67, v17
	v_readlane_b32 s1, v255, 50
	v_mul_f32_e32 v25, v66, v21
	s_nop 0
	v_cndmask_b32_e64 v24, v24, 0, s[0:1]
	v_readlane_b32 s0, v255, 51
	v_readlane_b32 s1, v255, 52
	s_nop 1
	v_cndmask_b32_e64 v25, v25, 0, s[0:1]
	v_add_f32_e32 v24, v24, v25
	v_readlane_b32 s0, v255, 53
	v_mul_f32_e32 v13, v13, v24
	v_mul_f32_e32 v24, v67, v18
	v_readlane_b32 s1, v255, 54
	v_mul_f32_e32 v25, v66, v22
	v_cvt_pk_bf16_f32 v12, v12, v13
	v_cndmask_b32_e64 v24, v24, 0, s[0:1]
	v_readlane_b32 s0, v255, 55
	v_readlane_b32 s1, v255, 56
	s_nop 1
	v_cndmask_b32_e64 v25, v25, 0, s[0:1]
	v_add_f32_e32 v24, v24, v25
	v_mul_f32_e32 v14, v14, v24
	v_mul_f32_e32 v24, v67, v19
	v_mul_f32_e32 v25, v66, v23
	v_cndmask_b32_e64 v24, v24, 0, s[20:21]
	v_cndmask_b32_e64 v25, v25, 0, s[26:27]
	v_add_f32_e32 v24, v24, v25
	v_mul_f32_e32 v15, v15, v24
	v_cvt_pk_bf16_f32 v13, v14, v15
	ds_write_b64 v235, v[12:13] offset:37056
	v_mul_f32_e32 v12, v64, v16
	v_mul_f32_e32 v13, v65, v20
	v_cndmask_b32_e64 v12, v12, 0, s[28:29]
	v_cndmask_b32_e64 v13, v13, 0, s[30:31]
	v_add_f32_e32 v12, v12, v13
	v_mul_f32_e32 v8, v8, v12
	v_mul_f32_e32 v12, v64, v17
	v_mul_f32_e32 v13, v65, v21
	v_cndmask_b32_e64 v12, v12, 0, s[34:35]
	v_cndmask_b32_e64 v13, v13, 0, s[36:37]
	v_add_f32_e32 v12, v12, v13
	v_mul_f32_e32 v9, v9, v12
	v_mul_f32_e32 v12, v64, v18
	v_mul_f32_e32 v13, v65, v22
	v_cndmask_b32_e64 v12, v12, 0, s[38:39]
	v_cndmask_b32_e64 v13, v13, 0, s[40:41]
	v_add_f32_e32 v12, v12, v13
	v_mul_f32_e32 v10, v10, v12
	v_mul_f32_e32 v12, v64, v19
	v_mul_f32_e32 v13, v65, v23
	v_cndmask_b32_e64 v12, v12, 0, s[42:43]
	v_cndmask_b32_e64 v13, v13, 0, s[44:45]
	v_add_f32_e32 v12, v12, v13
	v_mul_f32_e32 v11, v11, v12
	v_cvt_pk_bf16_f32 v8, v8, v9
	v_cvt_pk_bf16_f32 v9, v10, v11
	ds_write_b64 v235, v[8:9] offset:41408
	ds_read_b128 v[8:11], v207
	ds_read_b128 v[12:15], v208
	s_mul_i32 s0, s12, 0x300
	s_add_i32 s0, s78, s0
	s_mul_hi_i32 s1, s0, 0x4200
	s_waitcnt lgkmcnt(1)
	v_mul_f32_e32 v16, v67, v8
	s_waitcnt lgkmcnt(0)
	v_mul_f32_e32 v17, v66, v12
	v_cndmask_b32_e64 v16, v16, 0, s[46:47]
	v_cndmask_b32_e64 v17, v17, 0, s[48:49]
	v_add_f32_e32 v16, v16, v17
	v_mul_f32_e32 v4, v4, v16
	v_mul_f32_e32 v16, v67, v9
	v_mul_f32_e32 v17, v66, v13
	v_cndmask_b32_e64 v16, v16, 0, s[50:51]
	v_cndmask_b32_e64 v17, v17, 0, s[52:53]
	v_add_f32_e32 v16, v16, v17
	v_mul_f32_e32 v5, v5, v16
	v_mul_f32_e32 v16, v67, v10
	v_mul_f32_e32 v17, v66, v14
	v_cndmask_b32_e64 v16, v16, 0, s[54:55]
	v_cndmask_b32_e64 v17, v17, 0, s[56:57]
	v_add_f32_e32 v16, v16, v17
	v_mul_f32_e32 v6, v6, v16
	v_mul_f32_e32 v16, v67, v11
	v_mul_f32_e32 v17, v66, v15
	v_cndmask_b32_e64 v16, v16, 0, s[58:59]
	v_cndmask_b32_e64 v17, v17, 0, s[60:61]
	v_add_f32_e32 v16, v16, v17
	v_mul_f32_e32 v7, v7, v16
	v_cvt_pk_bf16_f32 v4, v4, v5
	v_cvt_pk_bf16_f32 v5, v6, v7
	ds_write_b64 v235, v[4:5] offset:37088
	v_mul_f32_e32 v4, v64, v8
	v_mul_f32_e32 v5, v65, v12
	v_cndmask_b32_e64 v4, v4, 0, s[62:63]
	v_cndmask_b32_e64 v5, v5, 0, s[64:65]
	v_add_f32_e32 v4, v4, v5
	v_mul_f32_e32 v0, v0, v4
	v_mul_f32_e32 v4, v64, v9
	v_mul_f32_e32 v5, v65, v13
	v_cndmask_b32_e64 v4, v4, 0, s[66:67]
	v_cndmask_b32_e64 v5, v5, 0, s[68:69]
	v_add_f32_e32 v4, v4, v5
	v_mul_f32_e32 v1, v1, v4
	v_mul_f32_e32 v4, v64, v10
	v_mul_f32_e32 v5, v65, v14
	v_cndmask_b32_e64 v4, v4, 0, s[70:71]
	v_cndmask_b32_e64 v5, v5, 0, s[72:73]
	v_add_f32_e32 v4, v4, v5
	s_mulk_i32 s0, 0x4200
	v_mul_f32_e32 v2, v2, v4
	v_mul_f32_e32 v4, v64, v11
	v_mul_f32_e32 v5, v65, v15
	s_add_u32 s2, s2, s0
	v_readlane_b32 s0, v252, 48
	v_cndmask_b32_e64 v4, v4, 0, s[74:75]
	v_cndmask_b32_e64 v5, v5, 0, s[76:77]
	s_addc_u32 s3, s0, s1
	s_ashr_i32 s5, s4, 31
	v_add_f32_e32 v4, v4, v5
	s_lshl_b64 s[0:1], s[4:5], 1
	v_mul_f32_e32 v3, v3, v4
	s_add_u32 s0, s2, s0
	v_cvt_pk_bf16_f32 v0, v0, v1
	v_cvt_pk_bf16_f32 v1, v2, v3
	s_addc_u32 s1, s3, s1
	ds_write_b64 v235, v[0:1] offset:41440
	v_lshl_add_u64 v[0:1], s[0:1], 0, v[154:155]
	v_lshl_add_u64 v[2:3], v[0:1], 0, v[130:131]
	s_waitcnt lgkmcnt(0)
	s_barrier
	v_lshl_add_u64 v[4:5], v[0:1], 0, v[132:133]
	v_lshl_add_u64 v[6:7], v[0:1], 0, v[134:135]
	v_lshl_add_u64 v[0:1], v[0:1], 0, v[136:137]
	global_load_dwordx4 v[8:11], v[2:3], off
	global_load_dwordx4 v[12:15], v[4:5], off
	global_load_dwordx4 v[16:19], v[6:7], off
	global_load_dwordx4 v[20:23], v[0:1], off
	s_barrier
	s_waitcnt vmcnt(3)
	ds_write_b128 v236, v[8:11] offset:18432
	s_waitcnt vmcnt(2)
	ds_write_b128 v236, v[12:15] offset:23040
	s_waitcnt vmcnt(1)
	ds_write_b128 v236, v[16:19] offset:27648
	s_waitcnt vmcnt(0)
	ds_write_b128 v236, v[20:23] offset:32256
	s_waitcnt lgkmcnt(0)
	s_barrier
	ds_read_b128 v[8:11], v237 offset:36864
	ds_read_b128 v[12:15], v237 offset:41216
	ds_read_b128 v[16:19], v181 offset:18432
	ds_read_b128 v[20:23], v181 offset:20736
	ds_read_b128 v[24:27], v181 offset:23040
	ds_read_b128 v[28:31], v181 offset:25344
	ds_read_b128 v[32:35], v181 offset:27648
	ds_read_b128 v[36:39], v181 offset:29952
	ds_read_b128 v[40:43], v181 offset:32256
	ds_read_b128 v[44:47], v181 offset:34560
	s_waitcnt lgkmcnt(7)
	v_mfma_f32_16x16x32_bf16 v[48:51], v[16:19], v[8:11], 0
	s_mul_i32 s0, s12, 6
	s_add_i32 s0, s0, s96
	s_mulk_i32 s0, 0x42
	s_waitcnt lgkmcnt(6)
	v_mfma_f32_16x16x32_bf16 v[52:55], v[20:23], v[8:11], 0
	s_add_i32 s4, s0, s11
	s_ashr_i32 s5, s4, 31
	s_lshl_b64 s[0:1], s[4:5], 15
	s_waitcnt lgkmcnt(5)
	v_mfma_f32_16x16x32_bf16 v[56:59], v[24:27], v[8:11], 0
	s_movk_i32 s96, 0x600
	s_waitcnt lgkmcnt(4)
	v_mfma_f32_16x16x32_bf16 v[60:63], v[28:31], v[8:11], 0
	s_waitcnt lgkmcnt(3)
	v_mfma_f32_16x16x32_bf16 v[64:67], v[32:35], v[8:11], 0
	s_waitcnt lgkmcnt(2)
	v_mfma_f32_16x16x32_bf16 v[68:71], v[36:39], v[8:11], 0
	s_waitcnt lgkmcnt(1)
	v_mfma_f32_16x16x32_bf16 v[72:75], v[40:43], v[8:11], 0
	s_waitcnt lgkmcnt(0)
	v_mfma_f32_16x16x32_bf16 v[8:11], v[44:47], v[8:11], 0
	v_mfma_f32_16x16x32_bf16 v[16:19], v[16:19], v[12:15], 0
	v_mfma_f32_16x16x32_bf16 v[20:23], v[20:23], v[12:15], 0
	v_mfma_f32_16x16x32_bf16 v[24:27], v[24:27], v[12:15], 0
	v_mfma_f32_16x16x32_bf16 v[28:31], v[28:31], v[12:15], 0
	v_mfma_f32_16x16x32_bf16 v[32:35], v[32:35], v[12:15], 0
	v_mfma_f32_16x16x32_bf16 v[36:39], v[36:39], v[12:15], 0
	v_mfma_f32_16x16x32_bf16 v[40:43], v[40:43], v[12:15], 0
	v_mfma_f32_16x16x32_bf16 v[12:15], v[44:47], v[12:15], 0
	ds_read_b128 v[44:47], v237 offset:36928
	ds_read_b128 v[76:79], v237 offset:41280
	ds_read_b128 v[80:83], v181 offset:18496
	ds_read_b128 v[84:87], v181 offset:20800
	ds_read_b128 v[88:91], v181 offset:23104
	ds_read_b128 v[92:95], v181 offset:25408
	ds_read_b128 v[96:99], v181 offset:27712
	ds_read_b128 v[100:103], v181 offset:30016
	ds_read_b128 v[104:107], v181 offset:32320
	ds_read_b128 v[108:111], v181 offset:34624
	s_waitcnt lgkmcnt(7)
	v_mfma_f32_16x16x32_bf16 v[48:51], v[80:83], v[44:47], v[48:51]
	s_waitcnt lgkmcnt(6)
	v_mfma_f32_16x16x32_bf16 v[52:55], v[84:87], v[44:47], v[52:55]
	s_waitcnt lgkmcnt(5)
	v_mfma_f32_16x16x32_bf16 v[56:59], v[88:91], v[44:47], v[56:59]
	s_waitcnt lgkmcnt(4)
	v_mfma_f32_16x16x32_bf16 v[60:63], v[92:95], v[44:47], v[60:63]
	s_waitcnt lgkmcnt(3)
	v_mfma_f32_16x16x32_bf16 v[64:67], v[96:99], v[44:47], v[64:67]
	s_waitcnt lgkmcnt(2)
	v_mfma_f32_16x16x32_bf16 v[68:71], v[100:103], v[44:47], v[68:71]
	s_waitcnt lgkmcnt(1)
	v_mfma_f32_16x16x32_bf16 v[72:75], v[104:107], v[44:47], v[72:75]
	s_waitcnt lgkmcnt(0)
	v_mfma_f32_16x16x32_bf16 v[8:11], v[108:111], v[44:47], v[8:11]
	v_mfma_f32_16x16x32_bf16 v[16:19], v[80:83], v[76:79], v[16:19]
	v_mfma_f32_16x16x32_bf16 v[20:23], v[84:87], v[76:79], v[20:23]
	v_mfma_f32_16x16x32_bf16 v[24:27], v[88:91], v[76:79], v[24:27]
	v_mfma_f32_16x16x32_bf16 v[28:31], v[92:95], v[76:79], v[28:31]
	v_mfma_f32_16x16x32_bf16 v[32:35], v[96:99], v[76:79], v[32:35]
	v_mfma_f32_16x16x32_bf16 v[36:39], v[100:103], v[76:79], v[36:39]
	v_mfma_f32_16x16x32_bf16 v[40:43], v[104:107], v[76:79], v[40:43]
	v_mfma_f32_16x16x32_bf16 v[12:15], v[108:111], v[76:79], v[12:15]
	global_load_dwordx4 v[44:47], v[2:3], off offset:128
	s_nop 0
	global_load_dwordx4 v[2:5], v[4:5], off offset:128
	s_nop 0
	global_load_dwordx4 v[76:79], v[6:7], off offset:128
	global_load_dwordx4 v[80:83], v[0:1], off offset:128
	s_barrier
	s_waitcnt vmcnt(3)
	ds_write_b128 v236, v[44:47] offset:18432
	s_waitcnt vmcnt(2)
	ds_write_b128 v236, v[2:5] offset:23040
	s_waitcnt vmcnt(1)
	ds_write_b128 v236, v[76:79] offset:27648
	s_waitcnt vmcnt(0)
	ds_write_b128 v236, v[80:83] offset:32256
	s_waitcnt lgkmcnt(0)
	s_barrier
	ds_read_b128 v[0:3], v237 offset:36992
	ds_read_b128 v[4:7], v237 offset:41344
	ds_read_b128 v[44:47], v181 offset:18432
	ds_read_b128 v[76:79], v181 offset:20736
	ds_read_b128 v[80:83], v181 offset:23040
	ds_read_b128 v[84:87], v181 offset:25344
	ds_read_b128 v[88:91], v181 offset:27648
	ds_read_b128 v[92:95], v181 offset:29952
	ds_read_b128 v[96:99], v181 offset:32256
	ds_read_b128 v[100:103], v181 offset:34560
	s_waitcnt lgkmcnt(3)
	v_mfma_f32_16x16x32_bf16 v[64:67], v[88:91], v[0:3], v[64:67]
	v_mfma_f32_16x16x32_bf16 v[60:63], v[84:87], v[0:3], v[60:63]
	s_waitcnt lgkmcnt(2)
	v_mfma_f32_16x16x32_bf16 v[68:71], v[92:95], v[0:3], v[68:71]
	s_waitcnt lgkmcnt(1)
	v_mfma_f32_16x16x32_bf16 v[72:75], v[96:99], v[0:3], v[72:75]
	v_mfma_f32_16x16x32_bf16 v[84:87], v[84:87], v[4:7], v[28:31]
	v_mfma_f32_16x16x32_bf16 v[88:91], v[88:91], v[4:7], v[32:35]
	v_mfma_f32_16x16x32_bf16 v[92:95], v[92:95], v[4:7], v[36:39]
	v_mfma_f32_16x16x32_bf16 v[96:99], v[96:99], v[4:7], v[40:43]
	ds_read_b128 v[28:31], v237 offset:37056
	ds_read_b128 v[108:111], v237 offset:41408
	ds_read_b128 v[32:35], v181 offset:18496
	ds_read_b128 v[36:39], v181 offset:20800
	ds_read_b128 v[40:43], v181 offset:23104
	ds_read_b128 v[112:115], v181 offset:25408
	ds_read_b128 v[116:119], v181 offset:27712
	ds_read_b128 v[120:123], v181 offset:30016
	ds_read_b128 v[242:245], v181 offset:32320
	ds_read_b128 v[246:249], v181 offset:34624
	v_mfma_f32_16x16x32_bf16 v[48:51], v[44:47], v[0:3], v[48:51]
	v_mfma_f32_16x16x32_bf16 v[44:47], v[44:47], v[4:7], v[16:19]
	s_waitcnt lgkmcnt(3)
	v_mfma_f32_16x16x32_bf16 v[16:19], v[116:119], v[28:31], v[64:67]
	s_nop 2
	global_load_dwordx4 v[64:67], v[158:159], off
	v_mfma_f32_16x16x32_bf16 v[52:55], v[76:79], v[0:3], v[52:55]
	v_mfma_f32_16x16x32_bf16 v[76:79], v[76:79], v[4:7], v[20:23]
	s_waitcnt lgkmcnt(2)
	v_mfma_f32_16x16x32_bf16 v[20:23], v[120:123], v[28:31], v[68:71]
	s_nop 2
	ds_read_b32 v68, v229
	v_mfma_f32_16x16x32_bf16 v[56:59], v[80:83], v[0:3], v[56:59]
	s_waitcnt vmcnt(0)
	v_lshlrev_b32_e32 v70, 16, v64
	v_mfma_f32_16x16x32_bf16 v[80:83], v[80:83], v[4:7], v[24:27]
	v_and_b32_e32 v71, 0xffff0000, v64
	v_mfma_f32_16x16x32_bf16 v[104:107], v[100:103], v[0:3], v[8:11]
	v_mfma_f32_16x16x32_bf16 v[100:103], v[100:103], v[4:7], v[12:15]
	v_mfma_f32_16x16x32_bf16 v[4:7], v[36:39], v[28:31], v[52:55]
	v_mfma_f32_16x16x32_bf16 v[8:11], v[40:43], v[28:31], v[56:59]
	s_waitcnt lgkmcnt(2)
	v_mfma_f32_16x16x32_bf16 v[24:27], v[242:245], v[28:31], v[72:75]
	v_mfma_f32_16x16x32_bf16 v[36:39], v[36:39], v[108:111], v[76:79]
	s_nop 1
	ds_read_b32 v72, v230
	ds_read_b32 v76, v231
	v_mfma_f32_16x16x32_bf16 v[40:43], v[40:43], v[108:111], v[80:83]
	s_nop 2
	ds_read_b32 v82, v232
	s_waitcnt lgkmcnt(3)
	v_mul_f32_e32 v70, v68, v70
	v_mul_f32_e32 v71, v68, v71
	v_cvt_pk_bf16_f32 v64, v70, v71
	v_lshlrev_b32_e32 v70, 16, v65
	v_and_b32_e32 v71, 0xffff0000, v65
	v_mul_f32_e32 v70, v68, v70
	v_mul_f32_e32 v71, v68, v71
	v_cvt_pk_bf16_f32 v65, v70, v71
	v_lshlrev_b32_e32 v70, 16, v66
	v_and_b32_e32 v71, 0xffff0000, v66
	v_mul_f32_e32 v70, v68, v70
	v_mul_f32_e32 v71, v68, v71
	v_cvt_pk_bf16_f32 v66, v70, v71
	v_lshlrev_b32_e32 v70, 16, v67
	v_and_b32_e32 v71, 0xffff0000, v67
	v_mul_f32_e32 v69, v68, v71
	v_mul_f32_e32 v68, v68, v70
	v_cvt_pk_bf16_f32 v67, v68, v69
	global_load_dwordx4 v[68:71], v[160:161], off
	v_mfma_f32_16x16x32_bf16 v[0:3], v[32:35], v[28:31], v[48:51]
	v_lshl_add_u64 v[80:81], v[150:151], 0, s[0:1]
	s_add_i32 s0, s4, 0x318
	s_ashr_i32 s1, s0, 31
	v_mfma_f32_16x16x32_bf16 v[32:35], v[32:35], v[108:111], v[44:47]
	s_lshl_b64 s[0:1], s[0:1], 15
	s_waitcnt vmcnt(0)
	v_lshlrev_b32_e32 v74, 16, v68
	v_and_b32_e32 v75, 0xffff0000, v68
	s_waitcnt lgkmcnt(2)
	v_mul_f32_e32 v74, v72, v74
	v_mul_f32_e32 v75, v72, v75
	v_cvt_pk_bf16_f32 v68, v74, v75
	v_lshlrev_b32_e32 v74, 16, v69
	v_and_b32_e32 v75, 0xffff0000, v69
	v_mul_f32_e32 v74, v72, v74
	v_mul_f32_e32 v75, v72, v75
	v_cvt_pk_bf16_f32 v69, v74, v75
	v_lshlrev_b32_e32 v74, 16, v70
	v_and_b32_e32 v75, 0xffff0000, v70
	v_mul_f32_e32 v74, v72, v74
	v_mul_f32_e32 v75, v72, v75
	v_cvt_pk_bf16_f32 v70, v74, v75
	v_lshlrev_b32_e32 v74, 16, v71
	v_and_b32_e32 v75, 0xffff0000, v71
	v_mul_f32_e32 v73, v72, v75
	v_mul_f32_e32 v72, v72, v74
	v_cvt_pk_bf16_f32 v71, v72, v73
	global_load_dwordx4 v[72:75], v[162:163], off
	v_mfma_f32_16x16x32_bf16 v[44:47], v[112:115], v[108:111], v[84:87]
	s_waitcnt vmcnt(0)
	v_lshlrev_b32_e32 v78, 16, v72
	v_and_b32_e32 v79, 0xffff0000, v72
	s_waitcnt lgkmcnt(1)
	v_mul_f32_e32 v78, v76, v78
	v_mul_f32_e32 v79, v76, v79
	v_cvt_pk_bf16_f32 v72, v78, v79
	v_lshlrev_b32_e32 v78, 16, v73
	v_and_b32_e32 v79, 0xffff0000, v73
	v_mul_f32_e32 v78, v76, v78
	v_mul_f32_e32 v79, v76, v79
	v_cvt_pk_bf16_f32 v73, v78, v79
	v_lshlrev_b32_e32 v78, 16, v74
	v_and_b32_e32 v79, 0xffff0000, v74
	v_mul_f32_e32 v78, v76, v78
	v_mul_f32_e32 v79, v76, v79
	v_cvt_pk_bf16_f32 v74, v78, v79
	v_lshlrev_b32_e32 v78, 16, v75
	v_and_b32_e32 v79, 0xffff0000, v75
	v_mul_f32_e32 v77, v76, v79
	v_mul_f32_e32 v76, v76, v78
	v_cvt_pk_bf16_f32 v75, v76, v77
	global_load_dwordx4 v[76:79], v[164:165], off
	v_mfma_f32_16x16x32_bf16 v[56:59], v[242:245], v[108:111], v[96:99]
	s_waitcnt vmcnt(0)
	v_lshlrev_b32_e32 v84, 16, v76
	v_and_b32_e32 v85, 0xffff0000, v76
	s_waitcnt lgkmcnt(0)
	v_mul_f32_e32 v84, v82, v84
	v_mul_f32_e32 v85, v82, v85
	v_cvt_pk_bf16_f32 v76, v84, v85
	v_lshlrev_b32_e32 v84, 16, v77
	v_and_b32_e32 v85, 0xffff0000, v77
	v_mul_f32_e32 v84, v82, v84
	v_mul_f32_e32 v85, v82, v85
	v_cvt_pk_bf16_f32 v77, v84, v85
	v_lshlrev_b32_e32 v84, 16, v78
	v_and_b32_e32 v85, 0xffff0000, v78
	v_mul_f32_e32 v84, v82, v84
	v_mul_f32_e32 v85, v82, v85
	v_cvt_pk_bf16_f32 v78, v84, v85
	v_lshlrev_b32_e32 v84, 16, v79
	v_and_b32_e32 v85, 0xffff0000, v79
	v_lshl_add_u64 v[96:97], v[80:81], 0, v[138:139]
	v_mul_f32_e32 v83, v82, v85
	v_mul_f32_e32 v82, v82, v84
	v_mfma_f32_16x16x32_bf16 v[12:15], v[112:115], v[28:31], v[60:63]
	v_lshl_add_u64 v[98:99], v[80:81], 0, v[140:141]
	v_cvt_pk_bf16_f32 v79, v82, v83
	v_mfma_f32_16x16x32_bf16 v[48:51], v[116:119], v[108:111], v[88:91]
	v_mfma_f32_16x16x32_bf16 v[52:55], v[120:123], v[108:111], v[92:95]
	v_mfma_f32_16x16x32_bf16 v[60:63], v[246:249], v[108:111], v[100:103]
	s_nop 2
	v_lshl_add_u64 v[100:101], v[80:81], 0, v[142:143]
	v_lshl_add_u64 v[102:103], v[80:81], 0, v[146:147]
	global_load_dwordx4 v[92:95], v[96:97], off
	global_load_dwordx4 v[88:91], v[98:99], off
	global_load_dwordx4 v[84:87], v[100:101], off
	global_load_dwordx4 v[80:83], v[102:103], off
	s_barrier
	ds_write_b128 v180, v[64:67]
	s_waitcnt vmcnt(3)
	ds_write_b128 v180, v[92:95] offset:18432
	ds_write_b128 v180, v[68:71] offset:4608
	s_waitcnt vmcnt(2)
	ds_write_b128 v180, v[88:91] offset:23040
	ds_write_b128 v180, v[72:75] offset:9216
	s_waitcnt vmcnt(1)
	ds_write_b128 v180, v[84:87] offset:27648
	ds_write_b128 v180, v[76:79] offset:13824
	s_waitcnt vmcnt(0)
	ds_write_b128 v180, v[80:83] offset:32256
	s_waitcnt lgkmcnt(0)
	s_barrier
	global_load_dwordx4 v[64:67], v[164:165], off offset:128
	ds_read_b32 v68, v232
	ds_read_b32 v72, v231
	ds_read_b32 v76, v230
	ds_read_b32 v80, v229
	v_mfma_f32_16x16x32_bf16 v[28:31], v[246:249], v[28:31], v[104:107]
	s_waitcnt vmcnt(0)
	v_lshlrev_b32_e32 v70, 16, v67
	v_and_b32_e32 v71, 0xffff0000, v67
	s_waitcnt lgkmcnt(3)
	v_mul_f32_e32 v70, v68, v70
	v_mul_f32_e32 v71, v68, v71
	v_cvt_pk_bf16_f32 v67, v70, v71
	v_lshlrev_b32_e32 v70, 16, v66
	v_and_b32_e32 v71, 0xffff0000, v66
	v_mul_f32_e32 v70, v68, v70
	v_mul_f32_e32 v71, v68, v71
	v_cvt_pk_bf16_f32 v66, v70, v71
	v_lshlrev_b32_e32 v70, 16, v65
	v_and_b32_e32 v71, 0xffff0000, v65
	v_mul_f32_e32 v70, v68, v70
	v_mul_f32_e32 v71, v68, v71
	v_cvt_pk_bf16_f32 v65, v70, v71
	v_lshlrev_b32_e32 v70, 16, v64
	v_and_b32_e32 v71, 0xffff0000, v64
	v_mul_f32_e32 v69, v68, v71
	v_mul_f32_e32 v68, v68, v70
	v_cvt_pk_bf16_f32 v64, v68, v69
	global_load_dwordx4 v[68:71], v[162:163], off offset:128
	s_waitcnt vmcnt(0)
	v_lshlrev_b32_e32 v74, 16, v71
	v_and_b32_e32 v75, 0xffff0000, v71
	s_waitcnt lgkmcnt(2)
	v_mul_f32_e32 v74, v72, v74
	v_mul_f32_e32 v75, v72, v75
	v_cvt_pk_bf16_f32 v71, v74, v75
	v_lshlrev_b32_e32 v74, 16, v70
	v_and_b32_e32 v75, 0xffff0000, v70
	v_mul_f32_e32 v74, v72, v74
	v_mul_f32_e32 v75, v72, v75
	v_cvt_pk_bf16_f32 v70, v74, v75
	v_lshlrev_b32_e32 v74, 16, v69
	v_and_b32_e32 v75, 0xffff0000, v69
	v_mul_f32_e32 v74, v72, v74
	v_mul_f32_e32 v75, v72, v75
	v_cvt_pk_bf16_f32 v69, v74, v75
	v_lshlrev_b32_e32 v74, 16, v68
	v_and_b32_e32 v75, 0xffff0000, v68
	v_mul_f32_e32 v73, v72, v75
	v_mul_f32_e32 v72, v72, v74
	v_cvt_pk_bf16_f32 v68, v72, v73
	global_load_dwordx4 v[72:75], v[160:161], off offset:128
	s_waitcnt vmcnt(0)
	v_lshlrev_b32_e32 v78, 16, v75
	v_and_b32_e32 v79, 0xffff0000, v75
	s_waitcnt lgkmcnt(1)
	v_mul_f32_e32 v78, v76, v78
	v_mul_f32_e32 v79, v76, v79
	v_cvt_pk_bf16_f32 v75, v78, v79
	v_lshlrev_b32_e32 v78, 16, v74
	v_and_b32_e32 v79, 0xffff0000, v74
	v_mul_f32_e32 v78, v76, v78
	v_mul_f32_e32 v79, v76, v79
	v_cvt_pk_bf16_f32 v74, v78, v79
	v_lshlrev_b32_e32 v78, 16, v73
	v_and_b32_e32 v79, 0xffff0000, v73
	v_mul_f32_e32 v78, v76, v78
	v_mul_f32_e32 v79, v76, v79
	v_cvt_pk_bf16_f32 v73, v78, v79
	v_lshlrev_b32_e32 v78, 16, v72
	v_and_b32_e32 v79, 0xffff0000, v72
	v_mul_f32_e32 v77, v76, v79
	v_mul_f32_e32 v76, v76, v78
	v_cvt_pk_bf16_f32 v72, v76, v77
	global_load_dwordx4 v[76:79], v[158:159], off offset:128
	s_waitcnt vmcnt(0)
	v_lshlrev_b32_e32 v82, 16, v79
	v_and_b32_e32 v83, 0xffff0000, v79
	s_waitcnt lgkmcnt(0)
	v_mul_f32_e32 v82, v80, v82
	v_mul_f32_e32 v83, v80, v83
	v_cvt_pk_bf16_f32 v79, v82, v83
	v_lshlrev_b32_e32 v82, 16, v78
	v_and_b32_e32 v83, 0xffff0000, v78
	v_mul_f32_e32 v82, v80, v82
	v_mul_f32_e32 v83, v80, v83
	v_cvt_pk_bf16_f32 v78, v82, v83
	v_lshlrev_b32_e32 v82, 16, v77
	v_and_b32_e32 v83, 0xffff0000, v77
	v_mul_f32_e32 v82, v80, v82
	v_mul_f32_e32 v83, v80, v83
	v_cvt_pk_bf16_f32 v77, v82, v83
	v_lshlrev_b32_e32 v82, 16, v76
	v_and_b32_e32 v83, 0xffff0000, v76
	v_mul_f32_e32 v81, v80, v83
	v_mul_f32_e32 v80, v80, v82
	v_cvt_pk_bf16_f32 v76, v80, v81
	ds_read_b128 v[84:87], v241
	ds_read_b128 v[80:83], v241 offset:2304
	ds_read_b128 v[88:91], v181 offset:18432
	ds_read_b128 v[92:95], v181 offset:20736
	ds_read_b128 v[104:107], v181 offset:23040
	ds_read_b128 v[108:111], v181 offset:25344
	ds_read_b128 v[112:115], v181 offset:27648
	ds_read_b128 v[116:119], v181 offset:29952
	ds_read_b128 v[120:123], v181 offset:32256
	ds_read_b128 v[242:245], v181 offset:34560
	s_waitcnt lgkmcnt(7)
	v_mfma_f32_16x16x32_bf16 v[0:3], v[88:91], v[84:87], v[0:3]
	s_waitcnt lgkmcnt(6)
	v_mfma_f32_16x16x32_bf16 v[4:7], v[92:95], v[84:87], v[4:7]
	s_waitcnt lgkmcnt(5)
	v_mfma_f32_16x16x32_bf16 v[8:11], v[104:107], v[84:87], v[8:11]
	s_waitcnt lgkmcnt(4)
	v_mfma_f32_16x16x32_bf16 v[12:15], v[108:111], v[84:87], v[12:15]
	s_waitcnt lgkmcnt(3)
	v_mfma_f32_16x16x32_bf16 v[16:19], v[112:115], v[84:87], v[16:19]
	s_waitcnt lgkmcnt(2)
	v_mfma_f32_16x16x32_bf16 v[20:23], v[116:119], v[84:87], v[20:23]
	s_waitcnt lgkmcnt(1)
	v_mfma_f32_16x16x32_bf16 v[24:27], v[120:123], v[84:87], v[24:27]
	s_waitcnt lgkmcnt(0)
	v_mfma_f32_16x16x32_bf16 v[28:31], v[242:245], v[84:87], v[28:31]
	v_mfma_f32_16x16x32_bf16 v[32:35], v[88:91], v[80:83], v[32:35]
	v_mfma_f32_16x16x32_bf16 v[36:39], v[92:95], v[80:83], v[36:39]
	v_mfma_f32_16x16x32_bf16 v[40:43], v[104:107], v[80:83], v[40:43]
	v_mfma_f32_16x16x32_bf16 v[44:47], v[108:111], v[80:83], v[44:47]
	v_mfma_f32_16x16x32_bf16 v[48:51], v[112:115], v[80:83], v[48:51]
	v_mfma_f32_16x16x32_bf16 v[52:55], v[116:119], v[80:83], v[52:55]
	v_mfma_f32_16x16x32_bf16 v[56:59], v[120:123], v[80:83], v[56:59]
	v_mfma_f32_16x16x32_bf16 v[60:63], v[242:245], v[80:83], v[60:63]
	ds_read_b128 v[80:83], v241 offset:64
	ds_read_b128 v[84:87], v241 offset:2368
	ds_read_b128 v[88:91], v181 offset:18496
	ds_read_b128 v[92:95], v181 offset:20800
	ds_read_b128 v[104:107], v181 offset:23104
	ds_read_b128 v[108:111], v181 offset:25408
	ds_read_b128 v[112:115], v181 offset:27712
	ds_read_b128 v[116:119], v181 offset:30016
	ds_read_b128 v[120:123], v181 offset:32320
	ds_read_b128 v[242:245], v181 offset:34624
	s_waitcnt lgkmcnt(7)
	v_mfma_f32_16x16x32_bf16 v[0:3], v[88:91], v[80:83], v[0:3]
	s_waitcnt lgkmcnt(6)
	v_mfma_f32_16x16x32_bf16 v[4:7], v[92:95], v[80:83], v[4:7]
	s_waitcnt lgkmcnt(5)
	v_mfma_f32_16x16x32_bf16 v[8:11], v[104:107], v[80:83], v[8:11]
	s_waitcnt lgkmcnt(4)
	v_mfma_f32_16x16x32_bf16 v[12:15], v[108:111], v[80:83], v[12:15]
	s_waitcnt lgkmcnt(3)
	v_mfma_f32_16x16x32_bf16 v[16:19], v[112:115], v[80:83], v[16:19]
	s_waitcnt lgkmcnt(2)
	v_mfma_f32_16x16x32_bf16 v[20:23], v[116:119], v[80:83], v[20:23]
	s_waitcnt lgkmcnt(1)
	v_mfma_f32_16x16x32_bf16 v[24:27], v[120:123], v[80:83], v[24:27]
	s_waitcnt lgkmcnt(0)
	v_mfma_f32_16x16x32_bf16 v[28:31], v[242:245], v[80:83], v[28:31]
	v_mfma_f32_16x16x32_bf16 v[32:35], v[88:91], v[84:87], v[32:35]
	v_mfma_f32_16x16x32_bf16 v[36:39], v[92:95], v[84:87], v[36:39]
	v_mfma_f32_16x16x32_bf16 v[40:43], v[104:107], v[84:87], v[40:43]
	v_mfma_f32_16x16x32_bf16 v[44:47], v[108:111], v[84:87], v[44:47]
	v_mfma_f32_16x16x32_bf16 v[48:51], v[112:115], v[84:87], v[48:51]
	v_mfma_f32_16x16x32_bf16 v[52:55], v[116:119], v[84:87], v[52:55]
	v_mfma_f32_16x16x32_bf16 v[56:59], v[120:123], v[84:87], v[56:59]
	v_mfma_f32_16x16x32_bf16 v[60:63], v[242:245], v[84:87], v[60:63]
	global_load_dwordx4 v[92:95], v[96:97], off offset:128
	global_load_dwordx4 v[88:91], v[98:99], off offset:128
	global_load_dwordx4 v[84:87], v[100:101], off offset:128
	global_load_dwordx4 v[80:83], v[102:103], off offset:128
	s_barrier
	ds_write_b128 v180, v[76:79]
	s_waitcnt vmcnt(3)
	ds_write_b128 v180, v[92:95] offset:18432
	ds_write_b128 v180, v[72:75] offset:4608
	s_waitcnt vmcnt(2)
	ds_write_b128 v180, v[88:91] offset:23040
	ds_write_b128 v180, v[68:71] offset:9216
	s_waitcnt vmcnt(1)
	ds_write_b128 v180, v[84:87] offset:27648
	ds_write_b128 v180, v[64:67] offset:13824
	s_waitcnt vmcnt(0)
	ds_write_b128 v180, v[80:83] offset:32256
	s_waitcnt lgkmcnt(0)
	s_barrier
	ds_read_b128 v[64:67], v181 offset:34560
	ds_read_b128 v[68:71], v181 offset:32256
	ds_read_b128 v[72:75], v181 offset:29952
	ds_read_b128 v[76:79], v181 offset:27648
	ds_read_b128 v[80:83], v181 offset:25344
	ds_read_b128 v[84:87], v181 offset:23040
	ds_read_b128 v[88:91], v181 offset:20736
	ds_read_b128 v[92:95], v181 offset:18432
	ds_read_b128 v[96:99], v241 offset:2304
	ds_read_b128 v[100:103], v241
	s_waitcnt lgkmcnt(0)
	v_mfma_f32_16x16x32_bf16 v[0:3], v[92:95], v[100:103], v[0:3]
	v_mfma_f32_16x16x32_bf16 v[4:7], v[88:91], v[100:103], v[4:7]
	v_mfma_f32_16x16x32_bf16 v[8:11], v[84:87], v[100:103], v[8:11]
	v_mfma_f32_16x16x32_bf16 v[12:15], v[80:83], v[100:103], v[12:15]
	v_mfma_f32_16x16x32_bf16 v[16:19], v[76:79], v[100:103], v[16:19]
	v_mfma_f32_16x16x32_bf16 v[20:23], v[72:75], v[100:103], v[20:23]
	v_mfma_f32_16x16x32_bf16 v[24:27], v[68:71], v[100:103], v[24:27]
	v_mfma_f32_16x16x32_bf16 v[28:31], v[64:67], v[100:103], v[28:31]
	v_mfma_f32_16x16x32_bf16 v[32:35], v[92:95], v[96:99], v[32:35]
	v_mfma_f32_16x16x32_bf16 v[36:39], v[88:91], v[96:99], v[36:39]
	v_mfma_f32_16x16x32_bf16 v[40:43], v[84:87], v[96:99], v[40:43]
	v_mfma_f32_16x16x32_bf16 v[44:47], v[80:83], v[96:99], v[44:47]
	v_mfma_f32_16x16x32_bf16 v[48:51], v[76:79], v[96:99], v[48:51]
	v_mfma_f32_16x16x32_bf16 v[52:55], v[72:75], v[96:99], v[52:55]
	v_mfma_f32_16x16x32_bf16 v[56:59], v[68:71], v[96:99], v[56:59]
	v_mfma_f32_16x16x32_bf16 v[60:63], v[64:67], v[96:99], v[60:63]
	ds_read_b128 v[64:67], v241 offset:64
	ds_read_b128 v[68:71], v241 offset:2368
	ds_read_b128 v[72:75], v181 offset:18496
	ds_read_b128 v[76:79], v181 offset:20800
	ds_read_b128 v[80:83], v181 offset:23104
	ds_read_b128 v[84:87], v181 offset:25408
	ds_read_b128 v[88:91], v181 offset:27712
	ds_read_b128 v[92:95], v181 offset:30016
	ds_read_b128 v[96:99], v181 offset:32320
	ds_read_b128 v[100:103], v181 offset:34624
	s_waitcnt lgkmcnt(7)
	v_mfma_f32_16x16x32_bf16 v[0:3], v[72:75], v[64:67], v[0:3]
	s_waitcnt lgkmcnt(6)
	v_mfma_f32_16x16x32_bf16 v[4:7], v[76:79], v[64:67], v[4:7]
	s_waitcnt lgkmcnt(5)
	v_mfma_f32_16x16x32_bf16 v[8:11], v[80:83], v[64:67], v[8:11]
	s_waitcnt lgkmcnt(4)
	v_mfma_f32_16x16x32_bf16 v[12:15], v[84:87], v[64:67], v[12:15]
	s_waitcnt lgkmcnt(3)
	v_mfma_f32_16x16x32_bf16 v[16:19], v[88:91], v[64:67], v[16:19]
	s_waitcnt lgkmcnt(2)
	v_mfma_f32_16x16x32_bf16 v[20:23], v[92:95], v[64:67], v[20:23]
	s_waitcnt lgkmcnt(1)
	v_mfma_f32_16x16x32_bf16 v[24:27], v[96:99], v[64:67], v[24:27]
	s_waitcnt lgkmcnt(0)
	v_mfma_f32_16x16x32_bf16 v[28:31], v[100:103], v[64:67], v[28:31]
	global_load_dwordx4 v[64:67], v[158:159], off
	v_mfma_f32_16x16x32_bf16 v[32:35], v[72:75], v[68:71], v[32:35]
	ds_read2_b32 v[72:73], v229 offset0:128 offset1:160
	v_mfma_f32_16x16x32_bf16 v[36:39], v[76:79], v[68:71], v[36:39]
	v_mfma_f32_16x16x32_bf16 v[40:43], v[80:83], v[68:71], v[40:43]
	ds_read2_b32 v[82:83], v229 offset0:192 offset1:224
	v_lshl_add_u64 v[80:81], v[150:151], 0, s[0:1]
	v_readlane_b32 s0, v252, 53
	v_mfma_f32_16x16x32_bf16 v[44:47], v[84:87], v[68:71], v[44:47]
	v_readlane_b32 s1, v252, 54
	v_mfma_f32_16x16x32_bf16 v[48:51], v[88:91], v[68:71], v[48:51]
	v_mfma_f32_16x16x32_bf16 v[52:55], v[92:95], v[68:71], v[52:55]
	v_mfma_f32_16x16x32_bf16 v[56:59], v[96:99], v[68:71], v[56:59]
	v_lshl_add_u64 v[96:97], v[80:81], 0, v[138:139]
	v_lshl_add_u64 v[98:99], v[80:81], 0, v[140:141]
	v_mfma_f32_16x16x32_bf16 v[60:63], v[100:103], v[68:71], v[60:63]
	v_lshl_add_u64 v[100:101], v[80:81], 0, v[142:143]
	v_lshl_add_u64 v[102:103], v[80:81], 0, v[146:147]
	s_waitcnt vmcnt(0)
	v_lshlrev_b32_e32 v68, 16, v64
	v_and_b32_e32 v69, 0xffff0000, v64
	s_waitcnt lgkmcnt(1)
	v_mul_f32_e32 v68, v72, v68
	v_mul_f32_e32 v69, v72, v69
	v_cvt_pk_bf16_f32 v64, v68, v69
	v_lshlrev_b32_e32 v68, 16, v65
	v_and_b32_e32 v69, 0xffff0000, v65
	v_mul_f32_e32 v68, v72, v68
	v_mul_f32_e32 v69, v72, v69
	v_cvt_pk_bf16_f32 v65, v68, v69
	v_lshlrev_b32_e32 v68, 16, v66
	v_and_b32_e32 v69, 0xffff0000, v66
	v_mul_f32_e32 v68, v72, v68
	v_mul_f32_e32 v69, v72, v69
	v_cvt_pk_bf16_f32 v66, v68, v69
	v_lshlrev_b32_e32 v68, 16, v67
	v_and_b32_e32 v69, 0xffff0000, v67
	v_mul_f32_e32 v68, v72, v68
	v_mul_f32_e32 v69, v72, v69
	v_cvt_pk_bf16_f32 v67, v68, v69
	global_load_dwordx4 v[68:71], v[160:161], off
	v_mov_b32_e32 v72, v73
	s_waitcnt vmcnt(0)
	v_lshlrev_b32_e32 v74, 16, v68
	v_and_b32_e32 v75, 0xffff0000, v68
	v_mul_f32_e32 v74, v72, v74
	v_mul_f32_e32 v75, v72, v75
	v_cvt_pk_bf16_f32 v68, v74, v75
	v_lshlrev_b32_e32 v74, 16, v69
	v_and_b32_e32 v75, 0xffff0000, v69
	v_mul_f32_e32 v74, v72, v74
	v_mul_f32_e32 v75, v72, v75
	v_cvt_pk_bf16_f32 v69, v74, v75
	v_lshlrev_b32_e32 v74, 16, v70
	v_and_b32_e32 v75, 0xffff0000, v70
	v_mul_f32_e32 v74, v72, v74
	v_mul_f32_e32 v75, v72, v75
	v_cvt_pk_bf16_f32 v70, v74, v75
	v_lshlrev_b32_e32 v74, 16, v71
	v_and_b32_e32 v75, 0xffff0000, v71
	v_mul_f32_e32 v73, v72, v75
	v_mul_f32_e32 v72, v72, v74
	v_cvt_pk_bf16_f32 v71, v72, v73
	global_load_dwordx4 v[72:75], v[162:163], off
	s_waitcnt vmcnt(0)
	v_lshlrev_b32_e32 v76, 16, v72
	v_and_b32_e32 v77, 0xffff0000, v72
	s_waitcnt lgkmcnt(0)
	v_mul_f32_e32 v76, v82, v76
	v_mul_f32_e32 v77, v82, v77
	v_cvt_pk_bf16_f32 v72, v76, v77
	v_lshlrev_b32_e32 v76, 16, v73
	v_and_b32_e32 v77, 0xffff0000, v73
	v_mul_f32_e32 v76, v82, v76
	v_mul_f32_e32 v77, v82, v77
	v_cvt_pk_bf16_f32 v73, v76, v77
	v_lshlrev_b32_e32 v76, 16, v74
	v_and_b32_e32 v77, 0xffff0000, v74
	v_mul_f32_e32 v76, v82, v76
	v_mul_f32_e32 v77, v82, v77
	v_cvt_pk_bf16_f32 v74, v76, v77
	v_lshlrev_b32_e32 v76, 16, v75
	v_and_b32_e32 v77, 0xffff0000, v75
	v_mul_f32_e32 v76, v82, v76
	v_mul_f32_e32 v77, v82, v77
	v_cvt_pk_bf16_f32 v75, v76, v77
	global_load_dwordx4 v[76:79], v[164:165], off
	v_mov_b32_e32 v82, v83
	s_waitcnt vmcnt(0)
	v_lshlrev_b32_e32 v84, 16, v76
	v_and_b32_e32 v85, 0xffff0000, v76
	v_mul_f32_e32 v84, v82, v84
	v_mul_f32_e32 v85, v82, v85
	v_cvt_pk_bf16_f32 v76, v84, v85
	v_lshlrev_b32_e32 v84, 16, v77
	v_and_b32_e32 v85, 0xffff0000, v77
	v_mul_f32_e32 v84, v82, v84
	v_mul_f32_e32 v85, v82, v85
	v_cvt_pk_bf16_f32 v77, v84, v85
	v_lshlrev_b32_e32 v84, 16, v78
	v_and_b32_e32 v85, 0xffff0000, v78
	v_mul_f32_e32 v84, v82, v84
	v_mul_f32_e32 v85, v82, v85
	v_cvt_pk_bf16_f32 v78, v84, v85
	v_lshlrev_b32_e32 v84, 16, v79
	v_and_b32_e32 v85, 0xffff0000, v79
	v_mul_f32_e32 v83, v82, v85
	v_mul_f32_e32 v82, v82, v84
	v_cvt_pk_bf16_f32 v79, v82, v83
	global_load_dwordx4 v[92:95], v[96:97], off
	global_load_dwordx4 v[88:91], v[98:99], off
	global_load_dwordx4 v[84:87], v[100:101], off
	global_load_dwordx4 v[80:83], v[102:103], off
	s_barrier
	ds_write_b128 v180, v[64:67]
	s_waitcnt vmcnt(3)
	ds_write_b128 v180, v[92:95] offset:18432
	ds_write_b128 v180, v[68:71] offset:4608
	s_waitcnt vmcnt(2)
	ds_write_b128 v180, v[88:91] offset:23040
	ds_write_b128 v180, v[72:75] offset:9216
	s_waitcnt vmcnt(1)
	ds_write_b128 v180, v[84:87] offset:27648
	ds_write_b128 v180, v[76:79] offset:13824
	s_waitcnt vmcnt(0)
	ds_write_b128 v180, v[80:83] offset:32256
	s_waitcnt lgkmcnt(0)
	s_barrier
	global_load_dwordx4 v[64:67], v[164:165], off offset:128
	ds_read2_b32 v[72:73], v229 offset0:192 offset1:224
	ds_read2_b32 v[80:81], v229 offset0:128 offset1:160
	s_waitcnt lgkmcnt(1)
	v_mov_b32_e32 v70, v73
	s_waitcnt lgkmcnt(0)
	v_mov_b32_e32 v78, v81
	s_waitcnt vmcnt(0)
	v_lshlrev_b32_e32 v68, 16, v67
	v_and_b32_e32 v69, 0xffff0000, v67
	v_mul_f32_e32 v68, v70, v68
	v_mul_f32_e32 v69, v70, v69
	v_cvt_pk_bf16_f32 v67, v68, v69
	v_lshlrev_b32_e32 v68, 16, v66
	v_and_b32_e32 v69, 0xffff0000, v66
	v_mul_f32_e32 v68, v70, v68
	v_mul_f32_e32 v69, v70, v69
	v_cvt_pk_bf16_f32 v66, v68, v69
	v_lshlrev_b32_e32 v68, 16, v65
	v_and_b32_e32 v69, 0xffff0000, v65
	v_mul_f32_e32 v68, v70, v68
	v_mul_f32_e32 v69, v70, v69
	v_cvt_pk_bf16_f32 v65, v68, v69
	v_lshlrev_b32_e32 v68, 16, v64
	v_and_b32_e32 v69, 0xffff0000, v64
	v_mul_f32_e32 v68, v70, v68
	v_mul_f32_e32 v69, v70, v69
	v_cvt_pk_bf16_f32 v64, v68, v69
	global_load_dwordx4 v[68:71], v[162:163], off offset:128
	s_waitcnt vmcnt(0)
	v_lshlrev_b32_e32 v74, 16, v71
	v_and_b32_e32 v75, 0xffff0000, v71
	v_mul_f32_e32 v74, v72, v74
	v_mul_f32_e32 v75, v72, v75
	v_cvt_pk_bf16_f32 v71, v74, v75
	v_lshlrev_b32_e32 v74, 16, v70
	v_and_b32_e32 v75, 0xffff0000, v70
	v_mul_f32_e32 v74, v72, v74
	v_mul_f32_e32 v75, v72, v75
	v_cvt_pk_bf16_f32 v70, v74, v75
	v_lshlrev_b32_e32 v74, 16, v69
	v_and_b32_e32 v75, 0xffff0000, v69
	v_mul_f32_e32 v74, v72, v74
	v_mul_f32_e32 v75, v72, v75
	v_cvt_pk_bf16_f32 v69, v74, v75
	v_lshlrev_b32_e32 v74, 16, v68
	v_and_b32_e32 v75, 0xffff0000, v68
	v_mul_f32_e32 v73, v72, v75
	v_mul_f32_e32 v72, v72, v74
	v_cvt_pk_bf16_f32 v68, v72, v73
	global_load_dwordx4 v[72:75], v[160:161], off offset:128
	s_waitcnt vmcnt(0)
	v_lshlrev_b32_e32 v76, 16, v75
	v_and_b32_e32 v77, 0xffff0000, v75
	v_mul_f32_e32 v76, v78, v76
	v_mul_f32_e32 v77, v78, v77
	v_cvt_pk_bf16_f32 v75, v76, v77
	v_lshlrev_b32_e32 v76, 16, v74
	v_and_b32_e32 v77, 0xffff0000, v74
	v_mul_f32_e32 v76, v78, v76
	v_mul_f32_e32 v77, v78, v77
	v_cvt_pk_bf16_f32 v74, v76, v77
	v_lshlrev_b32_e32 v76, 16, v73
	v_and_b32_e32 v77, 0xffff0000, v73
	v_mul_f32_e32 v76, v78, v76
	v_mul_f32_e32 v77, v78, v77
	v_cvt_pk_bf16_f32 v73, v76, v77
	v_lshlrev_b32_e32 v76, 16, v72
	v_and_b32_e32 v77, 0xffff0000, v72
	v_mul_f32_e32 v76, v78, v76
	v_mul_f32_e32 v77, v78, v77
	v_cvt_pk_bf16_f32 v72, v76, v77
	global_load_dwordx4 v[76:79], v[158:159], off offset:128
	s_waitcnt vmcnt(0)
	v_lshlrev_b32_e32 v82, 16, v79
	v_and_b32_e32 v83, 0xffff0000, v79
	v_mul_f32_e32 v82, v80, v82
	v_mul_f32_e32 v83, v80, v83
	v_cvt_pk_bf16_f32 v79, v82, v83
	v_lshlrev_b32_e32 v82, 16, v78
	v_and_b32_e32 v83, 0xffff0000, v78
	v_mul_f32_e32 v82, v80, v82
	v_mul_f32_e32 v83, v80, v83
	v_cvt_pk_bf16_f32 v78, v82, v83
	v_lshlrev_b32_e32 v82, 16, v77
	v_and_b32_e32 v83, 0xffff0000, v77
	v_mul_f32_e32 v82, v80, v82
	v_mul_f32_e32 v83, v80, v83
	v_cvt_pk_bf16_f32 v77, v82, v83
	v_lshlrev_b32_e32 v82, 16, v76
	v_and_b32_e32 v83, 0xffff0000, v76
	v_mul_f32_e32 v81, v80, v83
	v_mul_f32_e32 v80, v80, v82
	v_cvt_pk_bf16_f32 v76, v80, v81
	ds_read_b128 v[84:87], v241
	ds_read_b128 v[80:83], v241 offset:2304
	ds_read_b128 v[88:91], v181 offset:18432
	ds_read_b128 v[92:95], v181 offset:20736
	ds_read_b128 v[104:107], v181 offset:23040
	ds_read_b128 v[108:111], v181 offset:25344
	ds_read_b128 v[112:115], v181 offset:27648
	ds_read_b128 v[116:119], v181 offset:29952
	ds_read_b128 v[120:123], v181 offset:32256
	ds_read_b128 v[158:161], v181 offset:34560
	s_waitcnt lgkmcnt(7)
	v_mfma_f32_16x16x32_bf16 v[0:3], v[88:91], v[84:87], v[0:3]
	s_waitcnt lgkmcnt(6)
	v_mfma_f32_16x16x32_bf16 v[4:7], v[92:95], v[84:87], v[4:7]
	s_waitcnt lgkmcnt(5)
	v_mfma_f32_16x16x32_bf16 v[8:11], v[104:107], v[84:87], v[8:11]
	s_waitcnt lgkmcnt(4)
	v_mfma_f32_16x16x32_bf16 v[12:15], v[108:111], v[84:87], v[12:15]
	s_waitcnt lgkmcnt(3)
	v_mfma_f32_16x16x32_bf16 v[16:19], v[112:115], v[84:87], v[16:19]
	s_waitcnt lgkmcnt(2)
	v_mfma_f32_16x16x32_bf16 v[20:23], v[116:119], v[84:87], v[20:23]
	s_waitcnt lgkmcnt(1)
	v_mfma_f32_16x16x32_bf16 v[24:27], v[120:123], v[84:87], v[24:27]
	s_waitcnt lgkmcnt(0)
	v_mfma_f32_16x16x32_bf16 v[28:31], v[158:161], v[84:87], v[28:31]
	v_mfma_f32_16x16x32_bf16 v[32:35], v[88:91], v[80:83], v[32:35]
	v_mfma_f32_16x16x32_bf16 v[36:39], v[92:95], v[80:83], v[36:39]
	v_mfma_f32_16x16x32_bf16 v[40:43], v[104:107], v[80:83], v[40:43]
	v_mfma_f32_16x16x32_bf16 v[44:47], v[108:111], v[80:83], v[44:47]
	v_mfma_f32_16x16x32_bf16 v[48:51], v[112:115], v[80:83], v[48:51]
	v_mfma_f32_16x16x32_bf16 v[52:55], v[116:119], v[80:83], v[52:55]
	v_mfma_f32_16x16x32_bf16 v[56:59], v[120:123], v[80:83], v[56:59]
	v_mfma_f32_16x16x32_bf16 v[60:63], v[158:161], v[80:83], v[60:63]
	ds_read_b128 v[80:83], v241 offset:64
	ds_read_b128 v[84:87], v241 offset:2368
	ds_read_b128 v[88:91], v181 offset:18496
	ds_read_b128 v[92:95], v181 offset:20800
	ds_read_b128 v[104:107], v181 offset:23104
	ds_read_b128 v[108:111], v181 offset:25408
	ds_read_b128 v[112:115], v181 offset:27712
	ds_read_b128 v[116:119], v181 offset:30016
	ds_read_b128 v[120:123], v181 offset:32320
	ds_read_b128 v[158:161], v181 offset:34624
	s_waitcnt lgkmcnt(7)
	v_mfma_f32_16x16x32_bf16 v[0:3], v[88:91], v[80:83], v[0:3]
	s_waitcnt lgkmcnt(6)
	v_mfma_f32_16x16x32_bf16 v[4:7], v[92:95], v[80:83], v[4:7]
	s_waitcnt lgkmcnt(5)
	v_mfma_f32_16x16x32_bf16 v[8:11], v[104:107], v[80:83], v[8:11]
	s_waitcnt lgkmcnt(4)
	v_mfma_f32_16x16x32_bf16 v[12:15], v[108:111], v[80:83], v[12:15]
	s_waitcnt lgkmcnt(3)
	v_mfma_f32_16x16x32_bf16 v[16:19], v[112:115], v[80:83], v[16:19]
	s_waitcnt lgkmcnt(2)
	v_mfma_f32_16x16x32_bf16 v[20:23], v[116:119], v[80:83], v[20:23]
	s_waitcnt lgkmcnt(1)
	v_mfma_f32_16x16x32_bf16 v[24:27], v[120:123], v[80:83], v[24:27]
	s_waitcnt lgkmcnt(0)
	v_mfma_f32_16x16x32_bf16 v[28:31], v[158:161], v[80:83], v[28:31]
	v_mfma_f32_16x16x32_bf16 v[32:35], v[88:91], v[84:87], v[32:35]
	v_mfma_f32_16x16x32_bf16 v[36:39], v[92:95], v[84:87], v[36:39]
	v_mfma_f32_16x16x32_bf16 v[40:43], v[104:107], v[84:87], v[40:43]
	v_mfma_f32_16x16x32_bf16 v[44:47], v[108:111], v[84:87], v[44:47]
	v_mfma_f32_16x16x32_bf16 v[48:51], v[112:115], v[84:87], v[48:51]
	v_mfma_f32_16x16x32_bf16 v[52:55], v[116:119], v[84:87], v[52:55]
	v_mfma_f32_16x16x32_bf16 v[56:59], v[120:123], v[84:87], v[56:59]
	v_mfma_f32_16x16x32_bf16 v[60:63], v[158:161], v[84:87], v[60:63]
	global_load_dwordx4 v[92:95], v[96:97], off offset:128
	global_load_dwordx4 v[88:91], v[98:99], off offset:128
	global_load_dwordx4 v[84:87], v[100:101], off offset:128
	global_load_dwordx4 v[80:83], v[102:103], off offset:128
	s_barrier
	ds_write_b128 v180, v[76:79]
	s_waitcnt vmcnt(3)
	ds_write_b128 v180, v[92:95] offset:18432
	ds_write_b128 v180, v[72:75] offset:4608
	s_waitcnt vmcnt(2)
	ds_write_b128 v180, v[88:91] offset:23040
	ds_write_b128 v180, v[68:71] offset:9216
	s_waitcnt vmcnt(1)
	ds_write_b128 v180, v[84:87] offset:27648
	ds_write_b128 v180, v[64:67] offset:13824
	s_waitcnt vmcnt(0)
	ds_write_b128 v180, v[80:83] offset:32256
	s_waitcnt lgkmcnt(0)
	s_barrier
	ds_read_b128 v[64:67], v181 offset:34560
	ds_read_b128 v[68:71], v181 offset:32256
	ds_read_b128 v[72:75], v181 offset:29952
	ds_read_b128 v[76:79], v181 offset:27648
	ds_read_b128 v[80:83], v181 offset:25344
	ds_read_b128 v[84:87], v181 offset:23040
	ds_read_b128 v[88:91], v181 offset:20736
	ds_read_b128 v[92:95], v181 offset:18432
	ds_read_b128 v[96:99], v241 offset:2304
	ds_read_b128 v[100:103], v241
	s_waitcnt lgkmcnt(0)
	v_mfma_f32_16x16x32_bf16 v[8:11], v[84:87], v[100:103], v[8:11]
	v_mfma_f32_16x16x32_bf16 v[12:15], v[80:83], v[100:103], v[12:15]
	v_mfma_f32_16x16x32_bf16 v[16:19], v[76:79], v[100:103], v[16:19]
	v_mfma_f32_16x16x32_bf16 v[20:23], v[72:75], v[100:103], v[20:23]
	v_mfma_f32_16x16x32_bf16 v[84:87], v[84:87], v[96:99], v[40:43]
	v_mfma_f32_16x16x32_bf16 v[76:79], v[76:79], v[96:99], v[48:51]
	v_mfma_f32_16x16x32_bf16 v[0:3], v[92:95], v[100:103], v[0:3]
	v_mfma_f32_16x16x32_bf16 v[4:7], v[88:91], v[100:103], v[4:7]
	v_mfma_f32_16x16x32_bf16 v[24:27], v[68:71], v[100:103], v[24:27]
	v_mfma_f32_16x16x32_bf16 v[28:31], v[64:67], v[100:103], v[28:31]
	v_mfma_f32_16x16x32_bf16 v[92:95], v[92:95], v[96:99], v[32:35]
	v_mfma_f32_16x16x32_bf16 v[88:91], v[88:91], v[96:99], v[36:39]
	v_mfma_f32_16x16x32_bf16 v[80:83], v[80:83], v[96:99], v[44:47]
	v_mfma_f32_16x16x32_bf16 v[72:75], v[72:75], v[96:99], v[52:55]
	v_mfma_f32_16x16x32_bf16 v[68:71], v[68:71], v[96:99], v[56:59]
	v_mfma_f32_16x16x32_bf16 v[64:67], v[64:67], v[96:99], v[60:63]
	ds_read_b128 v[32:35], v241 offset:64
	ds_read_b128 v[96:99], v241 offset:2368
	ds_read_b128 v[100:103], v181 offset:18496
	ds_read_b128 v[104:107], v181 offset:20800
	ds_read_b128 v[108:111], v181 offset:23104
	ds_read_b128 v[112:115], v181 offset:25408
	ds_read_b128 v[116:119], v181 offset:27712
	ds_read_b128 v[120:123], v181 offset:30016
	ds_read_b128 v[158:161], v181 offset:32320
	ds_read_b128 v[162:165], v181 offset:34624
	s_waitcnt lgkmcnt(5)
	v_mfma_f32_16x16x32_bf16 v[52:55], v[108:111], v[32:35], v[8:11]
	s_waitcnt lgkmcnt(4)
	v_mfma_f32_16x16x32_bf16 v[48:51], v[112:115], v[32:35], v[12:15]
	s_waitcnt lgkmcnt(2)
	v_mfma_f32_16x16x32_bf16 v[40:43], v[120:123], v[32:35], v[20:23]
	v_mfma_f32_16x16x32_bf16 v[20:23], v[108:111], v[96:99], v[84:87]
	v_add_u32_e32 v108, s10, v182
	v_mfma_f32_16x16x32_bf16 v[12:15], v[116:119], v[96:99], v[76:79]
	s_nop 2
	v_mov_b64_e32 v[76:77], s[0:1]
	v_mfma_f32_16x16x32_bf16 v[44:47], v[116:119], v[32:35], v[16:19]
	v_mfma_f32_16x16x32_bf16 v[16:19], v[112:115], v[96:99], v[80:83]
	s_nop 2
	v_mad_i64_i32 v[82:83], s[0:1], v108, s96, v[76:77]
	v_readlane_b32 s0, v252, 43
	v_readlane_b32 s1, v252, 44
	v_mfma_f32_16x16x32_bf16 v[60:63], v[100:103], v[32:35], v[0:3]
	s_nop 0
	v_mov_b64_e32 v[78:79], s[0:1]
	v_mfma_f32_16x16x32_bf16 v[56:59], v[104:107], v[32:35], v[4:7]
	s_waitcnt lgkmcnt(1)
	v_mfma_f32_16x16x32_bf16 v[36:39], v[158:161], v[32:35], v[24:27]
	s_nop 2
	v_mov_b32_e32 v113, v61
	v_mov_b32_e32 v111, v60
	s_waitcnt lgkmcnt(0)
	v_mfma_f32_16x16x32_bf16 v[32:35], v[162:165], v[32:35], v[28:31]
	v_mfma_f32_16x16x32_bf16 v[28:31], v[100:103], v[96:99], v[92:95]
	v_mad_i64_i32 v[100:101], s[0:1], v108, s97, v[78:79]
	v_readlane_b32 s0, v252, 21
	v_mfma_f32_16x16x32_bf16 v[8:11], v[120:123], v[96:99], v[72:75]
	v_readlane_b32 s4, v252, 25
	v_readlane_b32 s5, v252, 26
	s_nop 2
	v_mov_b32_e32 v112, v29
	v_or_b32_e32 v74, s78, v185
	v_ashrrev_i32_e32 v75, 31, v74
	v_lshl_add_u64 v[72:73], v[74:75], 2, s[4:5]
	v_lshlrev_b64 v[74:75], 1, v[74:75]
	v_lshl_add_u64 v[84:85], v[82:83], 0, v[74:75]
	v_mfma_f32_16x16x32_bf16 v[24:27], v[104:107], v[96:99], v[88:91]
	v_mov_b32_e32 v110, v28
	v_mul_f32_e32 v112, v112, v112
	v_mul_f32_e32 v113, v113, v113
	v_mul_f32_e32 v94, v36, v36
	v_mul_f32_e32 v95, v37, v37
	v_mfma_f32_16x16x32_bf16 v[4:7], v[158:161], v[96:99], v[68:71]
	v_fma_f32 v110, v110, v110, v112
	v_fma_f32 v111, v111, v111, v113
	v_mov_b32_e32 v112, v30
	v_mov_b32_e32 v113, v62
	v_mfma_f32_16x16x32_bf16 v[0:3], v[162:165], v[96:99], v[64:67]
	s_nop 2
	global_load_dwordx4 v[64:67], v[72:73], off offset:16
	global_load_dwordx4 v[68:71], v[72:73], off
	global_load_dwordx4 v[96:99], v[84:85], off
	global_load_dwordx4 v[104:107], v[84:85], off offset:64
	v_fma_f32 v110, v112, v112, v110
	v_fma_f32 v111, v113, v113, v111
	v_mov_b32_e32 v112, v31
	v_mov_b32_e32 v113, v63
	v_fma_f32 v110, v112, v112, v110
	v_fma_f32 v111, v113, v113, v111
	v_mov_b32_e32 v112, v24
	v_mov_b32_e32 v113, v56
	v_fma_f32 v110, v112, v112, v110
	v_fma_f32 v111, v113, v113, v111
	v_mov_b32_e32 v112, v25
	v_mov_b32_e32 v113, v57
	v_fma_f32 v110, v112, v112, v110
	v_fma_f32 v111, v113, v113, v111
	v_mov_b32_e32 v112, v26
	v_mov_b32_e32 v113, v58
	v_fma_f32 v110, v112, v112, v110
	v_fma_f32 v111, v113, v113, v111
	v_mov_b32_e32 v112, v27
	v_mov_b32_e32 v113, v59
	v_fma_f32 v110, v112, v112, v110
	v_fma_f32 v111, v113, v113, v111
	v_mov_b32_e32 v112, v20
	v_mov_b32_e32 v113, v52
	v_fma_f32 v110, v112, v112, v110
	v_fma_f32 v111, v113, v113, v111
	v_mov_b32_e32 v112, v21
	v_mov_b32_e32 v113, v53
	v_fma_f32 v110, v112, v112, v110
	v_fma_f32 v111, v113, v113, v111
	v_mov_b32_e32 v112, v22
	v_mov_b32_e32 v113, v54
	v_fma_f32 v110, v112, v112, v110
	v_fma_f32 v111, v113, v113, v111
	v_mov_b32_e32 v112, v23
	v_mov_b32_e32 v113, v55
	v_fma_f32 v110, v112, v112, v110
	v_fma_f32 v111, v113, v113, v111
	v_mov_b32_e32 v112, v16
	v_mov_b32_e32 v113, v48
	v_fma_f32 v110, v112, v112, v110
	v_fma_f32 v111, v113, v113, v111
	v_mov_b32_e32 v112, v17
	v_mov_b32_e32 v113, v49
	v_fma_f32 v110, v112, v112, v110
	v_fma_f32 v111, v113, v113, v111
	v_mov_b32_e32 v112, v18
	v_mov_b32_e32 v113, v50
	v_fma_f32 v110, v112, v112, v110
	v_fma_f32 v111, v113, v113, v111
	v_mov_b32_e32 v112, v19
	v_mov_b32_e32 v113, v51
	v_fma_f32 v110, v112, v112, v110
	v_fma_f32 v111, v113, v113, v111
	v_mov_b32_e32 v112, v12
	v_mov_b32_e32 v113, v44
	v_fma_f32 v110, v112, v112, v110
	v_fma_f32 v111, v113, v113, v111
	v_mov_b32_e32 v112, v13
	v_mov_b32_e32 v113, v45
	v_fma_f32 v110, v112, v112, v110
	v_fma_f32 v111, v113, v113, v111
	v_mov_b32_e32 v112, v14
	v_mov_b32_e32 v113, v46
	v_fma_f32 v110, v112, v112, v110
	v_fma_f32 v111, v113, v113, v111
	v_mov_b32_e32 v112, v15
	v_mov_b32_e32 v113, v47
	v_fma_f32 v110, v112, v112, v110
	v_fma_f32 v111, v113, v113, v111
	v_mov_b32_e32 v112, v8
	v_mov_b32_e32 v113, v40
	v_fma_f32 v110, v112, v112, v110
	v_fma_f32 v111, v113, v113, v111
	v_mov_b32_e32 v112, v9
	v_mov_b32_e32 v113, v41
	v_fma_f32 v110, v112, v112, v110
	v_fma_f32 v111, v113, v113, v111
	v_mov_b32_e32 v112, v10
	v_mov_b32_e32 v113, v42
	v_mul_f32_e32 v116, v4, v4
	v_mul_f32_e32 v117, v5, v5
	v_fma_f32 v110, v112, v112, v110
	v_fma_f32 v111, v113, v113, v111
	v_mov_b32_e32 v112, v11
	v_mov_b32_e32 v113, v43
	v_fma_f32 v110, v112, v112, v110
	v_fma_f32 v111, v113, v113, v111
	v_mov_b32_e32 v112, v116
	v_mov_b32_e32 v113, v94
	v_mul_f32_e32 v90, v38, v38
	v_mul_f32_e32 v91, v39, v39
	v_mul_f32_e32 v114, v6, v6
	v_mul_f32_e32 v115, v7, v7
	v_add_f32_e32 v110, v112, v110
	v_add_f32_e32 v111, v113, v111
	v_mov_b32_e32 v94, v117
	v_add_f32_e32 v94, v94, v110
	v_add_f32_e32 v95, v95, v111
	v_mov_b32_e32 v110, v114
	v_mov_b32_e32 v111, v90
	v_mul_f32_e32 v86, v32, v32
	v_mul_f32_e32 v87, v33, v33
	v_mul_f32_e32 v118, v0, v0
	v_mul_f32_e32 v119, v1, v1
	v_add_f32_e32 v94, v110, v94
	v_add_f32_e32 v95, v111, v95
	v_mov_b32_e32 v90, v115
	s_waitcnt vmcnt(1)
	v_lshlrev_b32_e32 v82, 16, v96
	v_mul_f32_e32 v82, 0xbfb8aa3b, v82
	v_exp_f32_e32 v82, v82
	v_add_f32_e32 v90, v90, v94
	v_add_f32_e32 v91, v91, v95
	v_mov_b32_e32 v94, v118
	v_mov_b32_e32 v95, v86
	v_add_f32_e32 v82, 1.0, v82
	v_rcp_f32_e32 v88, v82
	v_and_b32_e32 v82, 0xffff0000, v96
	v_mul_f32_e32 v82, 0xbfb8aa3b, v82
	v_exp_f32_e32 v82, v82
	v_mul_f32_e32 v80, v34, v34
	v_mul_f32_e32 v81, v35, v35
	v_mul_f32_e32 v112, v2, v2
	v_mul_f32_e32 v113, v3, v3
	v_add_f32_e32 v90, v94, v90
	v_add_f32_e32 v91, v95, v91
	v_add_f32_e32 v82, 1.0, v82
	v_rcp_f32_e32 v89, v82
	v_lshlrev_b32_e32 v82, 16, v97
	v_mul_f32_e32 v82, 0xbfb8aa3b, v82
	v_exp_f32_e32 v82, v82
	v_mov_b32_e32 v86, v119
	v_add_f32_e32 v86, v86, v90
	v_add_f32_e32 v87, v87, v91
	v_mov_b32_e32 v90, v112
	v_add_f32_e32 v82, 1.0, v82
	v_rcp_f32_e32 v92, v82
	v_and_b32_e32 v82, 0xffff0000, v97
	v_mul_f32_e32 v82, 0xbfb8aa3b, v82
	v_exp_f32_e32 v82, v82
	v_mov_b32_e32 v91, v80
	v_add_f32_e32 v86, v90, v86
	v_add_f32_e32 v87, v91, v87
	v_mov_b32_e32 v80, v113
	v_add_f32_e32 v82, 1.0, v82
	v_rcp_f32_e32 v93, v82
	v_lshlrev_b32_e32 v82, 16, v98
	v_mul_f32_e32 v82, 0xbfb8aa3b, v82
	v_exp_f32_e32 v82, v82
	v_add_f32_e32 v80, v80, v86
	v_add_f32_e32 v81, v81, v87
	ds_bpermute_b32 v87, v183, v81
	ds_bpermute_b32 v86, v183, v80
	v_add_f32_e32 v82, 1.0, v82
	v_rcp_f32_e32 v96, v82
	v_and_b32_e32 v82, 0xffff0000, v98
	v_mul_f32_e32 v82, 0xbfb8aa3b, v82
	v_exp_f32_e32 v82, v82
	s_waitcnt lgkmcnt(0)
	v_add_f32_e32 v80, v80, v86
	v_add_f32_e32 v81, v81, v87
	ds_bpermute_b32 v87, v184, v81
	ds_bpermute_b32 v86, v184, v80
	v_add_f32_e32 v82, 1.0, v82
	v_rcp_f32_e32 v97, v82
	v_lshlrev_b32_e32 v82, 16, v99
	v_mul_f32_e32 v82, 0xbfb8aa3b, v82
	v_exp_f32_e32 v82, v82
	v_readlane_b32 s1, v252, 22
	s_waitcnt lgkmcnt(0)
	v_add_f32_e32 v80, v80, v86
	v_add_f32_e32 v81, v81, v87
	s_brev_b32 s0, 60
	v_fma_f32 v80, v80, s0, v156
	v_fma_f32 v81, v81, s0, v156
	s_mov_b32 s0, 0x800000
	v_mul_f32_e32 v86, 0x4b800000, v81
	v_cmp_gt_f32_e32 vcc, s0, v81
	v_add_f32_e32 v82, 1.0, v82
	v_rcp_f32_e32 v98, v82
	v_cndmask_b32_e32 v81, v81, v86, vcc
	v_and_b32_e32 v82, 0xffff0000, v99
	v_rsq_f32_e32 v81, v81
	v_mul_f32_e32 v82, 0xbfb8aa3b, v82
	v_exp_f32_e32 v82, v82
	s_waitcnt vmcnt(0)
	v_lshlrev_b32_e32 v102, 16, v105
	v_mul_f32_e32 v86, 0x45800000, v81
	v_cndmask_b32_e32 v86, v81, v86, vcc
	v_add_f32_e32 v82, 1.0, v82
	v_mul_f32_e32 v60, v60, v86
	v_mul_f32_e32 v61, v61, v86
	v_mul_f32_e32 v62, v62, v86
	v_mul_f32_e32 v63, v63, v86
	v_mul_f32_e32 v56, v56, v86
	v_mul_f32_e32 v57, v57, v86
	v_rcp_f32_e32 v99, v82
	v_mul_f32_e32 v60, v68, v60
	v_mul_f32_e32 v61, v69, v61
	v_mul_f32_e32 v62, v70, v62
	v_mul_f32_e32 v63, v71, v63
	v_mul_f32_e32 v56, v64, v56
	v_mul_f32_e32 v57, v65, v57
	v_mul_f32_e32 v60, v88, v60
	v_mul_f32_e32 v61, v89, v61
	v_mul_f32_e32 v62, v92, v62
	v_mul_f32_e32 v63, v93, v63
	v_mul_f32_e32 v56, v96, v56
	v_mul_f32_e32 v57, v97, v57
	v_cvt_pk_bf16_f32 v60, v60, v61
	v_cvt_pk_bf16_f32 v61, v62, v63
	v_cvt_pk_bf16_f32 v62, v56, v57
	v_mul_f32_e32 v56, v58, v86
	v_mul_f32_e32 v57, v59, v86
	v_lshl_add_u64 v[82:83], v[100:101], 0, v[74:75]
	v_mul_f32_e32 v56, v66, v56
	v_mul_f32_e32 v57, v67, v57
	v_lshlrev_b32_e32 v100, 16, v104
	v_mul_f32_e32 v56, v98, v56
	v_mul_f32_e32 v57, v99, v57
	v_and_b32_e32 v101, 0xffff0000, v104
	v_cvt_pk_bf16_f32 v63, v56, v57
	global_store_dwordx4 v[82:83], v[60:63], off
	global_load_dwordx4 v[56:59], v[72:73], off offset:144
	s_nop 0
	global_load_dwordx4 v[60:63], v[72:73], off offset:128
	v_and_b32_e32 v103, 0xffff0000, v105
	v_lshlrev_b32_e32 v104, 16, v106
	v_and_b32_e32 v105, 0xffff0000, v106
	v_mul_f32_e32 v100, 0xbfb8aa3b, v100
	v_mul_f32_e32 v101, 0xbfb8aa3b, v101
	v_mul_f32_e32 v102, 0xbfb8aa3b, v102
	v_mul_f32_e32 v103, 0xbfb8aa3b, v103
	v_mul_f32_e32 v104, 0xbfb8aa3b, v104
	v_mul_f32_e32 v105, 0xbfb8aa3b, v105
	v_exp_f32_e32 v100, v100
	v_exp_f32_e32 v101, v101
	v_exp_f32_e32 v102, v102
	v_exp_f32_e32 v103, v103
	v_exp_f32_e32 v104, v104
	v_exp_f32_e32 v105, v105
	v_lshlrev_b32_e32 v106, 16, v107
	v_and_b32_e32 v107, 0xffff0000, v107
	v_mul_f32_e32 v106, 0xbfb8aa3b, v106
	v_mul_f32_e32 v107, 0xbfb8aa3b, v107
	v_exp_f32_e32 v106, v106
	v_exp_f32_e32 v107, v107
	v_add_f32_e32 v100, 1.0, v100
	v_add_f32_e32 v101, 1.0, v101
	v_add_f32_e32 v102, 1.0, v102
	v_add_f32_e32 v103, 1.0, v103
	v_add_f32_e32 v104, 1.0, v104
	v_add_f32_e32 v105, 1.0, v105
	v_rcp_f32_e32 v100, v100
	v_rcp_f32_e32 v101, v101
	v_rcp_f32_e32 v102, v102
	v_rcp_f32_e32 v103, v103
	v_rcp_f32_e32 v104, v104
	v_rcp_f32_e32 v105, v105
	v_add_f32_e32 v106, 1.0, v106
	v_add_f32_e32 v107, 1.0, v107
	v_mul_f32_e32 v52, v52, v86
	v_mul_f32_e32 v53, v53, v86
	v_mul_f32_e32 v54, v54, v86
	v_mul_f32_e32 v55, v55, v86
	v_mul_f32_e32 v48, v48, v86
	v_mul_f32_e32 v49, v49, v86
	v_rcp_f32_e32 v106, v106
	v_rcp_f32_e32 v107, v107
	v_mul_f32_e32 v44, v44, v86
	v_mul_f32_e32 v45, v45, v86
	v_mul_f32_e32 v46, v46, v86
	v_mul_f32_e32 v47, v47, v86
	v_mul_f32_e32 v40, v40, v86
	v_mul_f32_e32 v41, v41, v86
	v_mul_f32_e32 v42, v42, v86
	v_mul_f32_e32 v43, v43, v86
	v_mul_f32_e32 v36, v36, v86
	v_mul_f32_e32 v37, v37, v86
	v_mul_f32_e32 v38, v38, v86
	v_mul_f32_e32 v39, v39, v86
	v_mul_f32_e32 v32, v32, v86
	v_mul_f32_e32 v33, v33, v86
	v_mul_f32_e32 v34, v34, v86
	v_mul_f32_e32 v35, v35, v86
	v_cmp_gt_f32_e64 s[78:79], s0, v80
	v_or_b32_e32 v108, 16, v108
	v_readlane_b32 s2, v252, 23
	v_readlane_b32 s3, v252, 24
	v_readlane_b32 s6, v252, 27
	v_readlane_b32 s7, v252, 28
	v_readlane_b32 s8, v252, 29
	v_readlane_b32 s9, v252, 30
	v_readlane_b32 s10, v252, 31
	v_readlane_b32 s11, v252, 32
	v_readlane_b32 s12, v252, 33
	v_readlane_b32 s13, v252, 34
	v_readlane_b32 s14, v252, 35
	v_readlane_b32 s15, v252, 36
	s_waitcnt vmcnt(1)
	v_mul_f32_e32 v48, v56, v48
	v_mul_f32_e32 v49, v57, v49
	s_waitcnt vmcnt(0)
	v_mul_f32_e32 v52, v60, v52
	v_mul_f32_e32 v53, v61, v53
	v_mul_f32_e32 v54, v62, v54
	v_mul_f32_e32 v55, v63, v55
	v_mul_f32_e32 v52, v100, v52
	v_mul_f32_e32 v53, v101, v53
	v_mul_f32_e32 v54, v102, v54
	v_mul_f32_e32 v55, v103, v55
	v_mul_f32_e32 v48, v104, v48
	v_mul_f32_e32 v49, v105, v49
	v_cvt_pk_bf16_f32 v52, v52, v53
	v_cvt_pk_bf16_f32 v53, v54, v55
	v_cvt_pk_bf16_f32 v54, v48, v49
	v_mul_f32_e32 v48, v50, v86
	v_mul_f32_e32 v49, v51, v86
	s_nop 0
	v_mul_f32_e32 v48, v58, v48
	v_mul_f32_e32 v49, v59, v49
	s_nop 0
	v_mul_f32_e32 v48, v106, v48
	v_mul_f32_e32 v49, v107, v49
	s_nop 0
	v_cvt_pk_bf16_f32 v55, v48, v49
	global_store_dwordx4 v[82:83], v[52:55], off offset:64
	global_load_dwordx4 v[48:51], v[72:73], off offset:272
	s_nop 0
	global_load_dwordx4 v[52:55], v[72:73], off offset:256
	global_load_dwordx4 v[56:59], v[84:85], off offset:128
	s_waitcnt vmcnt(2)
	v_mul_f32_e32 v40, v48, v40
	v_mul_f32_e32 v41, v49, v41
	s_waitcnt vmcnt(1)
	v_mul_f32_e32 v44, v52, v44
	v_mul_f32_e32 v45, v53, v45
	s_waitcnt vmcnt(0)
	v_lshlrev_b32_e32 v60, 16, v56
	v_and_b32_e32 v56, 0xffff0000, v56
	v_mul_f32_e32 v60, 0xbfb8aa3b, v60
	v_mul_f32_e32 v56, 0xbfb8aa3b, v56
	v_exp_f32_e32 v60, v60
	v_exp_f32_e32 v56, v56
	v_mul_f32_e32 v46, v54, v46
	v_mul_f32_e32 v47, v55, v47
	v_mul_f32_e32 v42, v50, v42
	v_mul_f32_e32 v43, v51, v43
	v_add_f32_e32 v60, 1.0, v60
	v_add_f32_e32 v56, 1.0, v56
	v_rcp_f32_e32 v60, v60
	v_rcp_f32_e32 v61, v56
	s_nop 0
	v_mul_f32_e32 v44, v44, v60
	v_mul_f32_e32 v45, v45, v61
	s_nop 0
	v_cvt_pk_bf16_f32 v44, v44, v45
	v_lshlrev_b32_e32 v45, 16, v57
	v_mul_f32_e32 v45, 0xbfb8aa3b, v45
	v_exp_f32_e32 v45, v45
	s_nop 0
	v_add_f32_e32 v45, 1.0, v45
	v_rcp_f32_e32 v52, v45
	v_and_b32_e32 v45, 0xffff0000, v57
	v_mul_f32_e32 v45, 0xbfb8aa3b, v45
	v_exp_f32_e32 v45, v45
	s_nop 0
	v_add_f32_e32 v45, 1.0, v45
	v_rcp_f32_e32 v53, v45
	s_nop 0
	v_mul_f32_e32 v46, v46, v52
	v_mul_f32_e32 v47, v47, v53
	s_nop 0
	v_cvt_pk_bf16_f32 v45, v46, v47
	v_lshlrev_b32_e32 v46, 16, v58
	v_and_b32_e32 v47, 0xffff0000, v58
	v_mul_f32_e32 v46, 0xbfb8aa3b, v46
	v_mul_f32_e32 v47, 0xbfb8aa3b, v47
	v_exp_f32_e32 v46, v46
	v_exp_f32_e32 v47, v47
	v_add_f32_e32 v46, 1.0, v46
	v_add_f32_e32 v47, 1.0, v47
	v_rcp_f32_e32 v46, v46
	v_rcp_f32_e32 v47, v47
	s_nop 0
	v_mul_f32_e32 v40, v40, v46
	v_mul_f32_e32 v41, v41, v47
	s_nop 0
	v_cvt_pk_bf16_f32 v46, v40, v41
	v_lshlrev_b32_e32 v40, 16, v59
	v_and_b32_e32 v41, 0xffff0000, v59
	v_mul_f32_e32 v40, 0xbfb8aa3b, v40
	v_mul_f32_e32 v41, 0xbfb8aa3b, v41
	v_exp_f32_e32 v40, v40
	v_exp_f32_e32 v41, v41
	v_add_f32_e32 v40, 1.0, v40
	v_add_f32_e32 v41, 1.0, v41
	v_rcp_f32_e32 v40, v40
	v_rcp_f32_e32 v41, v41
	s_nop 0
	v_mul_f32_e32 v40, v42, v40
	v_mul_f32_e32 v41, v43, v41
	s_nop 0
	v_cvt_pk_bf16_f32 v47, v40, v41
	global_store_dwordx4 v[82:83], v[44:47], off offset:128
	global_load_dwordx4 v[40:43], v[72:73], off offset:400
	s_nop 0
	global_load_dwordx4 v[44:47], v[72:73], off offset:384
	global_load_dwordx4 v[48:51], v[84:85], off offset:192
	s_waitcnt vmcnt(2)
	v_mul_f32_e32 v32, v32, v40
	v_mul_f32_e32 v33, v33, v41
	s_waitcnt vmcnt(1)
	v_mul_f32_e32 v36, v36, v44
	v_mul_f32_e32 v37, v37, v45
	s_waitcnt vmcnt(0)
	v_lshlrev_b32_e32 v52, 16, v48
	v_and_b32_e32 v48, 0xffff0000, v48
	v_mul_f32_e32 v52, 0xbfb8aa3b, v52
	v_mul_f32_e32 v48, 0xbfb8aa3b, v48
	v_exp_f32_e32 v52, v52
	v_exp_f32_e32 v48, v48
	v_mul_f32_e32 v38, v38, v46
	v_mul_f32_e32 v39, v39, v47
	v_mul_f32_e32 v34, v34, v42
	v_mul_f32_e32 v35, v35, v43
	v_add_f32_e32 v52, 1.0, v52
	v_add_f32_e32 v48, 1.0, v48
	v_rcp_f32_e32 v52, v52
	v_rcp_f32_e32 v53, v48
	s_nop 0
	v_mul_f32_e32 v36, v36, v52
	v_mul_f32_e32 v37, v37, v53
	s_nop 0
	v_cvt_pk_bf16_f32 v36, v36, v37
	v_lshlrev_b32_e32 v37, 16, v49
	v_mul_f32_e32 v37, 0xbfb8aa3b, v37
	v_exp_f32_e32 v37, v37
	s_nop 0
	v_add_f32_e32 v37, 1.0, v37
	v_rcp_f32_e32 v44, v37
	v_and_b32_e32 v37, 0xffff0000, v49
	v_mul_f32_e32 v37, 0xbfb8aa3b, v37
	v_exp_f32_e32 v37, v37
	s_nop 0
	v_add_f32_e32 v37, 1.0, v37
	v_rcp_f32_e32 v45, v37
	s_nop 0
	v_mul_f32_e32 v38, v38, v44
	v_mul_f32_e32 v39, v39, v45
	s_nop 0
	v_cvt_pk_bf16_f32 v37, v38, v39
	v_lshlrev_b32_e32 v38, 16, v50
	v_and_b32_e32 v39, 0xffff0000, v50
	v_mul_f32_e32 v38, 0xbfb8aa3b, v38
	v_mul_f32_e32 v39, 0xbfb8aa3b, v39
	v_exp_f32_e32 v38, v38
	v_exp_f32_e32 v39, v39
	v_add_f32_e32 v38, 1.0, v38
	v_add_f32_e32 v39, 1.0, v39
	v_rcp_f32_e32 v38, v38
	v_rcp_f32_e32 v39, v39
	s_nop 0
	v_mul_f32_e32 v32, v32, v38
	v_mul_f32_e32 v33, v33, v39
	s_nop 0
	v_cvt_pk_bf16_f32 v38, v32, v33
	v_lshlrev_b32_e32 v32, 16, v51
	v_and_b32_e32 v33, 0xffff0000, v51
	v_mul_f32_e32 v32, 0xbfb8aa3b, v32
	v_mul_f32_e32 v33, 0xbfb8aa3b, v33
	v_exp_f32_e32 v32, v32
	v_exp_f32_e32 v33, v33
	v_mad_i64_i32 v[50:51], s[0:1], v108, s97, v[78:79]
	v_add_f32_e32 v32, 1.0, v32
	v_add_f32_e32 v33, 1.0, v33
	v_rcp_f32_e32 v32, v32
	v_rcp_f32_e32 v33, v33
	s_nop 0
	v_mul_f32_e32 v32, v34, v32
	v_mul_f32_e32 v33, v35, v33
	s_nop 0
	v_cvt_pk_bf16_f32 v39, v32, v33
	v_mul_f32_e32 v32, 0x4b800000, v80
	v_cndmask_b32_e64 v32, v80, v32, s[78:79]
	v_rsq_f32_e32 v32, v32
	global_store_dwordx4 v[82:83], v[36:39], off offset:192
	v_mul_f32_e32 v33, 0x45800000, v32
	s_nop 0
	v_mad_i64_i32 v[38:39], s[0:1], v108, s96, v[76:77]
	v_lshl_add_u64 v[40:41], v[38:39], 0, v[74:75]
	v_cndmask_b32_e64 v36, v32, v33, s[78:79]
	global_load_dwordx4 v[32:35], v[72:73], off offset:16
	global_load_dwordx4 v[42:45], v[72:73], off
	global_load_dwordx4 v[46:49], v[40:41], off
	s_mov_b64 s[78:79], s[18:19]
	s_waitcnt vmcnt(0)
	v_lshlrev_b32_e32 v37, 16, v46
	v_mul_f32_e32 v37, 0xbfb8aa3b, v37
	v_exp_f32_e32 v37, v37
	s_nop 0
	v_add_f32_e32 v37, 1.0, v37
	v_rcp_f32_e32 v38, v37
	v_and_b32_e32 v37, 0xffff0000, v46
	v_mul_f32_e32 v37, 0xbfb8aa3b, v37
	v_exp_f32_e32 v37, v37
	s_nop 0
	v_add_f32_e32 v37, 1.0, v37
	v_rcp_f32_e32 v39, v37
	v_mul_f32_e32 v28, v28, v36
	v_mul_f32_e32 v29, v29, v36
	v_mul_f32_e32 v30, v30, v36
	v_mul_f32_e32 v31, v31, v36
	v_mul_f32_e32 v28, v42, v28
	v_mul_f32_e32 v29, v43, v29
	v_mul_f32_e32 v30, v44, v30
	v_mul_f32_e32 v31, v45, v31
	v_mul_f32_e32 v28, v38, v28
	v_mul_f32_e32 v29, v39, v29
	v_mul_f32_e32 v24, v24, v36
	v_mul_f32_e32 v25, v25, v36
	v_cvt_pk_bf16_f32 v28, v28, v29
	v_lshlrev_b32_e32 v29, 16, v47
	v_mul_f32_e32 v29, 0xbfb8aa3b, v29
	v_exp_f32_e32 v29, v29
	v_mul_f32_e32 v24, v32, v24
	v_mul_f32_e32 v25, v33, v25
	v_mul_f32_e32 v26, v26, v36
	v_mul_f32_e32 v27, v27, v36
	v_add_f32_e32 v29, 1.0, v29
	v_rcp_f32_e32 v38, v29
	v_and_b32_e32 v29, 0xffff0000, v47
	v_mul_f32_e32 v29, 0xbfb8aa3b, v29
	v_exp_f32_e32 v29, v29
	v_mul_f32_e32 v26, v34, v26
	v_mul_f32_e32 v27, v35, v27
	v_add_f32_e32 v29, 1.0, v29
	v_rcp_f32_e32 v39, v29
	s_nop 0
	v_mul_f32_e32 v30, v38, v30
	v_mul_f32_e32 v31, v39, v31
	s_nop 0
	v_cvt_pk_bf16_f32 v29, v30, v31
	v_lshlrev_b32_e32 v30, 16, v48
	v_and_b32_e32 v31, 0xffff0000, v48
	v_mul_f32_e32 v30, 0xbfb8aa3b, v30
	v_mul_f32_e32 v31, 0xbfb8aa3b, v31
	v_exp_f32_e32 v30, v30
	v_exp_f32_e32 v31, v31
	v_lshl_add_u64 v[38:39], v[50:51], 0, v[74:75]
	v_add_f32_e32 v30, 1.0, v30
	v_add_f32_e32 v31, 1.0, v31
	v_rcp_f32_e32 v30, v30
	v_rcp_f32_e32 v31, v31
	s_nop 0
	v_mul_f32_e32 v24, v24, v30
	v_mul_f32_e32 v25, v25, v31
	s_nop 0
	v_cvt_pk_bf16_f32 v30, v24, v25
	v_lshlrev_b32_e32 v24, 16, v49
	v_and_b32_e32 v25, 0xffff0000, v49
	v_mul_f32_e32 v24, 0xbfb8aa3b, v24
	v_mul_f32_e32 v25, 0xbfb8aa3b, v25
	v_exp_f32_e32 v24, v24
	v_exp_f32_e32 v25, v25
	v_add_f32_e32 v24, 1.0, v24
	v_add_f32_e32 v25, 1.0, v25
	v_rcp_f32_e32 v24, v24
	v_rcp_f32_e32 v25, v25
	s_nop 0
	v_mul_f32_e32 v24, v26, v24
	v_mul_f32_e32 v25, v27, v25
	s_nop 0
	v_cvt_pk_bf16_f32 v31, v24, v25
	global_store_dwordx4 v[38:39], v[28:31], off
	global_load_dwordx4 v[24:27], v[72:73], off offset:144
	s_nop 0
	global_load_dwordx4 v[28:31], v[72:73], off offset:128
	global_load_dwordx4 v[32:35], v[40:41], off offset:64
	s_waitcnt vmcnt(0)
	v_lshlrev_b32_e32 v37, 16, v32
	v_and_b32_e32 v32, 0xffff0000, v32
	v_mul_f32_e32 v37, 0xbfb8aa3b, v37
	v_mul_f32_e32 v32, 0xbfb8aa3b, v32
	v_exp_f32_e32 v37, v37
	v_exp_f32_e32 v32, v32
	v_add_f32_e32 v37, 1.0, v37
	v_add_f32_e32 v32, 1.0, v32
	v_rcp_f32_e32 v42, v37
	v_rcp_f32_e32 v43, v32
	v_mul_f32_e32 v20, v20, v36
	v_mul_f32_e32 v21, v21, v36
	v_mul_f32_e32 v22, v22, v36
	v_mul_f32_e32 v23, v23, v36
	v_mul_f32_e32 v20, v20, v28
	v_mul_f32_e32 v21, v21, v29
	v_mul_f32_e32 v22, v22, v30
	v_mul_f32_e32 v23, v23, v31
	v_mul_f32_e32 v20, v20, v42
	v_mul_f32_e32 v21, v21, v43
	v_mul_f32_e32 v16, v16, v36
	v_mul_f32_e32 v17, v17, v36
	v_cvt_pk_bf16_f32 v20, v20, v21
	v_lshlrev_b32_e32 v21, 16, v33
	v_mul_f32_e32 v21, 0xbfb8aa3b, v21
	v_exp_f32_e32 v21, v21
	v_mul_f32_e32 v16, v16, v24
	v_mul_f32_e32 v17, v17, v25
	v_mul_f32_e32 v18, v18, v36
	v_mul_f32_e32 v19, v19, v36
	v_mul_f32_e32 v12, v12, v36
	v_mul_f32_e32 v13, v13, v36
	v_add_f32_e32 v21, 1.0, v21
	v_rcp_f32_e32 v28, v21
	v_and_b32_e32 v21, 0xffff0000, v33
	v_mul_f32_e32 v21, 0xbfb8aa3b, v21
	v_exp_f32_e32 v21, v21
	v_mul_f32_e32 v18, v18, v26
	v_mul_f32_e32 v19, v19, v27
	v_mul_f32_e32 v14, v14, v36
	v_mul_f32_e32 v15, v15, v36
	v_mul_f32_e32 v8, v8, v36
	v_mul_f32_e32 v9, v9, v36
	v_add_f32_e32 v21, 1.0, v21
	v_rcp_f32_e32 v29, v21
	v_mul_f32_e32 v10, v10, v36
	v_mul_f32_e32 v11, v11, v36
	v_mul_f32_e32 v4, v4, v36
	v_mul_f32_e32 v5, v5, v36
	v_mul_f32_e32 v6, v6, v36
	v_mul_f32_e32 v7, v7, v36
	v_mul_f32_e32 v22, v22, v28
	v_mul_f32_e32 v23, v23, v29
	v_mul_f32_e32 v0, v0, v36
	v_mul_f32_e32 v1, v1, v36
	v_cvt_pk_bf16_f32 v21, v22, v23
	v_lshlrev_b32_e32 v22, 16, v34
	v_and_b32_e32 v23, 0xffff0000, v34
	v_mul_f32_e32 v22, 0xbfb8aa3b, v22
	v_mul_f32_e32 v23, 0xbfb8aa3b, v23
	v_exp_f32_e32 v22, v22
	v_exp_f32_e32 v23, v23
	v_mul_f32_e32 v2, v2, v36
	v_mul_f32_e32 v3, v3, v36
	v_add_f32_e32 v22, 1.0, v22
	v_add_f32_e32 v23, 1.0, v23
	v_rcp_f32_e32 v22, v22
	v_rcp_f32_e32 v23, v23
	s_nop 0
	v_mul_f32_e32 v16, v16, v22
	v_mul_f32_e32 v17, v17, v23
	s_nop 0
	v_cvt_pk_bf16_f32 v22, v16, v17
	v_lshlrev_b32_e32 v16, 16, v35
	v_and_b32_e32 v17, 0xffff0000, v35
	v_mul_f32_e32 v16, 0xbfb8aa3b, v16
	v_mul_f32_e32 v17, 0xbfb8aa3b, v17
	v_exp_f32_e32 v16, v16
	v_exp_f32_e32 v17, v17
	v_add_f32_e32 v16, 1.0, v16
	v_add_f32_e32 v17, 1.0, v17
	v_rcp_f32_e32 v16, v16
	v_rcp_f32_e32 v17, v17
	s_nop 0
	v_mul_f32_e32 v16, v18, v16
	v_mul_f32_e32 v17, v19, v17
	s_nop 0
	v_cvt_pk_bf16_f32 v23, v16, v17
	global_store_dwordx4 v[38:39], v[20:23], off offset:64
	global_load_dwordx4 v[16:19], v[72:73], off offset:272
	s_nop 0
	global_load_dwordx4 v[20:23], v[72:73], off offset:256
	global_load_dwordx4 v[24:27], v[40:41], off offset:128
	s_waitcnt vmcnt(2)
	v_mul_f32_e32 v8, v8, v16
	v_mul_f32_e32 v9, v9, v17
	s_waitcnt vmcnt(1)
	v_mul_f32_e32 v12, v12, v20
	v_mul_f32_e32 v13, v13, v21
	s_waitcnt vmcnt(0)
	v_lshlrev_b32_e32 v28, 16, v24
	v_and_b32_e32 v24, 0xffff0000, v24
	v_mul_f32_e32 v28, 0xbfb8aa3b, v28
	v_mul_f32_e32 v24, 0xbfb8aa3b, v24
	v_exp_f32_e32 v28, v28
	v_exp_f32_e32 v24, v24
	v_mul_f32_e32 v14, v14, v22
	v_mul_f32_e32 v15, v15, v23
	v_mul_f32_e32 v10, v10, v18
	v_mul_f32_e32 v11, v11, v19
	v_add_f32_e32 v28, 1.0, v28
	v_add_f32_e32 v24, 1.0, v24
	v_rcp_f32_e32 v28, v28
	v_rcp_f32_e32 v29, v24
	s_nop 0
	v_mul_f32_e32 v12, v12, v28
	v_mul_f32_e32 v13, v13, v29
	s_nop 0
	v_cvt_pk_bf16_f32 v12, v12, v13
	v_lshlrev_b32_e32 v13, 16, v25
	v_mul_f32_e32 v13, 0xbfb8aa3b, v13
	v_exp_f32_e32 v13, v13
	s_nop 0
	v_add_f32_e32 v13, 1.0, v13
	v_rcp_f32_e32 v20, v13
	v_and_b32_e32 v13, 0xffff0000, v25
	v_mul_f32_e32 v13, 0xbfb8aa3b, v13
	v_exp_f32_e32 v13, v13
	s_nop 0
	v_add_f32_e32 v13, 1.0, v13
	v_rcp_f32_e32 v21, v13
	s_nop 0
	v_mul_f32_e32 v14, v14, v20
	v_mul_f32_e32 v15, v15, v21
	s_nop 0
	v_cvt_pk_bf16_f32 v13, v14, v15
	v_lshlrev_b32_e32 v14, 16, v26
	v_and_b32_e32 v15, 0xffff0000, v26
	v_mul_f32_e32 v14, 0xbfb8aa3b, v14
	v_mul_f32_e32 v15, 0xbfb8aa3b, v15
	v_exp_f32_e32 v14, v14
	v_exp_f32_e32 v15, v15
	v_add_f32_e32 v14, 1.0, v14
	v_add_f32_e32 v15, 1.0, v15
	v_rcp_f32_e32 v14, v14
	v_rcp_f32_e32 v15, v15
	s_nop 0
	v_mul_f32_e32 v8, v8, v14
	v_mul_f32_e32 v9, v9, v15
	s_nop 0
	v_cvt_pk_bf16_f32 v14, v8, v9
	v_lshlrev_b32_e32 v8, 16, v27
	v_and_b32_e32 v9, 0xffff0000, v27
	v_mul_f32_e32 v8, 0xbfb8aa3b, v8
	v_mul_f32_e32 v9, 0xbfb8aa3b, v9
	v_exp_f32_e32 v8, v8
	v_exp_f32_e32 v9, v9
	v_add_f32_e32 v8, 1.0, v8
	v_add_f32_e32 v9, 1.0, v9
	v_rcp_f32_e32 v8, v8
	v_rcp_f32_e32 v9, v9
	s_nop 0
	v_mul_f32_e32 v8, v10, v8
	v_mul_f32_e32 v9, v11, v9
	s_nop 0
	v_cvt_pk_bf16_f32 v15, v8, v9
	global_store_dwordx4 v[38:39], v[12:15], off offset:128
	global_load_dwordx4 v[8:11], v[72:73], off offset:400
	s_nop 0
	global_load_dwordx4 v[12:15], v[72:73], off offset:384
	global_load_dwordx4 v[16:19], v[40:41], off offset:192
	s_waitcnt vmcnt(2)
	v_mul_f32_e32 v0, v0, v8
	v_mul_f32_e32 v1, v1, v9
	s_waitcnt vmcnt(1)
	v_mul_f32_e32 v4, v4, v12
	v_mul_f32_e32 v5, v5, v13
	s_waitcnt vmcnt(0)
	v_lshlrev_b32_e32 v20, 16, v16
	v_and_b32_e32 v16, 0xffff0000, v16
	v_mul_f32_e32 v20, 0xbfb8aa3b, v20
	v_mul_f32_e32 v16, 0xbfb8aa3b, v16
	v_exp_f32_e32 v20, v20
	v_exp_f32_e32 v16, v16
	v_mul_f32_e32 v6, v6, v14
	v_mul_f32_e32 v7, v7, v15
	v_mul_f32_e32 v2, v2, v10
	v_mul_f32_e32 v3, v3, v11
	v_add_f32_e32 v20, 1.0, v20
	v_add_f32_e32 v16, 1.0, v16
	v_rcp_f32_e32 v20, v20
	v_rcp_f32_e32 v21, v16
	s_nop 0
	v_mul_f32_e32 v4, v4, v20
	v_mul_f32_e32 v5, v5, v21
	s_nop 0
	v_cvt_pk_bf16_f32 v4, v4, v5
	v_lshlrev_b32_e32 v5, 16, v17
	v_mul_f32_e32 v5, 0xbfb8aa3b, v5
	v_exp_f32_e32 v5, v5
	s_nop 0
	v_add_f32_e32 v5, 1.0, v5
	v_rcp_f32_e32 v12, v5
	v_and_b32_e32 v5, 0xffff0000, v17
	v_mul_f32_e32 v5, 0xbfb8aa3b, v5
	v_exp_f32_e32 v5, v5
	s_nop 0
	v_add_f32_e32 v5, 1.0, v5
	v_rcp_f32_e32 v13, v5
	s_nop 0
	v_mul_f32_e32 v6, v6, v12
	v_mul_f32_e32 v7, v7, v13
	s_nop 0
	v_cvt_pk_bf16_f32 v5, v6, v7
	v_lshlrev_b32_e32 v6, 16, v18
	v_and_b32_e32 v7, 0xffff0000, v18
	v_mul_f32_e32 v6, 0xbfb8aa3b, v6
	v_mul_f32_e32 v7, 0xbfb8aa3b, v7
	v_exp_f32_e32 v6, v6
	v_exp_f32_e32 v7, v7
	v_add_f32_e32 v6, 1.0, v6
	v_add_f32_e32 v7, 1.0, v7
	v_rcp_f32_e32 v6, v6
	v_rcp_f32_e32 v7, v7
	s_nop 0
	v_mul_f32_e32 v0, v0, v6
	v_mul_f32_e32 v1, v1, v7
	s_nop 0
	v_cvt_pk_bf16_f32 v6, v0, v1
	v_lshlrev_b32_e32 v0, 16, v19
	v_and_b32_e32 v1, 0xffff0000, v19
	v_mul_f32_e32 v0, 0xbfb8aa3b, v0
	v_mul_f32_e32 v1, 0xbfb8aa3b, v1
	v_exp_f32_e32 v0, v0
	v_exp_f32_e32 v1, v1
	v_add_f32_e32 v0, 1.0, v0
	v_add_f32_e32 v1, 1.0, v1
	v_rcp_f32_e32 v0, v0
	v_rcp_f32_e32 v1, v1
	s_nop 0
	v_mul_f32_e32 v0, v2, v0
	v_mul_f32_e32 v1, v3, v1
	s_nop 0
	v_cvt_pk_bf16_f32 v7, v0, v1
	global_store_dwordx4 v[38:39], v[4:7], off offset:192
	s_load_dword s0, s[18:19], 0xc8
	s_waitcnt lgkmcnt(0)
	s_add_i32 s33, s33, s0
	s_cmpk_gt_i32 s33, 0x317
	s_cbranch_scc1 .LBB0_748

.LBB0_849:
	s_or_b64 exec, exec, s[34:35]
	v_ashrrev_i32_e32 v35, 31, v34
	v_lshlrev_b64 v[34:35], 12, v[34:35]
	v_lshl_add_u64 v[34:35], v[36:37], 0, v[34:35]
	v_lshl_add_u64 v[36:37], s[94:95], 0, v[38:39]
	v_lshl_add_u64 v[38:39], v[36:37], 0, s[30:31]
	v_lshl_add_u64 v[46:47], v[34:35], 0, v[72:73]
	v_lshl_add_u64 v[34:35], v[38:39], 0, v[72:73]
	global_load_dwordx4 v[34:37], v[34:35], off
	s_nop 0
	global_load_dwordx4 v[76:79], v[46:47], off
	v_ashrrev_i32_e32 v33, 31, v32
	v_lshlrev_b64 v[32:33], 12, v[32:33]
	v_lshl_add_u64 v[32:33], v[42:43], 0, v[32:33]
	v_lshl_add_u64 v[50:51], v[32:33], 0, v[72:73]
	v_lshl_add_u64 v[42:43], v[74:75], 2, v[38:39]
	s_add_i32 s40, s40, s33
	s_cmpk_lt_i32 s40, 0x400
	s_waitcnt vmcnt(0)
	v_fma_f32 v30, v30, v36, v78
	v_fma_f32 v31, v31, v37, v79
	v_fma_f32 v28, v28, v34, v76
	v_fma_f32 v29, v29, v35, v77
	global_store_dwordx4 v[50:51], v[28:31], off
	global_load_dwordx4 v[28:31], v[46:47], off offset:16
	s_nop 0
	global_load_dwordx4 v[32:35], v[42:43], off
	v_lshl_add_u64 v[36:37], v[60:61], 2, v[38:39]
	s_waitcnt vmcnt(0)
	v_fma_f32 v26, v26, v34, v30
	v_fma_f32 v27, v27, v35, v31
	v_fma_f32 v24, v24, v32, v28
	v_fma_f32 v25, v25, v33, v29
	global_store_dwordx4 v[50:51], v[24:27], off offset:16
	global_load_dwordx4 v[24:27], v[46:47], off offset:128
	s_nop 0
	global_load_dwordx4 v[28:31], v[36:37], off
	v_lshl_add_u64 v[32:33], v[56:57], 2, v[38:39]
	s_waitcnt vmcnt(0)
	v_fma_f32 v22, v22, v30, v26
	v_fma_f32 v23, v23, v31, v27
	v_fma_f32 v20, v20, v28, v24
	v_fma_f32 v21, v21, v29, v25
	global_store_dwordx4 v[50:51], v[20:23], off offset:128
	global_load_dwordx4 v[20:23], v[46:47], off offset:144
	s_nop 0
	global_load_dwordx4 v[24:27], v[32:33], off
	v_lshl_add_u64 v[28:29], v[52:53], 2, v[38:39]
	s_waitcnt vmcnt(0)
	v_fma_f32 v18, v18, v26, v22
	v_fma_f32 v19, v19, v27, v23
	v_fma_f32 v16, v16, v24, v20
	v_fma_f32 v17, v17, v25, v21
	global_store_dwordx4 v[50:51], v[16:19], off offset:144
	global_load_dwordx4 v[16:19], v[46:47], off offset:256
	s_nop 0
	global_load_dwordx4 v[20:23], v[28:29], off
	v_lshl_add_u64 v[24:25], v[48:49], 2, v[38:39]
	s_waitcnt vmcnt(0)
	v_fma_f32 v14, v14, v22, v18
	v_fma_f32 v15, v15, v23, v19
	v_fma_f32 v12, v12, v20, v16
	v_fma_f32 v13, v13, v21, v17
	global_store_dwordx4 v[50:51], v[12:15], off offset:256
	global_load_dwordx4 v[12:15], v[46:47], off offset:272
	s_nop 0
	global_load_dwordx4 v[16:19], v[24:25], off
	v_lshl_add_u64 v[20:21], v[44:45], 2, v[38:39]
	s_waitcnt vmcnt(0)
	v_fma_f32 v10, v10, v18, v14
	v_fma_f32 v11, v11, v19, v15
	v_fma_f32 v8, v8, v16, v12
	v_fma_f32 v9, v9, v17, v13
	global_store_dwordx4 v[50:51], v[8:11], off offset:272
	global_load_dwordx4 v[8:11], v[46:47], off offset:384
	s_nop 0
	global_load_dwordx4 v[12:15], v[20:21], off
	v_lshl_add_u64 v[16:17], v[40:41], 2, v[38:39]
	s_waitcnt vmcnt(0)
	v_fma_f32 v2, v2, v14, v10
	v_fma_f32 v3, v3, v15, v11
	v_fma_f32 v0, v0, v12, v8
	v_fma_f32 v1, v1, v13, v9
	global_store_dwordx4 v[50:51], v[0:3], off offset:384
	global_load_dwordx4 v[0:3], v[46:47], off offset:400
	s_nop 0
	global_load_dwordx4 v[8:11], v[16:17], off
	s_waitcnt vmcnt(0)
	v_fma_f32 v2, v6, v10, v2
	v_fma_f32 v3, v7, v11, v3
	v_fma_f32 v0, v4, v8, v0
	v_fma_f32 v1, v5, v9, v1
	global_store_dwordx4 v[50:51], v[0:3], off offset:400
	s_cbranch_scc0 .LBB0_872

.LBB0_864:
	s_or_b64 exec, exec, s[34:35]
	v_ashrrev_i32_e32 v73, 31, v72
	v_lshlrev_b64 v[72:73], 12, v[72:73]
	v_lshl_or_b32 v108, s41, 7, v83
	v_lshl_add_u64 v[76:77], v[76:77], 0, v[72:73]
	v_lshl_add_u64 v[72:73], s[94:95], 0, v[78:79]
	v_ashrrev_i32_e32 v109, 31, v108
	v_lshl_add_u64 v[106:107], v[72:73], 0, s[30:31]
	v_lshlrev_b64 v[72:73], 2, v[108:109]
	v_lshl_add_u64 v[110:111], v[76:77], 0, v[72:73]
	v_lshl_add_u64 v[102:103], v[106:107], 0, v[72:73]
	global_load_dwordx4 v[76:79], v[110:111], off
	v_ashrrev_i32_e32 v75, 31, v74
	global_load_dwordx4 v[102:105], v[102:103], off
	v_lshlrev_b64 v[112:113], 12, v[74:75]
	v_lshl_add_u64 v[80:81], v[80:81], 0, v[112:113]
	v_or_b32_e32 v74, 4, v108
	v_lshl_add_u64 v[80:81], v[80:81], 0, v[72:73]
	v_ashrrev_i32_e32 v75, 31, v74
	v_lshl_add_u64 v[112:113], v[74:75], 2, v[106:107]
	v_readlane_b32 s44, v252, 5
	v_readlane_b32 s48, v252, 9
	v_readlane_b32 s49, v252, 10
	v_readlane_b32 s45, v252, 6
	v_readlane_b32 s46, v252, 7
	v_readlane_b32 s47, v252, 8
	v_readlane_b32 s50, v252, 11
	v_readlane_b32 s51, v252, 12
	v_readlane_b32 s52, v252, 13
	v_readlane_b32 s53, v252, 14
	v_readlane_b32 s54, v252, 15
	v_readlane_b32 s55, v252, 16
	v_readlane_b32 s56, v252, 17
	v_readlane_b32 s57, v252, 18
	v_readlane_b32 s58, v252, 19
	v_readlane_b32 s59, v252, 20
	s_waitcnt vmcnt(0)
	v_fma_f32 v62, v62, v104, v78
	v_fma_f32 v63, v63, v105, v79
	v_fma_f32 v60, v60, v102, v76
	v_fma_f32 v61, v61, v103, v77
	global_store_dwordx4 v[80:81], v[60:63], off
	global_load_dwordx4 v[76:79], v[110:111], off offset:16
	global_load_dwordx4 v[102:105], v[112:113], off
	v_or_b32_e32 v60, 32, v108
	v_ashrrev_i32_e32 v61, 31, v60
	v_lshl_add_u64 v[62:63], v[60:61], 2, v[106:107]
	s_waitcnt vmcnt(0)
	v_fma_f32 v58, v58, v104, v78
	v_fma_f32 v59, v59, v105, v79
	v_fma_f32 v56, v56, v102, v76
	v_fma_f32 v57, v57, v103, v77
	global_store_dwordx4 v[80:81], v[56:59], off offset:16
	global_load_dwordx4 v[76:79], v[110:111], off offset:128
	global_load_dwordx4 v[102:105], v[62:63], off
	v_or_b32_e32 v56, 36, v108
	v_ashrrev_i32_e32 v57, 31, v56
	v_lshl_add_u64 v[58:59], v[56:57], 2, v[106:107]
	s_waitcnt vmcnt(0)
	v_fma_f32 v54, v54, v104, v78
	v_fma_f32 v55, v55, v105, v79
	v_fma_f32 v52, v52, v102, v76
	v_fma_f32 v53, v53, v103, v77
	global_store_dwordx4 v[80:81], v[52:55], off offset:128
	global_load_dwordx4 v[76:79], v[110:111], off offset:144
	global_load_dwordx4 v[102:105], v[58:59], off
	v_or_b32_e32 v52, 64, v108
	v_ashrrev_i32_e32 v53, 31, v52
	v_lshl_add_u64 v[54:55], v[52:53], 2, v[106:107]
	s_waitcnt vmcnt(0)
	v_fma_f32 v50, v50, v104, v78
	v_fma_f32 v51, v51, v105, v79
	v_fma_f32 v48, v48, v102, v76
	v_fma_f32 v49, v49, v103, v77
	global_store_dwordx4 v[80:81], v[48:51], off offset:144
	global_load_dwordx4 v[76:79], v[110:111], off offset:256
	global_load_dwordx4 v[102:105], v[54:55], off
	v_or_b32_e32 v48, 0x44, v108
	v_ashrrev_i32_e32 v49, 31, v48
	v_lshl_add_u64 v[50:51], v[48:49], 2, v[106:107]
	s_waitcnt vmcnt(0)
	v_fma_f32 v46, v46, v104, v78
	v_fma_f32 v47, v47, v105, v79
	v_fma_f32 v44, v44, v102, v76
	v_fma_f32 v45, v45, v103, v77
	global_store_dwordx4 v[80:81], v[44:47], off offset:256
	global_load_dwordx4 v[76:79], v[110:111], off offset:272
	global_load_dwordx4 v[102:105], v[50:51], off
	v_or_b32_e32 v44, 0x60, v108
	v_ashrrev_i32_e32 v45, 31, v44
	v_lshl_add_u64 v[46:47], v[44:45], 2, v[106:107]
	s_waitcnt vmcnt(0)
	v_fma_f32 v42, v42, v104, v78
	v_fma_f32 v43, v43, v105, v79
	v_fma_f32 v40, v40, v102, v76
	v_fma_f32 v41, v41, v103, v77
	global_store_dwordx4 v[80:81], v[40:43], off offset:272
	global_load_dwordx4 v[76:79], v[110:111], off offset:384
	global_load_dwordx4 v[102:105], v[46:47], off
	v_or_b32_e32 v40, 0x64, v108
	v_ashrrev_i32_e32 v41, 31, v40
	v_lshl_add_u64 v[42:43], v[40:41], 2, v[106:107]
	s_waitcnt vmcnt(0)
	v_fma_f32 v38, v38, v104, v78
	v_fma_f32 v39, v39, v105, v79
	v_fma_f32 v36, v36, v102, v76
	v_fma_f32 v37, v37, v103, v77
	global_store_dwordx4 v[80:81], v[36:39], off offset:384
	global_load_dwordx4 v[76:79], v[110:111], off offset:400
	global_load_dwordx4 v[102:105], v[42:43], off
	v_add_u32_e32 v38, s42, v92
	v_mul_hi_i32 v39, v38, s36
	v_lshrrev_b32_e32 v42, 31, v39
	v_ashrrev_i32_e32 v39, 11, v39
	v_add_u32_e32 v42, v39, v42
	v_mad_i32_i24 v38, v42, s37, v38
	v_lshlrev_b32_e32 v39, 13, v42
	v_mov_b64_e32 v[36:37], s[48:49]
	v_cmp_lt_i32_e32 vcc, s38, v38
	s_waitcnt vmcnt(0)
	v_fma_f32 v34, v34, v104, v78
	v_fma_f32 v35, v35, v105, v79
	v_fma_f32 v32, v32, v102, v76
	v_fma_f32 v33, v33, v103, v77
	global_store_dwordx4 v[80:81], v[32:35], off offset:400
	s_nop 1
	v_add3_u32 v32, v39, v38, s39
	s_and_saveexec_b64 s[34:35], vcc
	s_xor_b64 s[34:35], exec, s[34:35]
	s_cbranch_execz .LBB0_866
	v_readlane_b32 s44, v252, 5
	v_readlane_b32 s45, v252, 6
	v_add3_u32 v34, v39, v38, s39
	v_readlane_b32 s46, v252, 7
	v_mov_b64_e32 v[36:37], s[44:45]
	v_readlane_b32 s47, v252, 8
	v_readlane_b32 s48, v252, 9
	v_readlane_b32 s49, v252, 10
	v_readlane_b32 s50, v252, 11
	v_readlane_b32 s51, v252, 12
	v_readlane_b32 s52, v252, 13
	v_readlane_b32 s53, v252, 14
	v_readlane_b32 s54, v252, 15
	v_readlane_b32 s55, v252, 16
	v_readlane_b32 s56, v252, 17
	v_readlane_b32 s57, v252, 18
	v_readlane_b32 s58, v252, 19
	v_readlane_b32 s59, v252, 20
	s_or_saveexec_b64 s[34:35], s[34:35]
	v_lshl_add_u32 v33, v42, 8, v38
	s_xor_b64 exec, exec, s[34:35]
	s_branch .LBB0_867

.LBB0_874:
	s_ashr_i32 s50, s48, 6
	s_bfe_u32 s67, s48, 0x10005
	s_mulk_i32 s50, 0x42
	s_or_b32 s50, s50, s67
	s_and_b32 s8, s48, 3
	s_bfe_u32 s49, s48, 0x30002
	s_mul_i32 s68, s50, 0x44000
	s_mul_hi_i32 s67, s50, 0x44000
	s_add_u32 s68, s2, s68
	s_addc_u32 s67, s3, s67
	s_lshl_b32 s8, s8, 9
	s_add_u32 s68, s68, s8
	s_mul_i32 s70, s49, 0x44000
	s_addc_u32 s69, s67, 0
	s_add_u32 s67, s4, s70
	v_lshl_add_u64 v[0:1], s[68:69], 0, v[10:11]
	s_addc_u32 s69, s5, 0
	s_add_u32 s68, s67, s8
	v_readfirstlane_b32 s66, v18
	s_addc_u32 s69, s69, 0
	v_readfirstlane_b32 s59, v19
	v_lshl_add_u64 v[0:1], v[0:1], 0, v[12:13]
	s_mov_b32 m0, s66
	v_lshl_add_u64 v[2:3], s[68:69], 0, v[14:15]
	s_waitcnt vmcnt(63) expcnt(7) lgkmcnt(15)
	s_barrier
	v_readfirstlane_b32 s60, v20
	global_load_lds_dwordx4 v[0:1], off
	v_lshl_add_u64 v[2:3], v[2:3], 0, v[12:13]
	s_mov_b32 m0, s59
	v_readfirstlane_b32 s61, v21
	v_lshl_add_u64 v[4:5], v[0:1], 0, s[10:11]
	global_load_lds_dwordx4 v[2:3], off
	s_mov_b32 m0, s60
	v_readfirstlane_b32 s62, v22
	v_lshl_add_u64 v[40:41], v[2:3], 0, s[10:11]
	global_load_lds_dwordx4 v[4:5], off
	s_mov_b32 m0, s61
	v_readfirstlane_b32 s63, v23
	v_lshl_add_u64 v[6:7], v[0:1], 0, s[12:13]
	global_load_lds_dwordx4 v[40:41], off
	s_mov_b32 m0, s62
	v_readfirstlane_b32 s64, v24
	v_lshl_add_u64 v[42:43], v[2:3], 0, s[12:13]
	global_load_lds_dwordx4 v[6:7], off
	s_mov_b32 m0, s63
	v_readfirstlane_b32 s65, v25
	v_lshl_add_u64 v[16:17], v[0:1], 0, s[14:15]
	global_load_lds_dwordx4 v[42:43], off
	s_mov_b32 m0, s64
	v_readfirstlane_b32 s58, v26
	v_lshl_add_u64 v[52:53], v[2:3], 0, s[14:15]
	global_load_lds_dwordx4 v[16:17], off
	s_mov_b32 m0, s65
	v_readfirstlane_b32 s51, v27
	v_lshl_add_u64 v[44:45], v[0:1], 0, s[16:17]
	global_load_lds_dwordx4 v[52:53], off
	s_mov_b32 m0, s58
	v_readfirstlane_b32 s52, v28
	v_lshl_add_u64 v[54:55], v[2:3], 0, s[16:17]
	s_waitcnt vmcnt(0) lgkmcnt(0)
	s_barrier
	ds_read_b128 v[4:7], v35 offset:16384
	ds_read_b128 v[40:43], v35 offset:18432
	global_load_lds_dwordx4 v[44:45], off
	s_mov_b32 m0, s51
	v_readfirstlane_b32 s53, v29
	v_lshl_add_u64 v[46:47], v[0:1], 0, s[18:19]
	global_load_lds_dwordx4 v[54:55], off
	s_mov_b32 m0, s52
	v_readfirstlane_b32 s54, v30
	v_lshl_add_u64 v[56:57], v[2:3], 0, s[18:19]
	global_load_lds_dwordx4 v[46:47], off
	s_mov_b32 m0, s53
	v_readfirstlane_b32 s55, v31
	v_lshl_add_u64 v[48:49], v[0:1], 0, s[20:21]
	global_load_lds_dwordx4 v[56:57], off
	s_mov_b32 m0, s54
	v_readfirstlane_b32 s56, v32
	v_lshl_add_u64 v[58:59], v[2:3], 0, s[20:21]
	global_load_lds_dwordx4 v[48:49], off
	s_mov_b32 m0, s55
	v_readfirstlane_b32 s57, v33
	v_lshl_add_u64 v[50:51], v[0:1], 0, s[22:23]
	global_load_lds_dwordx4 v[58:59], off
	s_mov_b32 m0, s56
	v_lshl_add_u64 v[60:61], v[2:3], 0, s[22:23]
	global_load_lds_dwordx4 v[50:51], off
	s_mov_b32 m0, s57
	v_lshl_add_u64 v[16:17], v[0:1], 0, s[24:25]
	global_load_lds_dwordx4 v[60:61], off
	ds_read_b128 v[44:47], v34
	ds_read_b128 v[48:51], v34 offset:2048
	ds_read_b128 v[56:59], v35 offset:20480
	ds_read_b128 v[64:67], v35 offset:22528
	ds_read_b128 v[72:75], v35 offset:24576
	ds_read_b128 v[84:87], v35 offset:26624
	ds_read_b128 v[92:95], v35 offset:28672
	ds_read_b128 v[100:103], v35 offset:30720
	s_waitcnt lgkmcnt(0)
	v_mfma_f32_16x16x32_bf16 v[52:55], v[4:7], v[44:47], 0
	ds_read_b128 v[108:111], v37 offset:16384
	ds_read_b128 v[112:115], v37 offset:18432
	s_mov_b32 m0, s66
	v_lshl_add_u64 v[154:155], v[2:3], 0, s[24:25]
	v_mfma_f32_16x16x32_bf16 v[60:63], v[40:43], v[44:47], 0
	v_lshl_add_u64 v[80:81], v[0:1], 0, s[26:27]
	v_lshl_add_u64 v[156:157], v[2:3], 0, s[26:27]
	v_lshl_add_u64 v[150:151], v[0:1], 0, s[28:29]
	v_mfma_f32_16x16x32_bf16 v[68:71], v[56:59], v[44:47], 0
	v_lshl_add_u64 v[158:159], v[2:3], 0, s[28:29]
	v_lshl_add_u64 v[152:153], v[0:1], 0, s[30:31]
	v_lshl_add_u64 v[160:161], v[2:3], 0, s[30:31]
	v_mfma_f32_16x16x32_bf16 v[76:79], v[64:67], v[44:47], 0
	v_lshl_add_u32 v39, s50, 7, v82
	v_lshl_or_b32 v8, s49, 9, v38
	v_mul_hi_i32 v83, v39, s44
	v_mfma_f32_16x16x32_bf16 v[88:91], v[72:75], v[44:47], 0
	v_lshrrev_b32_e32 v145, 31, v83
	v_lshrrev_b32_e32 v83, 11, v83
	v_add_u32_e32 v83, v83, v145
	v_mfma_f32_16x16x32_bf16 v[96:99], v[84:87], v[44:47], 0
	v_mov_b32_e32 v163, v9
	v_or_b32_e32 v162, 0x90, v8
	v_mov_b32_e32 v167, v9
	v_mfma_f32_16x16x32_bf16 v[104:107], v[92:95], v[44:47], 0
	v_or_b32_e32 v166, 0x110, v8
	s_add_i32 s48, s48, s33
	s_cmpk_lt_i32 s48, 0x80
	v_mfma_f32_16x16x32_bf16 v[44:47], v[100:103], v[44:47], 0
	v_mfma_f32_16x16x32_bf16 v[4:7], v[4:7], v[48:51], 0
	v_mfma_f32_16x16x32_bf16 v[40:43], v[40:43], v[48:51], 0
	v_mfma_f32_16x16x32_bf16 v[56:59], v[56:59], v[48:51], 0
	v_mfma_f32_16x16x32_bf16 v[64:67], v[64:67], v[48:51], 0
	v_mfma_f32_16x16x32_bf16 v[72:75], v[72:75], v[48:51], 0
	v_mfma_f32_16x16x32_bf16 v[84:87], v[84:87], v[48:51], 0
	v_mfma_f32_16x16x32_bf16 v[92:95], v[92:95], v[48:51], 0
	v_mfma_f32_16x16x32_bf16 v[48:51], v[100:103], v[48:51], 0
	ds_read_b128 v[100:103], v36
	ds_read_b128 v[116:119], v36 offset:2048
	ds_read_b128 v[120:123], v37 offset:20480
	ds_read_b128 v[124:127], v37 offset:22528
	ds_read_b128 v[128:131], v37 offset:24576
	ds_read_b128 v[132:135], v37 offset:26624
	ds_read_b128 v[136:139], v37 offset:28672
	ds_read_b128 v[140:143], v37 offset:30720
	s_waitcnt vmcnt(0) lgkmcnt(0)
	s_barrier
	global_load_lds_dwordx4 v[16:17], off
	s_mov_b32 m0, s59
	v_mfma_f32_16x16x32_bf16 v[52:55], v[108:111], v[100:103], v[52:55]
	v_lshl_add_u64 v[16:17], v[0:1], 0, s[34:35]
	v_mfma_f32_16x16x32_bf16 v[60:63], v[112:115], v[100:103], v[60:63]
	v_mfma_f32_16x16x32_bf16 v[68:71], v[120:123], v[100:103], v[68:71]
	v_mfma_f32_16x16x32_bf16 v[76:79], v[124:127], v[100:103], v[76:79]
	v_mfma_f32_16x16x32_bf16 v[88:91], v[128:131], v[100:103], v[88:91]
	v_mfma_f32_16x16x32_bf16 v[96:99], v[132:135], v[100:103], v[96:99]
	v_mfma_f32_16x16x32_bf16 v[104:107], v[136:139], v[100:103], v[104:107]
	v_mfma_f32_16x16x32_bf16 v[44:47], v[140:143], v[100:103], v[44:47]
	ds_read_b128 v[100:103], v35 offset:49152
	ds_read_b128 v[146:149], v35 offset:51200
	global_load_lds_dwordx4 v[154:155], off
	s_mov_b32 m0, s60
	v_mfma_f32_16x16x32_bf16 v[4:7], v[108:111], v[116:119], v[4:7]
	global_load_lds_dwordx4 v[80:81], off
	s_mov_b32 m0, s61
	v_mfma_f32_16x16x32_bf16 v[40:43], v[112:115], v[116:119], v[40:43]
	global_load_lds_dwordx4 v[156:157], off
	s_mov_b32 m0, s62
	v_mfma_f32_16x16x32_bf16 v[56:59], v[120:123], v[116:119], v[56:59]
	global_load_lds_dwordx4 v[150:151], off
	s_mov_b32 m0, s63
	v_mfma_f32_16x16x32_bf16 v[64:67], v[124:127], v[116:119], v[64:67]
	global_load_lds_dwordx4 v[158:159], off
	s_mov_b32 m0, s64
	v_mfma_f32_16x16x32_bf16 v[72:75], v[128:131], v[116:119], v[72:75]
	global_load_lds_dwordx4 v[152:153], off
	s_mov_b32 m0, s65
	v_mfma_f32_16x16x32_bf16 v[84:87], v[132:135], v[116:119], v[84:87]
	global_load_lds_dwordx4 v[160:161], off
	ds_read_b128 v[108:111], v34 offset:32768
	ds_read_b128 v[112:115], v34 offset:34816
	v_mfma_f32_16x16x32_bf16 v[92:95], v[136:139], v[116:119], v[92:95]
	ds_read_b128 v[120:123], v35 offset:55296
	ds_read_b128 v[124:127], v35 offset:57344
	ds_read_b128 v[128:131], v35 offset:59392
	v_mfma_f32_16x16x32_bf16 v[48:51], v[140:143], v[116:119], v[48:51]
	ds_read_b128 v[116:119], v35 offset:53248
	ds_read_b128 v[132:135], v35 offset:61440
	ds_read_b128 v[136:139], v35 offset:63488
	s_waitcnt lgkmcnt(0)
	v_mfma_f32_16x16x32_bf16 v[52:55], v[100:103], v[108:111], v[52:55]
	v_lshl_add_u64 v[80:81], v[0:1], 0, s[36:37]
	v_lshl_add_u64 v[150:151], v[2:3], 0, s[34:35]
	v_lshl_add_u64 v[152:153], v[2:3], 0, s[36:37]
	v_mfma_f32_16x16x32_bf16 v[60:63], v[146:149], v[108:111], v[60:63]
	v_lshl_add_u64 v[154:155], v[2:3], 0, s[38:39]
	v_lshl_add_u64 v[156:157], v[2:3], 0, s[40:41]
	s_mov_b32 m0, s58
	v_mfma_f32_16x16x32_bf16 v[68:71], v[116:119], v[108:111], v[68:71]
	v_mfma_f32_16x16x32_bf16 v[76:79], v[120:123], v[108:111], v[76:79]
	v_mfma_f32_16x16x32_bf16 v[88:91], v[124:127], v[108:111], v[88:91]
	v_mfma_f32_16x16x32_bf16 v[96:99], v[128:131], v[108:111], v[96:99]
	v_mfma_f32_16x16x32_bf16 v[104:107], v[132:135], v[108:111], v[104:107]
	v_mfma_f32_16x16x32_bf16 v[44:47], v[136:139], v[108:111], v[44:47]
	v_mfma_f32_16x16x32_bf16 v[4:7], v[100:103], v[112:115], v[4:7]
	v_mfma_f32_16x16x32_bf16 v[40:43], v[146:149], v[112:115], v[40:43]
	v_lshl_add_u64 v[146:147], v[0:1], 0, s[38:39]
	v_lshl_add_u64 v[148:149], v[0:1], 0, s[40:41]
	v_mfma_f32_16x16x32_bf16 v[56:59], v[116:119], v[112:115], v[56:59]
	v_mfma_f32_16x16x32_bf16 v[64:67], v[120:123], v[112:115], v[64:67]
	v_mfma_f32_16x16x32_bf16 v[72:75], v[124:127], v[112:115], v[72:75]
	v_mfma_f32_16x16x32_bf16 v[84:87], v[128:131], v[112:115], v[84:87]
	v_mfma_f32_16x16x32_bf16 v[0:3], v[132:135], v[112:115], v[92:95]
	s_nop 2
	ds_read_b128 v[92:95], v37 offset:49152
	ds_read_b128 v[100:103], v37 offset:51200
	v_mfma_f32_16x16x32_bf16 v[48:51], v[136:139], v[112:115], v[48:51]
	ds_read_b128 v[108:111], v36 offset:32768
	ds_read_b128 v[112:115], v36 offset:34816
	ds_read_b128 v[116:119], v37 offset:53248
	ds_read_b128 v[120:123], v37 offset:55296
	ds_read_b128 v[124:127], v37 offset:57344
	ds_read_b128 v[128:131], v37 offset:59392
	ds_read_b128 v[132:135], v37 offset:61440
	ds_read_b128 v[136:139], v37 offset:63488
	s_waitcnt vmcnt(0) lgkmcnt(0)
	s_barrier
	global_load_lds_dwordx4 v[16:17], off
	s_mov_b32 m0, s51
	v_mfma_f32_16x16x32_bf16 v[52:55], v[92:95], v[108:111], v[52:55]
	v_mul_hi_i32 v16, v39, s45
	v_lshrrev_b32_e32 v17, 31, v16
	v_ashrrev_i32_e32 v16, 11, v16
	v_mfma_f32_16x16x32_bf16 v[60:63], v[100:103], v[108:111], v[60:63]
	v_add_u32_e32 v16, v16, v17
	v_mad_i32_i24 v17, v16, s46, v39
	v_cmp_lt_i32_e32 vcc, s47, v17
	v_mfma_f32_16x16x32_bf16 v[68:71], v[116:119], v[108:111], v[68:71]
	s_nop 0
	v_cndmask_b32_e32 v16, 2, v16, vcc
	v_mul_hi_i32_i24_e32 v17, 0x6000, v16
	v_mfma_f32_16x16x32_bf16 v[76:79], v[120:123], v[108:111], v[76:79]
	v_mul_i32_i24_e32 v16, 0x6000, v16
	v_lshl_add_u64 v[16:17], s[94:95], 0, v[16:17]
	v_mfma_f32_16x16x32_bf16 v[88:91], v[124:127], v[108:111], v[88:91]
	v_mfma_f32_16x16x32_bf16 v[96:99], v[128:131], v[108:111], v[96:99]
	v_mfma_f32_16x16x32_bf16 v[104:107], v[132:135], v[108:111], v[104:107]
	v_mfma_f32_16x16x32_bf16 v[44:47], v[136:139], v[108:111], v[44:47]
	ds_read_b128 v[108:111], v35 offset:16384
	ds_read_b128 v[140:143], v35 offset:18432
	global_load_lds_dwordx4 v[150:151], off
	s_mov_b32 m0, s52
	v_mfma_f32_16x16x32_bf16 v[4:7], v[92:95], v[112:115], v[4:7]
	global_load_lds_dwordx4 v[80:81], off
	s_mov_b32 m0, s53
	v_mfma_f32_16x16x32_bf16 v[40:43], v[100:103], v[112:115], v[40:43]
	global_load_lds_dwordx4 v[152:153], off
	s_mov_b32 m0, s54
	v_mfma_f32_16x16x32_bf16 v[56:59], v[116:119], v[112:115], v[56:59]
	global_load_lds_dwordx4 v[146:147], off
	s_mov_b32 m0, s55
	v_mfma_f32_16x16x32_bf16 v[64:67], v[120:123], v[112:115], v[64:67]
	global_load_lds_dwordx4 v[154:155], off
	s_mov_b32 m0, s56
	v_mfma_f32_16x16x32_bf16 v[72:75], v[124:127], v[112:115], v[72:75]
	global_load_lds_dwordx4 v[148:149], off
	s_mov_b32 m0, s57
	v_mfma_f32_16x16x32_bf16 v[84:87], v[128:131], v[112:115], v[84:87]
	global_load_lds_dwordx4 v[156:157], off
	ds_read_b128 v[92:95], v34
	ds_read_b128 v[100:103], v34 offset:2048
	v_mfma_f32_16x16x32_bf16 v[0:3], v[132:135], v[112:115], v[0:3]
	ds_read_b128 v[116:119], v35 offset:22528
	ds_read_b128 v[120:123], v35 offset:24576
	ds_read_b128 v[124:127], v35 offset:26624
	v_mfma_f32_16x16x32_bf16 v[48:51], v[136:139], v[112:115], v[48:51]
	ds_read_b128 v[112:115], v35 offset:20480
	ds_read_b128 v[128:131], v35 offset:28672
	ds_read_b128 v[132:135], v35 offset:30720
	v_lshl_add_u64 v[80:81], v[16:17], 0, s[42:43]
	v_lshl_add_u64 v[16:17], v[80:81], 0, v[8:9]
	s_waitcnt lgkmcnt(0)
	v_mfma_f32_16x16x32_bf16 v[52:55], v[108:111], v[92:95], v[52:55]
	v_lshl_add_u32 v146, v83, 13, v39
	v_ashrrev_i32_e32 v147, 31, v146
	v_lshl_add_u64 v[164:165], v[80:81], 0, v[162:163]
	v_mfma_f32_16x16x32_bf16 v[60:63], v[140:143], v[92:95], v[60:63]
	v_lshl_add_u64 v[168:169], v[80:81], 0, v[166:167]
	v_or_b32_e32 v39, 16, v39
	v_mfma_f32_16x16x32_bf16 v[68:71], v[112:115], v[92:95], v[68:71]
	v_mfma_f32_16x16x32_bf16 v[76:79], v[116:119], v[92:95], v[76:79]
	v_mfma_f32_16x16x32_bf16 v[88:91], v[120:123], v[92:95], v[88:91]
	v_mfma_f32_16x16x32_bf16 v[96:99], v[124:127], v[92:95], v[96:99]
	v_mfma_f32_16x16x32_bf16 v[104:107], v[128:131], v[92:95], v[104:107]
	v_mfma_f32_16x16x32_bf16 v[44:47], v[132:135], v[92:95], v[44:47]
	v_mfma_f32_16x16x32_bf16 v[4:7], v[108:111], v[100:103], v[4:7]
	v_mfma_f32_16x16x32_bf16 v[40:43], v[140:143], v[100:103], v[40:43]
	v_mfma_f32_16x16x32_bf16 v[56:59], v[112:115], v[100:103], v[56:59]
	v_mfma_f32_16x16x32_bf16 v[64:67], v[116:119], v[100:103], v[64:67]
	v_mfma_f32_16x16x32_bf16 v[72:75], v[120:123], v[100:103], v[72:75]
	v_mfma_f32_16x16x32_bf16 v[84:87], v[124:127], v[100:103], v[84:87]
	v_mfma_f32_16x16x32_bf16 v[92:95], v[128:131], v[100:103], v[0:3]
	s_nop 2
	ds_read_b128 v[0:3], v37 offset:16384
	ds_read_b128 v[108:111], v37 offset:18432
	v_mfma_f32_16x16x32_bf16 v[48:51], v[132:135], v[100:103], v[48:51]
	ds_read_b128 v[100:103], v36
	ds_read_b128 v[112:115], v36 offset:2048
	ds_read_b128 v[116:119], v37 offset:20480
	ds_read_b128 v[120:123], v37 offset:22528
	ds_read_b128 v[124:127], v37 offset:24576
	ds_read_b128 v[128:131], v37 offset:26624
	ds_read_b128 v[132:135], v37 offset:28672
	ds_read_b128 v[136:139], v37 offset:30720
	s_waitcnt vmcnt(0) lgkmcnt(0)
	s_barrier
	global_load_dwordx4 v[140:143], v[16:17], off
	v_mfma_f32_16x16x32_bf16 v[60:63], v[108:111], v[100:103], v[60:63]
	v_mov_b32_e32 v17, v9
	v_or_b32_e32 v16, 16, v8
	v_lshl_add_u64 v[160:161], v[80:81], 0, v[16:17]
	v_mfma_f32_16x16x32_bf16 v[68:71], v[116:119], v[100:103], v[68:71]
	v_mfma_f32_16x16x32_bf16 v[40:43], v[108:111], v[112:115], v[40:43]
	v_mfma_f32_16x16x32_bf16 v[56:59], v[116:119], v[112:115], v[56:59]
	ds_read_b128 v[108:111], v35 offset:49152
	ds_read_b128 v[116:119], v34 offset:32768
	v_mfma_f32_16x16x32_bf16 v[52:55], v[0:3], v[100:103], v[52:55]
	v_mfma_f32_16x16x32_bf16 v[76:79], v[120:123], v[100:103], v[76:79]
	v_mfma_f32_16x16x32_bf16 v[88:91], v[124:127], v[100:103], v[88:91]
	v_mfma_f32_16x16x32_bf16 v[96:99], v[128:131], v[100:103], v[96:99]
	v_mfma_f32_16x16x32_bf16 v[104:107], v[132:135], v[100:103], v[104:107]
	v_mfma_f32_16x16x32_bf16 v[44:47], v[136:139], v[100:103], v[44:47]
	v_mfma_f32_16x16x32_bf16 v[100:103], v[0:3], v[112:115], v[4:7]
	v_lshl_add_u64 v[0:1], v[146:147], 0, s[8:9]
	v_lshlrev_b64 v[0:1], 12, v[0:1]
	v_lshl_add_u64 v[0:1], s[6:7], 0, v[0:1]
	s_waitcnt lgkmcnt(0)
	v_mfma_f32_16x16x32_bf16 v[52:55], v[108:111], v[116:119], v[52:55]
	v_lshl_add_u64 v[158:159], v[0:1], 0, v[8:9]
	v_mfma_f32_16x16x32_bf16 v[64:67], v[120:123], v[112:115], v[64:67]
	ds_read_b128 v[120:123], v37 offset:49152
	ds_read_b128 v[4:7], v34 offset:34816
	ds_read_b128 v[146:149], v35 offset:51200
	ds_read_b128 v[150:153], v36 offset:32768
	ds_read_b128 v[0:3], v36 offset:34816
	ds_read_b128 v[154:157], v37 offset:51200
	s_waitcnt lgkmcnt(2)
	v_mfma_f32_16x16x32_bf16 v[52:55], v[120:123], v[150:153], v[52:55]
	v_mfma_f32_16x16x32_bf16 v[60:63], v[146:149], v[116:119], v[60:63]
	s_waitcnt vmcnt(0)
	s_nop 5
	v_mul_f32_e32 v54, v54, v142
	v_mul_f32_e32 v55, v55, v143
	v_mul_f32_e32 v52, v52, v140
	v_mul_f32_e32 v53, v53, v141
	global_store_dwordx4 v[158:159], v[52:55], off
	global_load_dwordx4 v[52:55], v[160:161], off
	s_waitcnt lgkmcnt(0)
	v_mfma_f32_16x16x32_bf16 v[60:63], v[154:157], v[150:153], v[60:63]
	v_mov_b32_e32 v161, v9
	v_or_b32_e32 v160, 0x80, v8
	v_lshl_add_u64 v[140:141], v[80:81], 0, v[160:161]
	v_mfma_f32_16x16x32_bf16 v[48:51], v[136:139], v[112:115], v[48:51]
	v_mfma_f32_16x16x32_bf16 v[40:43], v[146:149], v[4:7], v[40:43]
	s_waitcnt vmcnt(0)
	s_nop 1
	v_mul_f32_e32 v54, v62, v54
	v_mul_f32_e32 v55, v63, v55
	v_mul_f32_e32 v52, v60, v52
	v_mul_f32_e32 v53, v61, v53
	global_store_dwordx4 v[158:159], v[52:55], off offset:16
	global_load_dwordx4 v[52:55], v[140:141], off
	v_mfma_f32_16x16x32_bf16 v[60:63], v[124:127], v[112:115], v[72:75]
	v_mfma_f32_16x16x32_bf16 v[72:75], v[128:131], v[112:115], v[84:87]
	s_nop 2
	ds_read_b128 v[84:87], v35 offset:53248
	ds_read_b128 v[124:127], v35 offset:55296
	ds_read_b128 v[128:131], v37 offset:53248
	ds_read_b128 v[140:143], v37 offset:55296
	s_waitcnt lgkmcnt(3)
	v_mfma_f32_16x16x32_bf16 v[68:71], v[84:87], v[116:119], v[68:71]
	s_waitcnt lgkmcnt(1)
	v_mfma_f32_16x16x32_bf16 v[68:71], v[128:131], v[150:153], v[68:71]
	v_mfma_f32_16x16x32_bf16 v[40:43], v[154:157], v[0:3], v[40:43]
	v_mfma_f32_16x16x32_bf16 v[56:59], v[84:87], v[4:7], v[56:59]
	s_waitcnt vmcnt(0)
	s_nop 4
	v_mul_f32_e32 v54, v70, v54
	v_mul_f32_e32 v55, v71, v55
	v_mul_f32_e32 v52, v68, v52
	v_mul_f32_e32 v53, v69, v53
	global_store_dwordx4 v[158:159], v[52:55], off offset:128
	global_load_dwordx4 v[52:55], v[164:165], off
	v_mfma_f32_16x16x32_bf16 v[68:71], v[124:127], v[116:119], v[76:79]
	v_mov_b32_e32 v165, v9
	v_or_b32_e32 v164, 0x100, v8
	s_waitcnt lgkmcnt(0)
	v_mfma_f32_16x16x32_bf16 v[68:71], v[140:143], v[150:153], v[68:71]
	v_lshl_add_u64 v[76:77], v[80:81], 0, v[164:165]
	v_mfma_f32_16x16x32_bf16 v[56:59], v[128:131], v[0:3], v[56:59]
	v_mfma_f32_16x16x32_bf16 v[64:67], v[124:127], v[4:7], v[64:67]
	s_waitcnt vmcnt(0)
	s_nop 3
	v_mul_f32_e32 v54, v70, v54
	v_mul_f32_e32 v55, v71, v55
	v_mul_f32_e32 v52, v68, v52
	v_mul_f32_e32 v53, v69, v53
	global_store_dwordx4 v[158:159], v[52:55], off offset:144
	global_load_dwordx4 v[52:55], v[76:77], off
	v_mfma_f32_16x16x32_bf16 v[68:71], v[132:135], v[112:115], v[92:95]
	ds_read_b128 v[76:79], v35 offset:57344
	s_nop 1
	ds_read_b128 v[92:95], v35 offset:59392
	ds_read_b128 v[112:115], v37 offset:57344
	ds_read_b128 v[132:135], v37 offset:59392
	s_waitcnt lgkmcnt(3)
	v_mfma_f32_16x16x32_bf16 v[88:91], v[76:79], v[116:119], v[88:91]
	s_waitcnt lgkmcnt(1)
	v_mfma_f32_16x16x32_bf16 v[88:91], v[112:115], v[150:153], v[88:91]
	v_mfma_f32_16x16x32_bf16 v[60:63], v[76:79], v[4:7], v[60:63]
	s_waitcnt vmcnt(0)
	s_nop 5
	v_mul_f32_e32 v54, v90, v54
	v_mul_f32_e32 v55, v91, v55
	v_mul_f32_e32 v52, v88, v52
	v_mul_f32_e32 v53, v89, v53
	global_store_dwordx4 v[158:159], v[52:55], off offset:256
	global_load_dwordx4 v[52:55], v[168:169], off
	v_mfma_f32_16x16x32_bf16 v[88:91], v[92:95], v[116:119], v[96:99]
	v_mov_b32_e32 v169, v9
	v_or_b32_e32 v168, 0x180, v8
	s_nop 0
	ds_read_b128 v[96:99], v35 offset:61440
	ds_read_b128 v[136:139], v35 offset:63488
	s_waitcnt lgkmcnt(2)
	v_mfma_f32_16x16x32_bf16 v[88:91], v[132:135], v[150:153], v[88:91]
	v_lshl_add_u64 v[170:171], v[80:81], 0, v[168:169]
	s_waitcnt lgkmcnt(1)
	v_mfma_f32_16x16x32_bf16 v[104:107], v[96:99], v[116:119], v[104:107]
	s_waitcnt lgkmcnt(0)
	v_mfma_f32_16x16x32_bf16 v[44:47], v[136:139], v[116:119], v[44:47]
	v_mov_b32_e32 v117, v9
	v_or_b32_e32 v116, 0x190, v8
	v_lshl_add_u64 v[80:81], v[80:81], 0, v[116:117]
	v_mfma_f32_16x16x32_bf16 v[68:71], v[96:99], v[4:7], v[68:71]
	s_waitcnt vmcnt(0)
	v_mul_f32_e32 v54, v90, v54
	v_mul_f32_e32 v55, v91, v55
	v_mul_f32_e32 v52, v88, v52
	v_mul_f32_e32 v53, v89, v53
	global_store_dwordx4 v[158:159], v[52:55], off offset:272
	global_load_dwordx4 v[52:55], v[170:171], off
	v_mfma_f32_16x16x32_bf16 v[88:91], v[108:111], v[4:7], v[100:103]
	s_nop 2
	ds_read_b128 v[100:103], v37 offset:61440
	ds_read_b128 v[108:111], v37 offset:63488
	s_waitcnt lgkmcnt(1)
	v_mfma_f32_16x16x32_bf16 v[104:107], v[100:103], v[150:153], v[104:107]
	s_waitcnt lgkmcnt(0)
	v_mfma_f32_16x16x32_bf16 v[44:47], v[108:111], v[150:153], v[44:47]
	s_waitcnt vmcnt(0)
	s_nop 4
	v_mul_f32_e32 v54, v106, v54
	v_mul_f32_e32 v55, v107, v55
	v_mul_f32_e32 v52, v104, v52
	v_mul_f32_e32 v53, v105, v53
	global_store_dwordx4 v[158:159], v[52:55], off offset:384
	global_load_dwordx4 v[52:55], v[80:81], off
	v_mul_hi_i32 v80, v39, s45
	v_lshrrev_b32_e32 v81, 31, v80
	v_ashrrev_i32_e32 v80, 11, v80
	v_add_u32_e32 v80, v80, v81
	v_mad_i32_i24 v81, v80, s46, v39
	v_cmp_lt_i32_e32 vcc, s47, v81
	s_waitcnt vmcnt(0)
	v_mul_f32_e32 v46, v46, v54
	v_mul_f32_e32 v47, v47, v55
	v_cndmask_b32_e32 v80, 2, v80, vcc
	v_mul_hi_i32_i24_e32 v81, 0x6000, v80
	v_mul_i32_i24_e32 v80, 0x6000, v80
	v_lshl_add_u64 v[76:77], s[94:95], 0, v[80:81]
	v_lshl_add_u64 v[76:77], v[76:77], 0, s[42:43]
	v_mul_f32_e32 v44, v44, v52
	v_mul_f32_e32 v45, v45, v53
	v_lshl_add_u64 v[78:79], v[76:77], 0, v[8:9]
	global_store_dwordx4 v[158:159], v[44:47], off offset:400
	global_load_dwordx4 v[44:47], v[78:79], off
	v_mul_hi_i32 v78, v39, s44
	v_lshrrev_b32_e32 v79, 31, v78
	v_mfma_f32_16x16x32_bf16 v[52:55], v[92:95], v[4:7], v[72:75]
	v_lshl_add_u64 v[16:17], v[76:77], 0, v[16:17]
	s_nop 1
	v_lshrrev_b32_e32 v72, 11, v78
	v_add_u32_e32 v72, v72, v79
	v_lshl_add_u32 v72, v72, 13, v39
	v_ashrrev_i32_e32 v73, 31, v72
	v_lshl_add_u64 v[72:73], v[72:73], 0, s[8:9]
	v_lshlrev_b64 v[78:79], 12, v[72:73]
	v_mfma_f32_16x16x32_bf16 v[72:75], v[120:123], v[0:3], v[88:91]
	v_lshl_add_u64 v[78:79], s[6:7], 0, v[78:79]
	v_lshl_add_u64 v[78:79], v[78:79], 0, v[8:9]
	v_mfma_f32_16x16x32_bf16 v[4:7], v[136:139], v[4:7], v[48:51]
	s_waitcnt vmcnt(0)
	s_nop 3
	v_mul_f32_e32 v46, v74, v46
	v_mul_f32_e32 v47, v75, v47
	v_mul_f32_e32 v44, v72, v44
	v_mul_f32_e32 v45, v73, v45
	global_store_dwordx4 v[78:79], v[44:47], off
	global_load_dwordx4 v[44:47], v[16:17], off
	v_lshl_add_u64 v[16:17], v[76:77], 0, v[160:161]
	s_waitcnt vmcnt(0)
	v_mul_f32_e32 v42, v42, v46
	v_mul_f32_e32 v43, v43, v47
	v_mul_f32_e32 v40, v40, v44
	v_mul_f32_e32 v41, v41, v45
	global_store_dwordx4 v[78:79], v[40:43], off offset:16
	global_load_dwordx4 v[40:43], v[16:17], off
	v_lshl_add_u64 v[16:17], v[76:77], 0, v[162:163]
	v_mfma_f32_16x16x32_bf16 v[44:47], v[140:143], v[0:3], v[64:67]
	s_waitcnt vmcnt(0)
	v_mul_f32_e32 v42, v58, v42
	v_mul_f32_e32 v43, v59, v43
	v_mul_f32_e32 v40, v56, v40
	v_mul_f32_e32 v41, v57, v41
	global_store_dwordx4 v[78:79], v[40:43], off offset:128
	global_load_dwordx4 v[40:43], v[16:17], off
	v_lshl_add_u64 v[16:17], v[76:77], 0, v[164:165]
	v_mfma_f32_16x16x32_bf16 v[56:59], v[112:115], v[0:3], v[60:63]
	s_waitcnt vmcnt(0)
	v_mul_f32_e32 v42, v46, v42
	v_mul_f32_e32 v43, v47, v43
	v_mul_f32_e32 v40, v44, v40
	v_mul_f32_e32 v41, v45, v41
	global_store_dwordx4 v[78:79], v[40:43], off offset:144
	global_load_dwordx4 v[40:43], v[16:17], off
	v_lshl_add_u64 v[16:17], v[76:77], 0, v[166:167]
	v_mfma_f32_16x16x32_bf16 v[44:47], v[132:135], v[0:3], v[52:55]
	s_waitcnt vmcnt(0)
	v_mul_f32_e32 v42, v58, v42
	v_mul_f32_e32 v43, v59, v43
	v_mul_f32_e32 v40, v56, v40
	v_mul_f32_e32 v41, v57, v41
	global_store_dwordx4 v[78:79], v[40:43], off offset:256
	global_load_dwordx4 v[40:43], v[16:17], off
	v_lshl_add_u64 v[16:17], v[76:77], 0, v[168:169]
	v_mfma_f32_16x16x32_bf16 v[52:55], v[100:103], v[0:3], v[68:71]
	s_waitcnt vmcnt(0)
	v_mul_f32_e32 v42, v46, v42
	v_mul_f32_e32 v43, v47, v43
	v_mul_f32_e32 v40, v44, v40
	v_mul_f32_e32 v41, v45, v41
	global_store_dwordx4 v[78:79], v[40:43], off offset:272
	global_load_dwordx4 v[40:43], v[16:17], off
	v_lshl_add_u64 v[16:17], v[76:77], 0, v[116:117]
	v_mfma_f32_16x16x32_bf16 v[0:3], v[108:111], v[0:3], v[4:7]
	s_waitcnt vmcnt(0)
	v_mul_f32_e32 v42, v54, v42
	v_mul_f32_e32 v43, v55, v43
	v_mul_f32_e32 v40, v52, v40
	v_mul_f32_e32 v41, v53, v41
	global_store_dwordx4 v[78:79], v[40:43], off offset:384
	global_load_dwordx4 v[40:43], v[16:17], off
	s_waitcnt vmcnt(0)
	s_nop 1
	v_mul_f32_e32 v2, v2, v42
	v_mul_f32_e32 v3, v3, v43
	v_mul_f32_e32 v0, v0, v40
	v_mul_f32_e32 v1, v1, v41
	global_store_dwordx4 v[78:79], v[0:3], off offset:400
	s_cbranch_scc1 .LBB0_874

.LBB0_932:
	s_or_b64 exec, exec, s[2:3]
	v_cndmask_b32_e64 v18, v33, 2, vcc
	v_mul_hi_i32_i24_e32 v41, 0x6000, v18
	v_mul_i32_i24_e32 v40, 0x6000, v18
	v_lshl_add_u64 v[50:51], s[94:95], 0, v[40:41]
	v_lshl_add_u64 v[40:41], v[50:51], 0, s[14:15]
	v_lshl_add_u64 v[64:65], v[50:51], 0, s[16:17]
	v_mov_b32_e32 v33, v19
	v_lshl_add_u64 v[54:55], v[40:41], 0, v[32:33]
	v_lshl_add_u64 v[58:59], v[64:65], 0, v[32:33]
	global_load_dwordx4 v[50:53], v[22:23], off
	s_nop 0
	global_load_dwordx4 v[54:57], v[54:55], off
	s_nop 0
	global_load_dwordx4 v[58:61], v[58:59], off
	s_waitcnt vmcnt(6)
	v_mul_f32_e32 v76, v12, v12
	v_mul_f32_e32 v77, v13, v13
	s_waitcnt vmcnt(5)
	v_mul_f32_e32 v78, v8, v8
	v_mul_f32_e32 v79, v9, v9
	v_mul_f32_e32 v72, v14, v14
	v_mul_f32_e32 v73, v15, v15
	v_mul_f32_e32 v74, v10, v10
	v_mul_f32_e32 v75, v11, v11
	v_mov_b32_e32 v80, v76
	v_mov_b32_e32 v81, v78
	v_mov_b32_e32 v78, v77
	v_add_f32_e32 v76, v80, v78
	v_add_f32_e32 v77, v81, v79
	v_mov_b32_e32 v78, v72
	v_mov_b32_e32 v79, v74
	s_waitcnt vmcnt(3)
	v_mul_f32_e32 v68, v0, v0
	v_mul_f32_e32 v69, v1, v1
	v_mul_f32_e32 v70, v4, v4
	v_mul_f32_e32 v71, v5, v5
	v_add_f32_e32 v76, v78, v76
	v_add_f32_e32 v77, v79, v77
	v_mov_b32_e32 v74, v73
	v_mul_f32_e32 v62, v2, v2
	v_mul_f32_e32 v63, v3, v3
	v_mul_f32_e32 v66, v6, v6
	v_mul_f32_e32 v67, v7, v7
	v_add_f32_e32 v72, v74, v76
	v_add_f32_e32 v73, v75, v77
	v_mov_b32_e32 v74, v68
	v_mov_b32_e32 v75, v70
	v_mov_b32_e32 v70, v69
	v_add_f32_e32 v68, v74, v70
	v_add_f32_e32 v69, v75, v71
	v_mov_b32_e32 v70, v62
	v_mov_b32_e32 v71, v66
	v_add_f32_e32 v68, v70, v68
	v_add_f32_e32 v69, v71, v69
	v_mov_b32_e32 v66, v63
	v_add_f32_e32 v62, v66, v68
	v_add_f32_e32 v63, v67, v69
	v_add_f32_e32 v18, v72, v73
	v_add_f32_e32 v18, v63, v18
	v_add_f32_e32 v18, v62, v18
	ds_bpermute_b32 v33, v42, v18
	v_mad_i64_i32 v[62:63], s[0:1], v17, s30, v[20:21]
	v_mov_b32_e32 v35, v19
	v_lshl_add_u64 v[66:67], v[64:65], 0, v[34:35]
	s_waitcnt lgkmcnt(0)
	v_add_f32_e32 v18, v18, v33
	ds_bpermute_b32 v33, v43, v18
	v_mov_b32_e32 v37, v19
	v_mov_b32_e32 v39, v19
	v_add_u32_e32 v17, s20, v17
	s_waitcnt lgkmcnt(0)
	v_add_f32_e32 v18, v18, v33
	ds_bpermute_b32 v33, v44, v18
	s_waitcnt lgkmcnt(0)
	v_add_f32_e32 v18, v18, v33
	ds_bpermute_b32 v33, v45, v18
	s_waitcnt lgkmcnt(0)
	v_add_f32_e32 v18, v18, v33
	ds_bpermute_b32 v33, v46, v18
	s_waitcnt lgkmcnt(0)
	v_add_f32_e32 v18, v18, v33
	ds_bpermute_b32 v33, v47, v18
	s_waitcnt lgkmcnt(0)
	v_add_f32_e32 v18, v18, v33
	v_fmamk_f32 v18, v18, 0x3a800000, v48
	v_mul_f32_e32 v33, 0x4b800000, v18
	v_cmp_gt_f32_e32 vcc, s29, v18
	s_nop 1
	v_cndmask_b32_e32 v18, v18, v33, vcc
	v_rsq_f32_e32 v18, v18
	s_nop 0
	v_mul_f32_e32 v33, 0x45800000, v18
	v_cndmask_b32_e32 v18, v18, v33, vcc
	v_mul_f32_e32 v12, v12, v18
	v_mul_f32_e32 v13, v13, v18
	v_mul_f32_e32 v14, v14, v18
	v_mul_f32_e32 v15, v15, v18
	s_waitcnt vmcnt(2)
	v_mul_f32_e32 v12, v50, v12
	v_mul_f32_e32 v13, v51, v13
	v_mul_f32_e32 v14, v52, v14
	v_mul_f32_e32 v15, v53, v15
	s_waitcnt vmcnt(0)
	v_pk_add_f32 v[50:51], v[58:59], 1.0 op_sel_hi:[1,0]
	v_pk_add_f32 v[52:53], v[60:61], 1.0 op_sel_hi:[1,0]
	v_fma_f32 v12, v50, v12, v54
	v_fma_f32 v13, v51, v13, v55
	v_fma_f32 v14, v52, v14, v56
	v_fma_f32 v15, v53, v15, v57
	v_cvt_pk_bf16_f32 v12, v12, v13
	v_cvt_pk_bf16_f32 v13, v14, v15
	global_store_dwordx2 v[62:63], v[12:13], off
	global_load_dwordx4 v[12:15], v[24:25], off
	s_nop 0
	global_load_dwordx4 v[50:53], v[66:67], off
	v_lshl_add_u64 v[54:55], v[40:41], 0, v[34:35]
	global_load_dwordx4 v[54:57], v[54:55], off
	v_mul_f32_e32 v8, v8, v18
	v_mul_f32_e32 v9, v9, v18
	v_mul_f32_e32 v10, v10, v18
	v_mul_f32_e32 v11, v11, v18
	v_lshl_add_u64 v[58:59], v[64:65], 0, v[36:37]
	v_mul_f32_e32 v4, v4, v18
	v_mul_f32_e32 v5, v5, v18
	v_mul_f32_e32 v6, v6, v18
	v_mul_f32_e32 v7, v7, v18
	v_mul_f32_e32 v0, v0, v18
	v_mul_f32_e32 v1, v1, v18
	v_mul_f32_e32 v2, v2, v18
	v_mul_f32_e32 v3, v3, v18
	v_cmp_lt_i32_e32 vcc, s31, v17
	s_or_b64 s[12:13], vcc, s[12:13]
	s_waitcnt vmcnt(2)
	v_mul_f32_e32 v8, v12, v8
	v_mul_f32_e32 v9, v13, v9
	s_waitcnt vmcnt(1)
	v_pk_add_f32 v[12:13], v[50:51], 1.0 op_sel_hi:[1,0]
	v_mul_f32_e32 v10, v14, v10
	v_mul_f32_e32 v11, v15, v11
	v_pk_add_f32 v[14:15], v[52:53], 1.0 op_sel_hi:[1,0]
	s_waitcnt vmcnt(0)
	v_fma_f32 v8, v12, v8, v54
	v_fma_f32 v9, v13, v9, v55
	v_fma_f32 v10, v14, v10, v56
	v_fma_f32 v11, v15, v11, v57
	v_cvt_pk_bf16_f32 v8, v8, v9
	v_cvt_pk_bf16_f32 v9, v10, v11
	global_store_dwordx2 v[62:63], v[8:9], off offset:512
	global_load_dwordx4 v[8:11], v[26:27], off
	s_nop 0
	global_load_dwordx4 v[12:15], v[58:59], off
	v_lshl_add_u64 v[50:51], v[40:41], 0, v[36:37]
	global_load_dwordx4 v[50:53], v[50:51], off
	v_lshl_add_u64 v[54:55], v[64:65], 0, v[38:39]
	s_waitcnt vmcnt(2)
	v_mul_f32_e32 v4, v8, v4
	v_mul_f32_e32 v5, v9, v5
	s_waitcnt vmcnt(1)
	v_pk_add_f32 v[8:9], v[12:13], 1.0 op_sel_hi:[1,0]
	v_mul_f32_e32 v6, v10, v6
	v_mul_f32_e32 v7, v11, v7
	v_pk_add_f32 v[10:11], v[14:15], 1.0 op_sel_hi:[1,0]
	s_waitcnt vmcnt(0)
	v_fma_f32 v4, v8, v4, v50
	v_fma_f32 v5, v9, v5, v51
	v_fma_f32 v6, v10, v6, v52
	v_fma_f32 v7, v11, v7, v53
	v_cvt_pk_bf16_f32 v4, v4, v5
	v_cvt_pk_bf16_f32 v5, v6, v7
	global_store_dwordx2 v[62:63], v[4:5], off offset:1024
	global_load_dwordx4 v[4:7], v[28:29], off
	s_nop 0
	global_load_dwordx4 v[8:11], v[54:55], off
	v_lshl_add_u64 v[12:13], v[40:41], 0, v[38:39]
	global_load_dwordx4 v[12:15], v[12:13], off
	s_waitcnt vmcnt(2)
	v_mul_f32_e32 v0, v0, v4
	v_mul_f32_e32 v1, v1, v5
	s_waitcnt vmcnt(1)
	v_pk_add_f32 v[4:5], v[8:9], 1.0 op_sel_hi:[1,0]
	v_mul_f32_e32 v2, v2, v6
	v_mul_f32_e32 v3, v3, v7
	v_pk_add_f32 v[6:7], v[10:11], 1.0 op_sel_hi:[1,0]
	s_waitcnt vmcnt(0)
	v_fma_f32 v0, v0, v4, v12
	v_fma_f32 v1, v1, v5, v13
	v_fma_f32 v2, v2, v6, v14
	v_fma_f32 v3, v3, v7, v15
	v_cvt_pk_bf16_f32 v0, v0, v1
	v_cvt_pk_bf16_f32 v1, v2, v3
	global_store_dwordx2 v[62:63], v[0:1], off offset:1536
	s_andn2_b64 exec, exec, s[12:13]
	s_cbranch_execz .LBB0_947

.LBB0_945:
	s_or_b64 exec, exec, s[4:5]
	v_ashrrev_i32_e32 v1, 31, v0
	v_lshlrev_b64 v[0:1], 12, v[0:1]
	v_lshl_add_u64 v[0:1], v[2:3], 0, v[0:1]
	v_lshlrev_b32_e32 v18, 4, v16
	v_lshl_add_u64 v[0:1], v[0:1], 0, v[18:19]
	global_load_dwordx4 v[12:15], v[0:1], off
	global_load_dwordx4 v[8:11], v[0:1], off offset:1024
	global_load_dwordx4 v[4:7], v[0:1], off offset:2048
	s_nop 0
	global_load_dwordx4 v[0:3], v[0:1], off offset:3072
	s_and_saveexec_b64 s[2:3], s[0:1]
	s_cbranch_execz .LBB0_932
	v_lshlrev_b32_e32 v39, 8, v33
	v_sub_u32_e32 v37, v39, v37
	v_add_u32_e32 v40, v17, v37
	v_ashrrev_i32_e32 v41, 31, v40
	v_lshlrev_b64 v[40:41], 12, v[40:41]
	v_lshl_add_u64 v[40:41], v[30:31], 0, v[40:41]
	v_add_co_u32_e64 v66, s[0:1], s26, v40
	v_lshl_add_u32 v37, v33, 13, v49
	s_nop 0
	v_addc_co_u32_e64 v67, s[0:1], 0, v41, s[0:1]
	v_add_co_u32_e64 v68, s[0:1], s27, v40
	global_load_dwordx4 v[50:53], v[40:41], off
	global_load_dwordx4 v[54:57], v[66:67], off
	v_addc_co_u32_e64 v69, s[0:1], 0, v41, s[0:1]
	v_add_co_u32_e64 v70, s[0:1], s28, v40
	v_mov_b32_e32 v72, s93
	s_nop 0
	v_addc_co_u32_e64 v71, s[0:1], 0, v41, s[0:1]
	global_load_dwordx4 v[58:61], v[68:69], off
	global_load_dwordx4 v[62:65], v[70:71], off
	v_mov_b32_e32 v73, s11
	v_mov_b32_e32 v74, s92
	v_mov_b32_e32 v75, s10
	v_cndmask_b32_e32 v37, v37, v39, vcc
	v_cndmask_b32_e32 v73, v72, v73, vcc
	v_cndmask_b32_e32 v72, v74, v75, vcc
	v_add3_u32 v74, v37, v35, v17
	v_ashrrev_i32_e32 v75, 31, v74
	v_lshlrev_b64 v[74:75], 12, v[74:75]
	v_lshl_add_u64 v[72:73], v[72:73], 0, v[74:75]
	v_lshl_add_u64 v[72:73], v[72:73], 0, v[18:19]
	s_waitcnt vmcnt(2)
	v_add_f32_e32 v52, v52, v56
	v_add_f32_e32 v53, v53, v57
	v_add_f32_e32 v50, v50, v54
	v_add_f32_e32 v51, v51, v55
	s_waitcnt vmcnt(0)
	v_add_f32_e32 v54, v60, v64
	v_add_f32_e32 v55, v61, v65
	v_add_f32_e32 v56, v58, v62
	v_add_f32_e32 v57, v59, v63
	v_add_f32_e32 v52, v52, v54
	v_add_f32_e32 v53, v53, v55
	v_add_f32_e32 v50, v50, v56
	v_add_f32_e32 v51, v51, v57
	v_add_f32_e32 v14, v14, v52
	v_add_f32_e32 v15, v15, v53
	v_add_f32_e32 v12, v12, v50
	v_add_f32_e32 v13, v13, v51
	global_store_dwordx4 v[72:73], v[12:15], off
	global_load_dwordx4 v[50:53], v[40:41], off offset:1024
	global_load_dwordx4 v[54:57], v[66:67], off offset:1024
	global_load_dwordx4 v[58:61], v[68:69], off offset:1024
	global_load_dwordx4 v[62:65], v[70:71], off offset:1024
	s_waitcnt vmcnt(2)
	v_add_f32_e32 v52, v52, v56
	v_add_f32_e32 v53, v53, v57
	v_add_f32_e32 v50, v50, v54
	v_add_f32_e32 v51, v51, v55
	s_waitcnt vmcnt(0)
	v_add_f32_e32 v54, v60, v64
	v_add_f32_e32 v55, v61, v65
	v_add_f32_e32 v56, v58, v62
	v_add_f32_e32 v57, v59, v63
	v_add_f32_e32 v52, v52, v54
	v_add_f32_e32 v53, v53, v55
	v_add_f32_e32 v50, v50, v56
	v_add_f32_e32 v51, v51, v57
	v_add_f32_e32 v10, v10, v52
	v_add_f32_e32 v11, v11, v53
	v_add_f32_e32 v8, v8, v50
	v_add_f32_e32 v9, v9, v51
	global_store_dwordx4 v[72:73], v[8:11], off offset:1024
	global_load_dwordx4 v[50:53], v[40:41], off offset:2048
	global_load_dwordx4 v[54:57], v[66:67], off offset:2048
	global_load_dwordx4 v[58:61], v[68:69], off offset:2048
	global_load_dwordx4 v[62:65], v[70:71], off offset:2048
	s_waitcnt vmcnt(2)
	v_add_f32_e32 v52, v52, v56
	v_add_f32_e32 v53, v53, v57
	v_add_f32_e32 v50, v50, v54
	v_add_f32_e32 v51, v51, v55
	s_waitcnt vmcnt(0)
	v_add_f32_e32 v54, v60, v64
	v_add_f32_e32 v55, v61, v65
	v_add_f32_e32 v56, v58, v62
	v_add_f32_e32 v57, v59, v63
	v_add_f32_e32 v52, v52, v54
	v_add_f32_e32 v53, v53, v55
	v_add_f32_e32 v50, v50, v56
	v_add_f32_e32 v51, v51, v57
	v_add_f32_e32 v6, v6, v52
	v_add_f32_e32 v7, v7, v53
	v_add_f32_e32 v4, v4, v50
	v_add_f32_e32 v5, v5, v51
	global_store_dwordx4 v[72:73], v[4:7], off offset:2048
	global_load_dwordx4 v[50:53], v[40:41], off offset:3072
	global_load_dwordx4 v[54:57], v[66:67], off offset:3072
	global_load_dwordx4 v[58:61], v[68:69], off offset:3072
	global_load_dwordx4 v[62:65], v[70:71], off offset:3072
	s_waitcnt vmcnt(2)
	v_add_f32_e32 v40, v52, v56
	v_add_f32_e32 v41, v53, v57
	v_add_f32_e32 v50, v50, v54
	v_add_f32_e32 v51, v51, v55
	s_waitcnt vmcnt(0)
	v_add_f32_e32 v52, v60, v64
	v_add_f32_e32 v53, v61, v65
	v_add_f32_e32 v54, v58, v62
	v_add_f32_e32 v55, v59, v63
	v_add_f32_e32 v40, v40, v52
	v_add_f32_e32 v41, v41, v53
	v_add_f32_e32 v50, v50, v54
	v_add_f32_e32 v51, v51, v55
	v_add_f32_e32 v2, v2, v40
	v_add_f32_e32 v3, v3, v41
	v_add_f32_e32 v0, v0, v50
	v_add_f32_e32 v1, v1, v51
	global_store_dwordx4 v[72:73], v[0:3], off offset:3072
	s_branch .LBB0_932

.LBB0_1006:
	s_add_i32 s37, s35, 0x8000
	s_and_b32 s36, s37, 0x8000
	s_add_i32 s36, s36, 0
	s_add_u32 s86, s36, s87
	s_mov_b32 m0, s86
	s_waitcnt vmcnt(0) lgkmcnt(0)
	s_barrier
	global_load_lds_dwordx4 v244, s[96:97]
	s_add_u32 m0, s86, 0x4000
	s_nop 0
	global_load_lds_dwordx4 v245, s[88:89]
	s_add_u32 m0, s86, 0x1000
	s_nop 0
	global_load_lds_dwordx4 v246, s[96:97]
	s_add_u32 m0, s86, 0x5000
	s_nop 0
	global_load_lds_dwordx4 v247, s[88:89]
	s_add_u32 m0, s86, 0x2000
	s_nop 0
	global_load_lds_dwordx4 v248, s[96:97]
	s_add_u32 m0, s86, 0x6000
	s_nop 0
	global_load_lds_dwordx4 v249, s[88:89]
	s_add_u32 m0, s86, 0x3000
	s_nop 0
	global_load_lds_dwordx4 v250, s[96:97]
	s_add_u32 m0, s86, 0x7000
	s_nop 0
	global_load_lds_dwordx4 v251, s[88:89]
	s_add_u32 s96, s96, 0x80
	s_addc_u32 s97, s97, 0
	s_add_u32 s88, s88, 0x80
	s_addc_u32 s89, s89, 0
	s_and_b32 s35, s35, 0x8000
	s_add_i32 s35, s35, 0
	v_add3_u32 v143, s35, v80, v81
	v_add3_u32 v145, s35, v81, v82
	v_add3_u32 v206, s35, v80, v83
	v_add3_u32 v207, s35, v82, v83
	ds_read_b128 v[102:105], v145
	ds_read_b128 v[94:97], v143 offset:16384
	ds_read_b128 v[98:101], v143 offset:18432
	ds_read_b128 v[106:109], v145 offset:2048
	ds_read_b128 v[110:113], v143 offset:20480
	ds_read_b128 v[114:117], v143 offset:22528
	ds_read_b128 v[118:121], v143 offset:24576
	ds_read_b128 v[122:125], v143 offset:26624
	ds_read_b128 v[126:129], v143 offset:28672
	ds_read_b128 v[130:133], v143 offset:30720
	ds_read_b128 v[174:177], v207
	ds_read_b128 v[166:169], v206 offset:16384
	ds_read_b128 v[170:173], v206 offset:18432
	ds_read_b128 v[178:181], v207 offset:2048
	ds_read_b128 v[182:185], v206 offset:20480
	ds_read_b128 v[186:189], v206 offset:22528
	ds_read_b128 v[190:193], v206 offset:24576
	ds_read_b128 v[194:197], v206 offset:26624
	ds_read_b128 v[198:201], v206 offset:28672
	ds_read_b128 v[202:205], v206 offset:30720
	s_add_u32 s26, s26, 0x80
	s_addc_u32 s27, s27, 0
	s_cmpk_eq_i32 s26, 0x780
	s_mov_b32 s35, s37
	s_waitcnt lgkmcnt(15)
	v_mfma_f32_16x16x32_bf16 v[60:63], v[94:97], v[102:105], v[60:63]
	v_mfma_f32_16x16x32_bf16 v[56:59], v[98:101], v[102:105], v[56:59]
	v_mfma_f32_16x16x32_bf16 v[28:31], v[94:97], v[106:109], v[28:31]
	v_mfma_f32_16x16x32_bf16 v[24:27], v[98:101], v[106:109], v[24:27]
	v_mfma_f32_16x16x32_bf16 v[52:55], v[110:113], v[102:105], v[52:55]
	v_mfma_f32_16x16x32_bf16 v[16:19], v[110:113], v[106:109], v[16:19]
	s_waitcnt lgkmcnt(14)
	v_mfma_f32_16x16x32_bf16 v[48:51], v[114:117], v[102:105], v[48:51]
	v_mfma_f32_16x16x32_bf16 v[12:15], v[114:117], v[106:109], v[12:15]
	s_waitcnt lgkmcnt(13)
	v_mfma_f32_16x16x32_bf16 v[44:47], v[118:121], v[102:105], v[44:47]
	v_mfma_f32_16x16x32_bf16 v[8:11], v[118:121], v[106:109], v[8:11]
	s_waitcnt lgkmcnt(12)
	v_mfma_f32_16x16x32_bf16 v[40:43], v[122:125], v[102:105], v[40:43]
	v_mfma_f32_16x16x32_bf16 v[4:7], v[122:125], v[106:109], v[4:7]
	s_waitcnt lgkmcnt(11)
	v_mfma_f32_16x16x32_bf16 v[36:39], v[126:129], v[102:105], v[36:39]
	v_mfma_f32_16x16x32_bf16 v[0:3], v[126:129], v[106:109], v[0:3]
	s_waitcnt lgkmcnt(10)
	v_mfma_f32_16x16x32_bf16 v[32:35], v[130:133], v[102:105], v[32:35]
	v_mfma_f32_16x16x32_bf16 v[20:23], v[130:133], v[106:109], v[20:23]
	s_waitcnt lgkmcnt(8)
	v_mfma_f32_16x16x32_bf16 v[60:63], v[166:169], v[174:177], v[60:63]
	s_waitcnt lgkmcnt(7)
	v_mfma_f32_16x16x32_bf16 v[56:59], v[170:173], v[174:177], v[56:59]
	s_waitcnt lgkmcnt(6)
	v_mfma_f32_16x16x32_bf16 v[28:31], v[166:169], v[178:181], v[28:31]
	v_mfma_f32_16x16x32_bf16 v[24:27], v[170:173], v[178:181], v[24:27]
	s_waitcnt lgkmcnt(5)
	v_mfma_f32_16x16x32_bf16 v[52:55], v[182:185], v[174:177], v[52:55]
	v_mfma_f32_16x16x32_bf16 v[16:19], v[182:185], v[178:181], v[16:19]
	s_waitcnt lgkmcnt(4)
	v_mfma_f32_16x16x32_bf16 v[48:51], v[186:189], v[174:177], v[48:51]
	v_mfma_f32_16x16x32_bf16 v[12:15], v[186:189], v[178:181], v[12:15]
	s_waitcnt lgkmcnt(3)
	v_mfma_f32_16x16x32_bf16 v[44:47], v[190:193], v[174:177], v[44:47]
	v_mfma_f32_16x16x32_bf16 v[8:11], v[190:193], v[178:181], v[8:11]
	s_waitcnt lgkmcnt(2)
	v_mfma_f32_16x16x32_bf16 v[40:43], v[194:197], v[174:177], v[40:43]
	v_mfma_f32_16x16x32_bf16 v[4:7], v[194:197], v[178:181], v[4:7]
	s_waitcnt lgkmcnt(1)
	v_mfma_f32_16x16x32_bf16 v[36:39], v[198:201], v[174:177], v[36:39]
	v_mfma_f32_16x16x32_bf16 v[0:3], v[198:201], v[178:181], v[0:3]
	s_waitcnt lgkmcnt(0)
	v_mfma_f32_16x16x32_bf16 v[32:35], v[202:205], v[174:177], v[32:35]
	v_mfma_f32_16x16x32_bf16 v[20:23], v[202:205], v[178:181], v[20:23]
	s_cbranch_scc0 .LBB0_1006
	v_add_u32_e32 v138, s36, v80
	v_add_u32_e32 v126, v138, v81
	s_waitcnt vmcnt(0)
	s_barrier
	ds_read_b128 v[74:77], v126 offset:16384
	v_add3_u32 v102, s36, v81, v82
	ds_read_b128 v[94:97], v102
	ds_read_b128 v[98:101], v126 offset:18432
	ds_read_b128 v[102:105], v102 offset:2048
	ds_read_b128 v[106:109], v126 offset:20480
	ds_read_b128 v[110:113], v126 offset:22528
	ds_read_b128 v[114:117], v126 offset:24576
	ds_read_b128 v[118:121], v126 offset:26624
	v_add3_u32 v134, s36, v83, v82
	v_add_u32_e32 v142, v138, v83
	ds_read_b128 v[122:125], v126 offset:28672
	ds_read_b128 v[126:129], v126 offset:30720
	ds_read_b128 v[130:133], v134
	ds_read_b128 v[134:137], v134 offset:2048
	ds_read_b128 v[138:141], v142 offset:16384
	ds_read_b128 v[146:149], v142 offset:18432
	s_waitcnt lgkmcnt(11)
	v_mfma_f32_16x16x32_bf16 v[56:59], v[98:101], v[94:97], v[56:59]
	s_lshl_b32 s36, s34, 7
	s_lshl_b32 s26, s33, 7
	s_ashr_i32 s27, s26, 31
	v_mfma_f32_16x16x32_bf16 v[60:63], v[74:77], v[94:97], v[60:63]
	s_lshl_b64 s[26:27], s[26:27], 1
	s_add_i32 s31, s31, s28
	s_cmpk_gt_i32 s31, 0x107f
	s_waitcnt lgkmcnt(0)
	v_mfma_f32_16x16x32_bf16 v[56:59], v[146:149], v[130:133], v[56:59]
	v_mfma_f32_16x16x32_bf16 v[48:51], v[110:113], v[94:97], v[48:51]
	v_mfma_f32_16x16x32_bf16 v[52:55], v[106:109], v[94:97], v[52:55]
	s_nop 5
	v_max_f32_e32 v56, v56, v56
	v_max_f32_e32 v57, v57, v57
	v_max_f32_e32 v56, 0, v56
	v_mfma_f32_16x16x32_bf16 v[44:47], v[114:117], v[94:97], v[44:47]
	v_max_f32_e32 v57, 0, v57
	v_max_f32_e32 v59, v59, v59
	v_max_f32_e32 v59, 0, v59
	v_mfma_f32_16x16x32_bf16 v[40:43], v[118:121], v[94:97], v[40:43]
	v_mfma_f32_16x16x32_bf16 v[36:39], v[122:125], v[94:97], v[36:39]
	v_mfma_f32_16x16x32_bf16 v[32:35], v[126:129], v[94:97], v[32:35]
	ds_read_b128 v[94:97], v142 offset:20480
	ds_read_b128 v[150:153], v142 offset:22528
	ds_read_b128 v[154:157], v142 offset:24576
	ds_read_b128 v[158:161], v142 offset:26624
	v_mfma_f32_16x16x32_bf16 v[60:63], v[138:141], v[130:133], v[60:63]
	s_waitcnt lgkmcnt(2)
	v_mfma_f32_16x16x32_bf16 v[48:51], v[150:153], v[130:133], v[48:51]
	v_mfma_f32_16x16x32_bf16 v[16:19], v[106:109], v[102:105], v[16:19]
	v_mul_f32_e64 v106, v56, v56
	v_mul_f32_e64 v107, v57, v57
	v_max_f32_e32 v57, v58, v58
	s_nop 1
	v_max_f32_e32 v60, v60, v60
	v_mfma_f32_16x16x32_bf16 v[24:27], v[98:101], v[102:105], v[24:27]
	v_add_u32_e32 v100, s36, v79
	v_mov_b64_e32 v[98:99], s[0:1]
	v_max_f32_e32 v61, v61, v61
	v_max_f32_e32 v56, v62, v62
	v_max_f32_e32 v58, 0, v57
	v_max_f32_e32 v57, v63, v63
	v_mad_i64_i32 v[100:101], s[34:35], v100, s30, v[98:99]
	v_max_f32_e32 v60, 0, v60
	v_max_f32_e32 v61, 0, v61
	v_max_f32_e32 v56, 0, v56
	v_max_f32_e32 v57, 0, v57
	v_mfma_f32_16x16x32_bf16 v[52:55], v[94:97], v[130:133], v[52:55]
	v_lshl_add_u64 v[100:101], v[100:101], 0, s[26:27]
	v_mul_f32_e32 v60, v60, v60
	v_mul_f32_e32 v61, v61, v61
	v_mul_f32_e32 v62, v56, v56
	v_mul_f32_e32 v63, v57, v57
	v_mfma_f32_16x16x32_bf16 v[28:31], v[74:77], v[102:105], v[28:31]
	v_max_f32_e32 v48, v48, v48
	v_max_f32_e32 v49, v49, v49
	ds_read_b128 v[74:77], v142 offset:28672
	ds_read_b128 v[162:165], v142 offset:30720
	v_mfma_f32_16x16x32_bf16 v[12:15], v[110:113], v[102:105], v[12:15]
	v_lshl_add_u64 v[100:101], v[100:101], 0, v[64:65]
	v_cvt_pk_bf16_f32 v56, v60, v61
	v_cvt_pk_bf16_f32 v57, v62, v63
	v_mfma_f32_16x16x32_bf16 v[8:11], v[114:117], v[102:105], v[8:11]
	v_max_f32_e32 v48, 0, v48
	v_max_f32_e32 v49, 0, v49
	v_max_f32_e32 v52, v52, v52
	v_mfma_f32_16x16x32_bf16 v[4:7], v[118:121], v[102:105], v[4:7]
	v_max_f32_e32 v53, v53, v53
	v_max_f32_e32 v51, v51, v51
	v_max_f32_e32 v52, 0, v52
	v_mfma_f32_16x16x32_bf16 v[0:3], v[122:125], v[102:105], v[0:3]
	v_max_f32_e32 v53, 0, v53
	v_max_f32_e32 v51, 0, v51
	v_mul_f32_e32 v52, v52, v52
	v_mul_f32_e32 v53, v53, v53
	v_mfma_f32_16x16x32_bf16 v[20:23], v[126:129], v[102:105], v[20:23]
	v_mul_f32_e64 v102, v58, v58
	v_mul_f32_e64 v103, v59, v59
	v_cvt_pk_bf16_f32 v58, v106, v107
	v_cvt_pk_bf16_f32 v59, v102, v103
	s_waitcnt lgkmcnt(2)
	v_mfma_f32_16x16x32_bf16 v[40:43], v[158:161], v[130:133], v[40:43]
	global_store_dwordx4 v[100:101], v[56:59], off
	s_nop 1
	v_mul_f32_e32 v56, v48, v48
	v_mul_f32_e32 v57, v49, v49
	v_max_f32_e32 v49, v50, v50
	v_max_f32_e32 v48, v54, v54
	v_max_f32_e32 v50, 0, v49
	v_max_f32_e32 v49, v55, v55
	v_mfma_f32_16x16x32_bf16 v[44:47], v[154:157], v[130:133], v[44:47]
	v_max_f32_e32 v48, 0, v48
	v_max_f32_e32 v49, 0, v49
	v_mul_f32_e32 v54, v48, v48
	v_mul_f32_e32 v55, v49, v49
	v_mul_f32_e32 v58, v50, v50
	v_mul_f32_e32 v59, v51, v51
	v_max_f32_e32 v40, v40, v40
	v_max_f32_e32 v41, v41, v41
	s_waitcnt lgkmcnt(0)
	v_mfma_f32_16x16x32_bf16 v[32:35], v[162:165], v[130:133], v[32:35]
	v_cvt_pk_bf16_f32 v48, v52, v53
	v_cvt_pk_bf16_f32 v49, v54, v55
	v_cvt_pk_bf16_f32 v50, v56, v57
	v_cvt_pk_bf16_f32 v51, v58, v59
	v_max_f32_e32 v40, 0, v40
	v_max_f32_e32 v41, 0, v41
	global_store_dwordx4 v[100:101], v[48:51], off offset:64
	v_max_f32_e32 v44, v44, v44
	v_max_f32_e32 v45, v45, v45
	v_mul_f32_e32 v48, v40, v40
	v_mul_f32_e32 v49, v41, v41
	v_max_f32_e32 v41, v42, v42
	v_max_f32_e32 v40, v46, v46
	v_max_f32_e32 v42, 0, v41
	v_max_f32_e32 v41, v47, v47
	v_max_f32_e32 v43, v43, v43
	v_mfma_f32_16x16x32_bf16 v[36:39], v[74:77], v[130:133], v[36:39]
	v_max_f32_e32 v44, 0, v44
	v_max_f32_e32 v45, 0, v45
	v_max_f32_e32 v40, 0, v40
	v_max_f32_e32 v41, 0, v41
	v_max_f32_e32 v43, 0, v43
	v_mul_f32_e32 v44, v44, v44
	v_mul_f32_e32 v45, v45, v45
	v_mul_f32_e32 v46, v40, v40
	v_mul_f32_e32 v47, v41, v41
	v_mul_f32_e32 v50, v42, v42
	v_mul_f32_e32 v51, v43, v43
	v_max_f32_e32 v32, v32, v32
	v_max_f32_e32 v33, v33, v33
	v_mfma_f32_16x16x32_bf16 v[24:27], v[146:149], v[134:137], v[24:27]
	v_cvt_pk_bf16_f32 v40, v44, v45
	v_cvt_pk_bf16_f32 v41, v46, v47
	v_cvt_pk_bf16_f32 v42, v48, v49
	v_cvt_pk_bf16_f32 v43, v50, v51
	v_max_f32_e32 v32, 0, v32
	v_max_f32_e32 v33, 0, v33
	global_store_dwordx4 v[100:101], v[40:43], off offset:128
	v_max_f32_e32 v36, v36, v36
	v_max_f32_e32 v37, v37, v37
	v_mul_f32_e32 v40, v32, v32
	v_mul_f32_e32 v41, v33, v33
	v_max_f32_e32 v33, v34, v34
	v_max_f32_e32 v32, v38, v38
	v_max_f32_e32 v34, 0, v33
	v_max_f32_e32 v33, v39, v39
	v_max_f32_e32 v35, v35, v35
	v_mfma_f32_16x16x32_bf16 v[28:31], v[138:141], v[134:137], v[28:31]
	v_max_f32_e32 v36, 0, v36
	v_max_f32_e32 v37, 0, v37
	v_max_f32_e32 v32, 0, v32
	v_max_f32_e32 v33, 0, v33
	v_max_f32_e32 v35, 0, v35
	v_mul_f32_e32 v36, v36, v36
	v_mul_f32_e32 v37, v37, v37
	v_mul_f32_e32 v38, v32, v32
	v_mul_f32_e32 v39, v33, v33
	v_mul_f32_e32 v42, v34, v34
	v_mul_f32_e32 v43, v35, v35
	v_max_f32_e32 v24, v24, v24
	v_max_f32_e32 v25, v25, v25
	v_mfma_f32_16x16x32_bf16 v[12:15], v[150:153], v[134:137], v[12:15]
	v_cvt_pk_bf16_f32 v32, v36, v37
	v_cvt_pk_bf16_f32 v33, v38, v39
	v_cvt_pk_bf16_f32 v34, v40, v41
	v_cvt_pk_bf16_f32 v35, v42, v43
	v_max_f32_e32 v24, 0, v24
	v_max_f32_e32 v25, 0, v25
	global_store_dwordx4 v[100:101], v[32:35], off offset:192
	v_max_f32_e32 v28, v28, v28
	v_max_f32_e32 v29, v29, v29
	v_mul_f32_e32 v34, v24, v24
	v_mul_f32_e32 v35, v25, v25
	v_max_f32_e32 v25, v26, v26
	v_add_u32_e32 v32, s36, v84
	v_max_f32_e32 v24, v30, v30
	v_max_f32_e32 v26, 0, v25
	v_max_f32_e32 v25, v31, v31
	v_max_f32_e32 v27, v27, v27
	v_mfma_f32_16x16x32_bf16 v[16:19], v[94:97], v[134:137], v[16:19]
	v_mad_i64_i32 v[32:33], s[34:35], v32, s30, v[98:99]
	v_max_f32_e32 v28, 0, v28
	v_max_f32_e32 v29, 0, v29
	v_max_f32_e32 v24, 0, v24
	v_max_f32_e32 v25, 0, v25
	v_max_f32_e32 v27, 0, v27
	v_lshl_add_u64 v[32:33], v[32:33], 0, s[26:27]
	v_mul_f32_e32 v28, v28, v28
	v_mul_f32_e32 v29, v29, v29
	v_mul_f32_e32 v30, v24, v24
	v_mul_f32_e32 v31, v25, v25
	v_mul_f32_e32 v36, v26, v26
	v_mul_f32_e32 v37, v27, v27
	v_max_f32_e32 v12, v12, v12
	v_max_f32_e32 v13, v13, v13
	v_mfma_f32_16x16x32_bf16 v[4:7], v[158:161], v[134:137], v[4:7]
	v_lshl_add_u64 v[32:33], v[32:33], 0, v[64:65]
	v_cvt_pk_bf16_f32 v24, v28, v29
	v_cvt_pk_bf16_f32 v25, v30, v31
	v_cvt_pk_bf16_f32 v26, v34, v35
	v_cvt_pk_bf16_f32 v27, v36, v37
	v_max_f32_e32 v12, 0, v12
	v_max_f32_e32 v13, 0, v13
	global_store_dwordx4 v[32:33], v[24:27], off
	v_max_f32_e32 v16, v16, v16
	v_max_f32_e32 v17, v17, v17
	v_mul_f32_e32 v24, v12, v12
	v_mul_f32_e32 v25, v13, v13
	v_max_f32_e32 v13, v14, v14
	v_max_f32_e32 v12, v18, v18
	v_max_f32_e32 v14, 0, v13
	v_max_f32_e32 v13, v19, v19
	v_max_f32_e32 v15, v15, v15
	v_mfma_f32_16x16x32_bf16 v[8:11], v[154:157], v[134:137], v[8:11]
	v_max_f32_e32 v16, 0, v16
	v_max_f32_e32 v17, 0, v17
	v_max_f32_e32 v12, 0, v12
	v_max_f32_e32 v13, 0, v13
	v_max_f32_e32 v15, 0, v15
	v_mul_f32_e32 v16, v16, v16
	v_mul_f32_e32 v17, v17, v17
	v_mul_f32_e32 v18, v12, v12
	v_mul_f32_e32 v19, v13, v13
	v_mul_f32_e32 v26, v14, v14
	v_mul_f32_e32 v27, v15, v15
	v_max_f32_e32 v4, v4, v4
	v_max_f32_e32 v5, v5, v5
	v_cvt_pk_bf16_f32 v12, v16, v17
	v_cvt_pk_bf16_f32 v13, v18, v19
	v_cvt_pk_bf16_f32 v14, v24, v25
	v_cvt_pk_bf16_f32 v15, v26, v27
	v_max_f32_e32 v4, 0, v4
	v_max_f32_e32 v5, 0, v5
	global_store_dwordx4 v[32:33], v[12:15], off offset:64
	v_mfma_f32_16x16x32_bf16 v[0:3], v[74:77], v[134:137], v[0:3]
	v_max_f32_e32 v8, v8, v8
	v_mul_f32_e32 v12, v4, v4
	v_mul_f32_e32 v13, v5, v5
	v_max_f32_e32 v5, v6, v6
	v_mfma_f32_16x16x32_bf16 v[20:23], v[162:165], v[134:137], v[20:23]
	v_max_f32_e32 v9, v9, v9
	v_max_f32_e32 v4, v10, v10
	v_max_f32_e32 v6, 0, v5
	v_max_f32_e32 v5, v11, v11
	v_max_f32_e32 v7, v7, v7
	v_max_f32_e32 v8, 0, v8
	v_max_f32_e32 v9, 0, v9
	v_max_f32_e32 v4, 0, v4
	v_max_f32_e32 v5, 0, v5
	v_max_f32_e32 v7, 0, v7
	v_mul_f32_e32 v8, v8, v8
	v_mul_f32_e32 v9, v9, v9
	v_mul_f32_e32 v10, v4, v4
	v_mul_f32_e32 v11, v5, v5
	v_mul_f32_e32 v14, v6, v6
	v_mul_f32_e32 v15, v7, v7
	v_cvt_pk_bf16_f32 v4, v8, v9
	v_cvt_pk_bf16_f32 v5, v10, v11
	v_cvt_pk_bf16_f32 v6, v12, v13
	v_cvt_pk_bf16_f32 v7, v14, v15
	global_store_dwordx4 v[32:33], v[4:7], off offset:128
	v_max_f32_e32 v0, v0, v0
	v_max_f32_e32 v1, v1, v1
	v_max_f32_e32 v4, v20, v20
	v_max_f32_e32 v5, v21, v21
	v_max_f32_e32 v2, v2, v2
	v_max_f32_e32 v6, v22, v22
	v_max_f32_e32 v3, v3, v3
	v_max_f32_e32 v7, v23, v23
	v_max_f32_e32 v0, 0, v0
	v_max_f32_e32 v4, 0, v4
	v_max_f32_e32 v1, 0, v1
	v_max_f32_e32 v5, 0, v5
	v_max_f32_e32 v2, 0, v2
	v_max_f32_e32 v6, 0, v6
	v_max_f32_e32 v3, 0, v3
	v_max_f32_e32 v7, 0, v7
	v_mul_f32_e32 v0, v0, v0
	v_mul_f32_e32 v1, v1, v1
	v_mul_f32_e32 v4, v4, v4
	v_mul_f32_e32 v5, v5, v5
	v_mul_f32_e32 v2, v2, v2
	v_mul_f32_e32 v3, v3, v3
	v_mul_f32_e32 v6, v6, v6
	v_mul_f32_e32 v7, v7, v7
	v_cvt_pk_bf16_f32 v0, v0, v1
	v_cvt_pk_bf16_f32 v1, v2, v3
	v_cvt_pk_bf16_f32 v2, v4, v5
	v_cvt_pk_bf16_f32 v3, v6, v7
	global_store_dwordx4 v[32:33], v[0:3], off offset:192
	s_cbranch_scc0 .LBB0_1005

.LBB0_1065:
	s_or_b64 exec, exec, s[34:35]
	v_ashrrev_i32_e32 v35, 31, v34
	v_lshlrev_b64 v[34:35], 12, v[34:35]
	v_lshl_add_u64 v[34:35], v[36:37], 0, v[34:35]
	v_lshl_add_u64 v[36:37], s[94:95], 0, v[38:39]
	v_lshl_add_u64 v[38:39], v[36:37], 0, s[30:31]
	v_lshl_add_u64 v[46:47], v[34:35], 0, v[72:73]
	v_lshl_add_u64 v[34:35], v[38:39], 0, v[72:73]
	global_load_dwordx4 v[34:37], v[34:35], off
	s_nop 0
	global_load_dwordx4 v[76:79], v[46:47], off
	v_ashrrev_i32_e32 v33, 31, v32
	v_lshlrev_b64 v[32:33], 12, v[32:33]
	v_lshl_add_u64 v[32:33], v[42:43], 0, v[32:33]
	v_lshl_add_u64 v[50:51], v[32:33], 0, v[72:73]
	v_lshl_add_u64 v[42:43], v[74:75], 2, v[38:39]
	s_add_i32 s40, s40, s33
	s_cmpk_lt_i32 s40, 0x400
	s_waitcnt vmcnt(0)
	v_fma_f32 v30, v30, v36, v78
	v_fma_f32 v31, v31, v37, v79
	v_fma_f32 v28, v28, v34, v76
	v_fma_f32 v29, v29, v35, v77
	global_store_dwordx4 v[50:51], v[28:31], off
	global_load_dwordx4 v[28:31], v[46:47], off offset:16
	s_nop 0
	global_load_dwordx4 v[32:35], v[42:43], off
	v_lshl_add_u64 v[36:37], v[60:61], 2, v[38:39]
	s_waitcnt vmcnt(0)
	v_fma_f32 v26, v26, v34, v30
	v_fma_f32 v27, v27, v35, v31
	v_fma_f32 v24, v24, v32, v28
	v_fma_f32 v25, v25, v33, v29
	global_store_dwordx4 v[50:51], v[24:27], off offset:16
	global_load_dwordx4 v[24:27], v[46:47], off offset:128
	s_nop 0
	global_load_dwordx4 v[28:31], v[36:37], off
	v_lshl_add_u64 v[32:33], v[56:57], 2, v[38:39]
	s_waitcnt vmcnt(0)
	v_fma_f32 v22, v22, v30, v26
	v_fma_f32 v23, v23, v31, v27
	v_fma_f32 v20, v20, v28, v24
	v_fma_f32 v21, v21, v29, v25
	global_store_dwordx4 v[50:51], v[20:23], off offset:128
	global_load_dwordx4 v[20:23], v[46:47], off offset:144
	s_nop 0
	global_load_dwordx4 v[24:27], v[32:33], off
	v_lshl_add_u64 v[28:29], v[52:53], 2, v[38:39]
	s_waitcnt vmcnt(0)
	v_fma_f32 v18, v18, v26, v22
	v_fma_f32 v19, v19, v27, v23
	v_fma_f32 v16, v16, v24, v20
	v_fma_f32 v17, v17, v25, v21
	global_store_dwordx4 v[50:51], v[16:19], off offset:144
	global_load_dwordx4 v[16:19], v[46:47], off offset:256
	s_nop 0
	global_load_dwordx4 v[20:23], v[28:29], off
	v_lshl_add_u64 v[24:25], v[48:49], 2, v[38:39]
	s_waitcnt vmcnt(0)
	v_fma_f32 v14, v14, v22, v18
	v_fma_f32 v15, v15, v23, v19
	v_fma_f32 v12, v12, v20, v16
	v_fma_f32 v13, v13, v21, v17
	global_store_dwordx4 v[50:51], v[12:15], off offset:256
	global_load_dwordx4 v[12:15], v[46:47], off offset:272
	s_nop 0
	global_load_dwordx4 v[16:19], v[24:25], off
	v_lshl_add_u64 v[20:21], v[44:45], 2, v[38:39]
	s_waitcnt vmcnt(0)
	v_fma_f32 v10, v10, v18, v14
	v_fma_f32 v11, v11, v19, v15
	v_fma_f32 v8, v8, v16, v12
	v_fma_f32 v9, v9, v17, v13
	global_store_dwordx4 v[50:51], v[8:11], off offset:272
	global_load_dwordx4 v[8:11], v[46:47], off offset:384
	s_nop 0
	global_load_dwordx4 v[12:15], v[20:21], off
	v_lshl_add_u64 v[16:17], v[40:41], 2, v[38:39]
	s_waitcnt vmcnt(0)
	v_fma_f32 v6, v6, v14, v10
	v_fma_f32 v7, v7, v15, v11
	v_fma_f32 v4, v4, v12, v8
	v_fma_f32 v5, v5, v13, v9
	global_store_dwordx4 v[50:51], v[4:7], off offset:384
	global_load_dwordx4 v[4:7], v[46:47], off offset:400
	s_nop 0
	global_load_dwordx4 v[8:11], v[16:17], off
	s_waitcnt vmcnt(0)
	v_fma_f32 v2, v2, v10, v6
	v_fma_f32 v3, v3, v11, v7
	v_fma_f32 v0, v0, v8, v4
	v_fma_f32 v1, v1, v9, v5
	global_store_dwordx4 v[50:51], v[0:3], off offset:400
	s_cbranch_scc0 .LBB0_1088

.LBB0_1080:
	s_or_b64 exec, exec, s[34:35]
	v_ashrrev_i32_e32 v73, 31, v72
	v_lshlrev_b64 v[72:73], 12, v[72:73]
	v_lshl_or_b32 v108, s41, 7, v86
	v_lshl_add_u64 v[76:77], v[76:77], 0, v[72:73]
	v_lshl_add_u64 v[72:73], s[94:95], 0, v[78:79]
	v_ashrrev_i32_e32 v109, 31, v108
	v_lshl_add_u64 v[106:107], v[72:73], 0, s[30:31]
	v_lshlrev_b64 v[72:73], 2, v[108:109]
	v_lshl_add_u64 v[110:111], v[76:77], 0, v[72:73]
	v_lshl_add_u64 v[102:103], v[106:107], 0, v[72:73]
	global_load_dwordx4 v[76:79], v[110:111], off
	v_ashrrev_i32_e32 v75, 31, v74
	global_load_dwordx4 v[102:105], v[102:103], off
	v_lshlrev_b64 v[112:113], 12, v[74:75]
	v_lshl_add_u64 v[80:81], v[80:81], 0, v[112:113]
	v_or_b32_e32 v74, 4, v108
	v_lshl_add_u64 v[80:81], v[80:81], 0, v[72:73]
	v_ashrrev_i32_e32 v75, 31, v74
	v_lshl_add_u64 v[112:113], v[74:75], 2, v[106:107]
	s_waitcnt vmcnt(0)
	v_fma_f32 v62, v62, v104, v78
	v_fma_f32 v63, v63, v105, v79
	v_fma_f32 v60, v60, v102, v76
	v_fma_f32 v61, v61, v103, v77
	global_store_dwordx4 v[80:81], v[60:63], off
	global_load_dwordx4 v[76:79], v[110:111], off offset:16
	global_load_dwordx4 v[102:105], v[112:113], off
	v_or_b32_e32 v60, 32, v108
	v_ashrrev_i32_e32 v61, 31, v60
	v_lshl_add_u64 v[62:63], v[60:61], 2, v[106:107]
	s_waitcnt vmcnt(0)
	v_fma_f32 v58, v58, v104, v78
	v_fma_f32 v59, v59, v105, v79
	v_fma_f32 v56, v56, v102, v76
	v_fma_f32 v57, v57, v103, v77
	global_store_dwordx4 v[80:81], v[56:59], off offset:16
	global_load_dwordx4 v[76:79], v[110:111], off offset:128
	global_load_dwordx4 v[102:105], v[62:63], off
	v_or_b32_e32 v56, 36, v108
	v_ashrrev_i32_e32 v57, 31, v56
	v_lshl_add_u64 v[58:59], v[56:57], 2, v[106:107]
	s_waitcnt vmcnt(0)
	v_fma_f32 v54, v54, v104, v78
	v_fma_f32 v55, v55, v105, v79
	v_fma_f32 v52, v52, v102, v76
	v_fma_f32 v53, v53, v103, v77
	global_store_dwordx4 v[80:81], v[52:55], off offset:128
	global_load_dwordx4 v[76:79], v[110:111], off offset:144
	global_load_dwordx4 v[102:105], v[58:59], off
	v_or_b32_e32 v52, 64, v108
	v_ashrrev_i32_e32 v53, 31, v52
	v_lshl_add_u64 v[54:55], v[52:53], 2, v[106:107]
	s_waitcnt vmcnt(0)
	v_fma_f32 v50, v50, v104, v78
	v_fma_f32 v51, v51, v105, v79
	v_fma_f32 v48, v48, v102, v76
	v_fma_f32 v49, v49, v103, v77
	global_store_dwordx4 v[80:81], v[48:51], off offset:144
	global_load_dwordx4 v[76:79], v[110:111], off offset:256
	global_load_dwordx4 v[102:105], v[54:55], off
	v_or_b32_e32 v48, 0x44, v108
	v_ashrrev_i32_e32 v49, 31, v48
	v_lshl_add_u64 v[50:51], v[48:49], 2, v[106:107]
	s_waitcnt vmcnt(0)
	v_fma_f32 v46, v46, v104, v78
	v_fma_f32 v47, v47, v105, v79
	v_fma_f32 v44, v44, v102, v76
	v_fma_f32 v45, v45, v103, v77
	global_store_dwordx4 v[80:81], v[44:47], off offset:256
	global_load_dwordx4 v[76:79], v[110:111], off offset:272
	global_load_dwordx4 v[102:105], v[50:51], off
	v_or_b32_e32 v44, 0x60, v108
	v_ashrrev_i32_e32 v45, 31, v44
	v_lshl_add_u64 v[46:47], v[44:45], 2, v[106:107]
	s_waitcnt vmcnt(0)
	v_fma_f32 v42, v42, v104, v78
	v_fma_f32 v43, v43, v105, v79
	v_fma_f32 v40, v40, v102, v76
	v_fma_f32 v41, v41, v103, v77
	global_store_dwordx4 v[80:81], v[40:43], off offset:272
	global_load_dwordx4 v[76:79], v[110:111], off offset:384
	global_load_dwordx4 v[102:105], v[46:47], off
	v_or_b32_e32 v40, 0x64, v108
	v_ashrrev_i32_e32 v41, 31, v40
	v_lshl_add_u64 v[42:43], v[40:41], 2, v[106:107]
	s_waitcnt vmcnt(0)
	v_fma_f32 v38, v38, v104, v78
	v_fma_f32 v39, v39, v105, v79
	v_fma_f32 v36, v36, v102, v76
	v_fma_f32 v37, v37, v103, v77
	global_store_dwordx4 v[80:81], v[36:39], off offset:384
	global_load_dwordx4 v[76:79], v[110:111], off offset:400
	global_load_dwordx4 v[102:105], v[42:43], off
	v_add_u32_e32 v36, s42, v92
	v_mul_hi_i32 v37, v36, s36
	v_lshrrev_b32_e32 v38, 31, v37
	v_ashrrev_i32_e32 v37, 11, v37
	v_add_u32_e32 v42, v37, v38
	v_mad_i32_i24 v38, v42, s37, v36
	v_lshlrev_b32_e32 v36, 13, v42
	v_cmp_lt_i32_e32 vcc, s38, v38
	s_waitcnt vmcnt(0)
	v_fma_f32 v34, v34, v104, v78
	v_fma_f32 v35, v35, v105, v79
	v_fma_f32 v32, v32, v102, v76
	v_fma_f32 v33, v33, v103, v77
	global_store_dwordx4 v[80:81], v[32:35], off offset:400
	s_nop 1
	v_add3_u32 v32, v36, v38, s39
	s_and_saveexec_b64 s[34:35], vcc
	s_xor_b64 s[34:35], exec, s[34:35]
	v_add3_u32 v34, v36, v38, s39
	s_or_saveexec_b64 s[34:35], s[34:35]
	v_mov_b64_e32 v[36:37], s[92:93]
	v_lshl_add_u32 v33, v42, 8, v38
	s_xor_b64 exec, exec, s[34:35]
	v_lshl_add_u32 v34, v42, 8, v38
	v_mov_b64_e32 v[36:37], s[6:7]
	s_or_b64 exec, exec, s[34:35]
	s_and_saveexec_b64 s[34:35], vcc
	s_xor_b64 s[34:35], exec, s[34:35]
	s_cbranch_execz .LBB0_1086
	v_mul_hi_i32_i24_e32 v39, 0x6000, v42
	v_mul_i32_i24_e32 v38, 0x6000, v42
	s_or_saveexec_b64 s[34:35], s[34:35]
	v_mov_b64_e32 v[42:43], s[92:93]
	s_xor_b64 exec, exec, s[34:35]
	s_cbranch_execz .LBB0_1065
	s_branch .LBB0_1087

.LBB0_1091:
	s_add_i32 s48, s47, 0x8000
	s_and_b32 s8, s47, 0x8000
	s_and_b32 s47, s48, 0x8000
	s_add_i32 s49, s8, 0
	s_add_i32 s8, s47, 0
	s_add_u32 s71, s8, s75
	s_mov_b32 m0, s71
	s_waitcnt vmcnt(0) lgkmcnt(0)
	s_barrier
	global_load_lds_dwordx4 v236, s[84:85]
	s_add_u32 m0, s71, 0x4000
	s_nop 0
	global_load_lds_dwordx4 v237, s[72:73]
	s_add_u32 m0, s71, 0x1000
	s_nop 0
	global_load_lds_dwordx4 v238, s[84:85]
	s_add_u32 m0, s71, 0x5000
	s_nop 0
	global_load_lds_dwordx4 v239, s[72:73]
	s_add_u32 m0, s71, 0x2000
	s_nop 0
	global_load_lds_dwordx4 v240, s[84:85]
	s_add_u32 m0, s71, 0x6000
	s_nop 0
	global_load_lds_dwordx4 v241, s[72:73]
	s_add_u32 m0, s71, 0x3000
	s_nop 0
	global_load_lds_dwordx4 v242, s[84:85]
	s_add_u32 m0, s71, 0x7000
	s_nop 0
	global_load_lds_dwordx4 v243, s[72:73]
	s_add_u32 s84, s84, 0x80
	s_addc_u32 s85, s85, 0
	s_add_u32 s72, s72, 0x80
	s_addc_u32 s73, s73, 0
	v_add3_u32 v169, s49, v84, v87
	v_add3_u32 v210, s49, v87, v89
	v_add3_u32 v211, s49, v84, v90
	v_add3_u32 v212, s49, v89, v90
	ds_read_b128 v[104:107], v210
	ds_read_b128 v[68:71], v169 offset:16384
	ds_read_b128 v[100:103], v169 offset:18432
	ds_read_b128 v[108:111], v210 offset:2048
	ds_read_b128 v[112:115], v169 offset:20480
	ds_read_b128 v[116:119], v169 offset:22528
	ds_read_b128 v[120:123], v169 offset:24576
	ds_read_b128 v[124:127], v169 offset:26624
	ds_read_b128 v[128:131], v169 offset:28672
	ds_read_b128 v[132:135], v169 offset:30720
	ds_read_b128 v[178:181], v212
	ds_read_b128 v[170:173], v211 offset:16384
	ds_read_b128 v[174:177], v211 offset:18432
	ds_read_b128 v[182:185], v212 offset:2048
	ds_read_b128 v[186:189], v211 offset:20480
	ds_read_b128 v[190:193], v211 offset:22528
	ds_read_b128 v[194:197], v211 offset:24576
	ds_read_b128 v[198:201], v211 offset:26624
	ds_read_b128 v[202:205], v211 offset:28672
	ds_read_b128 v[206:209], v211 offset:30720
	s_add_u32 s36, s36, 0x80
	s_addc_u32 s37, s37, 0
	s_cmpk_eq_i32 s36, 0x780
	s_mov_b32 s47, s48
	s_waitcnt lgkmcnt(15)
	v_mfma_f32_16x16x32_bf16 v[60:63], v[68:71], v[104:107], v[60:63]
	v_mfma_f32_16x16x32_bf16 v[56:59], v[100:103], v[104:107], v[56:59]
	v_mfma_f32_16x16x32_bf16 v[28:31], v[68:71], v[108:111], v[28:31]
	v_mfma_f32_16x16x32_bf16 v[24:27], v[100:103], v[108:111], v[24:27]
	v_mfma_f32_16x16x32_bf16 v[52:55], v[112:115], v[104:107], v[52:55]
	v_mfma_f32_16x16x32_bf16 v[16:19], v[112:115], v[108:111], v[16:19]
	s_waitcnt lgkmcnt(14)
	v_mfma_f32_16x16x32_bf16 v[48:51], v[116:119], v[104:107], v[48:51]
	v_mfma_f32_16x16x32_bf16 v[12:15], v[116:119], v[108:111], v[12:15]
	s_waitcnt lgkmcnt(13)
	v_mfma_f32_16x16x32_bf16 v[44:47], v[120:123], v[104:107], v[44:47]
	v_mfma_f32_16x16x32_bf16 v[8:11], v[120:123], v[108:111], v[8:11]
	s_waitcnt lgkmcnt(12)
	v_mfma_f32_16x16x32_bf16 v[40:43], v[124:127], v[104:107], v[40:43]
	v_mfma_f32_16x16x32_bf16 v[4:7], v[124:127], v[108:111], v[4:7]
	s_waitcnt lgkmcnt(11)
	v_mfma_f32_16x16x32_bf16 v[36:39], v[128:131], v[104:107], v[36:39]
	v_mfma_f32_16x16x32_bf16 v[0:3], v[128:131], v[108:111], v[0:3]
	s_waitcnt lgkmcnt(10)
	v_mfma_f32_16x16x32_bf16 v[32:35], v[132:135], v[104:107], v[32:35]
	v_mfma_f32_16x16x32_bf16 v[20:23], v[132:135], v[108:111], v[20:23]
	s_waitcnt lgkmcnt(8)
	v_mfma_f32_16x16x32_bf16 v[60:63], v[170:173], v[178:181], v[60:63]
	s_waitcnt lgkmcnt(7)
	v_mfma_f32_16x16x32_bf16 v[56:59], v[174:177], v[178:181], v[56:59]
	s_waitcnt lgkmcnt(6)
	v_mfma_f32_16x16x32_bf16 v[28:31], v[170:173], v[182:185], v[28:31]
	v_mfma_f32_16x16x32_bf16 v[24:27], v[174:177], v[182:185], v[24:27]
	s_waitcnt lgkmcnt(5)
	v_mfma_f32_16x16x32_bf16 v[52:55], v[186:189], v[178:181], v[52:55]
	v_mfma_f32_16x16x32_bf16 v[16:19], v[186:189], v[182:185], v[16:19]
	s_waitcnt lgkmcnt(4)
	v_mfma_f32_16x16x32_bf16 v[48:51], v[190:193], v[178:181], v[48:51]
	v_mfma_f32_16x16x32_bf16 v[12:15], v[190:193], v[182:185], v[12:15]
	s_waitcnt lgkmcnt(3)
	v_mfma_f32_16x16x32_bf16 v[44:47], v[194:197], v[178:181], v[44:47]
	v_mfma_f32_16x16x32_bf16 v[8:11], v[194:197], v[182:185], v[8:11]
	s_waitcnt lgkmcnt(2)
	v_mfma_f32_16x16x32_bf16 v[40:43], v[198:201], v[178:181], v[40:43]
	v_mfma_f32_16x16x32_bf16 v[4:7], v[198:201], v[182:185], v[4:7]
	s_waitcnt lgkmcnt(1)
	v_mfma_f32_16x16x32_bf16 v[36:39], v[202:205], v[178:181], v[36:39]
	v_mfma_f32_16x16x32_bf16 v[0:3], v[202:205], v[182:185], v[0:3]
	s_waitcnt lgkmcnt(0)
	v_mfma_f32_16x16x32_bf16 v[32:35], v[206:209], v[178:181], v[32:35]
	v_mfma_f32_16x16x32_bf16 v[20:23], v[206:209], v[182:185], v[20:23]
	s_cbranch_scc0 .LBB0_1091
	v_lshl_add_u32 v99, s46, 7, v85
	v_mul_hi_i32 v64, v99, s39
	v_lshrrev_b32_e32 v65, 31, v64
	v_ashrrev_i32_e32 v64, 11, v64
	v_add_u32_e32 v64, v64, v65
	v_mad_i32_i24 v65, v64, s40, v99
	v_cmp_lt_i32_e32 vcc, s41, v65
	v_lshl_or_b32 v72, s45, 9, v86
	s_waitcnt vmcnt(0)
	v_cndmask_b32_e32 v64, 2, v64, vcc
	v_mul_hi_i32_i24_e32 v65, 0x6000, v64
	v_mul_i32_i24_e32 v64, 0x6000, v64
	v_lshl_add_u64 v[64:65], s[94:95], 0, v[64:65]
	v_lshl_add_u64 v[150:151], v[64:65], 0, s[34:35]
	v_lshl_add_u64 v[64:65], v[150:151], 0, v[72:73]
	s_barrier
	global_load_dwordx4 v[100:103], v[64:65], off
	v_add3_u32 v64, s8, v87, v89
	v_add_u32_e32 v68, s8, v84
	ds_read_b128 v[104:107], v64
	ds_read_b128 v[108:111], v64 offset:2048
	v_add3_u32 v65, s8, v90, v89
	v_add_u32_e32 v145, v68, v87
	ds_read_b128 v[112:115], v65
	ds_read_b128 v[64:67], v65 offset:2048
	v_add_u32_e32 v168, v68, v90
	ds_read_b128 v[116:119], v145 offset:16384
	ds_read_b128 v[120:123], v145 offset:18432
	ds_read_b128 v[124:127], v168 offset:16384
	ds_read_b128 v[68:71], v168 offset:18432
	v_mul_hi_i32 v128, v99, s38
	s_waitcnt lgkmcnt(3)
	v_mfma_f32_16x16x32_bf16 v[60:63], v[116:119], v[104:107], v[60:63]
	v_lshrrev_b32_e32 v129, 31, v128
	v_lshrrev_b32_e32 v128, 11, v128
	v_add_u32_e32 v128, v128, v129
	v_lshl_add_u32 v128, v128, 13, v99
	s_lshl_b32 s8, s44, 9
	v_ashrrev_i32_e32 v129, 31, v128
	s_waitcnt lgkmcnt(1)
	v_mfma_f32_16x16x32_bf16 v[60:63], v[124:127], v[112:115], v[60:63]
	v_lshl_add_u64 v[128:129], v[128:129], 0, s[8:9]
	v_lshlrev_b64 v[128:129], 12, v[128:129]
	v_lshl_add_u64 v[128:129], s[6:7], 0, v[128:129]
	v_mov_b32_e32 v153, v73
	v_or_b32_e32 v152, 16, v72
	v_lshl_add_u64 v[154:155], v[128:129], 0, v[72:73]
	v_lshl_add_u64 v[128:129], v[150:151], 0, v[152:153]
	v_mfma_f32_16x16x32_bf16 v[56:59], v[120:123], v[104:107], v[56:59]
	v_mov_b32_e32 v157, v73
	v_or_b32_e32 v156, 0x80, v72
	v_mov_b32_e32 v159, v73
	s_waitcnt lgkmcnt(0)
	v_mfma_f32_16x16x32_bf16 v[56:59], v[68:71], v[112:115], v[56:59]
	v_or_b32_e32 v158, 0x90, v72
	v_lshl_add_u64 v[136:137], v[150:151], 0, v[158:159]
	v_mov_b32_e32 v161, v73
	v_or_b32_e32 v160, 0x100, v72
	v_mov_b32_e32 v163, v73
	v_or_b32_e32 v162, 0x110, v72
	v_lshl_add_u64 v[146:147], v[150:151], 0, v[162:163]
	v_mov_b32_e32 v165, v73
	v_or_b32_e32 v164, 0x180, v72
	v_lshl_add_u64 v[166:167], v[150:151], 0, v[164:165]
	v_mfma_f32_16x16x32_bf16 v[28:31], v[116:119], v[108:111], v[28:31]
	v_or_b32_e32 v99, 16, v99
	s_add_i32 s43, s43, s33
	s_add_i32 s42, s42, s33
	v_mfma_f32_16x16x32_bf16 v[28:31], v[124:127], v[64:67], v[28:31]
	s_cmpk_gt_i32 s43, 0x7f
	s_waitcnt vmcnt(0)
	v_mul_f32_e32 v62, v62, v102
	v_mul_f32_e32 v63, v63, v103
	v_mul_f32_e32 v60, v60, v100
	v_mul_f32_e32 v61, v61, v101
	global_store_dwordx4 v[154:155], v[60:63], off
	global_load_dwordx4 v[60:63], v[128:129], off
	v_lshl_add_u64 v[100:101], v[150:151], 0, v[156:157]
	v_mfma_f32_16x16x32_bf16 v[24:27], v[120:123], v[108:111], v[24:27]
	s_waitcnt vmcnt(0)
	v_mul_f32_e32 v58, v58, v62
	v_mul_f32_e32 v59, v59, v63
	v_mul_f32_e32 v56, v56, v60
	v_mul_f32_e32 v57, v57, v61
	global_store_dwordx4 v[154:155], v[56:59], off offset:16
	global_load_dwordx4 v[56:59], v[100:101], off
	ds_read_b128 v[60:63], v145 offset:20480
	ds_read_b128 v[100:103], v168 offset:20480
	s_waitcnt lgkmcnt(1)
	v_mfma_f32_16x16x32_bf16 v[52:55], v[60:63], v[104:107], v[52:55]
	ds_read_b128 v[128:131], v145 offset:22528
	ds_read_b128 v[132:135], v168 offset:22528
	s_waitcnt lgkmcnt(2)
	v_mfma_f32_16x16x32_bf16 v[52:55], v[100:103], v[112:115], v[52:55]
	s_waitcnt lgkmcnt(1)
	v_mfma_f32_16x16x32_bf16 v[48:51], v[128:131], v[104:107], v[48:51]
	s_waitcnt vmcnt(0)
	s_nop 4
	v_mul_f32_e32 v54, v54, v58
	v_mul_f32_e32 v55, v55, v59
	v_mul_f32_e32 v52, v52, v56
	v_mul_f32_e32 v53, v53, v57
	global_store_dwordx4 v[154:155], v[52:55], off offset:128
	global_load_dwordx4 v[52:55], v[136:137], off
	s_waitcnt lgkmcnt(0)
	v_mfma_f32_16x16x32_bf16 v[48:51], v[132:135], v[112:115], v[48:51]
	v_lshl_add_u64 v[56:57], v[150:151], 0, v[160:161]
	v_mfma_f32_16x16x32_bf16 v[24:27], v[68:71], v[64:67], v[24:27]
	v_mfma_f32_16x16x32_bf16 v[16:19], v[60:63], v[108:111], v[16:19]
	s_waitcnt vmcnt(0)
	s_nop 3
	v_mul_f32_e32 v50, v50, v54
	v_mul_f32_e32 v51, v51, v55
	v_mul_f32_e32 v48, v48, v52
	v_mul_f32_e32 v49, v49, v53
	global_store_dwordx4 v[154:155], v[48:51], off offset:144
	global_load_dwordx4 v[48:51], v[56:57], off
	ds_read_b128 v[52:55], v145 offset:24576
	ds_read_b128 v[56:59], v168 offset:24576
	s_waitcnt lgkmcnt(1)
	v_mfma_f32_16x16x32_bf16 v[44:47], v[52:55], v[104:107], v[44:47]
	ds_read_b128 v[136:139], v145 offset:26624
	ds_read_b128 v[140:143], v168 offset:26624
	s_waitcnt lgkmcnt(2)
	v_mfma_f32_16x16x32_bf16 v[44:47], v[56:59], v[112:115], v[44:47]
	s_waitcnt lgkmcnt(1)
	v_mfma_f32_16x16x32_bf16 v[40:43], v[136:139], v[104:107], v[40:43]
	s_waitcnt vmcnt(0)
	s_nop 4
	v_mul_f32_e32 v46, v46, v50
	v_mul_f32_e32 v47, v47, v51
	v_mul_f32_e32 v44, v44, v48
	v_mul_f32_e32 v45, v45, v49
	global_store_dwordx4 v[154:155], v[44:47], off offset:256
	global_load_dwordx4 v[44:47], v[146:147], off
	s_waitcnt lgkmcnt(0)
	v_mfma_f32_16x16x32_bf16 v[40:43], v[140:143], v[112:115], v[40:43]
	ds_read_b128 v[48:51], v145 offset:28672
	ds_read_b128 v[146:149], v145 offset:30720
	s_waitcnt lgkmcnt(1)
	v_mfma_f32_16x16x32_bf16 v[36:39], v[48:51], v[104:107], v[36:39]
	s_waitcnt vmcnt(0)
	s_nop 2
	v_mul_f32_e32 v42, v42, v46
	v_mul_f32_e32 v43, v43, v47
	v_mul_f32_e32 v40, v40, v44
	v_mul_f32_e32 v41, v41, v45
	global_store_dwordx4 v[154:155], v[40:43], off offset:272
	global_load_dwordx4 v[40:43], v[166:167], off
	ds_read_b128 v[44:47], v168 offset:28672
	s_waitcnt lgkmcnt(1)
	v_mfma_f32_16x16x32_bf16 v[32:35], v[146:149], v[104:107], v[32:35]
	ds_read_b128 v[104:107], v168 offset:30720
	v_mov_b32_e32 v167, v73
	v_or_b32_e32 v166, 0x190, v72
	s_waitcnt lgkmcnt(1)
	v_mfma_f32_16x16x32_bf16 v[36:39], v[44:47], v[112:115], v[36:39]
	v_lshl_add_u64 v[116:117], v[150:151], 0, v[166:167]
	s_waitcnt vmcnt(0)
	s_nop 5
	v_mul_f32_e32 v38, v38, v42
	v_mul_f32_e32 v39, v39, v43
	v_mul_f32_e32 v36, v36, v40
	v_mul_f32_e32 v37, v37, v41
	global_store_dwordx4 v[154:155], v[36:39], off offset:384
	global_load_dwordx4 v[36:39], v[116:117], off
	v_mul_hi_i32 v40, v99, s39
	v_lshrrev_b32_e32 v41, 31, v40
	v_ashrrev_i32_e32 v40, 11, v40
	v_add_u32_e32 v40, v40, v41
	v_mad_i32_i24 v41, v40, s40, v99
	v_cmp_lt_i32_e32 vcc, s41, v41
	s_waitcnt lgkmcnt(0)
	v_mfma_f32_16x16x32_bf16 v[32:35], v[104:107], v[112:115], v[32:35]
	v_cndmask_b32_e32 v40, 2, v40, vcc
	v_mul_hi_i32_i24_e32 v41, 0x6000, v40
	v_mul_i32_i24_e32 v40, 0x6000, v40
	v_lshl_add_u64 v[40:41], s[94:95], 0, v[40:41]
	v_lshl_add_u64 v[40:41], v[40:41], 0, s[34:35]
	v_lshl_add_u64 v[42:43], v[40:41], 0, v[72:73]
	v_mfma_f32_16x16x32_bf16 v[16:19], v[100:103], v[64:67], v[16:19]
	s_waitcnt vmcnt(0)
	v_mul_f32_e32 v34, v34, v38
	v_mul_f32_e32 v35, v35, v39
	v_mul_f32_e32 v32, v32, v36
	v_mul_f32_e32 v33, v33, v37
	global_store_dwordx4 v[154:155], v[32:35], off offset:400
	global_load_dwordx4 v[32:35], v[42:43], off
	v_mul_hi_i32 v36, v99, s38
	v_lshrrev_b32_e32 v37, 31, v36
	v_lshrrev_b32_e32 v36, 11, v36
	v_add_u32_e32 v36, v36, v37
	v_lshl_add_u32 v36, v36, 13, v99
	v_ashrrev_i32_e32 v37, 31, v36
	v_lshl_add_u64 v[36:37], v[36:37], 0, s[8:9]
	v_lshlrev_b64 v[36:37], 12, v[36:37]
	v_lshl_add_u64 v[36:37], s[6:7], 0, v[36:37]
	v_lshl_add_u64 v[36:37], v[36:37], 0, v[72:73]
	v_lshl_add_u64 v[38:39], v[40:41], 0, v[152:153]
	v_mfma_f32_16x16x32_bf16 v[12:15], v[128:131], v[108:111], v[12:15]
	s_waitcnt vmcnt(0)
	v_mul_f32_e32 v30, v30, v34
	v_mul_f32_e32 v31, v31, v35
	v_mul_f32_e32 v28, v28, v32
	v_mul_f32_e32 v29, v29, v33
	global_store_dwordx4 v[36:37], v[28:31], off
	global_load_dwordx4 v[28:31], v[38:39], off
	v_lshl_add_u64 v[32:33], v[40:41], 0, v[156:157]
	v_mfma_f32_16x16x32_bf16 v[12:15], v[132:135], v[64:67], v[12:15]
	s_waitcnt vmcnt(0)
	v_mul_f32_e32 v26, v26, v30
	v_mul_f32_e32 v27, v27, v31
	v_mul_f32_e32 v24, v24, v28
	v_mul_f32_e32 v25, v25, v29
	global_store_dwordx4 v[36:37], v[24:27], off offset:16
	global_load_dwordx4 v[24:27], v[32:33], off
	v_lshl_add_u64 v[28:29], v[40:41], 0, v[158:159]
	v_mfma_f32_16x16x32_bf16 v[8:11], v[52:55], v[108:111], v[8:11]
	s_waitcnt vmcnt(0)
	v_mul_f32_e32 v18, v18, v26
	v_mul_f32_e32 v19, v19, v27
	v_mul_f32_e32 v16, v16, v24
	v_mul_f32_e32 v17, v17, v25
	global_store_dwordx4 v[36:37], v[16:19], off offset:128
	global_load_dwordx4 v[16:19], v[28:29], off
	v_lshl_add_u64 v[24:25], v[40:41], 0, v[160:161]
	v_mfma_f32_16x16x32_bf16 v[8:11], v[56:59], v[64:67], v[8:11]
	s_waitcnt vmcnt(0)
	v_mul_f32_e32 v14, v14, v18
	v_mul_f32_e32 v15, v15, v19
	v_mul_f32_e32 v12, v12, v16
	v_mul_f32_e32 v13, v13, v17
	global_store_dwordx4 v[36:37], v[12:15], off offset:144
	global_load_dwordx4 v[12:15], v[24:25], off
	v_lshl_add_u64 v[16:17], v[40:41], 0, v[162:163]
	v_mfma_f32_16x16x32_bf16 v[4:7], v[136:139], v[108:111], v[4:7]
	s_waitcnt vmcnt(0)
	v_mul_f32_e32 v10, v10, v14
	v_mul_f32_e32 v11, v11, v15
	v_mul_f32_e32 v8, v8, v12
	v_mul_f32_e32 v9, v9, v13
	global_store_dwordx4 v[36:37], v[8:11], off offset:256
	global_load_dwordx4 v[8:11], v[16:17], off
	v_mfma_f32_16x16x32_bf16 v[4:7], v[140:143], v[64:67], v[4:7]
	v_lshl_add_u64 v[12:13], v[40:41], 0, v[164:165]
	v_mfma_f32_16x16x32_bf16 v[0:3], v[48:51], v[108:111], v[0:3]
	v_mfma_f32_16x16x32_bf16 v[0:3], v[44:47], v[64:67], v[0:3]
	s_waitcnt vmcnt(0)
	s_nop 3
	v_mul_f32_e32 v6, v6, v10
	v_mul_f32_e32 v7, v7, v11
	v_mul_f32_e32 v4, v4, v8
	v_mul_f32_e32 v5, v5, v9
	global_store_dwordx4 v[36:37], v[4:7], off offset:272
	global_load_dwordx4 v[4:7], v[12:13], off
	v_lshl_add_u64 v[8:9], v[40:41], 0, v[166:167]
	v_mfma_f32_16x16x32_bf16 v[20:23], v[146:149], v[108:111], v[20:23]
	s_waitcnt vmcnt(0)
	v_mul_f32_e32 v2, v2, v6
	v_mul_f32_e32 v3, v3, v7
	v_mul_f32_e32 v0, v0, v4
	v_mul_f32_e32 v1, v1, v5
	global_store_dwordx4 v[36:37], v[0:3], off offset:384
	global_load_dwordx4 v[0:3], v[8:9], off
	v_mfma_f32_16x16x32_bf16 v[4:7], v[104:107], v[64:67], v[20:23]
	s_waitcnt vmcnt(0)
	s_nop 6
	v_mul_f32_e32 v2, v6, v2
	v_mul_f32_e32 v3, v7, v3
	v_mul_f32_e32 v0, v4, v0
	v_mul_f32_e32 v1, v5, v1
	global_store_dwordx4 v[36:37], v[0:3], off offset:400
	s_cbranch_scc0 .LBB0_1090

.LBB0_1150:
	s_or_b64 exec, exec, s[12:13]
	v_lshl_add_u64 v[40:41], s[94:95], 0, v[40:41]
	v_lshl_add_u64 v[64:65], v[40:41], 0, s[10:11]
	v_mov_b32_e32 v33, v19
	v_lshl_add_u64 v[40:41], v[40:41], 0, v[32:33]
	v_lshl_add_u64 v[58:59], v[64:65], 0, v[32:33]
	global_load_dwordx4 v[50:53], v[22:23], off
	global_load_dwordx4 v[54:57], v[40:41], off
	s_nop 0
	global_load_dwordx4 v[58:61], v[58:59], off
	s_waitcnt vmcnt(6)
	v_mul_f32_e32 v76, v12, v12
	v_mul_f32_e32 v77, v13, v13
	s_waitcnt vmcnt(5)
	v_mul_f32_e32 v78, v8, v8
	v_mul_f32_e32 v79, v9, v9
	v_mul_f32_e32 v72, v14, v14
	v_mul_f32_e32 v73, v15, v15
	v_mul_f32_e32 v74, v10, v10
	v_mul_f32_e32 v75, v11, v11
	v_mov_b32_e32 v80, v76
	v_mov_b32_e32 v81, v78
	v_mov_b32_e32 v78, v77
	v_add_f32_e32 v76, v80, v78
	v_add_f32_e32 v77, v81, v79
	v_mov_b32_e32 v78, v72
	v_mov_b32_e32 v79, v74
	s_waitcnt vmcnt(3)
	v_mul_f32_e32 v68, v0, v0
	v_mul_f32_e32 v69, v1, v1
	v_mul_f32_e32 v70, v4, v4
	v_mul_f32_e32 v71, v5, v5
	v_add_f32_e32 v76, v78, v76
	v_add_f32_e32 v77, v79, v77
	v_mov_b32_e32 v74, v73
	v_mul_f32_e32 v62, v2, v2
	v_mul_f32_e32 v63, v3, v3
	v_mul_f32_e32 v66, v6, v6
	v_mul_f32_e32 v67, v7, v7
	v_add_f32_e32 v72, v74, v76
	v_add_f32_e32 v73, v75, v77
	v_mov_b32_e32 v74, v68
	v_mov_b32_e32 v75, v70
	v_mov_b32_e32 v70, v69
	v_add_f32_e32 v68, v74, v70
	v_add_f32_e32 v69, v75, v71
	v_mov_b32_e32 v70, v62
	v_mov_b32_e32 v71, v66
	v_add_f32_e32 v68, v70, v68
	v_add_f32_e32 v69, v71, v69
	v_mov_b32_e32 v66, v63
	v_add_f32_e32 v62, v66, v68
	v_add_f32_e32 v63, v67, v69
	v_add_f32_e32 v18, v72, v73
	v_add_f32_e32 v18, v63, v18
	v_add_f32_e32 v18, v62, v18
	ds_bpermute_b32 v33, v42, v18
	v_mad_i64_i32 v[62:63], s[0:1], v17, s24, v[20:21]
	v_mov_b32_e32 v35, v19
	v_lshl_add_u64 v[66:67], v[64:65], 0, v[34:35]
	s_waitcnt lgkmcnt(0)
	v_add_f32_e32 v18, v18, v33
	ds_bpermute_b32 v33, v43, v18
	v_mov_b32_e32 v37, v19
	v_mov_b32_e32 v39, v19
	v_add_u32_e32 v17, s14, v17
	s_waitcnt lgkmcnt(0)
	v_add_f32_e32 v18, v18, v33
	ds_bpermute_b32 v33, v44, v18
	s_waitcnt lgkmcnt(0)
	v_add_f32_e32 v18, v18, v33
	ds_bpermute_b32 v33, v45, v18
	s_waitcnt lgkmcnt(0)
	v_add_f32_e32 v18, v18, v33
	ds_bpermute_b32 v33, v46, v18
	s_waitcnt lgkmcnt(0)
	v_add_f32_e32 v18, v18, v33
	ds_bpermute_b32 v33, v47, v18
	s_waitcnt lgkmcnt(0)
	v_add_f32_e32 v18, v18, v33
	v_fmamk_f32 v18, v18, 0x3a800000, v48
	v_mul_f32_e32 v33, 0x4b800000, v18
	v_cmp_gt_f32_e32 vcc, s23, v18
	s_nop 1
	v_cndmask_b32_e32 v18, v18, v33, vcc
	v_rsq_f32_e32 v18, v18
	s_nop 0
	v_mul_f32_e32 v33, 0x45800000, v18
	v_cndmask_b32_e32 v18, v18, v33, vcc
	v_mul_f32_e32 v12, v12, v18
	v_mul_f32_e32 v13, v13, v18
	v_mul_f32_e32 v14, v14, v18
	v_mul_f32_e32 v15, v15, v18
	s_waitcnt vmcnt(2)
	v_mul_f32_e32 v12, v50, v12
	v_mul_f32_e32 v13, v51, v13
	v_mul_f32_e32 v14, v52, v14
	v_mul_f32_e32 v15, v53, v15
	s_waitcnt vmcnt(0)
	v_pk_add_f32 v[50:51], v[58:59], 1.0 op_sel_hi:[1,0]
	v_pk_add_f32 v[52:53], v[60:61], 1.0 op_sel_hi:[1,0]
	v_fma_f32 v12, v50, v12, v54
	v_fma_f32 v13, v51, v13, v55
	v_fma_f32 v14, v52, v14, v56
	v_fma_f32 v15, v53, v15, v57
	v_cvt_pk_bf16_f32 v12, v12, v13
	v_cvt_pk_bf16_f32 v13, v14, v15
	global_store_dwordx2 v[62:63], v[12:13], off
	global_load_dwordx4 v[12:15], v[24:25], off
	s_nop 0
	global_load_dwordx4 v[50:53], v[66:67], off
	global_load_dwordx4 v[54:57], v[40:41], off offset:1024
	v_mul_f32_e32 v8, v8, v18
	v_mul_f32_e32 v9, v9, v18
	v_mul_f32_e32 v10, v10, v18
	v_mul_f32_e32 v11, v11, v18
	v_lshl_add_u64 v[58:59], v[64:65], 0, v[36:37]
	v_mul_f32_e32 v4, v4, v18
	v_mul_f32_e32 v5, v5, v18
	v_mul_f32_e32 v6, v6, v18
	v_mul_f32_e32 v7, v7, v18
	v_mul_f32_e32 v0, v0, v18
	v_mul_f32_e32 v1, v1, v18
	v_mul_f32_e32 v2, v2, v18
	v_mul_f32_e32 v3, v3, v18
	v_cmp_lt_i32_e32 vcc, s25, v17
	s_or_b64 s[8:9], vcc, s[8:9]
	s_waitcnt vmcnt(2)
	v_mul_f32_e32 v8, v12, v8
	v_mul_f32_e32 v9, v13, v9
	s_waitcnt vmcnt(1)
	v_pk_add_f32 v[12:13], v[50:51], 1.0 op_sel_hi:[1,0]
	v_mul_f32_e32 v10, v14, v10
	v_mul_f32_e32 v11, v15, v11
	v_pk_add_f32 v[14:15], v[52:53], 1.0 op_sel_hi:[1,0]
	s_waitcnt vmcnt(0)
	v_fma_f32 v8, v12, v8, v54
	v_fma_f32 v9, v13, v9, v55
	v_fma_f32 v10, v14, v10, v56
	v_fma_f32 v11, v15, v11, v57
	v_cvt_pk_bf16_f32 v8, v8, v9
	v_cvt_pk_bf16_f32 v9, v10, v11
	global_store_dwordx2 v[62:63], v[8:9], off offset:512
	global_load_dwordx4 v[8:11], v[26:27], off
	s_nop 0
	global_load_dwordx4 v[12:15], v[58:59], off
	global_load_dwordx4 v[50:53], v[40:41], off offset:2048
	v_lshl_add_u64 v[54:55], v[64:65], 0, v[38:39]
	s_waitcnt vmcnt(2)
	v_mul_f32_e32 v4, v8, v4
	v_mul_f32_e32 v5, v9, v5
	s_waitcnt vmcnt(1)
	v_pk_add_f32 v[8:9], v[12:13], 1.0 op_sel_hi:[1,0]
	v_mul_f32_e32 v6, v10, v6
	v_mul_f32_e32 v7, v11, v7
	v_pk_add_f32 v[10:11], v[14:15], 1.0 op_sel_hi:[1,0]
	s_waitcnt vmcnt(0)
	v_fma_f32 v4, v8, v4, v50
	v_fma_f32 v5, v9, v5, v51
	v_fma_f32 v6, v10, v6, v52
	v_fma_f32 v7, v11, v7, v53
	v_cvt_pk_bf16_f32 v4, v4, v5
	v_cvt_pk_bf16_f32 v5, v6, v7
	global_store_dwordx2 v[62:63], v[4:5], off offset:1024
	global_load_dwordx4 v[4:7], v[28:29], off
	s_nop 0
	global_load_dwordx4 v[8:11], v[54:55], off
	global_load_dwordx4 v[12:15], v[40:41], off offset:3072
	s_waitcnt vmcnt(2)
	v_mul_f32_e32 v0, v0, v4
	v_mul_f32_e32 v1, v1, v5
	s_waitcnt vmcnt(1)
	v_pk_add_f32 v[4:5], v[8:9], 1.0 op_sel_hi:[1,0]
	v_mul_f32_e32 v2, v2, v6
	v_mul_f32_e32 v3, v3, v7
	v_pk_add_f32 v[6:7], v[10:11], 1.0 op_sel_hi:[1,0]
	s_waitcnt vmcnt(0)
	v_fma_f32 v0, v0, v4, v12
	v_fma_f32 v1, v1, v5, v13
	v_fma_f32 v2, v2, v6, v14
	v_fma_f32 v3, v3, v7, v15
	v_cvt_pk_bf16_f32 v0, v0, v1
	v_cvt_pk_bf16_f32 v1, v2, v3
	global_store_dwordx2 v[62:63], v[0:1], off offset:1536
	s_andn2_b64 exec, exec, s[8:9]
	s_cbranch_execz .LBB0_1157
.LBB0_1151:
	v_mul_hi_i32 v0, v17, s16
	v_lshrrev_b32_e32 v1, 31, v0
	v_ashrrev_i32_e32 v0, 11, v0
	v_add_u32_e32 v35, v0, v1
	v_mad_i32_i24 v1, v35, s17, v17
	v_mul_i32_i24_e32 v33, 0xffffdf00, v35
	v_cmp_gt_i32_e32 vcc, s15, v1
	v_cmp_lt_i32_e64 s[0:1], s18, v1
	s_and_saveexec_b64 s[12:13], s[0:1]
	s_xor_b64 s[0:1], exec, s[12:13]
	v_lshl_add_u32 v0, v35, 13, v33
	v_add_u32_e32 v1, 3, v35
	v_add3_u32 v0, v17, v0, s19
	v_mul_hi_i32_i24_e32 v41, 0x6000, v1
	v_mul_i32_i24_e32 v40, 0x6000, v1
	s_or_saveexec_b64 s[0:1], s[0:1]
	v_mov_b64_e32 v[2:3], s[92:93]
	s_xor_b64 exec, exec, s[0:1]
	v_lshl_add_u32 v0, v35, 8, v1
	v_mov_b64_e32 v[40:41], 0x1e000
	v_mov_b64_e32 v[2:3], s[6:7]
	s_or_b64 exec, exec, s[0:1]
	v_ashrrev_i32_e32 v1, 31, v0
	v_lshlrev_b64 v[0:1], 12, v[0:1]
	v_lshl_add_u64 v[0:1], v[2:3], 0, v[0:1]
	v_lshlrev_b32_e32 v18, 4, v16
	v_lshl_add_u64 v[0:1], v[0:1], 0, v[18:19]
	global_load_dwordx4 v[12:15], v[0:1], off
	global_load_dwordx4 v[8:11], v[0:1], off offset:1024
	global_load_dwordx4 v[4:7], v[0:1], off offset:2048
	s_nop 0
	global_load_dwordx4 v[0:3], v[0:1], off offset:3072
	v_mul_i32_i24_e32 v37, 0x2100, v35
	v_sub_u32_e32 v39, v17, v37
	v_cmp_gt_i32_e64 s[0:1], s15, v39
	s_and_saveexec_b64 s[12:13], s[0:1]
	s_cbranch_execz .LBB0_1150
	v_lshlrev_b32_e32 v39, 8, v35
	v_sub_u32_e32 v37, v39, v37
	v_add_u32_e32 v50, v17, v37
	v_ashrrev_i32_e32 v51, 31, v50
	v_lshlrev_b64 v[50:51], 12, v[50:51]
	v_lshl_add_u64 v[66:67], v[30:31], 0, v[50:51]
	v_add_co_u32_e64 v68, s[0:1], s20, v66
	v_lshl_add_u32 v35, v35, 13, v49
	s_nop 0
	v_addc_co_u32_e64 v69, s[0:1], 0, v67, s[0:1]
	v_add_co_u32_e64 v70, s[0:1], s21, v66
	global_load_dwordx4 v[50:53], v[66:67], off
	global_load_dwordx4 v[54:57], v[68:69], off
	v_addc_co_u32_e64 v71, s[0:1], 0, v67, s[0:1]
	v_add_co_u32_e64 v72, s[0:1], s22, v66
	v_mov_b32_e32 v37, s93
	s_nop 0
	v_addc_co_u32_e64 v73, s[0:1], 0, v67, s[0:1]
	global_load_dwordx4 v[58:61], v[70:71], off
	global_load_dwordx4 v[62:65], v[72:73], off
	v_mov_b32_e32 v74, s7
	v_mov_b32_e32 v76, s92
	v_mov_b32_e32 v77, s6
	v_cndmask_b32_e32 v35, v35, v39, vcc
	v_cndmask_b32_e32 v75, v37, v74, vcc
	v_cndmask_b32_e32 v74, v76, v77, vcc
	v_add3_u32 v76, v35, v33, v17
	v_ashrrev_i32_e32 v77, 31, v76
	v_lshlrev_b64 v[76:77], 12, v[76:77]
	v_lshl_add_u64 v[74:75], v[74:75], 0, v[76:77]
	v_lshl_add_u64 v[74:75], v[74:75], 0, v[18:19]
	s_waitcnt vmcnt(2)
	v_add_f32_e32 v52, v52, v56
	v_add_f32_e32 v53, v53, v57
	v_add_f32_e32 v50, v50, v54
	v_add_f32_e32 v51, v51, v55
	s_waitcnt vmcnt(0)
	v_add_f32_e32 v54, v60, v64
	v_add_f32_e32 v55, v61, v65
	v_add_f32_e32 v56, v58, v62
	v_add_f32_e32 v57, v59, v63
	v_add_f32_e32 v52, v52, v54
	v_add_f32_e32 v53, v53, v55
	v_add_f32_e32 v50, v50, v56
	v_add_f32_e32 v51, v51, v57
	v_add_f32_e32 v14, v14, v52
	v_add_f32_e32 v15, v15, v53
	v_add_f32_e32 v12, v12, v50
	v_add_f32_e32 v13, v13, v51
	global_store_dwordx4 v[74:75], v[12:15], off
	global_load_dwordx4 v[50:53], v[66:67], off offset:1024
	global_load_dwordx4 v[54:57], v[68:69], off offset:1024
	global_load_dwordx4 v[58:61], v[70:71], off offset:1024
	global_load_dwordx4 v[62:65], v[72:73], off offset:1024
	s_waitcnt vmcnt(2)
	v_add_f32_e32 v52, v52, v56
	v_add_f32_e32 v53, v53, v57
	v_add_f32_e32 v50, v50, v54
	v_add_f32_e32 v51, v51, v55
	s_waitcnt vmcnt(0)
	v_add_f32_e32 v54, v60, v64
	v_add_f32_e32 v55, v61, v65
	v_add_f32_e32 v56, v58, v62
	v_add_f32_e32 v57, v59, v63
	v_add_f32_e32 v52, v52, v54
	v_add_f32_e32 v53, v53, v55
	v_add_f32_e32 v50, v50, v56
	v_add_f32_e32 v51, v51, v57
	v_add_f32_e32 v10, v10, v52
	v_add_f32_e32 v11, v11, v53
	v_add_f32_e32 v8, v8, v50
	v_add_f32_e32 v9, v9, v51
	global_store_dwordx4 v[74:75], v[8:11], off offset:1024
	global_load_dwordx4 v[50:53], v[66:67], off offset:2048
	global_load_dwordx4 v[54:57], v[68:69], off offset:2048
	global_load_dwordx4 v[58:61], v[70:71], off offset:2048
	global_load_dwordx4 v[62:65], v[72:73], off offset:2048
	s_waitcnt vmcnt(2)
	v_add_f32_e32 v52, v52, v56
	v_add_f32_e32 v53, v53, v57
	v_add_f32_e32 v50, v50, v54
	v_add_f32_e32 v51, v51, v55
	s_waitcnt vmcnt(0)
	v_add_f32_e32 v54, v60, v64
	v_add_f32_e32 v55, v61, v65
	v_add_f32_e32 v56, v58, v62
	v_add_f32_e32 v57, v59, v63
	v_add_f32_e32 v52, v52, v54
	v_add_f32_e32 v53, v53, v55
	v_add_f32_e32 v50, v50, v56
	v_add_f32_e32 v51, v51, v57
	v_add_f32_e32 v6, v6, v52
	v_add_f32_e32 v7, v7, v53
	v_add_f32_e32 v4, v4, v50
	v_add_f32_e32 v5, v5, v51
	global_store_dwordx4 v[74:75], v[4:7], off offset:2048
	global_load_dwordx4 v[50:53], v[66:67], off offset:3072
	global_load_dwordx4 v[54:57], v[68:69], off offset:3072
	global_load_dwordx4 v[58:61], v[70:71], off offset:3072
	global_load_dwordx4 v[62:65], v[72:73], off offset:3072
	s_waitcnt vmcnt(2)
	v_add_f32_e32 v52, v52, v56
	v_add_f32_e32 v53, v53, v57
	v_add_f32_e32 v50, v50, v54
	v_add_f32_e32 v51, v51, v55
	s_waitcnt vmcnt(0)
	v_add_f32_e32 v54, v60, v64
	v_add_f32_e32 v55, v61, v65
	v_add_f32_e32 v56, v58, v62
	v_add_f32_e32 v57, v59, v63
	v_add_f32_e32 v52, v52, v54
	v_add_f32_e32 v53, v53, v55
	v_add_f32_e32 v50, v50, v56
	v_add_f32_e32 v51, v51, v57
	v_add_f32_e32 v2, v2, v52
	v_add_f32_e32 v3, v3, v53
	v_add_f32_e32 v0, v0, v50
	v_add_f32_e32 v1, v1, v51
	global_store_dwordx4 v[74:75], v[0:3], off offset:3072
	s_branch .LBB0_1150

.LBB0_1217:
	s_add_i32 s41, s3, 0x8000
	s_and_b32 s40, s41, 0x8000
	s_add_i32 s40, s40, 0
	s_add_u32 s86, s40, s87
	s_mov_b32 m0, s86
	s_waitcnt vmcnt(0) lgkmcnt(0)
	s_barrier
	global_load_lds_dwordx4 v244, s[96:97]
	s_add_u32 m0, s86, 0x4000
	s_nop 0
	global_load_lds_dwordx4 v245, s[88:89]
	s_add_u32 m0, s86, 0x1000
	s_nop 0
	global_load_lds_dwordx4 v246, s[96:97]
	s_add_u32 m0, s86, 0x5000
	s_nop 0
	global_load_lds_dwordx4 v247, s[88:89]
	s_add_u32 m0, s86, 0x2000
	s_nop 0
	global_load_lds_dwordx4 v248, s[96:97]
	s_add_u32 m0, s86, 0x6000
	s_nop 0
	global_load_lds_dwordx4 v249, s[88:89]
	s_add_u32 m0, s86, 0x3000
	s_nop 0
	global_load_lds_dwordx4 v250, s[96:97]
	s_add_u32 m0, s86, 0x7000
	s_nop 0
	global_load_lds_dwordx4 v251, s[88:89]
	s_add_u32 s96, s96, 0x80
	s_addc_u32 s97, s97, 0
	s_add_u32 s88, s88, 0x80
	s_addc_u32 s89, s89, 0
	s_and_b32 s3, s3, 0x8000
	s_add_i32 s3, s3, 0
	v_add3_u32 v145, s3, v87, v88
	v_add3_u32 v186, s3, v88, v89
	v_add3_u32 v187, s3, v87, v90
	v_add3_u32 v188, s3, v89, v90
	ds_read_b128 v[112:115], v186
	ds_read_b128 v[104:107], v145 offset:16384
	ds_read_b128 v[108:111], v145 offset:18432
	ds_read_b128 v[116:119], v186 offset:2048
	ds_read_b128 v[120:123], v145 offset:20480
	ds_read_b128 v[124:127], v145 offset:22528
	ds_read_b128 v[128:131], v145 offset:24576
	ds_read_b128 v[132:135], v145 offset:26624
	ds_read_b128 v[136:139], v145 offset:28672
	ds_read_b128 v[140:143], v145 offset:30720
	ds_read_b128 v[154:157], v188
	ds_read_b128 v[146:149], v187 offset:16384
	ds_read_b128 v[150:153], v187 offset:18432
	ds_read_b128 v[158:161], v188 offset:2048
	ds_read_b128 v[162:165], v187 offset:20480
	ds_read_b128 v[166:169], v187 offset:22528
	ds_read_b128 v[170:173], v187 offset:24576
	ds_read_b128 v[174:177], v187 offset:26624
	ds_read_b128 v[178:181], v187 offset:28672
	ds_read_b128 v[182:185], v187 offset:30720
	s_add_u32 s0, s0, 0x80
	s_addc_u32 s1, s1, 0
	s_cmpk_eq_i32 s0, 0x780
	s_mov_b32 s3, s41
	s_waitcnt lgkmcnt(15)
	v_mfma_f32_16x16x32_bf16 v[60:63], v[104:107], v[112:115], v[60:63]
	v_mfma_f32_16x16x32_bf16 v[56:59], v[108:111], v[112:115], v[56:59]
	v_mfma_f32_16x16x32_bf16 v[24:27], v[104:107], v[116:119], v[24:27]
	v_mfma_f32_16x16x32_bf16 v[20:23], v[108:111], v[116:119], v[20:23]
	v_mfma_f32_16x16x32_bf16 v[52:55], v[120:123], v[112:115], v[52:55]
	v_mfma_f32_16x16x32_bf16 v[16:19], v[120:123], v[116:119], v[16:19]
	s_waitcnt lgkmcnt(14)
	v_mfma_f32_16x16x32_bf16 v[48:51], v[124:127], v[112:115], v[48:51]
	v_mfma_f32_16x16x32_bf16 v[12:15], v[124:127], v[116:119], v[12:15]
	s_waitcnt lgkmcnt(13)
	v_mfma_f32_16x16x32_bf16 v[44:47], v[128:131], v[112:115], v[44:47]
	v_mfma_f32_16x16x32_bf16 v[8:11], v[128:131], v[116:119], v[8:11]
	s_waitcnt lgkmcnt(12)
	v_mfma_f32_16x16x32_bf16 v[36:39], v[132:135], v[112:115], v[36:39]
	v_mfma_f32_16x16x32_bf16 v[4:7], v[132:135], v[116:119], v[4:7]
	s_waitcnt lgkmcnt(11)
	v_mfma_f32_16x16x32_bf16 v[32:35], v[136:139], v[112:115], v[32:35]
	v_mfma_f32_16x16x32_bf16 v[0:3], v[136:139], v[116:119], v[0:3]
	s_waitcnt lgkmcnt(10)
	v_mfma_f32_16x16x32_bf16 v[28:31], v[140:143], v[112:115], v[28:31]
	v_mfma_f32_16x16x32_bf16 v[40:43], v[140:143], v[116:119], v[40:43]
	s_waitcnt lgkmcnt(8)
	v_mfma_f32_16x16x32_bf16 v[60:63], v[146:149], v[154:157], v[60:63]
	s_waitcnt lgkmcnt(7)
	v_mfma_f32_16x16x32_bf16 v[56:59], v[150:153], v[154:157], v[56:59]
	s_waitcnt lgkmcnt(6)
	v_mfma_f32_16x16x32_bf16 v[24:27], v[146:149], v[158:161], v[24:27]
	v_mfma_f32_16x16x32_bf16 v[20:23], v[150:153], v[158:161], v[20:23]
	s_waitcnt lgkmcnt(5)
	v_mfma_f32_16x16x32_bf16 v[52:55], v[162:165], v[154:157], v[52:55]
	v_mfma_f32_16x16x32_bf16 v[16:19], v[162:165], v[158:161], v[16:19]
	s_waitcnt lgkmcnt(4)
	v_mfma_f32_16x16x32_bf16 v[48:51], v[166:169], v[154:157], v[48:51]
	v_mfma_f32_16x16x32_bf16 v[12:15], v[166:169], v[158:161], v[12:15]
	s_waitcnt lgkmcnt(3)
	v_mfma_f32_16x16x32_bf16 v[44:47], v[170:173], v[154:157], v[44:47]
	v_mfma_f32_16x16x32_bf16 v[8:11], v[170:173], v[158:161], v[8:11]
	s_waitcnt lgkmcnt(2)
	v_mfma_f32_16x16x32_bf16 v[36:39], v[174:177], v[154:157], v[36:39]
	v_mfma_f32_16x16x32_bf16 v[4:7], v[174:177], v[158:161], v[4:7]
	s_waitcnt lgkmcnt(1)
	v_mfma_f32_16x16x32_bf16 v[32:35], v[178:181], v[154:157], v[32:35]
	v_mfma_f32_16x16x32_bf16 v[0:3], v[178:181], v[158:161], v[0:3]
	s_waitcnt lgkmcnt(0)
	v_mfma_f32_16x16x32_bf16 v[28:31], v[182:185], v[154:157], v[28:31]
	v_mfma_f32_16x16x32_bf16 v[40:43], v[182:185], v[158:161], v[40:43]
	s_cbranch_scc0 .LBB0_1217
	v_add_u32_e32 v64, s40, v87
	v_add_u32_e32 v103, v64, v88
	v_add3_u32 v112, s40, v88, v89
	s_waitcnt vmcnt(0)
	s_barrier
	ds_read_b128 v[82:85], v103 offset:16384
	ds_read_b128 v[104:107], v103 offset:18432
	ds_read_b128 v[108:111], v112
	ds_read_b128 v[112:115], v112 offset:2048
	ds_read_b128 v[116:119], v103 offset:20480
	ds_read_b128 v[120:123], v103 offset:22528
	ds_read_b128 v[124:127], v103 offset:24576
	ds_read_b128 v[128:131], v103 offset:26624
	ds_read_b128 v[132:135], v103 offset:28672
	ds_read_b128 v[136:139], v103 offset:30720
	v_add_u32_e32 v64, v64, v90
	s_waitcnt lgkmcnt(7)
	v_mfma_f32_16x16x32_bf16 v[60:63], v[82:85], v[108:111], v[60:63]
	s_mul_hi_i32 s0, s2, 0x3e0f83e1
	s_lshr_b32 s1, s0, 31
	s_ashr_i32 s56, s0, 4
	v_mfma_f32_16x16x32_bf16 v[56:59], v[104:107], v[108:111], v[56:59]
	s_add_i32 s56, s56, s1
	s_cmp_gt_i32 s39, 11
	s_cselect_b64 s[0:1], -1, 0
	s_waitcnt lgkmcnt(4)
	v_mfma_f32_16x16x32_bf16 v[48:51], v[120:123], v[108:111], v[48:51]
	s_lshl_b32 s53, s2, 7
	s_cmp_lt_i32 s39, 12
	s_mul_i32 s54, s56, 0xffffdf00
	s_waitcnt lgkmcnt(3)
	v_mfma_f32_16x16x32_bf16 v[44:47], v[124:127], v[108:111], v[44:47]
	s_waitcnt lgkmcnt(2)
	v_mfma_f32_16x16x32_bf16 v[36:39], v[128:131], v[108:111], v[36:39]
	s_waitcnt lgkmcnt(1)
	v_mfma_f32_16x16x32_bf16 v[32:35], v[132:135], v[108:111], v[32:35]
	s_waitcnt lgkmcnt(0)
	v_mfma_f32_16x16x32_bf16 v[28:31], v[136:139], v[108:111], v[28:31]
	v_mfma_f32_16x16x32_bf16 v[24:27], v[82:85], v[112:115], v[24:27]
	ds_read_b128 v[82:85], v64 offset:16384
	v_mfma_f32_16x16x32_bf16 v[52:55], v[116:119], v[108:111], v[52:55]
	v_mfma_f32_16x16x32_bf16 v[20:23], v[104:107], v[112:115], v[20:23]
	v_mfma_f32_16x16x32_bf16 v[16:19], v[116:119], v[112:115], v[16:19]
	v_mfma_f32_16x16x32_bf16 v[12:15], v[120:123], v[112:115], v[12:15]
	v_mfma_f32_16x16x32_bf16 v[8:11], v[124:127], v[112:115], v[8:11]
	v_mfma_f32_16x16x32_bf16 v[4:7], v[128:131], v[112:115], v[4:7]
	v_mfma_f32_16x16x32_bf16 v[0:3], v[132:135], v[112:115], v[0:3]
	v_mfma_f32_16x16x32_bf16 v[104:107], v[136:139], v[112:115], v[40:43]
	s_nop 2
	v_add3_u32 v40, s40, v90, v89
	ds_read_b128 v[108:111], v64 offset:18432
	ds_read_b128 v[112:115], v40
	ds_read_b128 v[116:119], v40 offset:2048
	ds_read_b128 v[120:123], v64 offset:20480
	ds_read_b128 v[124:127], v64 offset:22528
	ds_read_b128 v[128:131], v64 offset:24576
	ds_read_b128 v[132:135], v64 offset:26624
	ds_read_b128 v[136:139], v64 offset:28672
	ds_read_b128 v[140:143], v64 offset:30720
	s_waitcnt lgkmcnt(7)
	v_mfma_f32_16x16x32_bf16 v[60:63], v[82:85], v[112:115], v[60:63]
	v_mfma_f32_16x16x32_bf16 v[56:59], v[108:111], v[112:115], v[56:59]
	s_waitcnt lgkmcnt(5)
	v_mfma_f32_16x16x32_bf16 v[52:55], v[120:123], v[112:115], v[52:55]
	s_waitcnt lgkmcnt(4)
	v_mfma_f32_16x16x32_bf16 v[48:51], v[124:127], v[112:115], v[48:51]
	s_waitcnt lgkmcnt(3)
	v_mfma_f32_16x16x32_bf16 v[44:47], v[128:131], v[112:115], v[44:47]
	s_waitcnt lgkmcnt(2)
	v_mfma_f32_16x16x32_bf16 v[40:43], v[132:135], v[112:115], v[36:39]
	s_waitcnt lgkmcnt(1)
	v_mfma_f32_16x16x32_bf16 v[36:39], v[136:139], v[112:115], v[32:35]
	s_waitcnt lgkmcnt(0)
	v_mfma_f32_16x16x32_bf16 v[32:35], v[140:143], v[112:115], v[28:31]
	v_mfma_f32_16x16x32_bf16 v[28:31], v[82:85], v[116:119], v[24:27]
	v_mfma_f32_16x16x32_bf16 v[24:27], v[108:111], v[116:119], v[20:23]
	v_mfma_f32_16x16x32_bf16 v[20:23], v[120:123], v[116:119], v[16:19]
	v_mfma_f32_16x16x32_bf16 v[16:19], v[124:127], v[116:119], v[12:15]
	v_mfma_f32_16x16x32_bf16 v[12:15], v[128:131], v[116:119], v[8:11]
	v_mfma_f32_16x16x32_bf16 v[8:11], v[132:135], v[116:119], v[4:7]
	v_mfma_f32_16x16x32_bf16 v[4:7], v[136:139], v[116:119], v[0:3]
	v_mfma_f32_16x16x32_bf16 v[0:3], v[140:143], v[116:119], v[104:107]
	s_cbranch_scc0 .LBB0_1224
	s_add_i32 s40, s54, s53
	v_add_u32_e32 v64, s40, v70
	v_cmp_lt_i32_e32 vcc, s48, v64
	s_and_saveexec_b64 s[2:3], vcc
	s_cbranch_execz .LBB0_1221
	v_lshl_add_u32 v64, v64, 5, v102
	v_lshlrev_b64 v[108:109], 2, v[64:65]
	v_lshl_add_u64 v[104:105], v[76:77], 0, v[108:109]
	global_load_dwordx4 v[82:85], v[104:105], off
	s_nop 0
	global_load_dwordx4 v[104:107], v[104:105], off offset:16
	v_lshl_add_u64 v[112:113], v[74:75], 0, v[108:109]
	global_load_dwordx4 v[108:111], v[112:113], off
	s_nop 0
	global_load_dwordx4 v[112:115], v[112:113], off offset:16
	s_waitcnt vmcnt(3)
	v_mul_f32_e32 v116, v54, v84
	v_mul_f32_e32 v117, v55, v85
	v_mul_f32_e32 v118, v52, v82
	v_mul_f32_e32 v119, v53, v83
	v_mul_f32_e32 v120, v62, v84
	v_mul_f32_e32 v121, v63, v85
	v_mul_f32_e32 v122, v60, v82
	v_mul_f32_e32 v123, v61, v83
	s_waitcnt vmcnt(2)
	v_mul_f32_e32 v124, v50, v106
	v_mul_f32_e32 v125, v51, v107
	v_mul_f32_e32 v126, v48, v104
	v_mul_f32_e32 v127, v49, v105
	v_mul_f32_e32 v128, v58, v106
	v_mul_f32_e32 v129, v59, v107
	v_mul_f32_e32 v130, v56, v104
	v_mul_f32_e32 v131, v57, v105
	v_mul_f32_e32 v132, v38, v84
	v_mul_f32_e32 v133, v39, v85
	v_mul_f32_e32 v134, v36, v82
	v_mul_f32_e32 v135, v37, v83
	v_mul_f32_e32 v84, v46, v84
	v_mul_f32_e32 v85, v47, v85
	v_mul_f32_e32 v82, v44, v82
	v_mul_f32_e32 v83, v45, v83
	v_mul_f32_e32 v136, v34, v106
	v_mul_f32_e32 v137, v35, v107
	v_mul_f32_e32 v138, v32, v104
	v_mul_f32_e32 v139, v33, v105
	v_mul_f32_e32 v106, v42, v106
	v_mul_f32_e32 v107, v43, v107
	v_mul_f32_e32 v104, v40, v104
	v_mul_f32_e32 v105, v41, v105
	s_waitcnt vmcnt(1)
	v_fma_f32 v62, v62, v110, -v116
	v_fma_f32 v63, v63, v111, -v117
	v_fma_f32 v60, v60, v108, -v118
	v_fma_f32 v61, v61, v109, -v119
	v_fma_f32 v54, v54, v110, v120
	v_fma_f32 v55, v55, v111, v121
	v_fma_f32 v52, v52, v108, v122
	v_fma_f32 v53, v53, v109, v123
	s_waitcnt vmcnt(0)
	v_fma_f32 v58, v58, v114, -v124
	v_fma_f32 v59, v59, v115, -v125
	v_fma_f32 v56, v56, v112, -v126
	v_fma_f32 v57, v57, v113, -v127
	v_fma_f32 v50, v50, v114, v128
	v_fma_f32 v51, v51, v115, v129
	v_fma_f32 v48, v48, v112, v130
	v_fma_f32 v49, v49, v113, v131
	v_fma_f32 v46, v46, v110, -v132
	v_fma_f32 v47, v47, v111, -v133
	v_fma_f32 v44, v44, v108, -v134
	v_fma_f32 v45, v45, v109, -v135
	v_fma_f32 v38, v38, v110, v84
	v_fma_f32 v39, v39, v111, v85
	v_fma_f32 v36, v36, v108, v82
	v_fma_f32 v37, v37, v109, v83
	v_fma_f32 v42, v42, v114, -v136
	v_fma_f32 v43, v43, v115, -v137
	v_fma_f32 v40, v40, v112, -v138
	v_fma_f32 v41, v41, v113, -v139
	v_fma_f32 v34, v34, v114, v106
	v_fma_f32 v35, v35, v115, v107
	v_fma_f32 v32, v32, v112, v104
	v_fma_f32 v33, v33, v113, v105
.LBB0_1221:
	s_or_b64 exec, exec, s[2:3]
	v_add_u32_e32 v64, s40, v92
	v_cmp_lt_i32_e32 vcc, s48, v64
	s_and_saveexec_b64 s[2:3], vcc
	s_cbranch_execz .LBB0_1223
	v_lshl_add_u32 v64, v64, 5, v102
	v_lshlrev_b64 v[108:109], 2, v[64:65]
	v_lshl_add_u64 v[104:105], v[76:77], 0, v[108:109]
	global_load_dwordx4 v[82:85], v[104:105], off
	s_nop 0
	global_load_dwordx4 v[104:107], v[104:105], off offset:16
	v_lshl_add_u64 v[112:113], v[74:75], 0, v[108:109]
	global_load_dwordx4 v[108:111], v[112:113], off
	s_nop 0
	global_load_dwordx4 v[112:115], v[112:113], off offset:16
	s_waitcnt vmcnt(3)
	v_mul_f32_e32 v116, v22, v84
	v_mul_f32_e32 v117, v23, v85
	v_mul_f32_e32 v118, v20, v82
	v_mul_f32_e32 v119, v21, v83
	v_mul_f32_e32 v120, v30, v84
	v_mul_f32_e32 v121, v31, v85
	v_mul_f32_e32 v122, v28, v82
	v_mul_f32_e32 v123, v29, v83
	s_waitcnt vmcnt(2)
	v_mul_f32_e32 v124, v18, v106
	v_mul_f32_e32 v125, v19, v107
	v_mul_f32_e32 v126, v16, v104
	v_mul_f32_e32 v127, v17, v105
	v_mul_f32_e32 v128, v26, v106
	v_mul_f32_e32 v129, v27, v107
	v_mul_f32_e32 v130, v24, v104
	v_mul_f32_e32 v131, v25, v105
	v_mul_f32_e32 v132, v6, v84
	v_mul_f32_e32 v133, v7, v85
	v_mul_f32_e32 v134, v4, v82
	v_mul_f32_e32 v135, v5, v83
	v_mul_f32_e32 v84, v14, v84
	v_mul_f32_e32 v85, v15, v85
	v_mul_f32_e32 v82, v12, v82
	v_mul_f32_e32 v83, v13, v83
	v_mul_f32_e32 v136, v2, v106
	v_mul_f32_e32 v137, v3, v107
	v_mul_f32_e32 v138, v0, v104
	v_mul_f32_e32 v139, v1, v105
	v_mul_f32_e32 v106, v10, v106
	v_mul_f32_e32 v107, v11, v107
	v_mul_f32_e32 v104, v8, v104
	v_mul_f32_e32 v105, v9, v105
	s_waitcnt vmcnt(1)
	v_fma_f32 v30, v30, v110, -v116
	v_fma_f32 v31, v31, v111, -v117
	v_fma_f32 v28, v28, v108, -v118
	v_fma_f32 v29, v29, v109, -v119
	v_fma_f32 v22, v22, v110, v120
	v_fma_f32 v23, v23, v111, v121
	v_fma_f32 v20, v20, v108, v122
	v_fma_f32 v21, v21, v109, v123
	s_waitcnt vmcnt(0)
	v_fma_f32 v26, v26, v114, -v124
	v_fma_f32 v27, v27, v115, -v125
	v_fma_f32 v24, v24, v112, -v126
	v_fma_f32 v25, v25, v113, -v127
	v_fma_f32 v18, v18, v114, v128
	v_fma_f32 v19, v19, v115, v129
	v_fma_f32 v16, v16, v112, v130
	v_fma_f32 v17, v17, v113, v131
	v_fma_f32 v14, v14, v110, -v132
	v_fma_f32 v15, v15, v111, -v133
	v_fma_f32 v12, v12, v108, -v134
	v_fma_f32 v13, v13, v109, -v135
	v_fma_f32 v6, v6, v110, v84
	v_fma_f32 v7, v7, v111, v85
	v_fma_f32 v4, v4, v108, v82
	v_fma_f32 v5, v5, v109, v83
	v_fma_f32 v10, v10, v114, -v136
	v_fma_f32 v11, v11, v115, -v137
	v_fma_f32 v8, v8, v112, -v138
	v_fma_f32 v9, v9, v113, -v139
	v_fma_f32 v2, v2, v114, v106
	v_fma_f32 v3, v3, v115, v107
	v_fma_f32 v0, v0, v112, v104
	v_fma_f32 v1, v1, v113, v105

.LBB0_1234:
	s_andn2_b64 vcc, exec, s[2:3]
	v_ashrrev_i32_e32 v83, 31, v82
	s_cbranch_vccnz .LBB0_1236
	v_mul_f32_e32 v62, s36, v62
	v_mul_f32_e32 v63, s36, v63
	v_mul_f32_e32 v60, s36, v60
	v_mul_f32_e32 v61, s36, v61
	s_nop 0
	v_cvt_pk_bf16_f32 v60, v60, v61
	v_cvt_pk_bf16_f32 v61, v62, v63
	v_mov_b64_e32 v[62:63], s[6:7]
	v_mad_i64_i32 v[62:63], s[2:3], v84, s51, v[62:63]
	v_lshl_add_u64 v[62:63], v[82:83], 1, v[62:63]
	global_store_dwordx2 v[62:63], v[60:61], off

.LBB0_1387:
	v_mul_f32_e32 v58, s36, v58
	v_mul_f32_e32 v59, s36, v59
	v_mul_f32_e32 v56, s36, v56
	v_mul_f32_e32 v57, s36, v57
	s_ashr_i32 s41, s40, 31
	v_cvt_pk_bf16_f32 v56, v56, v57
	v_cvt_pk_bf16_f32 v57, v58, v59
	v_mov_b64_e32 v[58:59], s[6:7]
	v_mad_i64_i32 v[58:59], s[42:43], v84, s51, v[58:59]
	v_lshl_add_u64 v[62:63], s[40:41], 0, v[72:73]
	v_lshl_add_u64 v[58:59], v[62:63], 1, v[58:59]
	global_store_dwordx2 v[58:59], v[56:57], off offset:8
	v_or_b32_e32 v56, 32, v82
	s_and_b64 vcc, exec, s[2:3]
	s_mov_b64 s[42:43], -1
	s_cbranch_vccz .LBB0_1247

.LBB0_1389:
	v_mul_f32_e32 v54, s36, v54
	v_mul_f32_e32 v55, s36, v55
	v_mul_f32_e32 v52, s36, v52
	v_mul_f32_e32 v53, s36, v53
	s_nop 0
	v_cvt_pk_bf16_f32 v52, v52, v53
	v_cvt_pk_bf16_f32 v53, v54, v55
	v_mov_b64_e32 v[54:55], s[6:7]
	v_mad_i64_i32 v[54:55], s[42:43], v84, s51, v[54:55]
	v_lshl_add_u64 v[54:55], v[82:83], 1, v[54:55]
	global_store_dwordx2 v[54:55], v[52:53], off offset:64
	v_or_b32_e32 v52, 36, v82
	s_and_b64 vcc, exec, s[2:3]
	s_mov_b64 s[42:43], -1
	s_cbranch_vccz .LBB0_1257

.LBB0_1391:
	v_mul_f32_e32 v50, s36, v50
	v_mul_f32_e32 v51, s36, v51
	v_mul_f32_e32 v48, s36, v48
	v_mul_f32_e32 v49, s36, v49
	s_nop 0
	v_cvt_pk_bf16_f32 v48, v48, v49
	v_cvt_pk_bf16_f32 v49, v50, v51
	v_mov_b64_e32 v[50:51], s[6:7]
	v_mad_i64_i32 v[50:51], s[42:43], v84, s51, v[50:51]
	v_lshl_add_u64 v[50:51], v[82:83], 1, v[50:51]
	global_store_dwordx2 v[50:51], v[48:49], off offset:72
	v_or_b32_e32 v48, 64, v82
	s_and_b64 vcc, exec, s[2:3]
	s_mov_b64 s[42:43], -1
	s_cbranch_vccz .LBB0_1267

.LBB0_1393:
	v_mul_f32_e32 v46, s36, v46
	v_mul_f32_e32 v47, s36, v47
	v_mul_f32_e32 v44, s36, v44
	v_mul_f32_e32 v45, s36, v45
	s_nop 0
	v_cvt_pk_bf16_f32 v44, v44, v45
	v_cvt_pk_bf16_f32 v45, v46, v47
	v_mov_b64_e32 v[46:47], s[6:7]
	v_mad_i64_i32 v[46:47], s[42:43], v84, s51, v[46:47]
	v_lshl_add_u64 v[46:47], v[82:83], 1, v[46:47]
	global_store_dwordx2 v[46:47], v[44:45], off offset:128
	v_or_b32_e32 v44, 0x44, v82
	s_and_b64 vcc, exec, s[2:3]
	s_mov_b64 s[42:43], -1
	s_cbranch_vccz .LBB0_1277

.LBB0_1395:
	v_mul_f32_e32 v42, s36, v42
	v_mul_f32_e32 v43, s36, v43
	v_mul_f32_e32 v40, s36, v40
	v_mul_f32_e32 v41, s36, v41
	s_nop 0
	v_cvt_pk_bf16_f32 v40, v40, v41
	v_cvt_pk_bf16_f32 v41, v42, v43
	v_mov_b64_e32 v[42:43], s[6:7]
	v_mad_i64_i32 v[42:43], s[42:43], v84, s51, v[42:43]
	v_lshl_add_u64 v[42:43], v[82:83], 1, v[42:43]
	global_store_dwordx2 v[42:43], v[40:41], off offset:136
	v_or_b32_e32 v40, 0x60, v82
	s_and_b64 vcc, exec, s[2:3]
	s_mov_b64 s[42:43], -1
	s_cbranch_vccz .LBB0_1287

.LBB0_1397:
	v_mul_f32_e32 v38, s36, v38
	v_mul_f32_e32 v39, s36, v39
	v_mul_f32_e32 v36, s36, v36
	v_mul_f32_e32 v37, s36, v37
	s_nop 0
	v_cvt_pk_bf16_f32 v36, v36, v37
	v_cvt_pk_bf16_f32 v37, v38, v39
	v_mov_b64_e32 v[38:39], s[6:7]
	v_mad_i64_i32 v[38:39], s[42:43], v84, s51, v[38:39]
	v_lshl_add_u64 v[38:39], v[82:83], 1, v[38:39]
	global_store_dwordx2 v[38:39], v[36:37], off offset:192
	v_or_b32_e32 v36, 0x64, v82
	s_and_b64 vcc, exec, s[2:3]
	s_mov_b64 s[42:43], -1
	s_cbranch_vccz .LBB0_1297

.LBB0_1399:
	v_mul_f32_e32 v34, s36, v34
	v_mul_f32_e32 v35, s36, v35
	v_mul_f32_e32 v32, s36, v32
	v_mul_f32_e32 v33, s36, v33
	s_nop 0
	v_cvt_pk_bf16_f32 v32, v32, v33
	v_cvt_pk_bf16_f32 v33, v34, v35
	v_mov_b64_e32 v[34:35], s[6:7]
	v_mad_i64_i32 v[34:35], s[42:43], v84, s51, v[34:35]
	v_lshl_add_u64 v[34:35], v[82:83], 1, v[34:35]
	global_store_dwordx2 v[34:35], v[32:33], off offset:200
	v_add_u32_e32 v32, s53, v92
	s_and_b64 vcc, exec, s[2:3]
	s_mov_b64 s[42:43], -1
	s_cbranch_vccz .LBB0_1307

.LBB0_1401:
	v_mul_f32_e32 v30, s36, v30
	v_mul_f32_e32 v31, s36, v31
	v_mul_f32_e32 v28, s36, v28
	v_mul_f32_e32 v29, s36, v29
	s_nop 0
	v_cvt_pk_bf16_f32 v28, v28, v29
	v_cvt_pk_bf16_f32 v29, v30, v31
	v_mov_b64_e32 v[30:31], s[6:7]
	v_mad_i64_i32 v[30:31], s[42:43], v32, s51, v[30:31]
	v_lshl_add_u64 v[30:31], v[82:83], 1, v[30:31]
	global_store_dwordx2 v[30:31], v[28:29], off
	s_and_b64 vcc, exec, s[2:3]
	s_mov_b64 s[42:43], -1
	s_cbranch_vccz .LBB0_1317

.LBB0_1403:
	v_mul_f32_e32 v26, s36, v26
	v_mul_f32_e32 v27, s36, v27
	v_mul_f32_e32 v24, s36, v24
	v_mul_f32_e32 v25, s36, v25
	s_ashr_i32 s41, s40, 31
	v_cvt_pk_bf16_f32 v24, v24, v25
	v_cvt_pk_bf16_f32 v25, v26, v27
	v_mov_b64_e32 v[26:27], s[6:7]
	v_mad_i64_i32 v[26:27], s[42:43], v32, s51, v[26:27]
	v_lshl_add_u64 v[28:29], s[40:41], 0, v[72:73]
	v_lshl_add_u64 v[26:27], v[28:29], 1, v[26:27]
	global_store_dwordx2 v[26:27], v[24:25], off offset:8
	s_and_b64 vcc, exec, s[2:3]
	s_mov_b64 s[40:41], -1
	s_cbranch_vccz .LBB0_1327

.LBB0_1405:
	v_mul_f32_e32 v22, s36, v22
	v_mul_f32_e32 v23, s36, v23
	v_mul_f32_e32 v20, s36, v20
	v_mul_f32_e32 v21, s36, v21
	s_nop 0
	v_cvt_pk_bf16_f32 v20, v20, v21
	v_cvt_pk_bf16_f32 v21, v22, v23
	v_mov_b64_e32 v[22:23], s[6:7]
	v_mad_i64_i32 v[22:23], s[40:41], v32, s51, v[22:23]
	v_lshl_add_u64 v[22:23], v[82:83], 1, v[22:23]
	global_store_dwordx2 v[22:23], v[20:21], off offset:64
	s_and_b64 vcc, exec, s[2:3]
	s_mov_b64 s[40:41], -1
	s_cbranch_vccz .LBB0_1337

.LBB0_1407:
	v_mul_f32_e32 v18, s36, v18
	v_mul_f32_e32 v19, s36, v19
	v_mul_f32_e32 v16, s36, v16
	v_mul_f32_e32 v17, s36, v17
	s_nop 0
	v_cvt_pk_bf16_f32 v16, v16, v17
	v_cvt_pk_bf16_f32 v17, v18, v19
	v_mov_b64_e32 v[18:19], s[6:7]
	v_mad_i64_i32 v[18:19], s[40:41], v32, s51, v[18:19]
	v_lshl_add_u64 v[18:19], v[82:83], 1, v[18:19]
	global_store_dwordx2 v[18:19], v[16:17], off offset:72
	s_and_b64 vcc, exec, s[2:3]
	s_mov_b64 s[40:41], -1
	s_cbranch_vccz .LBB0_1347

.LBB0_1409:
	v_mul_f32_e32 v14, s36, v14
	v_mul_f32_e32 v15, s36, v15
	v_mul_f32_e32 v12, s36, v12
	v_mul_f32_e32 v13, s36, v13
	s_nop 0
	v_cvt_pk_bf16_f32 v12, v12, v13
	v_cvt_pk_bf16_f32 v13, v14, v15
	v_mov_b64_e32 v[14:15], s[6:7]
	v_mad_i64_i32 v[14:15], s[40:41], v32, s51, v[14:15]
	v_lshl_add_u64 v[14:15], v[82:83], 1, v[14:15]
	global_store_dwordx2 v[14:15], v[12:13], off offset:128
	s_and_b64 vcc, exec, s[2:3]
	s_mov_b64 s[40:41], -1
	s_cbranch_vccz .LBB0_1357

.LBB0_1411:
	v_mul_f32_e32 v10, s36, v10
	v_mul_f32_e32 v11, s36, v11
	v_mul_f32_e32 v8, s36, v8
	v_mul_f32_e32 v9, s36, v9
	s_nop 0
	v_cvt_pk_bf16_f32 v8, v8, v9
	v_cvt_pk_bf16_f32 v9, v10, v11
	v_mov_b64_e32 v[10:11], s[6:7]
	v_mad_i64_i32 v[10:11], s[40:41], v32, s51, v[10:11]
	v_lshl_add_u64 v[10:11], v[82:83], 1, v[10:11]
	global_store_dwordx2 v[10:11], v[8:9], off offset:136
	s_and_b64 vcc, exec, s[2:3]
	s_mov_b64 s[40:41], -1
	s_cbranch_vccz .LBB0_1367

.LBB0_1413:
	v_mul_f32_e32 v6, s36, v6
	v_mul_f32_e32 v7, s36, v7
	v_mul_f32_e32 v4, s36, v4
	v_mul_f32_e32 v5, s36, v5
	s_nop 0
	v_cvt_pk_bf16_f32 v4, v4, v5
	v_cvt_pk_bf16_f32 v5, v6, v7
	v_mov_b64_e32 v[6:7], s[6:7]
	v_mad_i64_i32 v[6:7], s[40:41], v32, s51, v[6:7]
	v_lshl_add_u64 v[6:7], v[82:83], 1, v[6:7]
	global_store_dwordx2 v[6:7], v[4:5], off offset:192
	s_and_b64 vcc, exec, s[2:3]
	s_mov_b64 s[2:3], -1
	s_cbranch_vccz .LBB0_1377

.LBB0_1415:
	v_mul_f32_e32 v2, s36, v2
	v_mul_f32_e32 v3, s36, v3
	v_mul_f32_e32 v0, s36, v0
	v_mul_f32_e32 v1, s36, v1
	s_nop 0
	v_cvt_pk_bf16_f32 v0, v0, v1
	v_cvt_pk_bf16_f32 v1, v2, v3
	v_mov_b64_e32 v[2:3], s[6:7]
	v_mad_i64_i32 v[2:3], s[0:1], v32, s51, v[2:3]
	v_lshl_add_u64 v[2:3], v[82:83], 1, v[2:3]
	global_store_dwordx2 v[2:3], v[0:1], off offset:200
	s_branch .LBB0_1215

.LBB0_1473:
	v_exp_f32_e32 v100, v80
	v_exp_f32_e32 v101, v81
	v_exp_f32_e32 v102, v82
	v_exp_f32_e32 v103, v83
	ds_read_b128 v[80:83], v173 offset:32768
	ds_read_b128 v[96:99], v173 offset:36864
	v_exp_f32_e32 v104, v84
	v_exp_f32_e32 v105, v85
	v_exp_f32_e32 v106, v86
	v_exp_f32_e32 v107, v87
	v_cvt_pk_bf16_f32 v84, v100, v101
	v_cvt_pk_bf16_f32 v85, v102, v103
	v_cvt_pk_bf16_f32 v86, v104, v105
	v_cvt_pk_bf16_f32 v87, v106, v107
	v_exp_f32_e32 v92, v92
	v_exp_f32_e32 v93, v93
	s_waitcnt lgkmcnt(1)
	v_mfma_f32_32x32x16_bf16 v[48:63], v[80:83], v[84:87], v[48:63]
	ds_read_b128 v[80:83], v173 offset:40960
	v_exp_f32_e32 v94, v94
	v_exp_f32_e32 v95, v95
	v_exp_f32_e32 v76, v76
	v_exp_f32_e32 v77, v77
	v_exp_f32_e32 v78, v78
	v_exp_f32_e32 v79, v79
	s_waitcnt lgkmcnt(1)
	v_mfma_f32_32x32x16_bf16 v[32:47], v[96:99], v[84:87], v[32:47]
	v_add_f32_e64 v96, v100, 0
	v_add_f32_e64 v97, v101, 0
	s_mul_i32 s31, s31, 0x18c0000
	v_add_f32_e64 v96, v102, v96
	v_add_f32_e64 v97, v103, v97
	v_exp_f32_e32 v102, v88
	v_add_f32_e32 v96, v104, v96
	v_add_f32_e32 v97, v105, v97
	v_exp_f32_e32 v103, v89
	v_add_f32_e32 v100, v106, v96
	v_add_f32_e32 v101, v107, v97
	ds_read_b128 v[96:99], v173 offset:45056
	s_waitcnt lgkmcnt(1)
	v_mfma_f32_32x32x16_bf16 v[16:31], v[80:83], v[84:87], v[16:31]
	ds_read_b128 v[80:83], v171 offset:32768
	v_exp_f32_e32 v104, v90
	v_exp_f32_e32 v105, v91
	ds_read_b128 v[88:91], v171 offset:36864
	s_add_u32 s14, s23, s31
	s_addc_u32 s15, s24, 0
	s_add_i32 s30, s30, s18
	s_waitcnt lgkmcnt(2)
	v_mfma_f32_32x32x16_bf16 v[0:15], v[96:99], v[84:87], v[0:15]
	v_cvt_pk_bf16_f32 v84, v102, v103
	v_cvt_pk_bf16_f32 v85, v104, v105
	v_cvt_pk_bf16_f32 v86, v92, v93
	v_cvt_pk_bf16_f32 v87, v94, v95
	v_exp_f32_e32 v96, v70
	v_exp_f32_e32 v97, v71
	s_cmpk_gt_i32 s30, 0x5ff
	s_waitcnt lgkmcnt(1)
	v_mfma_f32_32x32x16_bf16 v[48:63], v[80:83], v[84:87], v[48:63]
	v_add_f32_e64 v80, v102, v100
	v_add_f32_e64 v81, v103, v101
	v_add_f32_e64 v80, v104, v80
	v_add_f32_e64 v81, v105, v81
	v_add_f32_e64 v80, v92, v80
	v_add_f32_e64 v81, v93, v81
	v_add_f32_e32 v92, v94, v80
	v_add_f32_e32 v93, v95, v81
	ds_read_b128 v[80:83], v171 offset:40960
	v_exp_f32_e32 v94, v64
	v_exp_f32_e32 v95, v65
	s_waitcnt lgkmcnt(1)
	v_mfma_f32_32x32x16_bf16 v[32:47], v[88:91], v[84:87], v[32:47]
	v_exp_f32_e32 v88, v66
	v_exp_f32_e32 v89, v67
	ds_read_b128 v[64:67], v171 offset:45056
	v_exp_f32_e32 v90, v68
	v_exp_f32_e32 v91, v69
	v_add_f32_e32 v68, v94, v92
	v_add_f32_e32 v69, v95, v93
	s_nop 0
	v_add_f32_e32 v68, v88, v68
	v_add_f32_e32 v69, v89, v69
	s_waitcnt lgkmcnt(1)
	v_mfma_f32_32x32x16_bf16 v[16:31], v[80:83], v[84:87], v[16:31]
	v_add_f32_e64 v68, v90, v68
	v_add_f32_e64 v69, v91, v69
	v_exp_f32_e32 v82, v72
	v_add_f32_e32 v80, v96, v68
	v_add_f32_e32 v81, v97, v69
	ds_read_b128 v[68:71], v169 offset:32768
	v_exp_f32_e32 v83, v73
	s_waitcnt lgkmcnt(1)
	v_mfma_f32_32x32x16_bf16 v[0:15], v[64:67], v[84:87], v[0:15]
	v_exp_f32_e32 v84, v74
	v_exp_f32_e32 v85, v75
	ds_read_b128 v[72:75], v169 offset:36864
	v_cvt_pk_bf16_f32 v64, v94, v95
	v_cvt_pk_bf16_f32 v65, v88, v89
	v_cvt_pk_bf16_f32 v66, v90, v91
	v_cvt_pk_bf16_f32 v67, v96, v97
	s_waitcnt lgkmcnt(1)
	s_nop 0
	v_mfma_f32_32x32x16_bf16 v[48:63], v[68:71], v[64:67], v[48:63]
	v_add_f32_e64 v68, v82, v80
	v_add_f32_e64 v69, v83, v81
	v_add_f32_e64 v80, v84, v68
	v_add_f32_e64 v81, v85, v69
	ds_read_b128 v[68:71], v169 offset:40960
	s_waitcnt lgkmcnt(1)
	v_mfma_f32_32x32x16_bf16 v[32:47], v[72:75], v[64:67], v[32:47]
	v_add_f32_e64 v72, v76, v80
	v_add_f32_e64 v73, v77, v81
	v_add_f32_e64 v72, v78, v72
	v_add_f32_e64 v73, v79, v73
	v_add_f32_e64 v80, v72, v73
	v_add_f32_e64 v81, v73, v72
	ds_read_b128 v[72:75], v169 offset:45056
	v_mov_b32_e32 v81, v80
	s_nop 1
	v_permlane32_swap_b32_e32 v80, v81
	s_waitcnt lgkmcnt(1)
	v_mfma_f32_32x32x16_bf16 v[16:31], v[68:71], v[64:67], v[16:31]
	v_add_f32_e32 v86, v80, v81
	v_cvt_pk_bf16_f32 v68, v82, v83
	v_cvt_pk_bf16_f32 v70, v76, v77
	v_cvt_pk_bf16_f32 v71, v78, v79
	ds_read_b128 v[76:79], v167 offset:32768
	ds_read_b128 v[80:83], v167 offset:36864
	v_cvt_pk_bf16_f32 v69, v84, v85
	v_add_f32_e32 v84, v189, v86
	s_waitcnt lgkmcnt(2)
	v_mfma_f32_32x32x16_bf16 v[0:15], v[72:75], v[64:67], v[0:15]
	ds_read_b128 v[64:67], v167 offset:40960
	ds_read_b128 v[72:75], v167 offset:45056
	v_add_u32_e32 v85, s33, v145
	s_waitcnt lgkmcnt(3)
	v_mfma_f32_32x32x16_bf16 v[48:63], v[76:79], v[68:71], v[48:63]
	v_mov_b64_e32 v[76:77], s[14:15]
	v_div_scale_f32 v78, s[14:15], v84, v84, 1.0
	v_rcp_f32_e32 v79, v78
	v_mad_i64_i32 v[76:77], s[14:15], v85, s26, v[76:77]
	v_lshl_add_u64 v[76:77], s[12:13], 1, v[76:77]
	s_waitcnt lgkmcnt(2)
	v_mfma_f32_32x32x16_bf16 v[32:47], v[80:83], v[68:71], v[32:47]
	v_fma_f32 v80, -v78, v79, 1.0
	v_fmac_f32_e32 v79, v80, v79
	v_div_scale_f32 v80, vcc, 1.0, v84, 1.0
	v_mul_f32_e32 v81, v80, v79
	v_fma_f32 v82, -v78, v81, v80
	v_fmac_f32_e32 v81, v82, v79
	s_waitcnt lgkmcnt(1)
	v_mfma_f32_32x32x16_bf16 v[16:31], v[64:67], v[68:71], v[16:31]
	v_fma_f32 v64, -v78, v81, v80
	v_div_fmas_f32 v64, v64, v79, v81
	v_div_fixup_f32 v64, v64, v84, 1.0
	v_mul_f32_e64 v48, v64, v48
	v_mul_f32_e64 v49, v64, v49
	v_mul_f32_e32 v50, v64, v50
	v_mul_f32_e32 v51, v64, v51
	v_mul_f32_e32 v32, v64, v32
	v_mul_f32_e32 v33, v64, v33
	v_mul_f32_e32 v34, v64, v34
	v_mul_f32_e32 v35, v64, v35
	s_waitcnt lgkmcnt(0)
	v_mfma_f32_32x32x16_bf16 v[0:15], v[72:75], v[68:71], v[0:15]
	s_nop 1
	v_mul_f32_e64 v16, v64, v16
	v_mul_f32_e64 v17, v64, v17
	v_mul_f32_e64 v18, v64, v18
	v_mul_f32_e64 v19, v64, v19
	v_lshl_add_u64 v[66:67], v[76:77], 0, v[146:147]
	v_cvt_pk_bf16_f32 v48, v48, v49
	v_cvt_pk_bf16_f32 v49, v50, v51
	v_cvt_pk_bf16_f32 v32, v32, v33
	v_cvt_pk_bf16_f32 v33, v34, v35
	s_nop 0
	v_mul_f32_e32 v0, v64, v0
	v_mul_f32_e32 v1, v64, v1
	v_mul_f32_e32 v2, v64, v2
	v_mul_f32_e32 v3, v64, v3
	v_cvt_pk_bf16_f32 v16, v16, v17
	v_cvt_pk_bf16_f32 v17, v18, v19
	v_cvt_pk_bf16_f32 v0, v0, v1
	v_cvt_pk_bf16_f32 v1, v2, v3
	global_store_dwordx2 v[66:67], v[48:49], off
	v_mul_f32_e32 v48, v64, v52
	v_mul_f32_e32 v49, v64, v53
	v_mul_f32_e32 v50, v64, v54
	v_mul_f32_e32 v51, v64, v55
	global_store_dwordx2 v[66:67], v[32:33], off offset:64
	v_mul_f32_e32 v32, v64, v36
	v_mul_f32_e32 v33, v64, v37
	v_mul_f32_e32 v34, v64, v38
	v_mul_f32_e32 v35, v64, v39
	global_store_dwordx2 v[66:67], v[16:17], off offset:128
	v_mul_f32_e32 v16, v64, v20
	v_mul_f32_e32 v17, v64, v21
	v_mul_f32_e32 v18, v64, v22
	v_mul_f32_e32 v19, v64, v23
	global_store_dwordx2 v[66:67], v[0:1], off offset:192
	v_mul_f32_e32 v0, v64, v4
	v_mul_f32_e32 v1, v64, v5
	v_mul_f32_e32 v2, v64, v6
	v_mul_f32_e32 v3, v64, v7
	v_cvt_pk_bf16_f32 v48, v48, v49
	v_cvt_pk_bf16_f32 v49, v50, v51
	v_cvt_pk_bf16_f32 v32, v32, v33
	v_cvt_pk_bf16_f32 v33, v34, v35
	v_cvt_pk_bf16_f32 v16, v16, v17
	v_cvt_pk_bf16_f32 v17, v18, v19
	v_cvt_pk_bf16_f32 v0, v0, v1
	v_cvt_pk_bf16_f32 v1, v2, v3
	global_store_dwordx2 v[66:67], v[48:49], off offset:16
	v_mul_f32_e32 v48, v64, v56
	v_mul_f32_e32 v49, v64, v57
	v_mul_f32_e32 v50, v64, v58
	v_mul_f32_e32 v51, v64, v59
	global_store_dwordx2 v[66:67], v[32:33], off offset:80
	v_mul_f32_e32 v32, v64, v40
	v_mul_f32_e32 v33, v64, v41
	v_mul_f32_e32 v34, v64, v42
	v_mul_f32_e32 v35, v64, v43
	global_store_dwordx2 v[66:67], v[16:17], off offset:144
	v_mul_f32_e32 v16, v64, v24
	v_mul_f32_e32 v17, v64, v25
	v_mul_f32_e32 v18, v64, v26
	v_mul_f32_e32 v19, v64, v27
	global_store_dwordx2 v[66:67], v[0:1], off offset:208
	v_mul_f32_e32 v0, v64, v8
	v_mul_f32_e32 v1, v64, v9
	v_mul_f32_e32 v2, v64, v10
	v_mul_f32_e32 v3, v64, v11
	v_cvt_pk_bf16_f32 v48, v48, v49
	v_cvt_pk_bf16_f32 v49, v50, v51
	v_cvt_pk_bf16_f32 v32, v32, v33
	v_cvt_pk_bf16_f32 v33, v34, v35
	v_cvt_pk_bf16_f32 v16, v16, v17
	v_cvt_pk_bf16_f32 v17, v18, v19
	v_cvt_pk_bf16_f32 v0, v0, v1
	v_cvt_pk_bf16_f32 v1, v2, v3
	global_store_dwordx2 v[66:67], v[48:49], off offset:32
	v_mul_f32_e32 v48, v64, v60
	v_mul_f32_e32 v49, v64, v61
	v_mul_f32_e32 v50, v64, v62
	v_mul_f32_e32 v51, v64, v63
	global_store_dwordx2 v[66:67], v[32:33], off offset:96
	v_mul_f32_e32 v32, v64, v44
	v_mul_f32_e32 v33, v64, v45
	v_mul_f32_e32 v34, v64, v46
	v_mul_f32_e32 v35, v64, v47
	global_store_dwordx2 v[66:67], v[16:17], off offset:160
	v_mul_f32_e32 v16, v64, v28
	v_mul_f32_e32 v17, v64, v29
	v_mul_f32_e32 v18, v64, v30
	v_mul_f32_e32 v19, v64, v31
	global_store_dwordx2 v[66:67], v[0:1], off offset:224
	v_mul_f32_e32 v0, v64, v12
	v_mul_f32_e32 v1, v64, v13
	v_mul_f32_e32 v2, v64, v14
	v_mul_f32_e32 v3, v64, v15
	v_cvt_pk_bf16_f32 v48, v48, v49
	v_cvt_pk_bf16_f32 v49, v50, v51
	v_cvt_pk_bf16_f32 v32, v32, v33
	v_cvt_pk_bf16_f32 v33, v34, v35
	v_cvt_pk_bf16_f32 v16, v16, v17
	v_cvt_pk_bf16_f32 v17, v18, v19
	v_cvt_pk_bf16_f32 v0, v0, v1
	v_cvt_pk_bf16_f32 v1, v2, v3
	global_store_dwordx2 v[66:67], v[48:49], off offset:48
	global_store_dwordx2 v[66:67], v[32:33], off offset:112
	global_store_dwordx2 v[66:67], v[16:17], off offset:176
	global_store_dwordx2 v[66:67], v[0:1], off offset:240
	s_cbranch_scc1 .LBB0_1485

.LBB0_1477:
	s_ashr_i32 s12, s15, 6
	s_mul_hi_i32 s13, s12, 0x2aaaaaab
	s_and_b32 s31, s14, 1
	s_lshr_b32 s14, s13, 31
	s_add_i32 s34, s13, s14
	s_mul_i32 s13, s34, 6
	s_lshl_b32 s14, s15, 7
	s_sub_i32 s12, s12, s13
	s_mul_i32 s13, s34, 0x2100
	s_and_b32 s14, s14, 0x1f80
	s_add_i32 s33, s14, s13
	s_addk_i32 s33, 0x100
	s_mul_i32 s14, s33, 0x600
	s_mul_hi_i32 s13, s33, 0x600
	s_add_u32 s35, s16, s14
	s_addc_u32 s36, s17, s13
	s_lshl_b32 s12, s12, 7
	s_ashr_i32 s13, s12, 31
	s_lshl_b64 s[14:15], s[12:13], 1
	s_add_u32 s37, s35, s14
	s_addc_u32 s36, s36, s15
	s_lshl_b32 s35, s31, 7
	s_add_u32 s40, s37, s35
	s_addc_u32 s41, s36, 0
	v_mov_b32_e32 v167, v147
	v_lshl_add_u64 v[0:1], s[40:41], 0, v[166:167]
	v_mov_b32_e32 v169, v147
	v_lshl_add_u64 v[0:1], v[0:1], 0, v[168:169]
	global_load_dwordx4 v[140:143], v[0:1], off
	global_load_dwordx4 v[136:139], v[0:1], off offset:32
	global_load_dwordx4 v[132:135], v[0:1], off offset:64
	global_load_dwordx4 v[128:131], v[0:1], off offset:96
	s_mul_i32 s38, s34, 0xc60000
	s_mul_hi_i32 s36, s34, 0xc60000
	s_add_u32 s37, s19, s38
	s_addc_u32 s39, s20, s36
	s_add_u32 s42, s37, s14
	s_mul_i32 s37, s34, 0x300
	s_addc_u32 s39, s39, s15
	s_add_i32 s37, s37, s12
	s_add_u32 s40, s42, s35
	s_addc_u32 s41, s39, 0
	v_mov_b32_e32 v171, v147
	v_lshl_add_u64 v[0:1], s[40:41], 0, v[170:171]
	v_mov_b32_e32 v173, v147
	v_add_u32_e32 v46, v202, v203
	v_mov_b32_e32 v175, v147
	s_mul_i32 s43, s37, 0x4200
	v_lshl_add_u64 v[38:39], v[0:1], 0, v[172:173]
	v_readfirstlane_b32 s39, v46
	v_lshl_add_u64 v[0:1], s[40:41], 0, v[174:175]
	v_mov_b32_e32 v177, v147
	v_add_u32_e32 v47, v202, v204
	s_mul_hi_i32 s34, s37, 0x4200
	s_mov_b32 m0, s39
	v_lshl_add_u64 v[40:41], v[0:1], 0, v[176:177]
	v_readfirstlane_b32 s39, v47
	s_add_u32 s40, s21, s43
	s_waitcnt vmcnt(63) expcnt(7) lgkmcnt(15)
	s_barrier
	global_load_lds_dwordx4 v[38:39], off
	v_lshl_add_u64 v[0:1], v[40:41], 0, s[4:5]
	s_mov_b32 m0, s39
	s_addc_u32 s41, s22, s34
	v_mov_b32_e32 v179, v147
	global_load_lds_dwordx4 v[0:1], off
	v_lshl_add_u64 v[0:1], s[40:41], 0, v[178:179]
	v_mov_b32_e32 v181, v147
	v_add_u32_e32 v48, v202, v205
	v_lshl_add_u64 v[42:43], v[0:1], 0, v[180:181]
	v_add_u32_e32 v0, 0x2000, v48
	v_mov_b32_e32 v183, v147
	v_readfirstlane_b32 s34, v0
	v_lshl_add_u64 v[0:1], v[148:149], 1, s[40:41]
	v_add_u32_e32 v49, v202, v206
	v_lshl_add_u64 v[44:45], v[0:1], 0, v[182:183]
	v_add_u32_e32 v0, 0x2000, v49
	s_mov_b32 m0, s34
	v_readfirstlane_b32 s34, v0
	v_lshl_add_u64 v[0:1], v[150:151], 1, s[40:41]
	v_mov_b32_e32 v185, v147
	v_add_u32_e32 v81, v202, v207
	v_lshl_add_u64 v[16:17], v[0:1], 0, v[184:185]
	v_add_u32_e32 v0, 0x2000, v81
	global_load_lds_dwordx4 v[42:43], off
	s_mov_b32 m0, s34
	v_readfirstlane_b32 s34, v0
	v_lshl_add_u64 v[0:1], v[152:153], 1, s[40:41]
	v_mov_b32_e32 v187, v147
	v_add_u32_e32 v114, v202, v208
	v_lshl_add_u64 v[82:83], v[0:1], 0, v[186:187]
	v_add_u32_e32 v0, 0x2000, v114
	global_load_lds_dwordx4 v[44:45], off
	s_mov_b32 m0, s34
	v_readfirstlane_b32 s34, v0
	global_load_lds_dwordx4 v[16:17], off
	s_mov_b32 m0, s34
	v_add_u32_e32 v173, v209, v210
	global_load_lds_dwordx4 v[82:83], off
	s_waitcnt vmcnt(0) lgkmcnt(0)
	s_barrier
	ds_read_b128 v[0:3], v173
	ds_read_b128 v[18:21], v173 offset:4096
	s_waitcnt lgkmcnt(1)
	v_mfma_f32_32x32x16_bf16 v[0:15], v[0:3], v[140:143], 0
	v_add_u32_e32 v171, v209, v211
	ds_read_b128 v[22:25], v171
	ds_read_b128 v[26:29], v171 offset:4096
	v_add_u32_e32 v169, v209, v212
	v_add_u32_e32 v167, v209, v213
	v_lshl_add_u64 v[104:105], v[16:17], 0, s[10:11]
	s_or_b32 s14, s14, s35
	s_add_u32 s14, s14, s38
	s_waitcnt lgkmcnt(2)
	v_mfma_f32_32x32x16_bf16 v[64:79], v[18:21], v[140:143], 0
	v_add_u32_e32 v20, 0x6000, v46
	v_lshl_add_u64 v[18:19], v[38:39], 0, s[6:7]
	v_readfirstlane_b32 s39, v20
	v_add_u32_e32 v20, 0x6000, v47
	s_mov_b32 m0, s39
	v_readfirstlane_b32 s39, v20
	v_add_u32_e32 v20, 0x8000, v48
	s_waitcnt lgkmcnt(1)
	v_mfma_f32_32x32x16_bf16 v[0:15], v[22:25], v[136:139], v[0:15]
	ds_read_b128 v[22:25], v169
	ds_read_b128 v[30:33], v169 offset:4096
	s_addc_u32 s15, s15, s36
	s_mov_b32 s34, 1
	v_lshl_add_u64 v[190:191], s[14:15], 0, v[154:155]
	v_lshl_add_u64 v[200:201], s[14:15], 0, v[164:165]
	s_waitcnt lgkmcnt(2)
	v_mfma_f32_32x32x16_bf16 v[64:79], v[26:29], v[136:139], v[64:79]
	s_waitcnt lgkmcnt(1)
	v_mfma_f32_32x32x16_bf16 v[0:15], v[22:25], v[132:135], v[0:15]
	ds_read_b128 v[22:25], v167
	ds_read_b128 v[34:37], v167 offset:4096
	global_load_lds_dwordx4 v[18:19], off
	v_lshl_add_u64 v[18:19], v[40:41], 0, s[8:9]
	s_mov_b32 m0, s39
	v_readfirstlane_b32 s39, v20
	global_load_lds_dwordx4 v[18:19], off
	s_waitcnt lgkmcnt(0)
	v_mfma_f32_32x32x16_bf16 v[64:79], v[30:33], v[132:135], v[64:79]
	v_lshl_add_u64 v[18:19], v[42:43], 0, s[10:11]
	s_mov_b32 m0, s39
	ds_read_b128 v[92:95], v171 offset:12288
	global_load_lds_dwordx4 v[18:19], off
	v_add_u32_e32 v18, 0x8000, v49
	v_mfma_f32_32x32x16_bf16 v[0:15], v[22:25], v[128:131], v[0:15]
	v_readfirstlane_b32 s39, v18
	v_lshl_add_u64 v[22:23], v[44:45], 0, s[10:11]
	s_mov_b32 m0, s39
	s_nop 0
	global_load_lds_dwordx4 v[22:23], off
	s_nop 6
	v_max_f32_e32 v19, v0, v0
	v_mfma_f32_32x32x16_bf16 v[64:79], v[34:37], v[128:131], v[64:79]
	s_nop 11
	v_max_f32_e32 v18, v64, v64
	v_max_f32_e32 v18, v19, v18
	v_max3_f32 v18, v18, v1, v65
	v_max3_f32 v18, v18, v2, v66
	v_max3_f32 v18, v18, v3, v67
	v_max3_f32 v18, v18, v4, v68
	v_max3_f32 v18, v18, v5, v69
	v_max3_f32 v18, v18, v6, v70
	v_max3_f32 v18, v18, v7, v71
	v_max3_f32 v18, v18, v8, v72
	v_max3_f32 v18, v18, v9, v73
	v_max3_f32 v18, v18, v10, v74
	v_max3_f32 v18, v18, v11, v75
	v_max3_f32 v18, v18, v12, v76
	v_max3_f32 v18, v18, v13, v77
	v_max3_f32 v18, v18, v14, v78
	v_max3_f32 v18, v18, v15, v79
	v_mov_b32_e32 v19, v18
	s_nop 1
	v_permlane32_swap_b32_e32 v18, v19
	v_max_f32_e32 v19, v19, v19
	v_max_f32_e32 v18, v18, v18
	v_max_f32_e32 v80, v18, v19
	v_sub_f32_e32 v0, v0, v80
	v_sub_f32_e32 v1, v1, v80
	v_sub_f32_e32 v2, v2, v80
	v_sub_f32_e32 v3, v3, v80
	v_exp_f32_e32 v96, v0
	v_exp_f32_e32 v97, v1
	v_exp_f32_e32 v98, v2
	v_exp_f32_e32 v99, v3
	ds_read_b128 v[0:3], v173 offset:8192
	ds_read_b128 v[18:21], v173 offset:12288
	v_sub_f32_e32 v4, v4, v80
	v_sub_f32_e32 v5, v5, v80
	v_sub_f32_e32 v6, v6, v80
	v_sub_f32_e32 v7, v7, v80
	v_exp_f32_e32 v100, v4
	v_exp_f32_e32 v101, v5
	v_exp_f32_e32 v102, v6
	v_exp_f32_e32 v103, v7
	v_sub_f32_e32 v84, v9, v80
	v_sub_f32_e32 v85, v10, v80
	v_sub_f32_e32 v86, v11, v80
	v_cvt_pk_bf16_f32 v4, v96, v97
	v_cvt_pk_bf16_f32 v5, v98, v99
	v_cvt_pk_bf16_f32 v6, v100, v101
	v_cvt_pk_bf16_f32 v7, v102, v103
	v_exp_f32_e32 v107, v84
	v_exp_f32_e32 v108, v85
	v_exp_f32_e32 v109, v86
	ds_read_b128 v[84:87], v171 offset:8192
	s_waitcnt lgkmcnt(0)
	v_mfma_f32_32x32x16_bf16 v[48:63], v[0:3], v[4:7], 0
	v_add_u32_e32 v0, 0x8000, v81
	v_sub_f32_e32 v81, v8, v80
	v_sub_f32_e32 v12, v12, v80
	v_sub_f32_e32 v13, v13, v80
	v_sub_f32_e32 v88, v14, v80
	v_sub_f32_e32 v89, v15, v80
	v_exp_f32_e32 v106, v81
	v_exp_f32_e32 v110, v12
	v_exp_f32_e32 v111, v13
	v_exp_f32_e32 v112, v88
	v_exp_f32_e32 v113, v89
	v_readfirstlane_b32 s39, v0
	v_add_u32_e32 v81, 0x8000, v114
	v_cvt_pk_bf16_f32 v88, v106, v107
	v_cvt_pk_bf16_f32 v89, v108, v109
	v_cvt_pk_bf16_f32 v90, v110, v111
	v_cvt_pk_bf16_f32 v91, v112, v113
	s_mov_b32 m0, s39
	v_readfirstlane_b32 s39, v81
	v_mfma_f32_32x32x16_bf16 v[48:63], v[84:87], v[88:91], v[48:63]
	global_load_lds_dwordx4 v[104:105], off
	v_lshl_add_u64 v[86:87], v[82:83], 0, s[10:11]
	s_mov_b32 m0, s39
	ds_read_b128 v[0:3], v173 offset:16384
	ds_read_b128 v[8:11], v173 offset:20480
	global_load_lds_dwordx4 v[86:87], off
	v_mfma_f32_32x32x16_bf16 v[32:47], v[18:21], v[4:7], 0
	v_sub_f32_e32 v81, v64, v80
	v_sub_f32_e32 v104, v65, v80
	ds_read_b128 v[82:85], v171 offset:16384
	v_sub_f32_e32 v68, v68, v80
	v_sub_f32_e32 v69, v69, v80
	v_sub_f32_e32 v114, v70, v80
	v_sub_f32_e32 v115, v71, v80
	v_mfma_f32_32x32x16_bf16 v[32:47], v[92:95], v[88:91], v[32:47]
	v_sub_f32_e32 v94, v66, v80
	v_sub_f32_e32 v95, v67, v80
	ds_read_b128 v[64:67], v171 offset:20480
	v_exp_f32_e32 v93, v104
	v_exp_f32_e32 v104, v68
	v_exp_f32_e32 v105, v69
	ds_read_b128 v[68:71], v169 offset:8192
	s_waitcnt lgkmcnt(0)
	v_mfma_f32_32x32x16_bf16 v[16:31], v[0:3], v[4:7], 0
	v_exp_f32_e32 v92, v81
	v_exp_f32_e32 v94, v94
	v_exp_f32_e32 v95, v95
	v_sub_f32_e32 v81, v72, v80
	v_sub_f32_e32 v86, v73, v80
	v_sub_f32_e32 v87, v74, v80
	v_mad_i64_i32 v[192:193], s[38:39], s37, v214, v[156:157]
	v_mfma_f32_32x32x16_bf16 v[0:15], v[8:11], v[4:7], 0
	v_mad_i64_i32 v[194:195], s[38:39], s37, v214, v[158:159]
	v_mad_i64_i32 v[196:197], s[38:39], s37, v214, v[160:161]
	v_mad_i64_i32 v[198:199], s[36:37], s37, v214, v[162:163]
	v_mfma_f32_32x32x16_bf16 v[16:31], v[82:85], v[88:91], v[16:31]
	ds_read_b128 v[82:85], v169 offset:12288
	v_mfma_f32_32x32x16_bf16 v[0:15], v[64:67], v[88:91], v[0:15]
	v_exp_f32_e32 v88, v114
	v_exp_f32_e32 v89, v115
	v_cvt_pk_bf16_f32 v64, v92, v93
	v_cvt_pk_bf16_f32 v65, v94, v95
	v_cvt_pk_bf16_f32 v66, v104, v105
	v_cvt_pk_bf16_f32 v67, v88, v89
	v_sub_f32_e32 v90, v78, v80
	v_sub_f32_e32 v91, v79, v80
	v_mfma_f32_32x32x16_bf16 v[48:63], v[68:71], v[64:67], v[48:63]
	ds_read_b128 v[68:71], v169 offset:16384
	v_exp_f32_e32 v78, v81
	v_exp_f32_e32 v79, v86
	v_exp_f32_e32 v86, v90
	s_waitcnt lgkmcnt(0)
	v_mfma_f32_32x32x16_bf16 v[32:47], v[82:85], v[64:67], v[32:47]
	v_sub_f32_e32 v83, v75, v80
	ds_read_b128 v[72:75], v169 offset:20480
	v_sub_f32_e32 v84, v76, v80
	v_sub_f32_e32 v85, v77, v80
	v_exp_f32_e32 v82, v87
	v_exp_f32_e32 v83, v83
	v_exp_f32_e32 v84, v84
	v_mfma_f32_32x32x16_bf16 v[16:31], v[68:71], v[64:67], v[16:31]
	ds_read_b128 v[68:71], v167 offset:8192
	v_exp_f32_e32 v85, v85
	v_exp_f32_e32 v87, v91
	v_pk_add_f32 v[76:77], v[96:97], 0 op_sel_hi:[1,0]
	s_waitcnt lgkmcnt(0)
	v_mfma_f32_32x32x16_bf16 v[0:15], v[72:75], v[64:67], v[0:15]
	ds_read_b128 v[72:75], v167 offset:12288
	v_cvt_pk_bf16_f32 v64, v78, v79
	v_cvt_pk_bf16_f32 v65, v82, v83
	v_cvt_pk_bf16_f32 v66, v84, v85
	v_cvt_pk_bf16_f32 v67, v86, v87
	s_nop 1
	v_mfma_f32_32x32x16_bf16 v[48:63], v[68:71], v[64:67], v[48:63]
	v_add_f32_e64 v68, v98, v76
	v_add_f32_e64 v69, v99, v77
	v_add_f32_e64 v68, v100, v68
	v_add_f32_e64 v69, v101, v69
	v_add_f32_e64 v68, v102, v68
	v_add_f32_e64 v69, v103, v69
	v_add_f32_e32 v68, v106, v68
	v_add_f32_e32 v69, v107, v69
	s_waitcnt lgkmcnt(0)
	v_mfma_f32_32x32x16_bf16 v[32:47], v[72:75], v[64:67], v[32:47]
	v_add_f32_e64 v68, v108, v68
	v_add_f32_e64 v69, v109, v69
	v_add_f32_e64 v76, v110, v68
	v_add_f32_e64 v77, v111, v69
	ds_read_b128 v[68:71], v167 offset:16384
	v_add_f32_e32 v72, v112, v76
	v_add_f32_e32 v73, v113, v77
	s_nop 0
	v_add_f32_e32 v72, v92, v72
	v_add_f32_e32 v73, v93, v73
	s_nop 0
	v_add_f32_e32 v72, v94, v72
	v_add_f32_e32 v73, v95, v73
	s_nop 0
	v_add_f32_e32 v72, v104, v72
	v_add_f32_e32 v73, v105, v73
	s_nop 0
	v_add_f32_e32 v72, v88, v72
	v_add_f32_e32 v73, v89, v73
	s_nop 0
	v_add_f32_e32 v76, v78, v72
	v_add_f32_e32 v77, v79, v73
	ds_read_b128 v[72:75], v167 offset:20480
	s_waitcnt lgkmcnt(0)
	v_mfma_f32_32x32x16_bf16 v[16:31], v[68:71], v[64:67], v[16:31]
	v_add_f32_e64 v68, v82, v76
	v_add_f32_e64 v69, v83, v77
	v_add_f32_e64 v68, v84, v68
	v_add_f32_e64 v69, v85, v69
	v_add_f32_e64 v68, v86, v68
	v_add_f32_e64 v69, v87, v69
	v_pk_add_f32 v[68:69], v[68:69], v[68:69] op_sel:[0,1] op_sel_hi:[1,0]
	v_mfma_f32_32x32x16_bf16 v[0:15], v[72:75], v[64:67], v[0:15]
	v_mov_b32_e32 v69, v68
	s_nop 1
	v_permlane32_swap_b32_e32 v68, v69
	v_add_f32_e32 v81, v68, v69
	v_add_f32_e64 v188, v80, 0
	v_add_f32_e64 v189, v81, 0
	v_pk_add_f32 v[96:97], v[188:189], 0 neg_lo:[1,1] neg_hi:[1,1]
	s_nop 0
	v_mov_b32_e32 v97, v96
	v_mov_b32_e32 v98, v96
	v_mov_b32_e32 v99, v96
	v_mov_b32_e32 v100, v96
	v_mov_b32_e32 v101, v96
	v_mov_b32_e32 v102, v96
	v_mov_b32_e32 v103, v96
	v_mov_b32_e32 v104, v96
	v_mov_b32_e32 v105, v96
	v_mov_b32_e32 v106, v96
	v_mov_b32_e32 v107, v96
	v_mov_b32_e32 v108, v96
	v_mov_b32_e32 v109, v96
	v_mov_b32_e32 v110, v96
	v_mov_b32_e32 v111, v96
	s_branch .LBB0_1480

.Latt_resc_a:
	v_mov_b32_e32 v177, v175
	s_nop 1
	v_permlane32_swap_b32_e32 v175, v177
	v_max_f32_e32 v175, v175, v177
	v_max_f32_e32 v248, 0, v175
	v_exp_f32_e64 v250, -v248
	v_sub_f32_e32 v112, v112, v248
	v_sub_f32_e32 v113, v113, v248
	v_sub_f32_e32 v114, v114, v248
	v_sub_f32_e32 v115, v115, v248
	v_sub_f32_e32 v116, v116, v248
	v_sub_f32_e32 v117, v117, v248
	v_sub_f32_e32 v118, v118, v248
	v_sub_f32_e32 v119, v119, v248
	v_sub_f32_e32 v120, v120, v248
	v_sub_f32_e32 v121, v121, v248
	v_sub_f32_e32 v122, v122, v248
	v_sub_f32_e32 v123, v123, v248
	v_sub_f32_e32 v124, v124, v248
	v_sub_f32_e32 v125, v125, v248
	v_sub_f32_e32 v126, v126, v248
	v_sub_f32_e32 v127, v127, v248
	v_sub_f32_e32 v80, v80, v248
	v_sub_f32_e32 v81, v81, v248
	v_sub_f32_e32 v82, v82, v248
	v_sub_f32_e32 v83, v83, v248
	v_sub_f32_e32 v84, v84, v248
	v_sub_f32_e32 v85, v85, v248
	v_sub_f32_e32 v86, v86, v248
	v_sub_f32_e32 v87, v87, v248
	v_sub_f32_e32 v88, v88, v248
	v_sub_f32_e32 v89, v89, v248
	v_sub_f32_e32 v90, v90, v248
	v_sub_f32_e32 v91, v91, v248
	v_sub_f32_e32 v92, v92, v248
	v_sub_f32_e32 v93, v93, v248
	v_sub_f32_e32 v94, v94, v248
	v_sub_f32_e32 v95, v95, v248
	v_add_f32_e32 v188, v188, v248
	v_mul_f32_e32 v189, v189, v250
	v_mul_f32_e32 v0, v0, v250
	v_mul_f32_e32 v1, v1, v250
	v_mul_f32_e32 v2, v2, v250
	v_mul_f32_e32 v3, v3, v250
	v_mul_f32_e32 v4, v4, v250
	v_mul_f32_e32 v5, v5, v250
	v_mul_f32_e32 v6, v6, v250
	v_mul_f32_e32 v7, v7, v250
	v_mul_f32_e32 v8, v8, v250
	v_mul_f32_e32 v9, v9, v250
	v_mul_f32_e32 v10, v10, v250
	v_mul_f32_e32 v11, v11, v250
	v_mul_f32_e32 v12, v12, v250
	v_mul_f32_e32 v13, v13, v250
	v_mul_f32_e32 v14, v14, v250
	v_mul_f32_e32 v15, v15, v250
	v_mul_f32_e32 v16, v16, v250
	v_mul_f32_e32 v17, v17, v250
	v_mul_f32_e32 v18, v18, v250
	v_mul_f32_e32 v19, v19, v250
	v_mul_f32_e32 v20, v20, v250
	v_mul_f32_e32 v21, v21, v250
	v_mul_f32_e32 v22, v22, v250
	v_mul_f32_e32 v23, v23, v250
	v_mul_f32_e32 v24, v24, v250
	v_mul_f32_e32 v25, v25, v250
	v_mul_f32_e32 v26, v26, v250
	v_mul_f32_e32 v27, v27, v250
	v_mul_f32_e32 v28, v28, v250
	v_mul_f32_e32 v29, v29, v250
	v_mul_f32_e32 v30, v30, v250
	v_mul_f32_e32 v31, v31, v250
	v_mul_f32_e32 v32, v32, v250
	v_mul_f32_e32 v33, v33, v250
	v_mul_f32_e32 v34, v34, v250
	v_mul_f32_e32 v35, v35, v250
	v_mul_f32_e32 v36, v36, v250
	v_mul_f32_e32 v37, v37, v250
	v_mul_f32_e32 v38, v38, v250
	v_mul_f32_e32 v39, v39, v250
	v_mul_f32_e32 v40, v40, v250
	v_mul_f32_e32 v41, v41, v250
	v_mul_f32_e32 v42, v42, v250
	v_mul_f32_e32 v43, v43, v250
	v_mul_f32_e32 v44, v44, v250
	v_mul_f32_e32 v45, v45, v250
	v_mul_f32_e32 v46, v46, v250
	v_mul_f32_e32 v47, v47, v250
	v_mul_f32_e32 v48, v48, v250
	v_mul_f32_e32 v49, v49, v250
	v_mul_f32_e32 v50, v50, v250
	v_mul_f32_e32 v51, v51, v250
	v_mul_f32_e32 v52, v52, v250
	v_mul_f32_e32 v53, v53, v250
	v_mul_f32_e32 v54, v54, v250
	v_mul_f32_e32 v55, v55, v250
	v_mul_f32_e32 v56, v56, v250
	v_mul_f32_e32 v57, v57, v250
	v_mul_f32_e32 v58, v58, v250
	v_mul_f32_e32 v59, v59, v250
	v_mul_f32_e32 v60, v60, v250
	v_mul_f32_e32 v61, v61, v250
	v_mul_f32_e32 v62, v62, v250
	v_mul_f32_e32 v63, v63, v250
	v_sub_f32_e32 v96, 0, v188
	v_mov_b32_e32 v97, v96
	v_mov_b32_e32 v98, v96
	v_mov_b32_e32 v99, v96
	v_mov_b32_e32 v100, v96
	v_mov_b32_e32 v101, v96
	v_mov_b32_e32 v102, v96
	v_mov_b32_e32 v103, v96
	v_mov_b32_e32 v104, v96
	v_mov_b32_e32 v105, v96
	v_mov_b32_e32 v106, v96
	v_mov_b32_e32 v107, v96
	v_mov_b32_e32 v108, v96
	v_mov_b32_e32 v109, v96
	v_mov_b32_e32 v110, v96
	v_mov_b32_e32 v111, v96
	s_branch .Latt_cont_a

.LBB0_1482:
	s_waitcnt vmcnt(0)
	s_barrier
	ds_read_b128 v[96:99], v173 offset:24576
	s_waitcnt lgkmcnt(0)
	v_mfma_f32_32x32x16_bf16 v[80:95], v[96:99], v[140:143], v[64:79]
	ds_read_b128 v[96:99], v171 offset:24576
	s_waitcnt lgkmcnt(0)
	v_mfma_f32_32x32x16_bf16 v[80:95], v[96:99], v[136:139], v[80:95]
	ds_read_b128 v[96:99], v169 offset:24576
	s_waitcnt lgkmcnt(0)
	v_mfma_f32_32x32x16_bf16 v[80:95], v[96:99], v[132:135], v[80:95]
	ds_read_b128 v[96:99], v173 offset:28672
	s_waitcnt lgkmcnt(0)
	v_mfma_f32_32x32x16_bf16 v[64:79], v[96:99], v[140:143], v[64:79]
	ds_read_b128 v[96:99], v171 offset:28672
	s_waitcnt lgkmcnt(0)
	v_mfma_f32_32x32x16_bf16 v[64:79], v[96:99], v[136:139], v[64:79]
	ds_read_b128 v[96:99], v169 offset:28672
	s_waitcnt lgkmcnt(0)
	v_mfma_f32_32x32x16_bf16 v[64:79], v[96:99], v[132:135], v[64:79]
	ds_read_b128 v[96:99], v167 offset:28672
	ds_read_b128 v[100:103], v167 offset:24576
	s_waitcnt lgkmcnt(1)
	v_mfma_f32_32x32x16_bf16 v[64:79], v[96:99], v[128:131], v[64:79]
	s_waitcnt lgkmcnt(0)
	v_mfma_f32_32x32x16_bf16 v[80:95], v[100:103], v[128:131], v[80:95]
	s_nop 9
	v_max_f32_e32 v96, v64, v64
	s_nop 0
	v_max_f32_e32 v97, v80, v80
	v_max_f32_e32 v96, v97, v96
	v_max3_f32 v96, v96, v81, v65
	v_max3_f32 v96, v96, v82, v66
	v_max3_f32 v96, v96, v83, v67
	v_max3_f32 v96, v96, v84, v68
	v_max3_f32 v96, v96, v85, v69
	v_max3_f32 v96, v96, v86, v70
	v_max3_f32 v96, v96, v87, v71
	v_max3_f32 v96, v96, v88, v72
	v_max3_f32 v96, v96, v89, v73
	v_max3_f32 v96, v96, v90, v74
	v_max3_f32 v96, v96, v91, v75
	v_max3_f32 v96, v96, v92, v76
	v_max3_f32 v96, v96, v93, v77
	v_max3_f32 v96, v96, v94, v78
	v_max3_f32 v96, v96, v95, v79
	v_mov_b32_e32 v97, v96
	s_nop 1
	v_permlane32_swap_b32_e32 v96, v97
	v_max_f32_e32 v97, v97, v97
	v_max_f32_e32 v96, v96, v96
	v_max_f32_e32 v96, v96, v97
	v_cmp_lt_f32_e32 vcc, 0, v96
	s_cbranch_vccz .LBB0_1473
	v_max_f32_e32 v96, v96, v96
	v_max_f32_e32 v97, 0, v96
	v_exp_f32_e64 v96, -v97
	v_sub_f32_e32 v80, v80, v97
	v_sub_f32_e32 v81, v81, v97
	v_sub_f32_e32 v82, v82, v97
	v_sub_f32_e32 v83, v83, v97
	v_sub_f32_e32 v84, v84, v97
	v_sub_f32_e32 v85, v85, v97
	v_sub_f32_e32 v86, v86, v97
	v_sub_f32_e32 v87, v87, v97
	v_sub_f32_e32 v88, v88, v97
	v_sub_f32_e32 v89, v89, v97
	v_sub_f32_e32 v90, v90, v97
	v_sub_f32_e32 v91, v91, v97
	v_sub_f32_e32 v92, v92, v97
	v_sub_f32_e32 v93, v93, v97
	v_sub_f32_e32 v94, v94, v97
	v_sub_f32_e32 v95, v95, v97
	v_sub_f32_e32 v64, v64, v97
	v_sub_f32_e32 v65, v65, v97
	v_sub_f32_e32 v66, v66, v97
	v_sub_f32_e32 v67, v67, v97
	v_sub_f32_e32 v68, v68, v97
	v_sub_f32_e32 v69, v69, v97
	v_sub_f32_e32 v70, v70, v97
	v_sub_f32_e32 v71, v71, v97
	v_sub_f32_e32 v72, v72, v97
	v_sub_f32_e32 v73, v73, v97
	v_sub_f32_e32 v74, v74, v97
	v_sub_f32_e32 v75, v75, v97
	v_sub_f32_e32 v76, v76, v97
	v_sub_f32_e32 v77, v77, v97
	v_sub_f32_e32 v78, v78, v97
	v_sub_f32_e32 v79, v79, v97
	v_mul_f32_e32 v189, v189, v96
	v_mul_f32_e32 v14, v14, v96
	v_mul_f32_e32 v15, v15, v96
	v_mul_f32_e32 v12, v12, v96
	v_mul_f32_e32 v13, v13, v96
	v_mul_f32_e32 v10, v10, v96
	v_mul_f32_e32 v11, v11, v96
	v_mul_f32_e32 v8, v8, v96
	v_mul_f32_e32 v9, v9, v96
	v_mul_f32_e32 v6, v6, v96
	v_mul_f32_e32 v7, v7, v96
	v_mul_f32_e32 v4, v4, v96
	v_mul_f32_e32 v5, v5, v96
	v_mul_f32_e32 v2, v2, v96
	v_mul_f32_e32 v3, v3, v96
	v_mul_f32_e32 v0, v0, v96
	v_mul_f32_e32 v1, v1, v96
	v_mul_f32_e32 v30, v30, v96
	v_mul_f32_e32 v31, v31, v96
	v_mul_f32_e32 v28, v28, v96
	v_mul_f32_e32 v29, v29, v96
	v_mul_f32_e32 v26, v26, v96
	v_mul_f32_e32 v27, v27, v96
	v_mul_f32_e32 v24, v24, v96
	v_mul_f32_e32 v25, v25, v96
	v_mul_f32_e32 v22, v22, v96
	v_mul_f32_e32 v23, v23, v96
	v_mul_f32_e32 v20, v20, v96
	v_mul_f32_e32 v21, v21, v96
	v_mul_f32_e32 v18, v18, v96
	v_mul_f32_e32 v19, v19, v96
	v_mul_f32_e32 v16, v16, v96
	v_mul_f32_e32 v17, v17, v96
	v_mul_f32_e32 v46, v46, v96
	v_mul_f32_e32 v47, v47, v96
	v_mul_f32_e32 v44, v44, v96
	v_mul_f32_e32 v45, v45, v96
	v_mul_f32_e32 v42, v42, v96
	v_mul_f32_e32 v43, v43, v96
	v_mul_f32_e32 v40, v40, v96
	v_mul_f32_e32 v41, v41, v96
	v_mul_f32_e32 v38, v38, v96
	v_mul_f32_e32 v39, v39, v96
	v_mul_f32_e32 v36, v36, v96
	v_mul_f32_e32 v37, v37, v96
	v_mul_f32_e32 v34, v34, v96
	v_mul_f32_e32 v35, v35, v96
	v_mul_f32_e32 v32, v32, v96
	v_mul_f32_e32 v33, v33, v96
	v_mul_f32_e32 v62, v62, v96
	v_mul_f32_e32 v63, v63, v96
	v_mul_f32_e32 v60, v60, v96
	v_mul_f32_e32 v61, v61, v96
	v_mul_f32_e32 v58, v58, v96
	v_mul_f32_e32 v59, v59, v96
	v_mul_f32_e32 v56, v56, v96
	v_mul_f32_e32 v57, v57, v96
	v_mul_f32_e32 v54, v54, v96
	v_mul_f32_e32 v55, v55, v96
	v_mul_f32_e32 v52, v52, v96
	v_mul_f32_e32 v53, v53, v96
	v_mul_f32_e32 v50, v50, v96
	v_mul_f32_e32 v51, v51, v96
	v_mul_f32_e32 v48, v48, v96
	v_mul_f32_e32 v49, v49, v96
	s_branch .LBB0_1473

.LBB0_1542:
	v_mul_hi_i32 v20, v16, s14
	v_lshrrev_b32_e32 v21, 31, v20
	v_ashrrev_i32_e32 v22, 13, v20
	v_add_u32_e32 v23, v20, v21
	v_add_u32_e32 v20, v22, v21
	v_ashrrev_i32_e32 v22, 31, v23
	v_mul_i32_i24_e32 v24, 0x2100, v20
	v_mad_u64_u32 v[20:21], s[22:23], v23, s17, v[12:13]
	v_lshrrev_b32_e32 v22, 19, v22
	v_ashrrev_i32_e32 v21, 31, v20
	v_add_u32_e32 v22, v23, v22
	v_lshlrev_b64 v[26:27], 1, v[20:21]
	v_and_b32_e32 v20, 0xffffe000, v22
	v_sub_u32_e32 v20, v23, v20
	v_add3_u32 v32, v24, v20, s15
	v_mov_b64_e32 v[18:19], s[6:7]
	v_mad_i64_i32 v[20:21], s[22:23], v32, s16, v[14:15]
	v_mad_i64_i32 v[18:19], s[22:23], v32, s16, v[18:19]
	v_lshl_add_u64 v[20:21], v[20:21], 0, v[26:27]
	v_lshl_add_u64 v[18:19], v[18:19], 0, v[26:27]
	v_lshl_add_u64 v[28:29], v[20:21], 0, v[8:9]
	v_lshl_add_u64 v[30:31], v[18:19], 0, v[8:9]
	global_load_dwordx4 v[18:21], v[28:29], off
	global_load_dwordx4 v[22:25], v[30:31], off
	v_mov_b64_e32 v[28:29], s[0:1]
	v_mad_i64_i32 v[28:29], s[22:23], v32, s19, v[28:29]
	v_lshl_add_u64 v[26:27], v[28:29], 0, v[26:27]
	v_add_u32_e32 v13, s11, v13
	v_cmp_lt_i32_e32 vcc, s20, v13
	s_or_b64 s[8:9], vcc, s[8:9]
	v_add_u32_e32 v16, s12, v16
	v_add_u32_e32 v12, s13, v12
	v_lshl_add_u64 v[26:27], v[26:27], 0, v[8:9]
	s_waitcnt vmcnt(1)
	v_lshlrev_b32_e32 v28, 16, v18
	s_waitcnt vmcnt(0)
	v_lshlrev_b32_e32 v30, 16, v22
	v_and_b32_e32 v29, 0xffff0000, v18
	v_and_b32_e32 v31, 0xffff0000, v22
	v_lshlrev_b32_e32 v18, 16, v19
	v_lshlrev_b32_e32 v22, 16, v23
	v_and_b32_e32 v19, 0xffff0000, v19
	v_and_b32_e32 v23, 0xffff0000, v23
	v_lshlrev_b32_e32 v32, 16, v20
	v_lshlrev_b32_e32 v34, 16, v24
	v_and_b32_e32 v33, 0xffff0000, v20
	v_and_b32_e32 v35, 0xffff0000, v24
	v_lshlrev_b32_e32 v20, 16, v21
	v_lshlrev_b32_e32 v24, 16, v25
	v_and_b32_e32 v21, 0xffff0000, v21
	v_and_b32_e32 v25, 0xffff0000, v25
	v_fma_f32 v18, -v10, v22, v18
	v_fma_f32 v19, -v11, v23, v19
	v_fma_f32 v22, -v10, v30, v28
	v_fma_f32 v23, -v11, v31, v29
	v_fma_f32 v20, -v10, v24, v20
	v_fma_f32 v21, -v11, v25, v21
	v_fma_f32 v24, -v10, v34, v32
	v_fma_f32 v25, -v11, v35, v33
	v_mul_f32_e32 v34, v22, v22
	v_mul_f32_e32 v35, v23, v23
	v_mul_f32_e32 v32, v18, v18
	v_mul_f32_e32 v33, v19, v19
	v_add_f32_e32 v34, v34, v35
	v_add_f32_e32 v32, v34, v32
	v_mul_f32_e32 v30, v24, v24
	v_mul_f32_e32 v31, v25, v25
	v_add_f32_e32 v32, v33, v32
	v_add_f32_e32 v30, v30, v32
	v_mul_f32_e32 v28, v20, v20
	v_mul_f32_e32 v29, v21, v21
	v_add_f32_e32 v30, v31, v30
	v_add_f32_e32 v28, v28, v30
	v_add_f32_e32 v28, v29, v28
	ds_bpermute_b32 v29, v75, v28
	s_waitcnt lgkmcnt(0)
	v_add_f32_e32 v28, v28, v29
	ds_bpermute_b32 v29, v74, v28
	s_waitcnt lgkmcnt(0)
	v_add_f32_e32 v28, v28, v29
	ds_bpermute_b32 v29, v73, v28
	s_waitcnt lgkmcnt(0)
	v_add_f32_e32 v28, v28, v29
	ds_bpermute_b32 v29, v72, v28
	s_waitcnt lgkmcnt(0)
	v_add_f32_e32 v28, v28, v29
	v_fmamk_f32 v28, v28, 0x3c000000, v17
	v_mul_f32_e32 v29, 0x4b800000, v28
	v_cmp_gt_f32_e32 vcc, s18, v28
	s_nop 1
	v_cndmask_b32_e32 v28, v28, v29, vcc
	v_rsq_f32_e32 v28, v28
	s_nop 0
	v_mul_f32_e32 v29, 0x45800000, v28
	v_cndmask_b32_e32 v28, v28, v29, vcc
	v_mul_f32_e32 v28, 0x3f24fd5c, v28
	v_mul_f32_e32 v22, v22, v28
	v_mul_f32_e32 v23, v23, v28
	v_mul_f32_e32 v18, v18, v28
	v_mul_f32_e32 v19, v19, v28
	v_mul_f32_e32 v24, v24, v28
	v_mul_f32_e32 v25, v25, v28
	v_mul_f32_e32 v20, v20, v28
	v_mul_f32_e32 v21, v21, v28
	v_mul_f32_e32 v22, v0, v22
	v_mul_f32_e32 v23, v1, v23
	v_mul_f32_e32 v28, v2, v18
	v_mul_f32_e32 v29, v3, v19
	v_mul_f32_e32 v24, v4, v24
	v_mul_f32_e32 v25, v5, v25
	v_mul_f32_e32 v30, v6, v20
	v_mul_f32_e32 v31, v7, v21
	v_cvt_pk_bf16_f32 v18, v22, v23
	v_cvt_pk_bf16_f32 v19, v28, v29
	v_cvt_pk_bf16_f32 v20, v24, v25
	v_cvt_pk_bf16_f32 v21, v30, v31
	global_store_dwordx4 v[26:27], v[18:21], off
	s_andn2_b64 exec, exec, s[8:9]
	s_cbranch_execnz .LBB0_1542

.LBB0_1547:
	v_cmp_gt_u32_e32 vcc, s6, v83
	v_mov_b32_e32 v0, 0
	v_mov_b32_e32 v1, 0
	v_mov_b32_e32 v2, 0
	v_mov_b32_e32 v3, 0
	s_and_saveexec_b64 s[4:5], vcc
	s_cbranch_execz .LBB0_1546
	v_ashrrev_i32_e32 v69, 31, v68
	v_lshlrev_b64 v[0:1], 10, v[68:69]
	v_lshl_add_u64 v[0:1], v[64:65], 0, v[0:1]
	global_load_dwordx2 v[2:3], v[0:1], off
	global_load_dwordx2 v[86:87], v[0:1], off offset:512
	s_waitcnt vmcnt(1)
	v_lshlrev_b32_e32 v0, 16, v2
	s_waitcnt vmcnt(0)
	v_lshlrev_b32_e32 v69, 16, v86
	v_and_b32_e32 v1, 0xffff0000, v2
	v_and_b32_e32 v2, 0xffff0000, v86
	v_lshlrev_b32_e32 v86, 16, v87
	v_and_b32_e32 v87, 0xffff0000, v87
	v_mul_f32_e32 v69, 0xbfb8aa3b, v69
	v_mul_f32_e32 v2, 0xbfb8aa3b, v2
	v_mul_f32_e32 v86, 0xbfb8aa3b, v86
	v_mul_f32_e32 v87, 0xbfb8aa3b, v87
	v_exp_f32_e32 v69, v69
	v_exp_f32_e32 v2, v2
	v_exp_f32_e32 v86, v86
	v_exp_f32_e32 v87, v87
	v_add_f32_e32 v69, 1.0, v69
	v_add_f32_e32 v2, 1.0, v2
	v_add_f32_e32 v88, 1.0, v86
	v_add_f32_e32 v87, 1.0, v87
	v_rcp_f32_e32 v86, v69
	v_rcp_f32_e32 v88, v88
	v_rcp_f32_e32 v89, v87
	v_rcp_f32_e32 v87, v2
	v_lshlrev_b32_e32 v2, 16, v3
	v_and_b32_e32 v3, 0xffff0000, v3
	v_mul_f32_e32 v2, v88, v2
	v_mul_f32_e32 v3, v89, v3
	v_mul_f32_e32 v0, v86, v0
	v_mul_f32_e32 v1, v87, v1
	s_branch .LBB0_1546

.LBB0_1550:
	ds_read_b128 v[84:87], v0
	global_load_dwordx4 v[88:91], v[60:61], off
	global_load_dwordx4 v[92:95], v[62:63], off
	v_add_u32_e32 v2, s12, v1
	v_add_u32_e32 v2, 0x104, v2
	v_mad_i64_i32 v[2:3], s[0:1], v2, s9, v[66:67]
	s_waitcnt lgkmcnt(0)
	v_add_f32_e32 v68, v84, v85
	v_add_f32_e32 v68, v86, v68
	v_add_f32_e32 v68, v87, v68
	ds_bpermute_b32 v69, v70, v68
	v_add_u32_e32 v1, 4, v1
	v_cmp_lt_u32_e32 vcc, 27, v1
	v_add_u32_e32 v0, 0x1000, v0
	s_or_b64 s[4:5], vcc, s[4:5]
	s_waitcnt lgkmcnt(0)
	v_add_f32_e32 v68, v68, v69
	ds_bpermute_b32 v69, v71, v68
	s_waitcnt lgkmcnt(0)
	v_add_f32_e32 v68, v68, v69
	ds_bpermute_b32 v69, v72, v68
	s_waitcnt lgkmcnt(0)
	v_add_f32_e32 v68, v68, v69
	ds_bpermute_b32 v69, v73, v68
	s_waitcnt lgkmcnt(0)
	v_add_f32_e32 v68, v68, v69
	ds_bpermute_b32 v69, v74, v68
	s_waitcnt lgkmcnt(0)
	v_add_f32_e32 v68, v68, v69
	ds_bpermute_b32 v69, v75, v68
	s_waitcnt lgkmcnt(0)
	v_add_f32_e32 v83, v68, v69
	v_fmamk_f32 v69, v83, 0xbb800000, v85
	v_fmamk_f32 v68, v83, 0xbb800000, v84
	v_fmamk_f32 v87, v83, 0xbb800000, v87
	v_fmac_f32_e32 v86, 0xbb800000, v83
	v_mul_f32_e32 v96, v68, v68
	v_mul_f32_e32 v97, v69, v69
	v_mul_f32_e32 v84, v86, v86
	v_mul_f32_e32 v85, v87, v87
	v_add_f32_e32 v83, v96, v97
	v_add_f32_e32 v83, v84, v83
	v_add_f32_e32 v83, v85, v83
	ds_bpermute_b32 v84, v70, v83
	s_waitcnt lgkmcnt(0)
	v_add_f32_e32 v83, v83, v84
	ds_bpermute_b32 v84, v71, v83
	s_waitcnt lgkmcnt(0)
	v_add_f32_e32 v83, v83, v84
	ds_bpermute_b32 v84, v72, v83
	s_waitcnt lgkmcnt(0)
	v_add_f32_e32 v83, v83, v84
	ds_bpermute_b32 v84, v73, v83
	s_waitcnt lgkmcnt(0)
	v_add_f32_e32 v83, v83, v84
	ds_bpermute_b32 v84, v74, v83
	s_waitcnt lgkmcnt(0)
	v_add_f32_e32 v83, v83, v84
	ds_bpermute_b32 v84, v75, v83
	s_waitcnt lgkmcnt(0)
	v_add_f32_e32 v83, v83, v84
	v_fmamk_f32 v83, v83, 0x3b800000, v82
	v_mul_f32_e32 v84, 0x4b800000, v83
	v_cmp_gt_f32_e64 s[0:1], s8, v83
	s_nop 1
	v_cndmask_b32_e64 v83, v83, v84, s[0:1]
	v_rsq_f32_e32 v83, v83
	s_nop 0
	v_mul_f32_e32 v84, 0x45800000, v83
	v_cndmask_b32_e64 v84, v83, v84, s[0:1]
	v_mul_f32_e32 v68, v68, v84
	v_mul_f32_e32 v69, v69, v84
	v_mul_f32_e32 v85, v87, v84
	v_mul_f32_e32 v84, v86, v84
	s_waitcnt vmcnt(0)
	v_fma_f32 v68, v88, v68, v92
	v_fma_f32 v69, v89, v69, v93
	v_fma_f32 v84, v90, v84, v94
	v_fma_f32 v85, v91, v85, v95
	v_mul_f32_e32 v83, 0xbfb8aa3b, v68
	v_mul_f32_e32 v86, 0xbfb8aa3b, v69
	v_mul_f32_e32 v87, 0xbfb8aa3b, v84
	v_mul_f32_e32 v88, 0xbfb8aa3b, v85
	v_exp_f32_e32 v83, v83
	v_exp_f32_e32 v86, v86
	v_exp_f32_e32 v87, v87
	v_exp_f32_e32 v88, v88
	v_add_f32_e32 v83, 1.0, v83
	v_add_f32_e32 v89, 1.0, v86
	v_add_f32_e32 v90, 1.0, v87
	v_add_f32_e32 v91, 1.0, v88
	v_rcp_f32_e32 v86, v83
	v_rcp_f32_e32 v87, v89
	v_rcp_f32_e32 v88, v90
	v_rcp_f32_e32 v89, v91
	v_mul_f32_e32 v68, v68, v86
	v_mul_f32_e32 v69, v69, v87
	s_nop 0
	v_cvt_pk_bf16_f32 v68, v68, v69
	v_mul_f32_e32 v84, v84, v88
	v_mul_f32_e32 v85, v85, v89
	s_nop 0
	v_cvt_pk_bf16_f32 v69, v84, v85
	global_store_dwordx2 v[2:3], v[68:69], off offset:1536
	s_andn2_b64 exec, exec, s[4:5]
	s_cbranch_execnz .LBB0_1550
	s_or_b64 exec, exec, s[4:5]
	s_add_i32 s11, s11, s10
	s_cmpk_gt_i32 s11, 0x1ff
	s_cbranch_scc0 .LBB0_1545

.LBB0_1609:
	s_or_b64 exec, exec, s[28:29]
	v_ashrrev_i32_e32 v35, 31, v34
	v_lshlrev_b64 v[34:35], 12, v[34:35]
	v_lshl_add_u64 v[34:35], v[36:37], 0, v[34:35]
	v_lshl_add_u64 v[36:37], s[94:95], 0, v[38:39]
	v_lshl_add_u64 v[38:39], v[36:37], 0, s[26:27]
	v_lshl_add_u64 v[46:47], v[34:35], 0, v[72:73]
	v_lshl_add_u64 v[34:35], v[38:39], 0, v[72:73]
	global_load_dwordx4 v[34:37], v[34:35], off
	s_nop 0
	global_load_dwordx4 v[76:79], v[46:47], off
	v_ashrrev_i32_e32 v33, 31, v32
	v_lshlrev_b64 v[32:33], 12, v[32:33]
	v_lshl_add_u64 v[32:33], v[42:43], 0, v[32:33]
	v_lshl_add_u64 v[50:51], v[32:33], 0, v[72:73]
	v_lshl_add_u64 v[42:43], v[74:75], 2, v[38:39]
	s_add_i32 s36, s36, s30
	s_cmpk_lt_i32 s36, 0x400
	s_waitcnt vmcnt(0)
	v_fma_f32 v30, v30, v36, v78
	v_fma_f32 v31, v31, v37, v79
	v_fma_f32 v28, v28, v34, v76
	v_fma_f32 v29, v29, v35, v77
	global_store_dwordx4 v[50:51], v[28:31], off
	global_load_dwordx4 v[28:31], v[46:47], off offset:16
	s_nop 0
	global_load_dwordx4 v[32:35], v[42:43], off
	v_lshl_add_u64 v[36:37], v[60:61], 2, v[38:39]
	s_waitcnt vmcnt(0)
	v_fma_f32 v26, v26, v34, v30
	v_fma_f32 v27, v27, v35, v31
	v_fma_f32 v24, v24, v32, v28
	v_fma_f32 v25, v25, v33, v29
	global_store_dwordx4 v[50:51], v[24:27], off offset:16
	global_load_dwordx4 v[24:27], v[46:47], off offset:128
	s_nop 0
	global_load_dwordx4 v[28:31], v[36:37], off
	v_lshl_add_u64 v[32:33], v[56:57], 2, v[38:39]
	s_waitcnt vmcnt(0)
	v_fma_f32 v22, v22, v30, v26
	v_fma_f32 v23, v23, v31, v27
	v_fma_f32 v20, v20, v28, v24
	v_fma_f32 v21, v21, v29, v25
	global_store_dwordx4 v[50:51], v[20:23], off offset:128
	global_load_dwordx4 v[20:23], v[46:47], off offset:144
	s_nop 0
	global_load_dwordx4 v[24:27], v[32:33], off
	v_lshl_add_u64 v[28:29], v[52:53], 2, v[38:39]
	s_waitcnt vmcnt(0)
	v_fma_f32 v18, v18, v26, v22
	v_fma_f32 v19, v19, v27, v23
	v_fma_f32 v16, v16, v24, v20
	v_fma_f32 v17, v17, v25, v21
	global_store_dwordx4 v[50:51], v[16:19], off offset:144
	global_load_dwordx4 v[16:19], v[46:47], off offset:256
	s_nop 0
	global_load_dwordx4 v[20:23], v[28:29], off
	v_lshl_add_u64 v[24:25], v[48:49], 2, v[38:39]
	s_waitcnt vmcnt(0)
	v_fma_f32 v14, v14, v22, v18
	v_fma_f32 v15, v15, v23, v19
	v_fma_f32 v12, v12, v20, v16
	v_fma_f32 v13, v13, v21, v17
	global_store_dwordx4 v[50:51], v[12:15], off offset:256
	global_load_dwordx4 v[12:15], v[46:47], off offset:272
	s_nop 0
	global_load_dwordx4 v[16:19], v[24:25], off
	v_lshl_add_u64 v[20:21], v[44:45], 2, v[38:39]
	s_waitcnt vmcnt(0)
	v_fma_f32 v10, v10, v18, v14
	v_fma_f32 v11, v11, v19, v15
	v_fma_f32 v8, v8, v16, v12
	v_fma_f32 v9, v9, v17, v13
	global_store_dwordx4 v[50:51], v[8:11], off offset:272
	global_load_dwordx4 v[8:11], v[46:47], off offset:384
	s_nop 0
	global_load_dwordx4 v[12:15], v[20:21], off
	v_lshl_add_u64 v[16:17], v[40:41], 2, v[38:39]
	s_waitcnt vmcnt(0)
	v_fma_f32 v6, v6, v14, v10
	v_fma_f32 v7, v7, v15, v11
	v_fma_f32 v4, v4, v12, v8
	v_fma_f32 v5, v5, v13, v9
	global_store_dwordx4 v[50:51], v[4:7], off offset:384
	global_load_dwordx4 v[4:7], v[46:47], off offset:400
	s_nop 0
	global_load_dwordx4 v[8:11], v[16:17], off
	s_waitcnt vmcnt(0)
	v_fma_f32 v2, v2, v10, v6
	v_fma_f32 v3, v3, v11, v7
	v_fma_f32 v0, v0, v8, v4
	v_fma_f32 v1, v1, v9, v5
	global_store_dwordx4 v[50:51], v[0:3], off offset:400
	s_cbranch_scc0 .LBB0_1632

.LBB0_1624:
	s_or_b64 exec, exec, s[28:29]
	v_ashrrev_i32_e32 v73, 31, v72
	v_lshlrev_b64 v[72:73], 12, v[72:73]
	v_lshl_or_b32 v106, s37, 7, v88
	v_lshl_add_u64 v[76:77], v[76:77], 0, v[72:73]
	v_lshl_add_u64 v[72:73], s[94:95], 0, v[78:79]
	v_ashrrev_i32_e32 v107, 31, v106
	v_lshl_add_u64 v[104:105], v[72:73], 0, s[26:27]
	v_lshlrev_b64 v[72:73], 2, v[106:107]
	v_lshl_add_u64 v[108:109], v[76:77], 0, v[72:73]
	v_lshl_add_u64 v[100:101], v[104:105], 0, v[72:73]
	global_load_dwordx4 v[76:79], v[108:109], off
	v_ashrrev_i32_e32 v75, 31, v74
	global_load_dwordx4 v[100:103], v[100:101], off
	v_lshlrev_b64 v[110:111], 12, v[74:75]
	v_lshl_add_u64 v[80:81], v[80:81], 0, v[110:111]
	v_or_b32_e32 v74, 4, v106
	v_lshl_add_u64 v[80:81], v[80:81], 0, v[72:73]
	v_ashrrev_i32_e32 v75, 31, v74
	v_lshl_add_u64 v[110:111], v[74:75], 2, v[104:105]
	s_waitcnt vmcnt(0)
	v_fma_f32 v62, v62, v102, v78
	v_fma_f32 v63, v63, v103, v79
	v_fma_f32 v60, v60, v100, v76
	v_fma_f32 v61, v61, v101, v77
	global_store_dwordx4 v[80:81], v[60:63], off
	global_load_dwordx4 v[76:79], v[108:109], off offset:16
	global_load_dwordx4 v[100:103], v[110:111], off
	v_or_b32_e32 v60, 32, v106
	v_ashrrev_i32_e32 v61, 31, v60
	v_lshl_add_u64 v[62:63], v[60:61], 2, v[104:105]
	s_waitcnt vmcnt(0)
	v_fma_f32 v58, v58, v102, v78
	v_fma_f32 v59, v59, v103, v79
	v_fma_f32 v56, v56, v100, v76
	v_fma_f32 v57, v57, v101, v77
	global_store_dwordx4 v[80:81], v[56:59], off offset:16
	global_load_dwordx4 v[76:79], v[108:109], off offset:128
	global_load_dwordx4 v[100:103], v[62:63], off
	v_or_b32_e32 v56, 36, v106
	v_ashrrev_i32_e32 v57, 31, v56
	v_lshl_add_u64 v[58:59], v[56:57], 2, v[104:105]
	s_waitcnt vmcnt(0)
	v_fma_f32 v54, v54, v102, v78
	v_fma_f32 v55, v55, v103, v79
	v_fma_f32 v52, v52, v100, v76
	v_fma_f32 v53, v53, v101, v77
	global_store_dwordx4 v[80:81], v[52:55], off offset:128
	global_load_dwordx4 v[76:79], v[108:109], off offset:144
	global_load_dwordx4 v[100:103], v[58:59], off
	v_or_b32_e32 v52, 64, v106
	v_ashrrev_i32_e32 v53, 31, v52
	v_lshl_add_u64 v[54:55], v[52:53], 2, v[104:105]
	s_waitcnt vmcnt(0)
	v_fma_f32 v50, v50, v102, v78
	v_fma_f32 v51, v51, v103, v79
	v_fma_f32 v48, v48, v100, v76
	v_fma_f32 v49, v49, v101, v77
	global_store_dwordx4 v[80:81], v[48:51], off offset:144
	global_load_dwordx4 v[76:79], v[108:109], off offset:256
	global_load_dwordx4 v[100:103], v[54:55], off
	v_or_b32_e32 v48, 0x44, v106
	v_ashrrev_i32_e32 v49, 31, v48
	v_lshl_add_u64 v[50:51], v[48:49], 2, v[104:105]
	s_waitcnt vmcnt(0)
	v_fma_f32 v46, v46, v102, v78
	v_fma_f32 v47, v47, v103, v79
	v_fma_f32 v44, v44, v100, v76
	v_fma_f32 v45, v45, v101, v77
	global_store_dwordx4 v[80:81], v[44:47], off offset:256
	global_load_dwordx4 v[76:79], v[108:109], off offset:272
	global_load_dwordx4 v[100:103], v[50:51], off
	v_or_b32_e32 v44, 0x60, v106
	v_ashrrev_i32_e32 v45, 31, v44
	v_lshl_add_u64 v[46:47], v[44:45], 2, v[104:105]
	s_waitcnt vmcnt(0)
	v_fma_f32 v42, v42, v102, v78
	v_fma_f32 v43, v43, v103, v79
	v_fma_f32 v40, v40, v100, v76
	v_fma_f32 v41, v41, v101, v77
	global_store_dwordx4 v[80:81], v[40:43], off offset:272
	global_load_dwordx4 v[76:79], v[108:109], off offset:384
	global_load_dwordx4 v[100:103], v[46:47], off
	v_or_b32_e32 v40, 0x64, v106
	v_ashrrev_i32_e32 v41, 31, v40
	v_lshl_add_u64 v[42:43], v[40:41], 2, v[104:105]
	s_waitcnt vmcnt(0)
	v_fma_f32 v38, v38, v102, v78
	v_fma_f32 v39, v39, v103, v79
	v_fma_f32 v36, v36, v100, v76
	v_fma_f32 v37, v37, v101, v77
	global_store_dwordx4 v[80:81], v[36:39], off offset:384
	global_load_dwordx4 v[76:79], v[108:109], off offset:400
	global_load_dwordx4 v[100:103], v[42:43], off
	v_add_u32_e32 v36, s38, v89
	v_mul_hi_i32 v37, v36, s31
	v_lshrrev_b32_e32 v38, 31, v37
	v_ashrrev_i32_e32 v37, 11, v37
	v_add_u32_e32 v42, v37, v38
	v_mad_i32_i24 v38, v42, s33, v36
	v_lshlrev_b32_e32 v36, 13, v42
	v_cmp_lt_i32_e32 vcc, s34, v38
	s_waitcnt vmcnt(0)
	v_fma_f32 v34, v34, v102, v78
	v_fma_f32 v35, v35, v103, v79
	v_fma_f32 v32, v32, v100, v76
	v_fma_f32 v33, v33, v101, v77
	global_store_dwordx4 v[80:81], v[32:35], off offset:400
	s_nop 1
	v_add3_u32 v32, v36, v38, s35
	s_and_saveexec_b64 s[28:29], vcc
	s_xor_b64 s[28:29], exec, s[28:29]
	v_add3_u32 v34, v36, v38, s35
	s_or_saveexec_b64 s[28:29], s[28:29]
	v_mov_b64_e32 v[36:37], s[92:93]
	v_lshl_add_u32 v33, v42, 8, v38
	s_xor_b64 exec, exec, s[28:29]
	v_lshl_add_u32 v34, v42, 8, v38
	v_mov_b64_e32 v[36:37], s[2:3]
	s_or_b64 exec, exec, s[28:29]
	s_and_saveexec_b64 s[28:29], vcc
	s_xor_b64 s[28:29], exec, s[28:29]
	s_cbranch_execz .LBB0_1630
	v_add_u32_e32 v33, 3, v42
	v_mul_hi_i32_i24_e32 v39, 0x6000, v33
	v_mul_i32_i24_e32 v38, 0x6000, v33
	s_or_saveexec_b64 s[28:29], s[28:29]
	v_mov_b64_e32 v[42:43], s[92:93]
	s_xor_b64 exec, exec, s[28:29]
	s_cbranch_execz .LBB0_1609
	s_branch .LBB0_1631

.LBB0_1689:
	s_or_b64 exec, exec, s[14:15]
	v_ashrrev_i32_e32 v1, 31, v0
	v_lshlrev_b64 v[0:1], 12, v[0:1]
	v_lshl_add_u64 v[0:1], v[2:3], 0, v[0:1]
	v_lshl_add_u64 v[48:49], v[0:1], 0, v[8:9]
	global_load_dwordx4 v[40:43], v[48:49], off
	global_load_dwordx4 v[44:47], v[48:49], off offset:1024
	global_load_dwordx4 v[4:7], v[48:49], off offset:2048
	global_load_dwordx4 v[0:3], v[48:49], off offset:3072
	v_lshl_add_u64 v[28:29], s[94:95], 0, v[28:29]
	v_mov_b32_e32 v21, v9
	v_lshl_add_u64 v[60:61], v[28:29], 0, s[10:11]
	v_lshl_add_u64 v[56:57], v[60:61], 0, v[20:21]
	v_lshl_add_u64 v[28:29], v[28:29], 0, s[2:3]
	global_load_dwordx4 v[48:51], v[56:57], off
	global_load_dwordx4 v[52:55], v[12:13], off
	v_lshl_add_u64 v[56:57], v[28:29], 0, v[20:21]
	global_load_dwordx4 v[56:59], v[56:57], off
	v_cmp_lt_i32_e32 vcc, v34, v33
	v_mov_b32_e32 v27, v9
	s_waitcnt vmcnt(6)
	v_mov_b32_e32 v64, v41
	s_waitcnt vmcnt(5)
	v_mov_b32_e32 v65, v45
	v_mov_b32_e32 v62, v40
	v_mov_b32_e32 v63, v44
	s_waitcnt vmcnt(4)
	v_mov_b32_e32 v72, v5
	s_waitcnt vmcnt(3)
	v_mov_b32_e32 v73, v1
	v_mul_f32_e32 v64, v64, v64
	v_mul_f32_e32 v65, v65, v65
	v_mov_b32_e32 v66, v42
	v_mov_b32_e32 v67, v46
	v_mov_b32_e32 v70, v4
	v_mov_b32_e32 v71, v0
	v_mul_f32_e32 v72, v72, v72
	v_mul_f32_e32 v73, v73, v73
	v_fma_f32 v62, v62, v62, v64
	v_fma_f32 v63, v63, v63, v65
	v_mov_b32_e32 v68, v43
	v_mov_b32_e32 v69, v47
	v_mov_b32_e32 v74, v6
	v_mov_b32_e32 v75, v2
	v_fma_f32 v64, v70, v70, v72
	v_fma_f32 v65, v71, v71, v73
	v_fma_f32 v62, v66, v66, v62
	v_fma_f32 v63, v67, v67, v63
	v_mov_b32_e32 v76, v7
	v_mov_b32_e32 v77, v3
	v_fma_f32 v64, v74, v74, v64
	v_fma_f32 v65, v75, v75, v65
	v_fma_f32 v62, v68, v68, v62
	v_fma_f32 v63, v69, v69, v63
	v_fma_f32 v64, v76, v76, v64
	v_fma_f32 v65, v77, v77, v65
	v_add_f32_e32 v23, v62, v63
	v_cndmask_b32_e32 v21, v32, v34, vcc
	v_add_f32_e32 v23, v23, v64
	v_lshlrev_b32_e32 v21, 2, v21
	v_add_f32_e32 v23, v23, v65
	ds_bpermute_b32 v21, v21, v23
	v_cmp_lt_i32_e32 vcc, v35, v33
	s_waitcnt vmcnt(2)
	v_pk_add_f32 v[48:49], v[48:49], 1.0 op_sel_hi:[1,0]
	v_pk_add_f32 v[50:51], v[50:51], 1.0 op_sel_hi:[1,0]
	v_cndmask_b32_e32 v25, v32, v35, vcc
	v_lshlrev_b32_e32 v25, 2, v25
	s_waitcnt lgkmcnt(0)
	v_add_f32_e32 v21, v23, v21
	ds_bpermute_b32 v23, v25, v21
	v_cmp_lt_i32_e32 vcc, v36, v33
	v_mad_i64_i32 v[62:63], s[14:15], v30, s22, v[10:11]
	s_nop 0
	v_cndmask_b32_e32 v25, v32, v36, vcc
	v_lshlrev_b32_e32 v25, 2, v25
	s_waitcnt lgkmcnt(0)
	v_add_f32_e32 v21, v21, v23
	ds_bpermute_b32 v23, v25, v21
	v_cmp_lt_i32_e32 vcc, v37, v33
	s_waitcnt lgkmcnt(0)
	v_add_f32_e32 v21, v21, v23
	v_cndmask_b32_e32 v25, v32, v37, vcc
	v_lshlrev_b32_e32 v25, 2, v25
	ds_bpermute_b32 v23, v25, v21
	v_cmp_lt_i32_e32 vcc, v38, v33
	s_waitcnt lgkmcnt(0)
	v_add_f32_e32 v21, v21, v23
	v_cndmask_b32_e32 v25, v32, v38, vcc
	v_lshlrev_b32_e32 v25, 2, v25
	ds_bpermute_b32 v23, v25, v21
	v_cmp_lt_i32_e32 vcc, v39, v33
	s_waitcnt lgkmcnt(0)
	v_add_f32_e32 v21, v21, v23
	v_cndmask_b32_e32 v25, v32, v39, vcc
	v_lshlrev_b32_e32 v25, 2, v25
	ds_bpermute_b32 v25, v25, v21
	v_mov_b32_e32 v23, v9
	v_lshl_add_u64 v[64:65], v[60:61], 0, v[22:23]
	s_waitcnt lgkmcnt(0)
	v_add_f32_e32 v21, v21, v25
	v_fmamk_f32 v21, v21, 0x3a800000, v31
	v_mul_f32_e32 v25, 0x4b800000, v21
	v_cmp_gt_f32_e32 vcc, s21, v21
	s_nop 1
	v_cndmask_b32_e32 v21, v21, v25, vcc
	v_rsq_f32_e32 v21, v21
	s_nop 0
	v_mul_f32_e32 v25, 0x45800000, v21
	v_cndmask_b32_e32 v66, v21, v25, vcc
	v_mul_f32_e32 v40, v40, v66
	v_mul_f32_e32 v41, v41, v66
	v_mul_f32_e32 v42, v42, v66
	v_mul_f32_e32 v43, v43, v66
	s_waitcnt vmcnt(1)
	v_mul_f32_e32 v40, v52, v40
	v_mul_f32_e32 v41, v53, v41
	v_mul_f32_e32 v42, v54, v42
	v_mul_f32_e32 v43, v55, v43
	s_waitcnt vmcnt(0)
	v_fma_f32 v40, v48, v40, v56
	v_fma_f32 v41, v49, v41, v57
	v_fma_f32 v42, v50, v42, v58
	v_fma_f32 v43, v51, v43, v59
	v_cvt_pk_bf16_f32 v40, v40, v41
	v_cvt_pk_bf16_f32 v41, v42, v43
	global_store_dwordx2 v[62:63], v[40:41], off
	global_load_dwordx4 v[40:43], v[14:15], off
	s_nop 0
	global_load_dwordx4 v[48:51], v[64:65], off
	v_lshl_add_u64 v[52:53], v[28:29], 0, v[22:23]
	global_load_dwordx4 v[52:55], v[52:53], off
	v_mul_f32_e32 v44, v44, v66
	v_mul_f32_e32 v45, v45, v66
	v_mul_f32_e32 v46, v46, v66
	v_mul_f32_e32 v47, v47, v66
	v_mov_b32_e32 v25, v9
	v_lshl_add_u64 v[56:57], v[60:61], 0, v[24:25]
	v_mul_f32_e32 v4, v4, v66
	v_mul_f32_e32 v5, v5, v66
	v_mul_f32_e32 v6, v6, v66
	v_mul_f32_e32 v7, v7, v66
	v_mul_f32_e32 v0, v0, v66
	v_mul_f32_e32 v1, v1, v66
	v_mul_f32_e32 v2, v2, v66
	v_mul_f32_e32 v3, v3, v66
	s_waitcnt vmcnt(2)
	v_mul_f32_e32 v40, v40, v44
	v_mul_f32_e32 v41, v41, v45
	s_waitcnt vmcnt(1)
	v_pk_add_f32 v[44:45], v[48:49], 1.0 op_sel_hi:[1,0]
	v_mul_f32_e32 v42, v42, v46
	v_mul_f32_e32 v43, v43, v47
	v_pk_add_f32 v[46:47], v[50:51], 1.0 op_sel_hi:[1,0]
	s_waitcnt vmcnt(0)
	v_fma_f32 v40, v44, v40, v52
	v_fma_f32 v41, v45, v41, v53
	v_fma_f32 v42, v46, v42, v54
	v_fma_f32 v43, v47, v43, v55
	v_cvt_pk_bf16_f32 v40, v40, v41
	v_cvt_pk_bf16_f32 v41, v42, v43
	global_store_dwordx2 v[62:63], v[40:41], off offset:512
	global_load_dwordx4 v[40:43], v[16:17], off
	s_nop 0
	global_load_dwordx4 v[44:47], v[56:57], off
	v_lshl_add_u64 v[48:49], v[28:29], 0, v[24:25]
	global_load_dwordx4 v[48:51], v[48:49], off
	v_lshl_add_u64 v[52:53], v[60:61], 0, v[26:27]
	v_lshl_add_u64 v[28:29], v[28:29], 0, v[26:27]
	s_waitcnt vmcnt(2)
	v_mul_f32_e32 v4, v40, v4
	v_mul_f32_e32 v5, v41, v5
	s_waitcnt vmcnt(1)
	v_pk_add_f32 v[40:41], v[44:45], 1.0 op_sel_hi:[1,0]
	v_mul_f32_e32 v6, v42, v6
	v_mul_f32_e32 v7, v43, v7
	v_pk_add_f32 v[42:43], v[46:47], 1.0 op_sel_hi:[1,0]
	s_waitcnt vmcnt(0)
	v_fma_f32 v4, v4, v40, v48
	v_fma_f32 v5, v5, v41, v49
	v_fma_f32 v6, v6, v42, v50
	v_fma_f32 v7, v7, v43, v51
	v_cvt_pk_bf16_f32 v4, v4, v5
	v_cvt_pk_bf16_f32 v5, v6, v7
	global_store_dwordx2 v[62:63], v[4:5], off offset:1024
	global_load_dwordx4 v[4:7], v[18:19], off
	s_nop 0
	global_load_dwordx4 v[40:43], v[52:53], off
	global_load_dwordx4 v[44:47], v[28:29], off
	s_waitcnt vmcnt(2)
	v_mul_f32_e32 v0, v0, v4
	v_mul_f32_e32 v1, v1, v5
	s_waitcnt vmcnt(1)
	v_pk_add_f32 v[4:5], v[40:41], 1.0 op_sel_hi:[1,0]
	v_mul_f32_e32 v2, v2, v6
	v_mul_f32_e32 v3, v3, v7
	v_pk_add_f32 v[6:7], v[42:43], 1.0 op_sel_hi:[1,0]
	s_waitcnt vmcnt(0)
	v_fma_f32 v0, v0, v4, v44
	v_fma_f32 v1, v1, v5, v45
	v_fma_f32 v2, v2, v6, v46
	v_fma_f32 v3, v3, v7, v47
	v_cvt_pk_bf16_f32 v0, v0, v1
	v_cvt_pk_bf16_f32 v1, v2, v3
	global_store_dwordx2 v[62:63], v[0:1], off offset:1536

.LBB0_1759:
	s_add_i32 s36, s34, 0x8000
	s_and_b32 s35, s36, 0x8000
	s_add_i32 s35, s35, 0
	s_add_u32 s86, s35, s87
	s_mov_b32 m0, s86
	s_waitcnt vmcnt(0) lgkmcnt(0)
	s_barrier
	global_load_lds_dwordx4 v244, s[96:97]
	s_add_u32 m0, s86, 0x4000
	s_nop 0
	global_load_lds_dwordx4 v245, s[88:89]
	s_add_u32 m0, s86, 0x1000
	s_nop 0
	global_load_lds_dwordx4 v246, s[96:97]
	s_add_u32 m0, s86, 0x5000
	s_nop 0
	global_load_lds_dwordx4 v247, s[88:89]
	s_add_u32 m0, s86, 0x2000
	s_nop 0
	global_load_lds_dwordx4 v248, s[96:97]
	s_add_u32 m0, s86, 0x6000
	s_nop 0
	global_load_lds_dwordx4 v249, s[88:89]
	s_add_u32 m0, s86, 0x3000
	s_nop 0
	global_load_lds_dwordx4 v250, s[96:97]
	s_add_u32 m0, s86, 0x7000
	s_nop 0
	global_load_lds_dwordx4 v251, s[88:89]
	s_add_u32 s96, s96, 0x80
	s_addc_u32 s97, s97, 0
	s_add_u32 s88, s88, 0x80
	s_addc_u32 s89, s89, 0
	s_and_b32 s34, s34, 0x8000
	s_add_i32 s34, s34, 0
	v_add3_u32 v143, s34, v80, v81
	v_add3_u32 v145, s34, v81, v82
	v_add3_u32 v206, s34, v80, v83
	v_add3_u32 v207, s34, v82, v83
	ds_read_b128 v[102:105], v145
	ds_read_b128 v[94:97], v143 offset:16384
	ds_read_b128 v[98:101], v143 offset:18432
	ds_read_b128 v[106:109], v145 offset:2048
	ds_read_b128 v[110:113], v143 offset:20480
	ds_read_b128 v[114:117], v143 offset:22528
	ds_read_b128 v[118:121], v143 offset:24576
	ds_read_b128 v[122:125], v143 offset:26624
	ds_read_b128 v[126:129], v143 offset:28672
	ds_read_b128 v[130:133], v143 offset:30720
	ds_read_b128 v[174:177], v207
	ds_read_b128 v[166:169], v206 offset:16384
	ds_read_b128 v[170:173], v206 offset:18432
	ds_read_b128 v[178:181], v207 offset:2048
	ds_read_b128 v[182:185], v206 offset:20480
	ds_read_b128 v[186:189], v206 offset:22528
	ds_read_b128 v[190:193], v206 offset:24576
	ds_read_b128 v[194:197], v206 offset:26624
	ds_read_b128 v[198:201], v206 offset:28672
	ds_read_b128 v[202:205], v206 offset:30720
	s_add_u32 s26, s26, 0x80
	s_addc_u32 s27, s27, 0
	s_cmpk_eq_i32 s26, 0x780
	s_mov_b32 s34, s36
	s_waitcnt lgkmcnt(15)
	v_mfma_f32_16x16x32_bf16 v[60:63], v[94:97], v[102:105], v[60:63]
	v_mfma_f32_16x16x32_bf16 v[56:59], v[98:101], v[102:105], v[56:59]
	v_mfma_f32_16x16x32_bf16 v[28:31], v[94:97], v[106:109], v[28:31]
	v_mfma_f32_16x16x32_bf16 v[24:27], v[98:101], v[106:109], v[24:27]
	v_mfma_f32_16x16x32_bf16 v[52:55], v[110:113], v[102:105], v[52:55]
	v_mfma_f32_16x16x32_bf16 v[20:23], v[110:113], v[106:109], v[20:23]
	s_waitcnt lgkmcnt(14)
	v_mfma_f32_16x16x32_bf16 v[48:51], v[114:117], v[102:105], v[48:51]
	v_mfma_f32_16x16x32_bf16 v[12:15], v[114:117], v[106:109], v[12:15]
	s_waitcnt lgkmcnt(13)
	v_mfma_f32_16x16x32_bf16 v[44:47], v[118:121], v[102:105], v[44:47]
	v_mfma_f32_16x16x32_bf16 v[8:11], v[118:121], v[106:109], v[8:11]
	s_waitcnt lgkmcnt(12)
	v_mfma_f32_16x16x32_bf16 v[40:43], v[122:125], v[102:105], v[40:43]
	v_mfma_f32_16x16x32_bf16 v[4:7], v[122:125], v[106:109], v[4:7]
	s_waitcnt lgkmcnt(11)
	v_mfma_f32_16x16x32_bf16 v[36:39], v[126:129], v[102:105], v[36:39]
	v_mfma_f32_16x16x32_bf16 v[0:3], v[126:129], v[106:109], v[0:3]
	s_waitcnt lgkmcnt(10)
	v_mfma_f32_16x16x32_bf16 v[32:35], v[130:133], v[102:105], v[32:35]
	v_mfma_f32_16x16x32_bf16 v[16:19], v[130:133], v[106:109], v[16:19]
	s_waitcnt lgkmcnt(8)
	v_mfma_f32_16x16x32_bf16 v[60:63], v[166:169], v[174:177], v[60:63]
	s_waitcnt lgkmcnt(7)
	v_mfma_f32_16x16x32_bf16 v[56:59], v[170:173], v[174:177], v[56:59]
	s_waitcnt lgkmcnt(6)
	v_mfma_f32_16x16x32_bf16 v[28:31], v[166:169], v[178:181], v[28:31]
	v_mfma_f32_16x16x32_bf16 v[24:27], v[170:173], v[178:181], v[24:27]
	s_waitcnt lgkmcnt(5)
	v_mfma_f32_16x16x32_bf16 v[52:55], v[182:185], v[174:177], v[52:55]
	v_mfma_f32_16x16x32_bf16 v[20:23], v[182:185], v[178:181], v[20:23]
	s_waitcnt lgkmcnt(4)
	v_mfma_f32_16x16x32_bf16 v[48:51], v[186:189], v[174:177], v[48:51]
	v_mfma_f32_16x16x32_bf16 v[12:15], v[186:189], v[178:181], v[12:15]
	s_waitcnt lgkmcnt(3)
	v_mfma_f32_16x16x32_bf16 v[44:47], v[190:193], v[174:177], v[44:47]
	v_mfma_f32_16x16x32_bf16 v[8:11], v[190:193], v[178:181], v[8:11]
	s_waitcnt lgkmcnt(2)
	v_mfma_f32_16x16x32_bf16 v[40:43], v[194:197], v[174:177], v[40:43]
	v_mfma_f32_16x16x32_bf16 v[4:7], v[194:197], v[178:181], v[4:7]
	s_waitcnt lgkmcnt(1)
	v_mfma_f32_16x16x32_bf16 v[36:39], v[198:201], v[174:177], v[36:39]
	v_mfma_f32_16x16x32_bf16 v[0:3], v[198:201], v[178:181], v[0:3]
	s_waitcnt lgkmcnt(0)
	v_mfma_f32_16x16x32_bf16 v[32:35], v[202:205], v[174:177], v[32:35]
	v_mfma_f32_16x16x32_bf16 v[16:19], v[202:205], v[178:181], v[16:19]
	s_cbranch_scc0 .LBB0_1759
	v_add_u32_e32 v138, s35, v80
	v_add_u32_e32 v126, v138, v81
	s_waitcnt vmcnt(0)
	s_barrier
	ds_read_b128 v[74:77], v126 offset:16384
	v_add3_u32 v102, s35, v81, v82
	ds_read_b128 v[94:97], v102
	ds_read_b128 v[98:101], v126 offset:18432
	ds_read_b128 v[102:105], v102 offset:2048
	ds_read_b128 v[106:109], v126 offset:20480
	ds_read_b128 v[110:113], v126 offset:22528
	ds_read_b128 v[114:117], v126 offset:24576
	ds_read_b128 v[118:121], v126 offset:26624
	v_add3_u32 v134, s35, v83, v82
	v_add_u32_e32 v142, v138, v83
	ds_read_b128 v[122:125], v126 offset:28672
	ds_read_b128 v[126:129], v126 offset:30720
	ds_read_b128 v[130:133], v134
	ds_read_b128 v[134:137], v134 offset:2048
	ds_read_b128 v[138:141], v142 offset:16384
	ds_read_b128 v[146:149], v142 offset:18432
	s_waitcnt lgkmcnt(11)
	v_mfma_f32_16x16x32_bf16 v[56:59], v[98:101], v[94:97], v[56:59]
	s_lshl_b32 s33, s33, 7
	s_lshl_b32 s26, s31, 7
	s_ashr_i32 s27, s26, 31
	v_mfma_f32_16x16x32_bf16 v[60:63], v[74:77], v[94:97], v[60:63]
	s_lshl_b64 s[26:27], s[26:27], 1
	s_add_i32 s30, s30, s28
	s_cmpk_gt_i32 s30, 0xfff
	s_waitcnt lgkmcnt(0)
	v_mfma_f32_16x16x32_bf16 v[56:59], v[146:149], v[130:133], v[56:59]
	v_mfma_f32_16x16x32_bf16 v[48:51], v[110:113], v[94:97], v[48:51]
	v_mfma_f32_16x16x32_bf16 v[52:55], v[106:109], v[94:97], v[52:55]
	s_nop 5
	v_max_f32_e32 v56, v56, v56
	v_max_f32_e32 v57, v57, v57
	v_max_f32_e32 v56, 0, v56
	v_mfma_f32_16x16x32_bf16 v[44:47], v[114:117], v[94:97], v[44:47]
	v_max_f32_e32 v57, 0, v57
	v_max_f32_e32 v59, v59, v59
	v_max_f32_e32 v59, 0, v59
	v_mfma_f32_16x16x32_bf16 v[40:43], v[118:121], v[94:97], v[40:43]
	v_mfma_f32_16x16x32_bf16 v[36:39], v[122:125], v[94:97], v[36:39]
	v_mfma_f32_16x16x32_bf16 v[32:35], v[126:129], v[94:97], v[32:35]
	ds_read_b128 v[94:97], v142 offset:20480
	ds_read_b128 v[150:153], v142 offset:22528
	ds_read_b128 v[154:157], v142 offset:24576
	ds_read_b128 v[158:161], v142 offset:26624
	v_mfma_f32_16x16x32_bf16 v[60:63], v[138:141], v[130:133], v[60:63]
	s_waitcnt lgkmcnt(2)
	v_mfma_f32_16x16x32_bf16 v[48:51], v[150:153], v[130:133], v[48:51]
	v_mfma_f32_16x16x32_bf16 v[20:23], v[106:109], v[102:105], v[20:23]
	v_mul_f32_e64 v106, v56, v56
	v_mul_f32_e64 v107, v57, v57
	v_max_f32_e32 v57, v58, v58
	s_nop 1
	v_max_f32_e32 v60, v60, v60
	v_mfma_f32_16x16x32_bf16 v[24:27], v[98:101], v[102:105], v[24:27]
	v_add_u32_e32 v100, s33, v79
	v_mov_b64_e32 v[98:99], s[0:1]
	v_max_f32_e32 v61, v61, v61
	v_max_f32_e32 v56, v62, v62
	v_max_f32_e32 v58, 0, v57
	v_max_f32_e32 v57, v63, v63
	v_mad_i64_i32 v[100:101], s[34:35], v100, s29, v[98:99]
	v_max_f32_e32 v60, 0, v60
	v_max_f32_e32 v61, 0, v61
	v_max_f32_e32 v56, 0, v56
	v_max_f32_e32 v57, 0, v57
	v_mfma_f32_16x16x32_bf16 v[52:55], v[94:97], v[130:133], v[52:55]
	v_lshl_add_u64 v[100:101], v[100:101], 0, s[26:27]
	v_mul_f32_e32 v60, v60, v60
	v_mul_f32_e32 v61, v61, v61
	v_mul_f32_e32 v62, v56, v56
	v_mul_f32_e32 v63, v57, v57
	v_mfma_f32_16x16x32_bf16 v[28:31], v[74:77], v[102:105], v[28:31]
	v_max_f32_e32 v48, v48, v48
	v_max_f32_e32 v49, v49, v49
	ds_read_b128 v[74:77], v142 offset:28672
	ds_read_b128 v[162:165], v142 offset:30720
	v_mfma_f32_16x16x32_bf16 v[12:15], v[110:113], v[102:105], v[12:15]
	v_lshl_add_u64 v[100:101], v[100:101], 0, v[64:65]
	v_cvt_pk_bf16_f32 v56, v60, v61
	v_cvt_pk_bf16_f32 v57, v62, v63
	v_mfma_f32_16x16x32_bf16 v[8:11], v[114:117], v[102:105], v[8:11]
	v_max_f32_e32 v48, 0, v48
	v_max_f32_e32 v49, 0, v49
	v_max_f32_e32 v52, v52, v52
	v_mfma_f32_16x16x32_bf16 v[4:7], v[118:121], v[102:105], v[4:7]
	v_max_f32_e32 v53, v53, v53
	v_max_f32_e32 v51, v51, v51
	v_max_f32_e32 v52, 0, v52
	v_mfma_f32_16x16x32_bf16 v[0:3], v[122:125], v[102:105], v[0:3]
	v_max_f32_e32 v53, 0, v53
	v_max_f32_e32 v51, 0, v51
	v_mul_f32_e32 v52, v52, v52
	v_mul_f32_e32 v53, v53, v53
	v_mfma_f32_16x16x32_bf16 v[16:19], v[126:129], v[102:105], v[16:19]
	v_mul_f32_e64 v102, v58, v58
	v_mul_f32_e64 v103, v59, v59
	v_cvt_pk_bf16_f32 v58, v106, v107
	v_cvt_pk_bf16_f32 v59, v102, v103
	s_waitcnt lgkmcnt(2)
	v_mfma_f32_16x16x32_bf16 v[40:43], v[158:161], v[130:133], v[40:43]
	global_store_dwordx4 v[100:101], v[56:59], off
	s_nop 1
	v_mul_f32_e32 v56, v48, v48
	v_mul_f32_e32 v57, v49, v49
	v_max_f32_e32 v49, v50, v50
	v_max_f32_e32 v48, v54, v54
	v_max_f32_e32 v50, 0, v49
	v_max_f32_e32 v49, v55, v55
	v_mfma_f32_16x16x32_bf16 v[44:47], v[154:157], v[130:133], v[44:47]
	v_max_f32_e32 v48, 0, v48
	v_max_f32_e32 v49, 0, v49
	v_mul_f32_e32 v54, v48, v48
	v_mul_f32_e32 v55, v49, v49
	v_mul_f32_e32 v58, v50, v50
	v_mul_f32_e32 v59, v51, v51
	v_max_f32_e32 v40, v40, v40
	v_max_f32_e32 v41, v41, v41
	s_waitcnt lgkmcnt(0)
	v_mfma_f32_16x16x32_bf16 v[32:35], v[162:165], v[130:133], v[32:35]
	v_cvt_pk_bf16_f32 v48, v52, v53
	v_cvt_pk_bf16_f32 v49, v54, v55
	v_cvt_pk_bf16_f32 v50, v56, v57
	v_cvt_pk_bf16_f32 v51, v58, v59
	v_max_f32_e32 v40, 0, v40
	v_max_f32_e32 v41, 0, v41
	global_store_dwordx4 v[100:101], v[48:51], off offset:64
	v_max_f32_e32 v44, v44, v44
	v_max_f32_e32 v45, v45, v45
	v_mul_f32_e32 v48, v40, v40
	v_mul_f32_e32 v49, v41, v41
	v_max_f32_e32 v41, v42, v42
	v_max_f32_e32 v40, v46, v46
	v_max_f32_e32 v42, 0, v41
	v_max_f32_e32 v41, v47, v47
	v_max_f32_e32 v43, v43, v43
	v_mfma_f32_16x16x32_bf16 v[36:39], v[74:77], v[130:133], v[36:39]
	v_max_f32_e32 v44, 0, v44
	v_max_f32_e32 v45, 0, v45
	v_max_f32_e32 v40, 0, v40
	v_max_f32_e32 v41, 0, v41
	v_max_f32_e32 v43, 0, v43
	v_mul_f32_e32 v44, v44, v44
	v_mul_f32_e32 v45, v45, v45
	v_mul_f32_e32 v46, v40, v40
	v_mul_f32_e32 v47, v41, v41
	v_mul_f32_e32 v50, v42, v42
	v_mul_f32_e32 v51, v43, v43
	v_max_f32_e32 v32, v32, v32
	v_max_f32_e32 v33, v33, v33
	v_mfma_f32_16x16x32_bf16 v[24:27], v[146:149], v[134:137], v[24:27]
	v_cvt_pk_bf16_f32 v40, v44, v45
	v_cvt_pk_bf16_f32 v41, v46, v47
	v_cvt_pk_bf16_f32 v42, v48, v49
	v_cvt_pk_bf16_f32 v43, v50, v51
	v_max_f32_e32 v32, 0, v32
	v_max_f32_e32 v33, 0, v33
	global_store_dwordx4 v[100:101], v[40:43], off offset:128
	v_max_f32_e32 v36, v36, v36
	v_max_f32_e32 v37, v37, v37
	v_mul_f32_e32 v40, v32, v32
	v_mul_f32_e32 v41, v33, v33
	v_max_f32_e32 v33, v34, v34
	v_max_f32_e32 v32, v38, v38
	v_max_f32_e32 v34, 0, v33
	v_max_f32_e32 v33, v39, v39
	v_max_f32_e32 v35, v35, v35
	v_mfma_f32_16x16x32_bf16 v[28:31], v[138:141], v[134:137], v[28:31]
	v_max_f32_e32 v36, 0, v36
	v_max_f32_e32 v37, 0, v37
	v_max_f32_e32 v32, 0, v32
	v_max_f32_e32 v33, 0, v33
	v_max_f32_e32 v35, 0, v35
	v_mul_f32_e32 v36, v36, v36
	v_mul_f32_e32 v37, v37, v37
	v_mul_f32_e32 v38, v32, v32
	v_mul_f32_e32 v39, v33, v33
	v_mul_f32_e32 v42, v34, v34
	v_mul_f32_e32 v43, v35, v35
	v_max_f32_e32 v24, v24, v24
	v_max_f32_e32 v25, v25, v25
	v_mfma_f32_16x16x32_bf16 v[12:15], v[150:153], v[134:137], v[12:15]
	v_cvt_pk_bf16_f32 v32, v36, v37
	v_cvt_pk_bf16_f32 v33, v38, v39
	v_cvt_pk_bf16_f32 v34, v40, v41
	v_cvt_pk_bf16_f32 v35, v42, v43
	v_max_f32_e32 v24, 0, v24
	v_max_f32_e32 v25, 0, v25
	global_store_dwordx4 v[100:101], v[32:35], off offset:192
	v_max_f32_e32 v28, v28, v28
	v_max_f32_e32 v29, v29, v29
	v_mul_f32_e32 v34, v24, v24
	v_mul_f32_e32 v35, v25, v25
	v_max_f32_e32 v25, v26, v26
	v_add_u32_e32 v32, s33, v84
	v_max_f32_e32 v24, v30, v30
	v_max_f32_e32 v26, 0, v25
	v_max_f32_e32 v25, v31, v31
	v_max_f32_e32 v27, v27, v27
	v_mfma_f32_16x16x32_bf16 v[20:23], v[94:97], v[134:137], v[20:23]
	v_mad_i64_i32 v[32:33], s[34:35], v32, s29, v[98:99]
	v_max_f32_e32 v28, 0, v28
	v_max_f32_e32 v29, 0, v29
	v_max_f32_e32 v24, 0, v24
	v_max_f32_e32 v25, 0, v25
	v_max_f32_e32 v27, 0, v27
	v_lshl_add_u64 v[32:33], v[32:33], 0, s[26:27]
	v_mul_f32_e32 v28, v28, v28
	v_mul_f32_e32 v29, v29, v29
	v_mul_f32_e32 v30, v24, v24
	v_mul_f32_e32 v31, v25, v25
	v_mul_f32_e32 v36, v26, v26
	v_mul_f32_e32 v37, v27, v27
	v_max_f32_e32 v12, v12, v12
	v_max_f32_e32 v13, v13, v13
	v_mfma_f32_16x16x32_bf16 v[4:7], v[158:161], v[134:137], v[4:7]
	v_lshl_add_u64 v[32:33], v[32:33], 0, v[64:65]
	v_cvt_pk_bf16_f32 v24, v28, v29
	v_cvt_pk_bf16_f32 v25, v30, v31
	v_cvt_pk_bf16_f32 v26, v34, v35
	v_cvt_pk_bf16_f32 v27, v36, v37
	v_max_f32_e32 v12, 0, v12
	v_max_f32_e32 v13, 0, v13
	global_store_dwordx4 v[32:33], v[24:27], off
	v_max_f32_e32 v20, v20, v20
	v_max_f32_e32 v21, v21, v21
	v_mul_f32_e32 v24, v12, v12
	v_mul_f32_e32 v25, v13, v13
	v_max_f32_e32 v13, v14, v14
	v_max_f32_e32 v12, v22, v22
	v_max_f32_e32 v14, 0, v13
	v_max_f32_e32 v13, v23, v23
	v_max_f32_e32 v15, v15, v15
	v_mfma_f32_16x16x32_bf16 v[8:11], v[154:157], v[134:137], v[8:11]
	v_max_f32_e32 v20, 0, v20
	v_max_f32_e32 v21, 0, v21
	v_max_f32_e32 v12, 0, v12
	v_max_f32_e32 v13, 0, v13
	v_max_f32_e32 v15, 0, v15
	v_mul_f32_e32 v20, v20, v20
	v_mul_f32_e32 v21, v21, v21
	v_mul_f32_e32 v22, v12, v12
	v_mul_f32_e32 v23, v13, v13
	v_mul_f32_e32 v26, v14, v14
	v_mul_f32_e32 v27, v15, v15
	v_max_f32_e32 v4, v4, v4
	v_max_f32_e32 v5, v5, v5
	v_cvt_pk_bf16_f32 v12, v20, v21
	v_cvt_pk_bf16_f32 v13, v22, v23
	v_cvt_pk_bf16_f32 v14, v24, v25
	v_cvt_pk_bf16_f32 v15, v26, v27
	v_max_f32_e32 v4, 0, v4
	v_max_f32_e32 v5, 0, v5
	global_store_dwordx4 v[32:33], v[12:15], off offset:64
	v_mfma_f32_16x16x32_bf16 v[0:3], v[74:77], v[134:137], v[0:3]
	v_max_f32_e32 v8, v8, v8
	v_mul_f32_e32 v12, v4, v4
	v_mul_f32_e32 v13, v5, v5
	v_max_f32_e32 v5, v6, v6
	v_mfma_f32_16x16x32_bf16 v[16:19], v[162:165], v[134:137], v[16:19]
	v_max_f32_e32 v9, v9, v9
	v_max_f32_e32 v4, v10, v10
	v_max_f32_e32 v6, 0, v5
	v_max_f32_e32 v5, v11, v11
	v_max_f32_e32 v7, v7, v7
	v_max_f32_e32 v8, 0, v8
	v_max_f32_e32 v9, 0, v9
	v_max_f32_e32 v4, 0, v4
	v_max_f32_e32 v5, 0, v5
	v_max_f32_e32 v7, 0, v7
	v_mul_f32_e32 v8, v8, v8
	v_mul_f32_e32 v9, v9, v9
	v_mul_f32_e32 v10, v4, v4
	v_mul_f32_e32 v11, v5, v5
	v_mul_f32_e32 v14, v6, v6
	v_mul_f32_e32 v15, v7, v7
	v_cvt_pk_bf16_f32 v4, v8, v9
	v_cvt_pk_bf16_f32 v5, v10, v11
	v_cvt_pk_bf16_f32 v6, v12, v13
	v_cvt_pk_bf16_f32 v7, v14, v15
	global_store_dwordx4 v[32:33], v[4:7], off offset:128
	v_max_f32_e32 v0, v0, v0
	v_max_f32_e32 v1, v1, v1
	v_max_f32_e32 v4, v16, v16
	v_max_f32_e32 v5, v17, v17
	v_max_f32_e32 v2, v2, v2
	v_max_f32_e32 v6, v18, v18
	v_max_f32_e32 v3, v3, v3
	v_max_f32_e32 v7, v19, v19
	v_max_f32_e32 v0, 0, v0
	v_max_f32_e32 v4, 0, v4
	v_max_f32_e32 v1, 0, v1
	v_max_f32_e32 v5, 0, v5
	v_max_f32_e32 v2, 0, v2
	v_max_f32_e32 v6, 0, v6
	v_max_f32_e32 v3, 0, v3
	v_max_f32_e32 v7, 0, v7
	v_mul_f32_e32 v0, v0, v0
	v_mul_f32_e32 v1, v1, v1
	v_mul_f32_e32 v4, v4, v4
	v_mul_f32_e32 v5, v5, v5
	v_mul_f32_e32 v2, v2, v2
	v_mul_f32_e32 v3, v3, v3
	v_mul_f32_e32 v6, v6, v6
	v_mul_f32_e32 v7, v7, v7
	v_cvt_pk_bf16_f32 v0, v0, v1
	v_cvt_pk_bf16_f32 v1, v2, v3
	v_cvt_pk_bf16_f32 v2, v4, v5
	v_cvt_pk_bf16_f32 v3, v6, v7
	global_store_dwordx4 v[32:33], v[0:3], off offset:192
	s_cbranch_scc0 .LBB0_1754

.LBB0_1898:
	global_load_dwordx4 v[12:15], v[4:5], off offset:-3072
	global_load_dwordx4 v[16:19], v[4:5], off offset:-2048
	global_load_dwordx4 v[20:23], v[4:5], off offset:-1024
	global_load_dwordx4 v[24:27], v[4:5], off
	global_load_dwordx4 v[28:31], v[2:3], off
	v_add_u32_e32 v0, s2, v0
	s_waitcnt vmcnt(4)
	v_mov_b32_e32 v34, v13
	s_waitcnt vmcnt(3)
	v_mov_b32_e32 v35, v17
	v_mov_b32_e32 v32, v12
	v_mov_b32_e32 v33, v16
	s_waitcnt vmcnt(2)
	v_mov_b32_e32 v42, v21
	s_waitcnt vmcnt(1)
	v_mov_b32_e32 v43, v25
	v_mul_f32_e32 v34, v34, v34
	v_mul_f32_e32 v35, v35, v35
	v_mov_b32_e32 v36, v14
	v_mov_b32_e32 v37, v18
	v_mov_b32_e32 v40, v20
	v_mov_b32_e32 v41, v24
	v_mul_f32_e32 v42, v42, v42
	v_mul_f32_e32 v43, v43, v43
	v_fma_f32 v32, v32, v32, v34
	v_fma_f32 v33, v33, v33, v35
	v_mov_b32_e32 v38, v15
	v_mov_b32_e32 v39, v19
	v_mov_b32_e32 v44, v22
	v_mov_b32_e32 v45, v26
	v_fma_f32 v34, v40, v40, v42
	v_fma_f32 v35, v41, v41, v43
	v_fma_f32 v32, v36, v36, v32
	v_fma_f32 v33, v37, v37, v33
	v_mov_b32_e32 v46, v23
	v_mov_b32_e32 v47, v27
	v_fma_f32 v34, v44, v44, v34
	v_fma_f32 v35, v45, v45, v35
	v_fma_f32 v32, v38, v38, v32
	v_fma_f32 v33, v39, v39, v33
	v_fma_f32 v34, v46, v46, v34
	v_fma_f32 v35, v47, v47, v35
	v_add_f32_e32 v32, v32, v33
	v_add_f32_e32 v32, v32, v34
	v_add_f32_e32 v32, v32, v35
	ds_bpermute_b32 v33, v6, v32
	s_waitcnt lgkmcnt(0)
	v_add_f32_e32 v32, v32, v33
	ds_bpermute_b32 v33, v7, v32
	s_waitcnt lgkmcnt(0)
	v_add_f32_e32 v32, v32, v33
	ds_bpermute_b32 v33, v8, v32
	s_waitcnt lgkmcnt(0)
	v_add_f32_e32 v32, v32, v33
	ds_bpermute_b32 v33, v9, v32
	s_waitcnt lgkmcnt(0)
	v_add_f32_e32 v32, v32, v33
	ds_bpermute_b32 v33, v10, v32
	s_waitcnt lgkmcnt(0)
	v_add_f32_e32 v32, v32, v33
	ds_bpermute_b32 v33, v11, v32
	s_waitcnt lgkmcnt(0)
	v_add_f32_e32 v32, v32, v33
	v_fmamk_f32 v32, v32, 0x3a800000, v1
	v_mul_f32_e32 v33, 0x4b800000, v32
	v_cmp_gt_f32_e32 vcc, s3, v32
	s_nop 1
	v_cndmask_b32_e32 v32, v32, v33, vcc
	v_rsq_f32_e32 v32, v32
	s_nop 0
	v_mul_f32_e32 v33, 0x45800000, v32
	v_cndmask_b32_e32 v32, v32, v33, vcc
	v_mul_f32_e32 v12, v12, v32
	v_mul_f32_e32 v13, v13, v32
	v_mul_f32_e32 v14, v14, v32
	v_mul_f32_e32 v15, v15, v32
	s_waitcnt vmcnt(0)
	v_mul_f32_e32 v12, v28, v12
	v_mul_f32_e32 v13, v29, v13
	v_mul_f32_e32 v14, v30, v14
	v_mul_f32_e32 v15, v31, v15
	global_store_dwordx4 v[4:5], v[12:15], off offset:-3072
	global_load_dwordx4 v[12:15], v[2:3], off offset:1024
	v_mul_f32_e32 v18, v18, v32
	v_mul_f32_e32 v19, v19, v32
	v_mul_f32_e32 v16, v16, v32
	v_mul_f32_e32 v17, v17, v32
	v_cmp_lt_i32_e32 vcc, s8, v0
	s_or_b64 s[6:7], vcc, s[6:7]
	s_waitcnt vmcnt(0)
	v_mul_f32_e32 v12, v12, v16
	v_mul_f32_e32 v13, v13, v17
	v_mul_f32_e32 v14, v14, v18
	v_mul_f32_e32 v15, v15, v19
	global_store_dwordx4 v[4:5], v[12:15], off offset:-2048
	global_load_dwordx4 v[12:15], v[2:3], off offset:2048
	v_mul_f32_e32 v16, v22, v32
	v_mul_f32_e32 v17, v23, v32
	v_mul_f32_e32 v18, v20, v32
	v_mul_f32_e32 v19, v21, v32
	s_waitcnt vmcnt(0)
	v_mul_f32_e32 v14, v14, v16
	v_mul_f32_e32 v15, v15, v17
	v_mul_f32_e32 v12, v12, v18
	v_mul_f32_e32 v13, v13, v19
	global_store_dwordx4 v[4:5], v[12:15], off offset:-1024
	global_load_dwordx4 v[12:15], v[2:3], off offset:3072
	v_mul_f32_e32 v16, v26, v32
	v_mul_f32_e32 v17, v27, v32
	v_mul_f32_e32 v18, v24, v32
	v_mul_f32_e32 v19, v25, v32
	s_waitcnt vmcnt(0)
	v_mul_f32_e32 v14, v14, v16
	v_mul_f32_e32 v15, v15, v17
	v_mul_f32_e32 v12, v12, v18
	v_mul_f32_e32 v13, v13, v19
	global_store_dwordx4 v[4:5], v[12:15], off
	v_lshl_add_u64 v[4:5], v[4:5], 0, s[4:5]
	s_andn2_b64 exec, exec, s[6:7]
	s_cbranch_execnz .LBB0_1898

.LBB0_1908:
	v_lshl_add_u64 v[12:13], s[12:13], 0, v[6:7]
	v_add_co_u32_e32 v16, vcc, 0x4510000, v12
	v_lshl_add_u64 v[14:15], s[10:11], 0, v[6:7]
	s_nop 0
	v_addc_co_u32_e32 v17, vcc, 0, v13, vcc
	v_add_co_u32_e32 v18, vcc, 0x4510000, v14
	global_load_ushort v16, v[16:17], off
	s_nop 0
	v_addc_co_u32_e32 v19, vcc, 0, v15, vcc
	v_add_co_u32_e32 v12, vcc, 0x2200000, v12
	global_load_ushort v17, v[18:19], off
	s_nop 0
	v_addc_co_u32_e32 v13, vcc, 0, v13, vcc
	v_add_co_u32_e32 v14, vcc, 0x2200000, v14
	global_load_ushort v18, v[12:13], off
	s_nop 0
	v_addc_co_u32_e32 v15, vcc, 0, v15, vcc
	global_load_ushort v19, v[14:15], off
	s_add_u32 s10, s10, s8
	s_addc_u32 s11, s11, s9
	v_lshl_add_u64 v[10:11], v[10:11], 0, -2
	s_add_u32 s12, s12, s8
	v_cmp_eq_u64_e32 vcc, 0, v[10:11]
	s_addc_u32 s13, s13, s9
	v_lshl_add_u64 v[12:13], v[8:9], 0, s[8:9]
	s_or_b64 s[14:15], vcc, s[14:15]
	s_waitcnt vmcnt(3)
	v_lshlrev_b32_e32 v14, 16, v16
	s_waitcnt vmcnt(2)
	v_lshlrev_b32_e32 v15, 16, v17
	s_waitcnt vmcnt(1)
	v_lshlrev_b32_e32 v16, 16, v18
	s_waitcnt vmcnt(0)
	v_lshlrev_b32_e32 v17, 16, v19
	v_add_f32_e32 v14, v14, v16
	v_add_f32_e32 v15, v15, v17
	global_store_dword v[8:9], v14, off
	global_store_dword v[12:13], v15, off
	v_lshl_add_u64 v[8:9], v[8:9], 0, s[16:17]
	s_andn2_b64 exec, exec, s[14:15]
	s_cbranch_execnz .LBB0_1908
	s_or_b64 exec, exec, s[14:15]
	v_mad_u64_u32 v[0:1], s[10:11], v4, s2, v[0:1]
	v_mul_lo_u32 v6, v4, s3
	v_mul_lo_u32 v7, v5, s2
	v_cmp_ne_u64_e32 vcc, v[2:3], v[4:5]
	v_add3_u32 v1, v7, v1, v6
	v_mov_b64_e32 v[6:7], s[8:9]
	v_mov_b64_e32 v[4:5], s[6:7]
	s_and_b64 s[6:7], vcc, exec
	s_andn2_saveexec_b64 s[0:1], s[0:1]
	s_cbranch_execnz .LBB0_1912
